# v41
# speedup vs baseline: 1.0015x; 1.0015x over previous
.LBB0_189:
	s_add_u32 s36, s34, 0xfffc0080
	s_addc_u32 s37, s35, -1
	s_add_i32 s75, 0, 0x10000
	v_add_u32_e32 v140, s75, v161
	ds_read_b128 v[164:167], v140
	ds_read_b128 v[168:171], v140 offset:1024
	ds_read_b128 v[172:175], v140 offset:2048
	ds_read_b128 v[176:179], v140 offset:3072
	s_cmp_eq_u32 s74, 12
	s_cselect_b32 s39, s25, s37
	s_cselect_b32 s38, s69, s36
	s_cselect_b32 s37, s23, s73
	s_cselect_b32 s36, s70, s71
	s_add_i32 m0, s31, 0xc000
	ds_read_b128 v[180:183], v163
	ds_read_b128 v[184:187], v163 offset:1024
	ds_read_b128 v[188:191], v163 offset:2048
	ds_read_b128 v[192:195], v163 offset:3072
	ds_read_b128 v[196:199], v163 offset:4096
	ds_read_b128 v[200:203], v163 offset:5120
	ds_read_b128 v[204:207], v163 offset:6144
	ds_read_b128 v[208:211], v163 offset:7168
	global_load_lds_dwordx4 v136, s[34:35]
	s_add_i32 m0, s31, 0xe000
	s_nop 0
	global_load_lds_dwordx4 v138, s[34:35]
	s_waitcnt lgkmcnt(8)
	s_barrier
	s_waitcnt lgkmcnt(0)
	v_mfma_f32_16x16x32_bf16 v[124:127], v[164:167], v[180:183], v[124:127]
	v_mfma_f32_16x16x32_bf16 v[120:123], v[172:175], v[180:183], v[120:123]
	v_mfma_f32_16x16x32_bf16 v[116:119], v[164:167], v[188:191], v[116:119]
	v_mfma_f32_16x16x32_bf16 v[108:111], v[172:175], v[188:191], v[108:111]
	v_mfma_f32_16x16x32_bf16 v[100:103], v[164:167], v[196:199], v[100:103]
	v_mfma_f32_16x16x32_bf16 v[92:95], v[172:175], v[196:199], v[92:95]
	v_mfma_f32_16x16x32_bf16 v[84:87], v[164:167], v[204:207], v[84:87]
	v_mfma_f32_16x16x32_bf16 v[76:79], v[172:175], v[204:207], v[76:79]
	v_mfma_f32_16x16x32_bf16 v[124:127], v[168:171], v[184:187], v[124:127]
	v_mfma_f32_16x16x32_bf16 v[120:123], v[176:179], v[184:187], v[120:123]
	v_mfma_f32_16x16x32_bf16 v[116:119], v[168:171], v[192:195], v[116:119]
	v_mfma_f32_16x16x32_bf16 v[108:111], v[176:179], v[192:195], v[108:111]
	v_mfma_f32_16x16x32_bf16 v[100:103], v[168:171], v[200:203], v[100:103]
	v_mfma_f32_16x16x32_bf16 v[92:95], v[176:179], v[200:203], v[92:95]
	v_mfma_f32_16x16x32_bf16 v[84:87], v[168:171], v[208:211], v[84:87]
	v_mfma_f32_16x16x32_bf16 v[76:79], v[176:179], v[208:211], v[76:79]
	s_barrier
	s_add_i32 s78, 0, 0x14000
	v_add_u32_e32 v140, s78, v161
	s_add_i32 s75, s75, s57
	ds_read_b128 v[212:215], v140
	ds_read_b128 v[216:219], v140 offset:1024
	ds_read_b128 v[220:223], v140 offset:2048
	ds_read_b128 v[224:227], v140 offset:3072
	s_add_u32 s98, s36, s14
	s_addc_u32 s99, s37, s15
	s_mov_b32 m0, s75
	s_nop 0
	global_load_lds_dwordx4 v128, s[36:37]
	s_add_i32 m0, s75, 0x2000
	s_nop 0
	global_load_lds_dwordx4 v130, s[36:37]
	s_barrier
	s_waitcnt lgkmcnt(0)
	v_mfma_f32_16x16x32_bf16 v[112:115], v[212:215], v[180:183], v[112:115]
	v_mfma_f32_16x16x32_bf16 v[104:107], v[220:223], v[180:183], v[104:107]
	v_mfma_f32_16x16x32_bf16 v[96:99], v[212:215], v[188:191], v[96:99]
	v_mfma_f32_16x16x32_bf16 v[88:91], v[220:223], v[188:191], v[88:91]
	v_mfma_f32_16x16x32_bf16 v[80:83], v[212:215], v[196:199], v[80:83]
	v_mfma_f32_16x16x32_bf16 v[72:75], v[220:223], v[196:199], v[72:75]
	v_mfma_f32_16x16x32_bf16 v[68:71], v[212:215], v[204:207], v[68:71]
	v_mfma_f32_16x16x32_bf16 v[64:67], v[220:223], v[204:207], v[64:67]
	v_mfma_f32_16x16x32_bf16 v[112:115], v[216:219], v[184:187], v[112:115]
	v_mfma_f32_16x16x32_bf16 v[104:107], v[224:227], v[184:187], v[104:107]
	v_mfma_f32_16x16x32_bf16 v[96:99], v[216:219], v[192:195], v[96:99]
	v_mfma_f32_16x16x32_bf16 v[88:91], v[224:227], v[192:195], v[88:91]
	v_mfma_f32_16x16x32_bf16 v[80:83], v[216:219], v[200:203], v[80:83]
	v_mfma_f32_16x16x32_bf16 v[72:75], v[224:227], v[200:203], v[72:75]
	v_mfma_f32_16x16x32_bf16 v[68:71], v[216:219], v[208:211], v[68:71]
	v_mfma_f32_16x16x32_bf16 v[64:67], v[224:227], v[208:211], v[64:67]
	s_mov_b32 m0, s31
	s_add_u32 s100, s38, s14
	s_addc_u32 s101, s39, s15
	s_barrier
	ds_read_b128 v[180:183], v163 offset:16384
	ds_read_b128 v[184:187], v163 offset:17408
	ds_read_b128 v[188:191], v163 offset:18432
	ds_read_b128 v[192:195], v163 offset:19456
	ds_read_b128 v[196:199], v163 offset:20480
	ds_read_b128 v[200:203], v163 offset:21504
	ds_read_b128 v[204:207], v163 offset:22528
	ds_read_b128 v[208:211], v163 offset:23552
	global_load_lds_dwordx4 v134, s[38:39]
	s_mov_b32 m0, s60
	s_nop 0
	global_load_lds_dwordx4 v132, s[38:39]
	s_barrier
	s_waitcnt lgkmcnt(0)
	v_mfma_f32_16x16x32_bf16 v[60:63], v[164:167], v[180:183], v[60:63]
	v_mfma_f32_16x16x32_bf16 v[56:59], v[172:175], v[180:183], v[56:59]
	v_mfma_f32_16x16x32_bf16 v[52:55], v[164:167], v[188:191], v[52:55]
	v_mfma_f32_16x16x32_bf16 v[44:47], v[172:175], v[188:191], v[44:47]
	v_mfma_f32_16x16x32_bf16 v[36:39], v[164:167], v[196:199], v[36:39]
	v_mfma_f32_16x16x32_bf16 v[28:31], v[172:175], v[196:199], v[28:31]
	v_mfma_f32_16x16x32_bf16 v[20:23], v[164:167], v[204:207], v[20:23]
	v_mfma_f32_16x16x32_bf16 v[12:15], v[172:175], v[204:207], v[12:15]
	v_mfma_f32_16x16x32_bf16 v[60:63], v[168:171], v[184:187], v[60:63]
	v_mfma_f32_16x16x32_bf16 v[56:59], v[176:179], v[184:187], v[56:59]
	v_mfma_f32_16x16x32_bf16 v[52:55], v[168:171], v[192:195], v[52:55]
	v_mfma_f32_16x16x32_bf16 v[44:47], v[176:179], v[192:195], v[44:47]
	v_mfma_f32_16x16x32_bf16 v[36:39], v[168:171], v[200:203], v[36:39]
	v_mfma_f32_16x16x32_bf16 v[28:31], v[176:179], v[200:203], v[28:31]
	v_mfma_f32_16x16x32_bf16 v[20:23], v[168:171], v[208:211], v[20:23]
	v_mfma_f32_16x16x32_bf16 v[12:15], v[176:179], v[208:211], v[12:15]
	s_barrier
	s_add_u32 s76, s36, 0x40000
	s_addc_u32 s77, s37, 0
	s_add_i32 s75, s78, s57
	s_mov_b32 m0, s75
	s_nop 0
	global_load_lds_dwordx4 v128, s[76:77]
	s_add_i32 m0, s75, 0x2000
	s_nop 0
	global_load_lds_dwordx4 v130, s[76:77]
	s_waitcnt vmcnt(6)
	s_barrier
	v_mfma_f32_16x16x32_bf16 v[48:51], v[212:215], v[180:183], v[48:51]
	v_mfma_f32_16x16x32_bf16 v[40:43], v[220:223], v[180:183], v[40:43]
	v_mfma_f32_16x16x32_bf16 v[32:35], v[212:215], v[188:191], v[32:35]
	v_mfma_f32_16x16x32_bf16 v[24:27], v[220:223], v[188:191], v[24:27]
	v_mfma_f32_16x16x32_bf16 v[16:19], v[212:215], v[196:199], v[16:19]
	v_mfma_f32_16x16x32_bf16 v[8:11], v[220:223], v[196:199], v[8:11]
	v_mfma_f32_16x16x32_bf16 v[4:7], v[212:215], v[204:207], v[4:7]
	v_mfma_f32_16x16x32_bf16 v[0:3], v[220:223], v[204:207], v[0:3]
	v_mfma_f32_16x16x32_bf16 v[48:51], v[216:219], v[184:187], v[48:51]
	v_mfma_f32_16x16x32_bf16 v[40:43], v[224:227], v[184:187], v[40:43]
	v_mfma_f32_16x16x32_bf16 v[32:35], v[216:219], v[192:195], v[32:35]
	v_mfma_f32_16x16x32_bf16 v[24:27], v[224:227], v[192:195], v[24:27]
	v_mfma_f32_16x16x32_bf16 v[16:19], v[216:219], v[200:203], v[16:19]
	v_mfma_f32_16x16x32_bf16 v[8:11], v[224:227], v[200:203], v[8:11]
	v_mfma_f32_16x16x32_bf16 v[4:7], v[216:219], v[208:211], v[4:7]
	v_mfma_f32_16x16x32_bf16 v[0:3], v[224:227], v[208:211], v[0:3]
	s_add_i32 s75, 0, 0x18000
	v_add_u32_e32 v176, s75, v161
	s_barrier
	ds_read_b128 v[164:167], v176
	ds_read_b128 v[168:171], v176 offset:1024
	ds_read_b128 v[172:175], v176 offset:2048
	ds_read_b128 v[176:179], v176 offset:3072
	s_add_u32 s38, s38, 0x40000
	s_addc_u32 s39, s39, 0
	s_mov_b32 m0, s61
	ds_read_b128 v[180:183], v163 offset:32768
	ds_read_b128 v[184:187], v163 offset:33792
	ds_read_b128 v[188:191], v163 offset:34816
	ds_read_b128 v[192:195], v163 offset:35840
	ds_read_b128 v[196:199], v163 offset:36864
	ds_read_b128 v[200:203], v163 offset:37888
	ds_read_b128 v[204:207], v163 offset:38912
	ds_read_b128 v[208:211], v163 offset:39936
	global_load_lds_dwordx4 v134, s[38:39]
	s_mov_b32 m0, s62
	s_nop 0
	global_load_lds_dwordx4 v132, s[38:39]
	s_waitcnt lgkmcnt(8)
	s_barrier
	s_waitcnt lgkmcnt(0)
	v_mfma_f32_16x16x32_bf16 v[124:127], v[164:167], v[180:183], v[124:127]
	v_mfma_f32_16x16x32_bf16 v[120:123], v[172:175], v[180:183], v[120:123]
	v_mfma_f32_16x16x32_bf16 v[116:119], v[164:167], v[188:191], v[116:119]
	v_mfma_f32_16x16x32_bf16 v[108:111], v[172:175], v[188:191], v[108:111]
	v_mfma_f32_16x16x32_bf16 v[100:103], v[164:167], v[196:199], v[100:103]
	v_mfma_f32_16x16x32_bf16 v[92:95], v[172:175], v[196:199], v[92:95]
	v_mfma_f32_16x16x32_bf16 v[84:87], v[164:167], v[204:207], v[84:87]
	v_mfma_f32_16x16x32_bf16 v[76:79], v[172:175], v[204:207], v[76:79]
	v_mfma_f32_16x16x32_bf16 v[124:127], v[168:171], v[184:187], v[124:127]
	v_mfma_f32_16x16x32_bf16 v[120:123], v[176:179], v[184:187], v[120:123]
	v_mfma_f32_16x16x32_bf16 v[116:119], v[168:171], v[192:195], v[116:119]
	v_mfma_f32_16x16x32_bf16 v[108:111], v[176:179], v[192:195], v[108:111]
	v_mfma_f32_16x16x32_bf16 v[100:103], v[168:171], v[200:203], v[100:103]
	v_mfma_f32_16x16x32_bf16 v[92:95], v[176:179], v[200:203], v[92:95]
	v_mfma_f32_16x16x32_bf16 v[84:87], v[168:171], v[208:211], v[84:87]
	v_mfma_f32_16x16x32_bf16 v[76:79], v[176:179], v[208:211], v[76:79]
	s_barrier
	s_add_i32 s38, 0, 0x1c000
	s_add_i32 s39, s75, s57
	v_add_u32_e32 v224, s38, v161
	s_mov_b32 m0, s39
	ds_read_b128 v[212:215], v224
	ds_read_b128 v[216:219], v224 offset:1024
	ds_read_b128 v[220:223], v224 offset:2048
	ds_read_b128 v[224:227], v224 offset:3072
	global_load_lds_dwordx4 v128, s[98:99]
	s_add_i32 m0, s39, 0x2000
	s_nop 0
	global_load_lds_dwordx4 v130, s[98:99]
	s_barrier
	s_waitcnt lgkmcnt(0)
	v_mfma_f32_16x16x32_bf16 v[112:115], v[212:215], v[180:183], v[112:115]
	v_mfma_f32_16x16x32_bf16 v[104:107], v[220:223], v[180:183], v[104:107]
	v_mfma_f32_16x16x32_bf16 v[96:99], v[212:215], v[188:191], v[96:99]
	v_mfma_f32_16x16x32_bf16 v[88:91], v[220:223], v[188:191], v[88:91]
	v_mfma_f32_16x16x32_bf16 v[80:83], v[212:215], v[196:199], v[80:83]
	v_mfma_f32_16x16x32_bf16 v[72:75], v[220:223], v[196:199], v[72:75]
	v_mfma_f32_16x16x32_bf16 v[68:71], v[212:215], v[204:207], v[68:71]
	v_mfma_f32_16x16x32_bf16 v[64:67], v[220:223], v[204:207], v[64:67]
	v_mfma_f32_16x16x32_bf16 v[112:115], v[216:219], v[184:187], v[112:115]
	v_mfma_f32_16x16x32_bf16 v[104:107], v[224:227], v[184:187], v[104:107]
	v_mfma_f32_16x16x32_bf16 v[96:99], v[216:219], v[192:195], v[96:99]
	v_mfma_f32_16x16x32_bf16 v[88:91], v[224:227], v[192:195], v[88:91]
	v_mfma_f32_16x16x32_bf16 v[80:83], v[216:219], v[200:203], v[80:83]
	v_mfma_f32_16x16x32_bf16 v[72:75], v[224:227], v[200:203], v[72:75]
	v_mfma_f32_16x16x32_bf16 v[68:71], v[216:219], v[208:211], v[68:71]
	v_mfma_f32_16x16x32_bf16 v[64:67], v[224:227], v[208:211], v[64:67]
	s_mov_b32 m0, s63
	s_barrier
	ds_read_b128 v[180:183], v163 offset:49152
	ds_read_b128 v[184:187], v163 offset:50176
	ds_read_b128 v[188:191], v163 offset:51200
	ds_read_b128 v[192:195], v163 offset:52224
	ds_read_b128 v[196:199], v163 offset:53248
	ds_read_b128 v[200:203], v163 offset:54272
	ds_read_b128 v[204:207], v163 offset:55296
	ds_read_b128 v[208:211], v163 offset:56320
	global_load_lds_dwordx4 v134, s[100:101]
	s_mov_b32 m0, s64
	s_nop 0
	global_load_lds_dwordx4 v132, s[100:101]
	s_barrier
	s_waitcnt lgkmcnt(0)
	v_mfma_f32_16x16x32_bf16 v[60:63], v[164:167], v[180:183], v[60:63]
	v_mfma_f32_16x16x32_bf16 v[56:59], v[172:175], v[180:183], v[56:59]
	v_mfma_f32_16x16x32_bf16 v[52:55], v[164:167], v[188:191], v[52:55]
	v_mfma_f32_16x16x32_bf16 v[44:47], v[172:175], v[188:191], v[44:47]
	v_mfma_f32_16x16x32_bf16 v[36:39], v[164:167], v[196:199], v[36:39]
	v_mfma_f32_16x16x32_bf16 v[28:31], v[172:175], v[196:199], v[28:31]
	v_mfma_f32_16x16x32_bf16 v[20:23], v[164:167], v[204:207], v[20:23]
	v_mfma_f32_16x16x32_bf16 v[12:15], v[172:175], v[204:207], v[12:15]
	v_mfma_f32_16x16x32_bf16 v[60:63], v[168:171], v[184:187], v[60:63]
	v_mfma_f32_16x16x32_bf16 v[56:59], v[176:179], v[184:187], v[56:59]
	v_mfma_f32_16x16x32_bf16 v[52:55], v[168:171], v[192:195], v[52:55]
	v_mfma_f32_16x16x32_bf16 v[44:47], v[176:179], v[192:195], v[44:47]
	v_mfma_f32_16x16x32_bf16 v[36:39], v[168:171], v[200:203], v[36:39]
	v_mfma_f32_16x16x32_bf16 v[28:31], v[176:179], v[200:203], v[28:31]
	v_mfma_f32_16x16x32_bf16 v[20:23], v[168:171], v[208:211], v[20:23]
	v_mfma_f32_16x16x32_bf16 v[12:15], v[176:179], v[208:211], v[12:15]
	s_barrier
	s_add_u32 s36, s36, 0x40080
	s_addc_u32 s37, s37, 0
	s_add_i32 s38, s38, s57
	s_mov_b32 m0, s38
	s_nop 0
	global_load_lds_dwordx4 v128, s[36:37]
	s_add_i32 m0, s38, 0x2000
	s_nop 0
	global_load_lds_dwordx4 v130, s[36:37]
	s_add_i32 s74, s74, 2
	s_add_u32 s34, s34, 0x100
	s_addc_u32 s35, s35, 0
	s_add_u32 s71, s71, 0x100
	s_addc_u32 s73, s73, 0
	s_waitcnt vmcnt(6)
	s_barrier
	v_mfma_f32_16x16x32_bf16 v[48:51], v[212:215], v[180:183], v[48:51]
	v_mfma_f32_16x16x32_bf16 v[40:43], v[220:223], v[180:183], v[40:43]
	v_mfma_f32_16x16x32_bf16 v[32:35], v[212:215], v[188:191], v[32:35]
	v_mfma_f32_16x16x32_bf16 v[24:27], v[220:223], v[188:191], v[24:27]
	v_mfma_f32_16x16x32_bf16 v[16:19], v[212:215], v[196:199], v[16:19]
	v_mfma_f32_16x16x32_bf16 v[8:11], v[220:223], v[196:199], v[8:11]
	v_mfma_f32_16x16x32_bf16 v[4:7], v[212:215], v[204:207], v[4:7]
	v_mfma_f32_16x16x32_bf16 v[0:3], v[220:223], v[204:207], v[0:3]
	v_mfma_f32_16x16x32_bf16 v[48:51], v[216:219], v[184:187], v[48:51]
	v_mfma_f32_16x16x32_bf16 v[40:43], v[224:227], v[184:187], v[40:43]
	v_mfma_f32_16x16x32_bf16 v[32:35], v[216:219], v[192:195], v[32:35]
	v_mfma_f32_16x16x32_bf16 v[24:27], v[224:227], v[192:195], v[24:27]
	v_mfma_f32_16x16x32_bf16 v[16:19], v[216:219], v[200:203], v[16:19]
	v_mfma_f32_16x16x32_bf16 v[8:11], v[224:227], v[200:203], v[8:11]
	v_mfma_f32_16x16x32_bf16 v[4:7], v[216:219], v[208:211], v[4:7]
	v_mfma_f32_16x16x32_bf16 v[0:3], v[224:227], v[208:211], v[0:3]
	s_cmp_gt_u32 s74, 13
	s_barrier
	s_cbranch_scc0 .LBB0_189
	v_lshl_or_b32 v140, s68, 8, v162
	v_lshl_add_u32 v166, s30, 8, v159
	v_ashrrev_i32_e32 v141, 31, v140
	v_lshl_add_u64 v[140:141], v[140:141], 1, s[20:21]
	v_mad_i64_i32 v[164:165], s[34:35], v166, s52, 0
	v_lshl_add_u64 v[164:165], v[164:165], 1, v[140:141]
	v_cvt_pk_bf16_f32 v124, v124, v125
	v_cvt_pk_bf16_f32 v125, v126, v127
	v_cvt_pk_bf16_f32 v126, v120, v121
	v_cvt_pk_bf16_f32 v127, v122, v123
	global_store_dwordx4 v[164:165], v[124:127], off
	v_cvt_pk_bf16_f32 v112, v112, v113
	v_cvt_pk_bf16_f32 v113, v114, v115
	v_cvt_pk_bf16_f32 v114, v104, v105
	v_or_b32_e32 v104, 16, v166
	v_mad_i64_i32 v[104:105], s[34:35], v104, s52, 0
	v_cvt_pk_bf16_f32 v115, v106, v107
	global_store_dwordx4 v[164:165], v[112:115], off offset:256
	s_and_b64 vcc, exec, s[4:5]
	s_mov_b32 s68, s22
	v_lshl_add_u64 v[112:113], v[104:105], 1, v[140:141]
	v_cvt_pk_bf16_f32 v104, v116, v117
	v_cvt_pk_bf16_f32 v105, v118, v119
	v_cvt_pk_bf16_f32 v106, v108, v109
	v_cvt_pk_bf16_f32 v107, v110, v111
	global_store_dwordx4 v[112:113], v[104:107], off
	v_cvt_pk_bf16_f32 v96, v96, v97
	v_cvt_pk_bf16_f32 v97, v98, v99
	v_cvt_pk_bf16_f32 v98, v88, v89
	v_or_b32_e32 v88, 32, v166
	v_mad_i64_i32 v[88:89], s[34:35], v88, s52, 0
	v_cvt_pk_bf16_f32 v99, v90, v91
	global_store_dwordx4 v[112:113], v[96:99], off offset:256
	s_mov_b32 s30, s24
	s_mov_b64 s[36:37], s[28:29]
	v_lshl_add_u64 v[96:97], v[88:89], 1, v[140:141]
	v_cvt_pk_bf16_f32 v88, v100, v101
	v_cvt_pk_bf16_f32 v89, v102, v103
	v_cvt_pk_bf16_f32 v90, v92, v93
	v_cvt_pk_bf16_f32 v91, v94, v95
	global_store_dwordx4 v[96:97], v[88:91], off
	v_cvt_pk_bf16_f32 v80, v80, v81
	v_cvt_pk_bf16_f32 v81, v82, v83
	v_cvt_pk_bf16_f32 v82, v72, v73
	v_or_b32_e32 v72, 48, v166
	v_mad_i64_i32 v[72:73], s[34:35], v72, s52, 0
	v_cvt_pk_bf16_f32 v83, v74, v75
	global_store_dwordx4 v[96:97], v[80:83], off offset:256
	s_nop 1
	v_lshl_add_u64 v[80:81], v[72:73], 1, v[140:141]
	v_cvt_pk_bf16_f32 v72, v84, v85
	v_cvt_pk_bf16_f32 v73, v86, v87
	v_cvt_pk_bf16_f32 v74, v76, v77
	v_cvt_pk_bf16_f32 v75, v78, v79
	global_store_dwordx4 v[80:81], v[72:75], off
	v_cvt_pk_bf16_f32 v68, v68, v69
	v_cvt_pk_bf16_f32 v69, v70, v71
	v_cvt_pk_bf16_f32 v70, v64, v65
	v_add_u32_e32 v64, 0x80, v166
	v_mad_i64_i32 v[64:65], s[34:35], v64, s52, 0
	v_lshl_add_u64 v[64:65], v[64:65], 1, v[140:141]
	v_cvt_pk_bf16_f32 v71, v66, v67
	global_store_dwordx4 v[80:81], v[68:71], off offset:256
	v_cvt_pk_bf16_f32 v60, v60, v61
	v_cvt_pk_bf16_f32 v61, v62, v63
	v_cvt_pk_bf16_f32 v62, v56, v57
	v_cvt_pk_bf16_f32 v63, v58, v59
	global_store_dwordx4 v[64:65], v[60:63], off
	v_cvt_pk_bf16_f32 v48, v48, v49
	v_cvt_pk_bf16_f32 v49, v50, v51
	v_cvt_pk_bf16_f32 v50, v40, v41
	v_add_u32_e32 v40, 0x90, v166
	v_mad_i64_i32 v[40:41], s[34:35], v40, s52, 0
	v_cvt_pk_bf16_f32 v51, v42, v43
	global_store_dwordx4 v[64:65], v[48:51], off offset:256
	s_nop 1
	v_lshl_add_u64 v[48:49], v[40:41], 1, v[140:141]
	v_cvt_pk_bf16_f32 v40, v52, v53
	v_cvt_pk_bf16_f32 v41, v54, v55
	v_cvt_pk_bf16_f32 v42, v44, v45
	v_cvt_pk_bf16_f32 v43, v46, v47
	global_store_dwordx4 v[48:49], v[40:43], off
	v_cvt_pk_bf16_f32 v32, v32, v33
	v_cvt_pk_bf16_f32 v33, v34, v35
	v_cvt_pk_bf16_f32 v34, v24, v25
	v_add_u32_e32 v24, 0xa0, v166
	v_mad_i64_i32 v[24:25], s[34:35], v24, s52, 0
	v_cvt_pk_bf16_f32 v35, v26, v27
	global_store_dwordx4 v[48:49], v[32:35], off offset:256
	s_nop 1
	v_lshl_add_u64 v[32:33], v[24:25], 1, v[140:141]
	v_cvt_pk_bf16_f32 v24, v36, v37
	v_cvt_pk_bf16_f32 v25, v38, v39
	v_cvt_pk_bf16_f32 v26, v28, v29
	v_cvt_pk_bf16_f32 v27, v30, v31
	global_store_dwordx4 v[32:33], v[24:27], off
	v_cvt_pk_bf16_f32 v16, v16, v17
	v_cvt_pk_bf16_f32 v17, v18, v19
	v_cvt_pk_bf16_f32 v18, v8, v9
	v_add_u32_e32 v8, 0xb0, v166
	v_mad_i64_i32 v[8:9], s[34:35], v8, s52, 0
	v_cvt_pk_bf16_f32 v19, v10, v11
	global_store_dwordx4 v[32:33], v[16:19], off offset:256
	s_mov_b64 s[34:35], s[26:27]
	s_nop 0
	v_lshl_add_u64 v[16:17], v[8:9], 1, v[140:141]
	v_cvt_pk_bf16_f32 v8, v20, v21
	v_cvt_pk_bf16_f32 v9, v22, v23
	v_cvt_pk_bf16_f32 v10, v12, v13
	v_cvt_pk_bf16_f32 v11, v14, v15
	global_store_dwordx4 v[16:17], v[8:11], off
	v_cvt_pk_bf16_f32 v4, v4, v5
	v_cvt_pk_bf16_f32 v5, v6, v7
	v_cvt_pk_bf16_f32 v6, v0, v1
	v_cvt_pk_bf16_f32 v7, v2, v3
	global_store_dwordx4 v[16:17], v[4:7], off offset:256
	s_cbranch_vccz .LBB0_186
	s_waitcnt vmcnt(0)
	s_cmpk_gt_u32 s56, 0xff
	s_cbranch_scc1 .LBB0_174
	s_barrier
	s_branch .LBB0_174

.LBB0_203:
	ds_read_b128 v[144:147], v153
	ds_read_b128 v[156:159], v153 offset:1024
	ds_read_b128 v[162:165], v153 offset:2048
	ds_read_b128 v[166:169], v153 offset:3072
	s_add_u32 s26, s24, 0xfffc0080
	s_addc_u32 s27, s25, -1
	s_cmp_eq_u32 s54, 12
	s_cselect_b32 s29, s5, s27
	s_cselect_b32 s28, s17, s26
	s_cselect_b32 s27, s15, s53
	s_cselect_b32 s26, s23, s52
	s_add_i32 m0, s36, 0xc000
	ds_read_b128 v[170:173], v154
	ds_read_b128 v[174:177], v154 offset:1024
	ds_read_b128 v[178:181], v154 offset:2048
	ds_read_b128 v[182:185], v154 offset:3072
	ds_read_b128 v[186:189], v154 offset:4096
	ds_read_b128 v[190:193], v154 offset:5120
	ds_read_b128 v[194:197], v154 offset:6144
	ds_read_b128 v[198:201], v154 offset:7168
	global_load_lds_dwordx4 v136, s[24:25]
	s_add_i32 m0, s36, 0xe000
	s_nop 0
	global_load_lds_dwordx4 v138, s[24:25]
	s_waitcnt lgkmcnt(8)
	s_barrier
	s_waitcnt lgkmcnt(0)
	v_mfma_f32_16x16x32_bf16 v[124:127], v[144:147], v[170:173], v[124:127]
	v_mfma_f32_16x16x32_bf16 v[120:123], v[162:165], v[170:173], v[120:123]
	v_mfma_f32_16x16x32_bf16 v[108:111], v[144:147], v[178:181], v[108:111]
	v_mfma_f32_16x16x32_bf16 v[104:107], v[162:165], v[178:181], v[104:107]
	v_mfma_f32_16x16x32_bf16 v[92:95], v[144:147], v[186:189], v[92:95]
	v_mfma_f32_16x16x32_bf16 v[88:91], v[162:165], v[186:189], v[88:91]
	v_mfma_f32_16x16x32_bf16 v[76:79], v[144:147], v[194:197], v[76:79]
	v_mfma_f32_16x16x32_bf16 v[72:75], v[162:165], v[194:197], v[72:75]
	v_mfma_f32_16x16x32_bf16 v[124:127], v[156:159], v[174:177], v[124:127]
	v_mfma_f32_16x16x32_bf16 v[120:123], v[166:169], v[174:177], v[120:123]
	v_mfma_f32_16x16x32_bf16 v[108:111], v[156:159], v[182:185], v[108:111]
	v_mfma_f32_16x16x32_bf16 v[104:107], v[166:169], v[182:185], v[104:107]
	v_mfma_f32_16x16x32_bf16 v[92:95], v[156:159], v[190:193], v[92:95]
	v_mfma_f32_16x16x32_bf16 v[88:91], v[166:169], v[190:193], v[88:91]
	v_mfma_f32_16x16x32_bf16 v[76:79], v[156:159], v[198:201], v[76:79]
	v_mfma_f32_16x16x32_bf16 v[72:75], v[166:169], v[198:201], v[72:75]
	s_barrier
	s_add_i32 s55, s48, s35
	s_add_u32 s98, s26, s12
	s_addc_u32 s99, s27, s13
	s_mov_b32 m0, s55
	ds_read_b128 v[202:205], v155
	ds_read_b128 v[206:209], v155 offset:1024
	ds_read_b128 v[210:213], v155 offset:2048
	ds_read_b128 v[214:217], v155 offset:3072
	global_load_lds_dwordx4 v130, s[26:27]
	s_add_i32 m0, s55, 0x2000
	s_nop 0
	global_load_lds_dwordx4 v134, s[26:27]
	s_barrier
	s_waitcnt lgkmcnt(0)
	v_mfma_f32_16x16x32_bf16 v[116:119], v[202:205], v[170:173], v[116:119]
	v_mfma_f32_16x16x32_bf16 v[112:115], v[210:213], v[170:173], v[112:115]
	v_mfma_f32_16x16x32_bf16 v[100:103], v[202:205], v[178:181], v[100:103]
	v_mfma_f32_16x16x32_bf16 v[96:99], v[210:213], v[178:181], v[96:99]
	v_mfma_f32_16x16x32_bf16 v[84:87], v[202:205], v[186:189], v[84:87]
	v_mfma_f32_16x16x32_bf16 v[80:83], v[210:213], v[186:189], v[80:83]
	v_mfma_f32_16x16x32_bf16 v[68:71], v[202:205], v[194:197], v[68:71]
	v_mfma_f32_16x16x32_bf16 v[64:67], v[210:213], v[194:197], v[64:67]
	v_mfma_f32_16x16x32_bf16 v[116:119], v[206:209], v[174:177], v[116:119]
	v_mfma_f32_16x16x32_bf16 v[112:115], v[214:217], v[174:177], v[112:115]
	v_mfma_f32_16x16x32_bf16 v[100:103], v[206:209], v[182:185], v[100:103]
	v_mfma_f32_16x16x32_bf16 v[96:99], v[214:217], v[182:185], v[96:99]
	v_mfma_f32_16x16x32_bf16 v[84:87], v[206:209], v[190:193], v[84:87]
	v_mfma_f32_16x16x32_bf16 v[80:83], v[214:217], v[190:193], v[80:83]
	v_mfma_f32_16x16x32_bf16 v[68:71], v[206:209], v[198:201], v[68:71]
	v_mfma_f32_16x16x32_bf16 v[64:67], v[214:217], v[198:201], v[64:67]
	s_mov_b32 m0, s36
	s_add_u32 s100, s28, s12
	s_addc_u32 s101, s29, s13
	s_barrier
	ds_read_b128 v[170:173], v154 offset:16384
	ds_read_b128 v[174:177], v154 offset:17408
	ds_read_b128 v[178:181], v154 offset:18432
	ds_read_b128 v[182:185], v154 offset:19456
	ds_read_b128 v[186:189], v154 offset:20480
	ds_read_b128 v[190:193], v154 offset:21504
	ds_read_b128 v[194:197], v154 offset:22528
	ds_read_b128 v[198:201], v154 offset:23552
	global_load_lds_dwordx4 v128, s[28:29]
	s_mov_b32 m0, s37
	s_nop 0
	global_load_lds_dwordx4 v132, s[28:29]
	s_barrier
	s_waitcnt lgkmcnt(0)
	v_mfma_f32_16x16x32_bf16 v[60:63], v[144:147], v[170:173], v[60:63]
	v_mfma_f32_16x16x32_bf16 v[56:59], v[162:165], v[170:173], v[56:59]
	v_mfma_f32_16x16x32_bf16 v[44:47], v[144:147], v[178:181], v[44:47]
	v_mfma_f32_16x16x32_bf16 v[40:43], v[162:165], v[178:181], v[40:43]
	v_mfma_f32_16x16x32_bf16 v[28:31], v[144:147], v[186:189], v[28:31]
	v_mfma_f32_16x16x32_bf16 v[24:27], v[162:165], v[186:189], v[24:27]
	v_mfma_f32_16x16x32_bf16 v[12:15], v[144:147], v[194:197], v[12:15]
	v_mfma_f32_16x16x32_bf16 v[8:11], v[162:165], v[194:197], v[8:11]
	v_mfma_f32_16x16x32_bf16 v[60:63], v[156:159], v[174:177], v[60:63]
	v_mfma_f32_16x16x32_bf16 v[56:59], v[166:169], v[174:177], v[56:59]
	v_mfma_f32_16x16x32_bf16 v[44:47], v[156:159], v[182:185], v[44:47]
	v_mfma_f32_16x16x32_bf16 v[40:43], v[166:169], v[182:185], v[40:43]
	v_mfma_f32_16x16x32_bf16 v[28:31], v[156:159], v[190:193], v[28:31]
	v_mfma_f32_16x16x32_bf16 v[24:27], v[166:169], v[190:193], v[24:27]
	v_mfma_f32_16x16x32_bf16 v[12:15], v[156:159], v[198:201], v[12:15]
	v_mfma_f32_16x16x32_bf16 v[8:11], v[166:169], v[198:201], v[8:11]
	s_barrier
	s_add_u32 s56, s26, 0x40000
	s_addc_u32 s57, s27, 0
	s_add_i32 s55, s49, s35
	s_mov_b32 m0, s55
	s_nop 0
	global_load_lds_dwordx4 v130, s[56:57]
	s_add_i32 m0, s55, 0x2000
	s_nop 0
	global_load_lds_dwordx4 v134, s[56:57]
	s_waitcnt vmcnt(6)
	s_barrier
	v_mfma_f32_16x16x32_bf16 v[52:55], v[202:205], v[170:173], v[52:55]
	v_mfma_f32_16x16x32_bf16 v[48:51], v[210:213], v[170:173], v[48:51]
	v_mfma_f32_16x16x32_bf16 v[36:39], v[202:205], v[178:181], v[36:39]
	v_mfma_f32_16x16x32_bf16 v[32:35], v[210:213], v[178:181], v[32:35]
	v_mfma_f32_16x16x32_bf16 v[20:23], v[202:205], v[186:189], v[20:23]
	v_mfma_f32_16x16x32_bf16 v[16:19], v[210:213], v[186:189], v[16:19]
	v_mfma_f32_16x16x32_bf16 v[4:7], v[202:205], v[194:197], v[4:7]
	v_mfma_f32_16x16x32_bf16 v[0:3], v[210:213], v[194:197], v[0:3]
	v_mfma_f32_16x16x32_bf16 v[52:55], v[206:209], v[174:177], v[52:55]
	v_mfma_f32_16x16x32_bf16 v[48:51], v[214:217], v[174:177], v[48:51]
	v_mfma_f32_16x16x32_bf16 v[36:39], v[206:209], v[182:185], v[36:39]
	v_mfma_f32_16x16x32_bf16 v[32:35], v[214:217], v[182:185], v[32:35]
	v_mfma_f32_16x16x32_bf16 v[20:23], v[206:209], v[190:193], v[20:23]
	v_mfma_f32_16x16x32_bf16 v[16:19], v[214:217], v[190:193], v[16:19]
	v_mfma_f32_16x16x32_bf16 v[4:7], v[206:209], v[198:201], v[4:7]
	v_mfma_f32_16x16x32_bf16 v[0:3], v[214:217], v[198:201], v[0:3]
	s_add_i32 s55, 0, 0x18000
	v_add_u32_e32 v161, s55, v151
	s_barrier
	ds_read_b128 v[144:147], v161
	ds_read_b128 v[156:159], v161 offset:1024
	ds_read_b128 v[162:165], v161 offset:2048
	ds_read_b128 v[166:169], v161 offset:3072
	s_add_u32 s28, s28, 0x40000
	s_addc_u32 s29, s29, 0
	s_mov_b32 m0, s38
	ds_read_b128 v[170:173], v154 offset:32768
	ds_read_b128 v[174:177], v154 offset:33792
	ds_read_b128 v[178:181], v154 offset:34816
	ds_read_b128 v[182:185], v154 offset:35840
	ds_read_b128 v[186:189], v154 offset:36864
	ds_read_b128 v[190:193], v154 offset:37888
	ds_read_b128 v[194:197], v154 offset:38912
	ds_read_b128 v[198:201], v154 offset:39936
	global_load_lds_dwordx4 v128, s[28:29]
	s_mov_b32 m0, s39
	s_nop 0
	global_load_lds_dwordx4 v132, s[28:29]
	s_waitcnt lgkmcnt(8)
	s_barrier
	s_waitcnt lgkmcnt(0)
	v_mfma_f32_16x16x32_bf16 v[124:127], v[144:147], v[170:173], v[124:127]
	v_mfma_f32_16x16x32_bf16 v[120:123], v[162:165], v[170:173], v[120:123]
	v_mfma_f32_16x16x32_bf16 v[108:111], v[144:147], v[178:181], v[108:111]
	v_mfma_f32_16x16x32_bf16 v[104:107], v[162:165], v[178:181], v[104:107]
	v_mfma_f32_16x16x32_bf16 v[92:95], v[144:147], v[186:189], v[92:95]
	v_mfma_f32_16x16x32_bf16 v[88:91], v[162:165], v[186:189], v[88:91]
	v_mfma_f32_16x16x32_bf16 v[76:79], v[144:147], v[194:197], v[76:79]
	v_mfma_f32_16x16x32_bf16 v[72:75], v[162:165], v[194:197], v[72:75]
	v_mfma_f32_16x16x32_bf16 v[124:127], v[156:159], v[174:177], v[124:127]
	v_mfma_f32_16x16x32_bf16 v[120:123], v[166:169], v[174:177], v[120:123]
	v_mfma_f32_16x16x32_bf16 v[108:111], v[156:159], v[182:185], v[108:111]
	v_mfma_f32_16x16x32_bf16 v[104:107], v[166:169], v[182:185], v[104:107]
	v_mfma_f32_16x16x32_bf16 v[92:95], v[156:159], v[190:193], v[92:95]
	v_mfma_f32_16x16x32_bf16 v[88:91], v[166:169], v[190:193], v[88:91]
	v_mfma_f32_16x16x32_bf16 v[76:79], v[156:159], v[198:201], v[76:79]
	v_mfma_f32_16x16x32_bf16 v[72:75], v[166:169], v[198:201], v[72:75]
	s_barrier
	s_add_i32 s28, 0, 0x1c000
	s_add_i32 s29, s55, s35
	v_add_u32_e32 v161, s28, v151
	s_mov_b32 m0, s29
	ds_read_b128 v[202:205], v161
	ds_read_b128 v[206:209], v161 offset:1024
	ds_read_b128 v[210:213], v161 offset:2048
	ds_read_b128 v[214:217], v161 offset:3072
	global_load_lds_dwordx4 v130, s[98:99]
	s_add_i32 m0, s29, 0x2000
	s_nop 0
	global_load_lds_dwordx4 v134, s[98:99]
	s_barrier
	s_waitcnt lgkmcnt(0)
	v_mfma_f32_16x16x32_bf16 v[116:119], v[202:205], v[170:173], v[116:119]
	v_mfma_f32_16x16x32_bf16 v[112:115], v[210:213], v[170:173], v[112:115]
	v_mfma_f32_16x16x32_bf16 v[100:103], v[202:205], v[178:181], v[100:103]
	v_mfma_f32_16x16x32_bf16 v[96:99], v[210:213], v[178:181], v[96:99]
	v_mfma_f32_16x16x32_bf16 v[84:87], v[202:205], v[186:189], v[84:87]
	v_mfma_f32_16x16x32_bf16 v[80:83], v[210:213], v[186:189], v[80:83]
	v_mfma_f32_16x16x32_bf16 v[68:71], v[202:205], v[194:197], v[68:71]
	v_mfma_f32_16x16x32_bf16 v[64:67], v[210:213], v[194:197], v[64:67]
	v_mfma_f32_16x16x32_bf16 v[116:119], v[206:209], v[174:177], v[116:119]
	v_mfma_f32_16x16x32_bf16 v[112:115], v[214:217], v[174:177], v[112:115]
	v_mfma_f32_16x16x32_bf16 v[100:103], v[206:209], v[182:185], v[100:103]
	v_mfma_f32_16x16x32_bf16 v[96:99], v[214:217], v[182:185], v[96:99]
	v_mfma_f32_16x16x32_bf16 v[84:87], v[206:209], v[190:193], v[84:87]
	v_mfma_f32_16x16x32_bf16 v[80:83], v[214:217], v[190:193], v[80:83]
	v_mfma_f32_16x16x32_bf16 v[68:71], v[206:209], v[198:201], v[68:71]
	v_mfma_f32_16x16x32_bf16 v[64:67], v[214:217], v[198:201], v[64:67]
	s_mov_b32 m0, s44
	s_barrier
	ds_read_b128 v[170:173], v154 offset:49152
	ds_read_b128 v[174:177], v154 offset:50176
	ds_read_b128 v[178:181], v154 offset:51200
	ds_read_b128 v[182:185], v154 offset:52224
	ds_read_b128 v[186:189], v154 offset:53248
	ds_read_b128 v[190:193], v154 offset:54272
	ds_read_b128 v[194:197], v154 offset:55296
	ds_read_b128 v[198:201], v154 offset:56320
	global_load_lds_dwordx4 v128, s[100:101]
	s_mov_b32 m0, s46
	s_nop 0
	global_load_lds_dwordx4 v132, s[100:101]
	s_barrier
	s_waitcnt lgkmcnt(0)
	v_mfma_f32_16x16x32_bf16 v[60:63], v[144:147], v[170:173], v[60:63]
	v_mfma_f32_16x16x32_bf16 v[56:59], v[162:165], v[170:173], v[56:59]
	v_mfma_f32_16x16x32_bf16 v[44:47], v[144:147], v[178:181], v[44:47]
	v_mfma_f32_16x16x32_bf16 v[40:43], v[162:165], v[178:181], v[40:43]
	v_mfma_f32_16x16x32_bf16 v[28:31], v[144:147], v[186:189], v[28:31]
	v_mfma_f32_16x16x32_bf16 v[24:27], v[162:165], v[186:189], v[24:27]
	v_mfma_f32_16x16x32_bf16 v[12:15], v[144:147], v[194:197], v[12:15]
	v_mfma_f32_16x16x32_bf16 v[8:11], v[162:165], v[194:197], v[8:11]
	v_mfma_f32_16x16x32_bf16 v[60:63], v[156:159], v[174:177], v[60:63]
	v_mfma_f32_16x16x32_bf16 v[56:59], v[166:169], v[174:177], v[56:59]
	v_mfma_f32_16x16x32_bf16 v[44:47], v[156:159], v[182:185], v[44:47]
	v_mfma_f32_16x16x32_bf16 v[40:43], v[166:169], v[182:185], v[40:43]
	v_mfma_f32_16x16x32_bf16 v[28:31], v[156:159], v[190:193], v[28:31]
	v_mfma_f32_16x16x32_bf16 v[24:27], v[166:169], v[190:193], v[24:27]
	v_mfma_f32_16x16x32_bf16 v[12:15], v[156:159], v[198:201], v[12:15]
	v_mfma_f32_16x16x32_bf16 v[8:11], v[166:169], v[198:201], v[8:11]
	s_barrier
	s_add_u32 s26, s26, 0x40080
	s_addc_u32 s27, s27, 0
	s_add_i32 s28, s28, s35
	s_mov_b32 m0, s28
	s_nop 0
	global_load_lds_dwordx4 v130, s[26:27]
	s_add_i32 m0, s28, 0x2000
	s_nop 0
	global_load_lds_dwordx4 v134, s[26:27]
	s_add_i32 s54, s54, 2
	s_add_u32 s24, s24, 0x100
	s_addc_u32 s25, s25, 0
	s_add_u32 s52, s52, 0x100
	s_addc_u32 s53, s53, 0
	s_waitcnt vmcnt(6)
	s_barrier
	v_mfma_f32_16x16x32_bf16 v[52:55], v[202:205], v[170:173], v[52:55]
	v_mfma_f32_16x16x32_bf16 v[48:51], v[210:213], v[170:173], v[48:51]
	v_mfma_f32_16x16x32_bf16 v[36:39], v[202:205], v[178:181], v[36:39]
	v_mfma_f32_16x16x32_bf16 v[32:35], v[210:213], v[178:181], v[32:35]
	v_mfma_f32_16x16x32_bf16 v[20:23], v[202:205], v[186:189], v[20:23]
	v_mfma_f32_16x16x32_bf16 v[16:19], v[210:213], v[186:189], v[16:19]
	v_mfma_f32_16x16x32_bf16 v[4:7], v[202:205], v[194:197], v[4:7]
	v_mfma_f32_16x16x32_bf16 v[0:3], v[210:213], v[194:197], v[0:3]
	v_mfma_f32_16x16x32_bf16 v[52:55], v[206:209], v[174:177], v[52:55]
	v_mfma_f32_16x16x32_bf16 v[48:51], v[214:217], v[174:177], v[48:51]
	v_mfma_f32_16x16x32_bf16 v[36:39], v[206:209], v[182:185], v[36:39]
	v_mfma_f32_16x16x32_bf16 v[32:35], v[214:217], v[182:185], v[32:35]
	v_mfma_f32_16x16x32_bf16 v[20:23], v[206:209], v[190:193], v[20:23]
	v_mfma_f32_16x16x32_bf16 v[16:19], v[214:217], v[190:193], v[16:19]
	v_mfma_f32_16x16x32_bf16 v[4:7], v[206:209], v[198:201], v[4:7]
	v_mfma_f32_16x16x32_bf16 v[0:3], v[214:217], v[198:201], v[0:3]
	s_cmp_gt_u32 s54, 13
	s_barrier
	s_cbranch_scc0 .LBB0_203
	v_lshl_or_b32 v148, s22, 8, v152
	v_cmp_lt_i32_e32 vcc, s50, v148
	s_and_saveexec_b64 s[22:23], vcc
	s_cbranch_execz .LBB0_206
	v_mul_f32_e32 v149, 0x3d372713, v126
	v_mul_f32_e32 v145, 0x3d372713, v120
	v_mul_f32_e32 v149, v126, v149
	v_mul_f32_e32 v156, 0x3d372713, v122
	v_mul_f32_e32 v145, v120, v145
	v_mul_f32_e32 v146, 0x3d372713, v125
	v_fma_f32 v149, v126, v149, v126
	v_mul_f32_e32 v156, v122, v156
	v_fma_f32 v145, v120, v145, v120
	v_mul_f32_e32 v146, v125, v146
	v_mul_f32_e32 v149, 0xc0135761, v149
	v_fma_f32 v156, v122, v156, v122
	v_mul_f32_e32 v145, 0xc0135761, v145
	v_fma_f32 v146, v125, v146, v125
	v_exp_f32_e32 v149, v149
	v_mul_f32_e32 v156, 0xc0135761, v156
	v_exp_f32_e32 v145, v145
	v_mul_f32_e32 v146, 0xc0135761, v146
	v_exp_f32_e32 v157, v156
	v_exp_f32_e32 v147, v146
	v_add_f32_e32 v149, 1.0, v149
	v_add_f32_e32 v145, 1.0, v145
	v_rcp_f32_e32 v156, v149
	v_add_f32_e32 v149, 1.0, v157
	v_mul_f32_e32 v157, 0x3d372713, v127
	v_mul_f32_e32 v144, 0x3d372713, v124
	v_rcp_f32_e32 v146, v145
	v_add_f32_e32 v145, 1.0, v147
	v_mul_f32_e32 v147, 0x3d372713, v121
	v_mul_f32_e32 v157, v127, v157
	v_mul_f32_e32 v158, 0x3d372713, v123
	v_mul_f32_e32 v144, v124, v144
	v_mul_f32_e32 v147, v121, v147
	v_fma_f32 v157, v127, v157, v127
	v_mul_f32_e32 v158, v123, v158
	v_fma_f32 v144, v124, v144, v124
	v_fma_f32 v147, v121, v147, v121
	v_mul_f32_e32 v157, 0xc0135761, v157
	v_fma_f32 v158, v123, v158, v123
	v_mul_f32_e32 v144, 0xc0135761, v144
	v_mul_f32_e32 v147, 0xc0135761, v147
	v_exp_f32_e32 v157, v157
	v_mul_f32_e32 v158, 0xc0135761, v158
	v_exp_f32_e32 v144, v144
	v_exp_f32_e32 v147, v147
	v_exp_f32_e32 v159, v158
	v_rcp_f32_e32 v158, v149
	v_add_f32_e32 v149, 1.0, v157
	v_add_f32_e32 v144, 1.0, v144
	v_add_f32_e32 v147, 1.0, v147
	v_rcp_f32_e32 v157, v149
	v_add_f32_e32 v149, 1.0, v159
	v_rcp_f32_e32 v144, v144
	v_rcp_f32_e32 v145, v145
	v_rcp_f32_e32 v159, v149
	v_rcp_f32_e32 v147, v147
	v_pk_mul_f32 v[126:127], v[126:127], v[156:157]
	v_pk_mul_f32 v[124:125], v[124:125], v[144:145]
	v_pk_mul_f32 v[122:123], v[122:123], v[158:159]
	v_pk_mul_f32 v[120:121], v[120:121], v[146:147]

.LBB0_321:
	ds_read_b128 v[144:147], v157
	ds_read_b128 v[148:151], v157 offset:1024
	ds_read_b128 v[164:167], v157 offset:2048
	ds_read_b128 v[168:171], v157 offset:3072
	s_add_u32 s4, s8, 0x100
	s_addc_u32 s5, s9, 0
	s_cmp_eq_u32 s60, 2
	s_cselect_b32 s11, s29, s5
	s_cselect_b32 s10, s28, s4
	s_cselect_b32 s7, s31, s37
	s_cselect_b32 s6, s30, s35
	s_add_i32 m0, s46, 0xc000
	ds_read_b128 v[172:175], v158
	ds_read_b128 v[176:179], v158 offset:1024
	ds_read_b128 v[180:183], v158 offset:2048
	ds_read_b128 v[184:187], v158 offset:3072
	ds_read_b128 v[188:191], v158 offset:4096
	ds_read_b128 v[192:195], v158 offset:5120
	ds_read_b128 v[196:199], v158 offset:6144
	ds_read_b128 v[200:203], v158 offset:7168
	global_load_lds_dwordx4 v136, s[8:9]
	s_add_i32 m0, s46, 0xe000
	s_nop 0
	global_load_lds_dwordx4 v138, s[8:9]
	s_waitcnt lgkmcnt(8)
	s_barrier
	s_waitcnt lgkmcnt(0)
	v_mfma_f32_16x16x32_bf16 v[124:127], v[144:147], v[172:175], v[124:127]
	v_mfma_f32_16x16x32_bf16 v[120:123], v[164:167], v[172:175], v[120:123]
	v_mfma_f32_16x16x32_bf16 v[116:119], v[144:147], v[180:183], v[116:119]
	v_mfma_f32_16x16x32_bf16 v[112:115], v[164:167], v[180:183], v[112:115]
	v_mfma_f32_16x16x32_bf16 v[108:111], v[144:147], v[188:191], v[108:111]
	v_mfma_f32_16x16x32_bf16 v[104:107], v[164:167], v[188:191], v[104:107]
	v_mfma_f32_16x16x32_bf16 v[100:103], v[144:147], v[196:199], v[100:103]
	v_mfma_f32_16x16x32_bf16 v[96:99], v[164:167], v[196:199], v[96:99]
	v_mfma_f32_16x16x32_bf16 v[124:127], v[148:151], v[176:179], v[124:127]
	v_mfma_f32_16x16x32_bf16 v[120:123], v[168:171], v[176:179], v[120:123]
	v_mfma_f32_16x16x32_bf16 v[116:119], v[148:151], v[184:187], v[116:119]
	v_mfma_f32_16x16x32_bf16 v[112:115], v[168:171], v[184:187], v[112:115]
	v_mfma_f32_16x16x32_bf16 v[108:111], v[148:151], v[192:195], v[108:111]
	v_mfma_f32_16x16x32_bf16 v[104:107], v[168:171], v[192:195], v[104:107]
	v_mfma_f32_16x16x32_bf16 v[100:103], v[148:151], v[200:203], v[100:103]
	v_mfma_f32_16x16x32_bf16 v[96:99], v[168:171], v[200:203], v[96:99]
	s_barrier
	s_add_i32 s8, s54, s44
	s_add_u32 s98, s6, s26
	s_addc_u32 s99, s7, s27
	s_mov_b32 m0, s8
	ds_read_b128 v[204:207], v159
	ds_read_b128 v[208:211], v159 offset:1024
	ds_read_b128 v[212:215], v159 offset:2048
	ds_read_b128 v[216:219], v159 offset:3072
	global_load_lds_dwordx4 v130, s[6:7]
	s_add_i32 m0, s8, 0x2000
	s_nop 0
	global_load_lds_dwordx4 v134, s[6:7]
	s_barrier
	s_waitcnt lgkmcnt(0)
	v_mfma_f32_16x16x32_bf16 v[60:63], v[204:207], v[172:175], v[60:63]
	v_mfma_f32_16x16x32_bf16 v[56:59], v[212:215], v[172:175], v[56:59]
	v_mfma_f32_16x16x32_bf16 v[52:55], v[204:207], v[180:183], v[52:55]
	v_mfma_f32_16x16x32_bf16 v[48:51], v[212:215], v[180:183], v[48:51]
	v_mfma_f32_16x16x32_bf16 v[44:47], v[204:207], v[188:191], v[44:47]
	v_mfma_f32_16x16x32_bf16 v[40:43], v[212:215], v[188:191], v[40:43]
	v_mfma_f32_16x16x32_bf16 v[36:39], v[204:207], v[196:199], v[36:39]
	v_mfma_f32_16x16x32_bf16 v[32:35], v[212:215], v[196:199], v[32:35]
	v_mfma_f32_16x16x32_bf16 v[60:63], v[208:211], v[176:179], v[60:63]
	v_mfma_f32_16x16x32_bf16 v[56:59], v[216:219], v[176:179], v[56:59]
	v_mfma_f32_16x16x32_bf16 v[52:55], v[208:211], v[184:187], v[52:55]
	v_mfma_f32_16x16x32_bf16 v[48:51], v[216:219], v[184:187], v[48:51]
	v_mfma_f32_16x16x32_bf16 v[44:47], v[208:211], v[192:195], v[44:47]
	v_mfma_f32_16x16x32_bf16 v[40:43], v[216:219], v[192:195], v[40:43]
	v_mfma_f32_16x16x32_bf16 v[36:39], v[208:211], v[200:203], v[36:39]
	v_mfma_f32_16x16x32_bf16 v[32:35], v[216:219], v[200:203], v[32:35]
	s_mov_b32 m0, s46
	s_add_u32 s100, s10, s26
	s_addc_u32 s101, s11, s27
	s_barrier
	ds_read_b128 v[172:175], v158 offset:16384
	ds_read_b128 v[176:179], v158 offset:17408
	ds_read_b128 v[180:183], v158 offset:18432
	ds_read_b128 v[184:187], v158 offset:19456
	ds_read_b128 v[188:191], v158 offset:20480
	ds_read_b128 v[192:195], v158 offset:21504
	ds_read_b128 v[196:199], v158 offset:22528
	ds_read_b128 v[200:203], v158 offset:23552
	global_load_lds_dwordx4 v128, s[10:11]
	s_mov_b32 m0, s47
	s_nop 0
	global_load_lds_dwordx4 v132, s[10:11]
	s_barrier
	s_waitcnt lgkmcnt(0)
	v_mfma_f32_16x16x32_bf16 v[92:95], v[144:147], v[172:175], v[92:95]
	v_mfma_f32_16x16x32_bf16 v[88:91], v[164:167], v[172:175], v[88:91]
	v_mfma_f32_16x16x32_bf16 v[84:87], v[144:147], v[180:183], v[84:87]
	v_mfma_f32_16x16x32_bf16 v[80:83], v[164:167], v[180:183], v[80:83]
	v_mfma_f32_16x16x32_bf16 v[76:79], v[144:147], v[188:191], v[76:79]
	v_mfma_f32_16x16x32_bf16 v[72:75], v[164:167], v[188:191], v[72:75]
	v_mfma_f32_16x16x32_bf16 v[68:71], v[144:147], v[196:199], v[68:71]
	v_mfma_f32_16x16x32_bf16 v[64:67], v[164:167], v[196:199], v[64:67]
	v_mfma_f32_16x16x32_bf16 v[92:95], v[148:151], v[176:179], v[92:95]
	v_mfma_f32_16x16x32_bf16 v[88:91], v[168:171], v[176:179], v[88:91]
	v_mfma_f32_16x16x32_bf16 v[84:87], v[148:151], v[184:187], v[84:87]
	v_mfma_f32_16x16x32_bf16 v[80:83], v[168:171], v[184:187], v[80:83]
	v_mfma_f32_16x16x32_bf16 v[76:79], v[148:151], v[192:195], v[76:79]
	v_mfma_f32_16x16x32_bf16 v[72:75], v[168:171], v[192:195], v[72:75]
	v_mfma_f32_16x16x32_bf16 v[68:71], v[148:151], v[200:203], v[68:71]
	v_mfma_f32_16x16x32_bf16 v[64:67], v[168:171], v[200:203], v[64:67]
	s_barrier
	s_add_u32 s8, s6, 0x18000
	s_addc_u32 s9, s7, 0
	s_add_i32 s61, s55, s44
	s_mov_b32 m0, s61
	s_nop 0
	global_load_lds_dwordx4 v130, s[8:9]
	s_add_i32 m0, s61, 0x2000
	s_nop 0
	global_load_lds_dwordx4 v134, s[8:9]
	s_waitcnt vmcnt(6)
	s_barrier
	v_mfma_f32_16x16x32_bf16 v[28:31], v[204:207], v[172:175], v[28:31]
	v_mfma_f32_16x16x32_bf16 v[24:27], v[212:215], v[172:175], v[24:27]
	v_mfma_f32_16x16x32_bf16 v[20:23], v[204:207], v[180:183], v[20:23]
	v_mfma_f32_16x16x32_bf16 v[16:19], v[212:215], v[180:183], v[16:19]
	v_mfma_f32_16x16x32_bf16 v[12:15], v[204:207], v[188:191], v[12:15]
	v_mfma_f32_16x16x32_bf16 v[8:11], v[212:215], v[188:191], v[8:11]
	v_mfma_f32_16x16x32_bf16 v[4:7], v[204:207], v[196:199], v[4:7]
	v_mfma_f32_16x16x32_bf16 v[0:3], v[212:215], v[196:199], v[0:3]
	v_mfma_f32_16x16x32_bf16 v[28:31], v[208:211], v[176:179], v[28:31]
	v_mfma_f32_16x16x32_bf16 v[24:27], v[216:219], v[176:179], v[24:27]
	v_mfma_f32_16x16x32_bf16 v[20:23], v[208:211], v[184:187], v[20:23]
	v_mfma_f32_16x16x32_bf16 v[16:19], v[216:219], v[184:187], v[16:19]
	v_mfma_f32_16x16x32_bf16 v[12:15], v[208:211], v[192:195], v[12:15]
	v_mfma_f32_16x16x32_bf16 v[8:11], v[216:219], v[192:195], v[8:11]
	v_mfma_f32_16x16x32_bf16 v[4:7], v[208:211], v[200:203], v[4:7]
	v_mfma_f32_16x16x32_bf16 v[0:3], v[216:219], v[200:203], v[0:3]
	s_add_i32 s61, 0, 0x18000
	v_add_u32_e32 v163, s61, v155
	s_barrier
	ds_read_b128 v[144:147], v163
	ds_read_b128 v[148:151], v163 offset:1024
	ds_read_b128 v[164:167], v163 offset:2048
	ds_read_b128 v[168:171], v163 offset:3072
	s_add_u32 s8, s10, 0x18000
	s_addc_u32 s9, s11, 0
	s_mov_b32 m0, s48
	ds_read_b128 v[172:175], v158 offset:32768
	ds_read_b128 v[176:179], v158 offset:33792
	ds_read_b128 v[180:183], v158 offset:34816
	ds_read_b128 v[184:187], v158 offset:35840
	ds_read_b128 v[188:191], v158 offset:36864
	ds_read_b128 v[192:195], v158 offset:37888
	ds_read_b128 v[196:199], v158 offset:38912
	ds_read_b128 v[200:203], v158 offset:39936
	global_load_lds_dwordx4 v128, s[8:9]
	s_mov_b32 m0, s49
	s_nop 0
	global_load_lds_dwordx4 v132, s[8:9]
	s_waitcnt lgkmcnt(8)
	s_barrier
	s_waitcnt lgkmcnt(0)
	v_mfma_f32_16x16x32_bf16 v[124:127], v[144:147], v[172:175], v[124:127]
	v_mfma_f32_16x16x32_bf16 v[120:123], v[164:167], v[172:175], v[120:123]
	v_mfma_f32_16x16x32_bf16 v[116:119], v[144:147], v[180:183], v[116:119]
	v_mfma_f32_16x16x32_bf16 v[112:115], v[164:167], v[180:183], v[112:115]
	v_mfma_f32_16x16x32_bf16 v[108:111], v[144:147], v[188:191], v[108:111]
	v_mfma_f32_16x16x32_bf16 v[104:107], v[164:167], v[188:191], v[104:107]
	v_mfma_f32_16x16x32_bf16 v[100:103], v[144:147], v[196:199], v[100:103]
	v_mfma_f32_16x16x32_bf16 v[96:99], v[164:167], v[196:199], v[96:99]
	v_mfma_f32_16x16x32_bf16 v[124:127], v[148:151], v[176:179], v[124:127]
	v_mfma_f32_16x16x32_bf16 v[120:123], v[168:171], v[176:179], v[120:123]
	v_mfma_f32_16x16x32_bf16 v[116:119], v[148:151], v[184:187], v[116:119]
	v_mfma_f32_16x16x32_bf16 v[112:115], v[168:171], v[184:187], v[112:115]
	v_mfma_f32_16x16x32_bf16 v[108:111], v[148:151], v[192:195], v[108:111]
	v_mfma_f32_16x16x32_bf16 v[104:107], v[168:171], v[192:195], v[104:107]
	v_mfma_f32_16x16x32_bf16 v[100:103], v[148:151], v[200:203], v[100:103]
	v_mfma_f32_16x16x32_bf16 v[96:99], v[168:171], v[200:203], v[96:99]
	s_barrier
	s_add_i32 s8, 0, 0x1c000
	s_add_i32 s9, s61, s44
	v_add_u32_e32 v163, s8, v155
	s_mov_b32 m0, s9
	ds_read_b128 v[204:207], v163
	ds_read_b128 v[208:211], v163 offset:1024
	ds_read_b128 v[212:215], v163 offset:2048
	ds_read_b128 v[216:219], v163 offset:3072
	global_load_lds_dwordx4 v130, s[98:99]
	s_add_i32 m0, s9, 0x2000
	s_nop 0
	global_load_lds_dwordx4 v134, s[98:99]
	s_barrier
	s_waitcnt lgkmcnt(0)
	v_mfma_f32_16x16x32_bf16 v[60:63], v[204:207], v[172:175], v[60:63]
	v_mfma_f32_16x16x32_bf16 v[56:59], v[212:215], v[172:175], v[56:59]
	v_mfma_f32_16x16x32_bf16 v[52:55], v[204:207], v[180:183], v[52:55]
	v_mfma_f32_16x16x32_bf16 v[48:51], v[212:215], v[180:183], v[48:51]
	v_mfma_f32_16x16x32_bf16 v[44:47], v[204:207], v[188:191], v[44:47]
	v_mfma_f32_16x16x32_bf16 v[40:43], v[212:215], v[188:191], v[40:43]
	v_mfma_f32_16x16x32_bf16 v[36:39], v[204:207], v[196:199], v[36:39]
	v_mfma_f32_16x16x32_bf16 v[32:35], v[212:215], v[196:199], v[32:35]
	v_mfma_f32_16x16x32_bf16 v[60:63], v[208:211], v[176:179], v[60:63]
	v_mfma_f32_16x16x32_bf16 v[56:59], v[216:219], v[176:179], v[56:59]
	v_mfma_f32_16x16x32_bf16 v[52:55], v[208:211], v[184:187], v[52:55]
	v_mfma_f32_16x16x32_bf16 v[48:51], v[216:219], v[184:187], v[48:51]
	v_mfma_f32_16x16x32_bf16 v[44:47], v[208:211], v[192:195], v[44:47]
	v_mfma_f32_16x16x32_bf16 v[40:43], v[216:219], v[192:195], v[40:43]
	v_mfma_f32_16x16x32_bf16 v[36:39], v[208:211], v[200:203], v[36:39]
	v_mfma_f32_16x16x32_bf16 v[32:35], v[216:219], v[200:203], v[32:35]
	s_mov_b32 m0, s51
	s_barrier
	ds_read_b128 v[172:175], v158 offset:49152
	ds_read_b128 v[176:179], v158 offset:50176
	ds_read_b128 v[180:183], v158 offset:51200
	ds_read_b128 v[184:187], v158 offset:52224
	ds_read_b128 v[188:191], v158 offset:53248
	ds_read_b128 v[192:195], v158 offset:54272
	ds_read_b128 v[196:199], v158 offset:55296
	ds_read_b128 v[200:203], v158 offset:56320
	global_load_lds_dwordx4 v128, s[100:101]
	s_mov_b32 m0, s52
	s_nop 0
	global_load_lds_dwordx4 v132, s[100:101]
	s_barrier
	s_waitcnt lgkmcnt(0)
	v_mfma_f32_16x16x32_bf16 v[92:95], v[144:147], v[172:175], v[92:95]
	v_mfma_f32_16x16x32_bf16 v[88:91], v[164:167], v[172:175], v[88:91]
	v_mfma_f32_16x16x32_bf16 v[84:87], v[144:147], v[180:183], v[84:87]
	v_mfma_f32_16x16x32_bf16 v[80:83], v[164:167], v[180:183], v[80:83]
	v_mfma_f32_16x16x32_bf16 v[76:79], v[144:147], v[188:191], v[76:79]
	v_mfma_f32_16x16x32_bf16 v[72:75], v[164:167], v[188:191], v[72:75]
	v_mfma_f32_16x16x32_bf16 v[68:71], v[144:147], v[196:199], v[68:71]
	v_mfma_f32_16x16x32_bf16 v[64:67], v[164:167], v[196:199], v[64:67]
	v_mfma_f32_16x16x32_bf16 v[92:95], v[148:151], v[176:179], v[92:95]
	v_mfma_f32_16x16x32_bf16 v[88:91], v[168:171], v[176:179], v[88:91]
	v_mfma_f32_16x16x32_bf16 v[84:87], v[148:151], v[184:187], v[84:87]
	v_mfma_f32_16x16x32_bf16 v[80:83], v[168:171], v[184:187], v[80:83]
	v_mfma_f32_16x16x32_bf16 v[76:79], v[148:151], v[192:195], v[76:79]
	v_mfma_f32_16x16x32_bf16 v[72:75], v[168:171], v[192:195], v[72:75]
	v_mfma_f32_16x16x32_bf16 v[68:71], v[148:151], v[200:203], v[68:71]
	v_mfma_f32_16x16x32_bf16 v[64:67], v[168:171], v[200:203], v[64:67]
	s_barrier
	s_add_u32 s6, s6, 0x18080
	s_addc_u32 s7, s7, 0
	s_add_i32 s8, s8, s44
	s_mov_b32 m0, s8
	s_nop 0
	global_load_lds_dwordx4 v130, s[6:7]
	s_add_i32 m0, s8, 0x2000
	s_nop 0
	global_load_lds_dwordx4 v134, s[6:7]
	s_add_i32 s60, s60, 2
	s_add_u32 s35, s35, 0x100
	s_addc_u32 s37, s37, 0
	s_mov_b64 s[8:9], s[4:5]
	s_waitcnt vmcnt(6)
	s_barrier
	v_mfma_f32_16x16x32_bf16 v[28:31], v[204:207], v[172:175], v[28:31]
	v_mfma_f32_16x16x32_bf16 v[24:27], v[212:215], v[172:175], v[24:27]
	v_mfma_f32_16x16x32_bf16 v[20:23], v[204:207], v[180:183], v[20:23]
	v_mfma_f32_16x16x32_bf16 v[16:19], v[212:215], v[180:183], v[16:19]
	v_mfma_f32_16x16x32_bf16 v[12:15], v[204:207], v[188:191], v[12:15]
	v_mfma_f32_16x16x32_bf16 v[8:11], v[212:215], v[188:191], v[8:11]
	v_mfma_f32_16x16x32_bf16 v[4:7], v[204:207], v[196:199], v[4:7]
	v_mfma_f32_16x16x32_bf16 v[0:3], v[212:215], v[196:199], v[0:3]
	v_mfma_f32_16x16x32_bf16 v[28:31], v[208:211], v[176:179], v[28:31]
	v_mfma_f32_16x16x32_bf16 v[24:27], v[216:219], v[176:179], v[24:27]
	v_mfma_f32_16x16x32_bf16 v[20:23], v[208:211], v[184:187], v[20:23]
	v_mfma_f32_16x16x32_bf16 v[16:19], v[216:219], v[184:187], v[16:19]
	v_mfma_f32_16x16x32_bf16 v[12:15], v[208:211], v[192:195], v[12:15]
	v_mfma_f32_16x16x32_bf16 v[8:11], v[216:219], v[192:195], v[8:11]
	v_mfma_f32_16x16x32_bf16 v[4:7], v[208:211], v[200:203], v[4:7]
	v_mfma_f32_16x16x32_bf16 v[0:3], v[216:219], v[200:203], v[0:3]
	s_cmp_gt_u32 s60, 3
	s_barrier
	s_cbranch_scc0 .LBB0_321
	s_lshl_b32 s37, s34, 8
	s_ashr_i32 s6, s34, 1
	s_cmp_lt_i32 s6, 2
	s_cselect_b64 s[8:9], -1, 0
	s_cmp_gt_i32 s6, 1
	s_cselect_b64 s[34:35], -1, 0
	s_lshl_b32 s60, s6, 9
	s_add_i32 s61, s60, 0xfffffc00
	v_bitop3_b32 v144, s37, v161, v156 bitop3:0xc8
	v_or_b32_e32 v146, s61, v144
	v_or_b32_e32 v144, s60, v144
	v_mov_b32_e32 v145, 0
	s_cmp_lt_i32 s6, 4
	v_cndmask_b32_e64 v152, v146, v144, s[8:9]
	s_cselect_b64 s[4:5], -1, 0
	s_cmp_gt_i32 s6, 3
	v_ashrrev_i32_e32 v153, 31, v152
	v_mov_b32_e32 v144, v145
	s_cbranch_scc1 .LBB0_330
	s_and_b64 s[10:11], s[8:9], exec
	s_cselect_b32 s7, s21, s23
	s_cselect_b32 s10, s20, s22
	v_mov_b32_e32 v146, s10
	v_mov_b32_e32 v147, s7
	v_lshl_add_u64 v[146:147], v[152:153], 2, v[146:147]
	global_load_dword v144, v[146:147], off
	v_cndmask_b32_e64 v146, 0, 1, s[4:5]
	v_cmp_ne_u32_e64 s[10:11], 1, v146
	s_andn2_b64 vcc, exec, s[4:5]
	s_cbranch_vccz .LBB0_331

.LBB0_583:
	ds_read_b128 v[128:131], v164
	ds_read_b128 v[132:135], v164 offset:1024
	ds_read_b128 v[152:155], v164 offset:2048
	ds_read_b128 v[156:159], v164 offset:3072
	s_add_u32 s38, s36, 0xfffc0080
	s_addc_u32 s39, s37, -1
	s_cmp_eq_u32 s63, 12
	s_cselect_b32 s41, s9, s39
	s_cselect_b32 s40, s29, s38
	s_cselect_b32 s39, s27, s62
	s_cselect_b32 s38, s60, s61
	s_add_i32 m0, s50, 0xc000
	ds_read_b128 v[168:171], v165
	ds_read_b128 v[172:175], v165 offset:1024
	ds_read_b128 v[176:179], v165 offset:2048
	ds_read_b128 v[180:183], v165 offset:3072
	ds_read_b128 v[184:187], v165 offset:4096
	ds_read_b128 v[188:191], v165 offset:5120
	ds_read_b128 v[192:195], v165 offset:6144
	ds_read_b128 v[196:199], v165 offset:7168
	global_load_lds_dwordx4 v144, s[36:37]
	s_add_i32 m0, s50, 0xe000
	s_nop 0
	global_load_lds_dwordx4 v146, s[36:37]
	s_waitcnt lgkmcnt(8)
	s_barrier
	s_waitcnt lgkmcnt(0)
	v_mfma_f32_16x16x32_bf16 v[120:123], v[128:131], v[168:171], v[120:123]
	v_mfma_f32_16x16x32_bf16 v[124:127], v[152:155], v[168:171], v[124:127]
	v_mfma_f32_16x16x32_bf16 v[104:107], v[128:131], v[176:179], v[104:107]
	v_mfma_f32_16x16x32_bf16 v[108:111], v[152:155], v[176:179], v[108:111]
	v_mfma_f32_16x16x32_bf16 v[88:91], v[128:131], v[184:187], v[88:91]
	v_mfma_f32_16x16x32_bf16 v[92:95], v[152:155], v[184:187], v[92:95]
	v_mfma_f32_16x16x32_bf16 v[72:75], v[128:131], v[192:195], v[72:75]
	v_mfma_f32_16x16x32_bf16 v[76:79], v[152:155], v[192:195], v[76:79]
	v_mfma_f32_16x16x32_bf16 v[120:123], v[132:135], v[172:175], v[120:123]
	v_mfma_f32_16x16x32_bf16 v[124:127], v[156:159], v[172:175], v[124:127]
	v_mfma_f32_16x16x32_bf16 v[104:107], v[132:135], v[180:183], v[104:107]
	v_mfma_f32_16x16x32_bf16 v[108:111], v[156:159], v[180:183], v[108:111]
	v_mfma_f32_16x16x32_bf16 v[88:91], v[132:135], v[188:191], v[88:91]
	v_mfma_f32_16x16x32_bf16 v[92:95], v[156:159], v[188:191], v[92:95]
	v_mfma_f32_16x16x32_bf16 v[72:75], v[132:135], v[196:199], v[72:75]
	v_mfma_f32_16x16x32_bf16 v[76:79], v[156:159], v[196:199], v[76:79]
	s_barrier
	s_add_i32 s64, s57, s49
	s_add_u32 s98, s38, s22
	s_addc_u32 s99, s39, s23
	s_mov_b32 m0, s64
	ds_read_b128 v[200:203], v166
	ds_read_b128 v[204:207], v166 offset:1024
	ds_read_b128 v[208:211], v166 offset:2048
	ds_read_b128 v[212:215], v166 offset:3072
	global_load_lds_dwordx4 v138, s[38:39]
	s_add_i32 m0, s64, 0x2000
	s_nop 0
	global_load_lds_dwordx4 v142, s[38:39]
	s_barrier
	s_waitcnt lgkmcnt(0)
	v_mfma_f32_16x16x32_bf16 v[112:115], v[200:203], v[168:171], v[112:115]
	v_mfma_f32_16x16x32_bf16 v[116:119], v[208:211], v[168:171], v[116:119]
	v_mfma_f32_16x16x32_bf16 v[96:99], v[200:203], v[176:179], v[96:99]
	v_mfma_f32_16x16x32_bf16 v[100:103], v[208:211], v[176:179], v[100:103]
	v_mfma_f32_16x16x32_bf16 v[80:83], v[200:203], v[184:187], v[80:83]
	v_mfma_f32_16x16x32_bf16 v[84:87], v[208:211], v[184:187], v[84:87]
	v_mfma_f32_16x16x32_bf16 v[64:67], v[200:203], v[192:195], v[64:67]
	v_mfma_f32_16x16x32_bf16 v[68:71], v[208:211], v[192:195], v[68:71]
	v_mfma_f32_16x16x32_bf16 v[112:115], v[204:207], v[172:175], v[112:115]
	v_mfma_f32_16x16x32_bf16 v[116:119], v[212:215], v[172:175], v[116:119]
	v_mfma_f32_16x16x32_bf16 v[96:99], v[204:207], v[180:183], v[96:99]
	v_mfma_f32_16x16x32_bf16 v[100:103], v[212:215], v[180:183], v[100:103]
	v_mfma_f32_16x16x32_bf16 v[80:83], v[204:207], v[188:191], v[80:83]
	v_mfma_f32_16x16x32_bf16 v[84:87], v[212:215], v[188:191], v[84:87]
	v_mfma_f32_16x16x32_bf16 v[64:67], v[204:207], v[196:199], v[64:67]
	v_mfma_f32_16x16x32_bf16 v[68:71], v[212:215], v[196:199], v[68:71]
	s_mov_b32 m0, s50
	s_add_u32 s100, s40, s22
	s_addc_u32 s101, s41, s23
	s_barrier
	ds_read_b128 v[168:171], v165 offset:16384
	ds_read_b128 v[172:175], v165 offset:17408
	ds_read_b128 v[176:179], v165 offset:18432
	ds_read_b128 v[180:183], v165 offset:19456
	ds_read_b128 v[184:187], v165 offset:20480
	ds_read_b128 v[188:191], v165 offset:21504
	ds_read_b128 v[192:195], v165 offset:22528
	ds_read_b128 v[196:199], v165 offset:23552
	global_load_lds_dwordx4 v136, s[40:41]
	s_mov_b32 m0, s51
	s_nop 0
	global_load_lds_dwordx4 v140, s[40:41]
	s_barrier
	s_waitcnt lgkmcnt(0)
	v_mfma_f32_16x16x32_bf16 v[56:59], v[128:131], v[168:171], v[56:59]
	v_mfma_f32_16x16x32_bf16 v[60:63], v[152:155], v[168:171], v[60:63]
	v_mfma_f32_16x16x32_bf16 v[40:43], v[128:131], v[176:179], v[40:43]
	v_mfma_f32_16x16x32_bf16 v[44:47], v[152:155], v[176:179], v[44:47]
	v_mfma_f32_16x16x32_bf16 v[24:27], v[128:131], v[184:187], v[24:27]
	v_mfma_f32_16x16x32_bf16 v[28:31], v[152:155], v[184:187], v[28:31]
	v_mfma_f32_16x16x32_bf16 v[8:11], v[128:131], v[192:195], v[8:11]
	v_mfma_f32_16x16x32_bf16 v[12:15], v[152:155], v[192:195], v[12:15]
	v_mfma_f32_16x16x32_bf16 v[56:59], v[132:135], v[172:175], v[56:59]
	v_mfma_f32_16x16x32_bf16 v[60:63], v[156:159], v[172:175], v[60:63]
	v_mfma_f32_16x16x32_bf16 v[40:43], v[132:135], v[180:183], v[40:43]
	v_mfma_f32_16x16x32_bf16 v[44:47], v[156:159], v[180:183], v[44:47]
	v_mfma_f32_16x16x32_bf16 v[24:27], v[132:135], v[188:191], v[24:27]
	v_mfma_f32_16x16x32_bf16 v[28:31], v[156:159], v[188:191], v[28:31]
	v_mfma_f32_16x16x32_bf16 v[8:11], v[132:135], v[196:199], v[8:11]
	v_mfma_f32_16x16x32_bf16 v[12:15], v[156:159], v[196:199], v[12:15]
	s_barrier
	s_add_u32 s64, s38, 0x40000
	s_addc_u32 s65, s39, 0
	s_add_i32 s66, s58, s49
	s_mov_b32 m0, s66
	s_nop 0
	global_load_lds_dwordx4 v138, s[64:65]
	s_add_i32 m0, s66, 0x2000
	s_nop 0
	global_load_lds_dwordx4 v142, s[64:65]
	s_waitcnt vmcnt(6)
	s_barrier
	v_mfma_f32_16x16x32_bf16 v[48:51], v[200:203], v[168:171], v[48:51]
	v_mfma_f32_16x16x32_bf16 v[52:55], v[208:211], v[168:171], v[52:55]
	v_mfma_f32_16x16x32_bf16 v[32:35], v[200:203], v[176:179], v[32:35]
	v_mfma_f32_16x16x32_bf16 v[36:39], v[208:211], v[176:179], v[36:39]
	v_mfma_f32_16x16x32_bf16 v[16:19], v[200:203], v[184:187], v[16:19]
	v_mfma_f32_16x16x32_bf16 v[20:23], v[208:211], v[184:187], v[20:23]
	v_mfma_f32_16x16x32_bf16 v[4:7], v[200:203], v[192:195], v[4:7]
	v_mfma_f32_16x16x32_bf16 v[0:3], v[208:211], v[192:195], v[0:3]
	v_mfma_f32_16x16x32_bf16 v[48:51], v[204:207], v[172:175], v[48:51]
	v_mfma_f32_16x16x32_bf16 v[52:55], v[212:215], v[172:175], v[52:55]
	v_mfma_f32_16x16x32_bf16 v[32:35], v[204:207], v[180:183], v[32:35]
	v_mfma_f32_16x16x32_bf16 v[36:39], v[212:215], v[180:183], v[36:39]
	v_mfma_f32_16x16x32_bf16 v[16:19], v[204:207], v[188:191], v[16:19]
	v_mfma_f32_16x16x32_bf16 v[20:23], v[212:215], v[188:191], v[20:23]
	v_mfma_f32_16x16x32_bf16 v[4:7], v[204:207], v[196:199], v[4:7]
	v_mfma_f32_16x16x32_bf16 v[0:3], v[212:215], v[196:199], v[0:3]
	s_add_i32 s64, 0, 0x18000
	v_add_u32_e32 v156, s64, v162
	s_barrier
	ds_read_b128 v[128:131], v156
	ds_read_b128 v[132:135], v156 offset:1024
	ds_read_b128 v[152:155], v156 offset:2048
	ds_read_b128 v[156:159], v156 offset:3072
	s_add_u32 s40, s40, 0x40000
	s_addc_u32 s41, s41, 0
	s_mov_b32 m0, s52
	ds_read_b128 v[168:171], v165 offset:32768
	ds_read_b128 v[172:175], v165 offset:33792
	ds_read_b128 v[176:179], v165 offset:34816
	ds_read_b128 v[180:183], v165 offset:35840
	ds_read_b128 v[184:187], v165 offset:36864
	ds_read_b128 v[188:191], v165 offset:37888
	ds_read_b128 v[192:195], v165 offset:38912
	ds_read_b128 v[196:199], v165 offset:39936
	global_load_lds_dwordx4 v136, s[40:41]
	s_mov_b32 m0, s53
	s_nop 0
	global_load_lds_dwordx4 v140, s[40:41]
	s_waitcnt lgkmcnt(8)
	s_barrier
	s_waitcnt lgkmcnt(0)
	v_mfma_f32_16x16x32_bf16 v[120:123], v[128:131], v[168:171], v[120:123]
	v_mfma_f32_16x16x32_bf16 v[124:127], v[152:155], v[168:171], v[124:127]
	v_mfma_f32_16x16x32_bf16 v[104:107], v[128:131], v[176:179], v[104:107]
	v_mfma_f32_16x16x32_bf16 v[108:111], v[152:155], v[176:179], v[108:111]
	v_mfma_f32_16x16x32_bf16 v[88:91], v[128:131], v[184:187], v[88:91]
	v_mfma_f32_16x16x32_bf16 v[92:95], v[152:155], v[184:187], v[92:95]
	v_mfma_f32_16x16x32_bf16 v[72:75], v[128:131], v[192:195], v[72:75]
	v_mfma_f32_16x16x32_bf16 v[76:79], v[152:155], v[192:195], v[76:79]
	v_mfma_f32_16x16x32_bf16 v[120:123], v[132:135], v[172:175], v[120:123]
	v_mfma_f32_16x16x32_bf16 v[124:127], v[156:159], v[172:175], v[124:127]
	v_mfma_f32_16x16x32_bf16 v[104:107], v[132:135], v[180:183], v[104:107]
	v_mfma_f32_16x16x32_bf16 v[108:111], v[156:159], v[180:183], v[108:111]
	v_mfma_f32_16x16x32_bf16 v[88:91], v[132:135], v[188:191], v[88:91]
	v_mfma_f32_16x16x32_bf16 v[92:95], v[156:159], v[188:191], v[92:95]
	v_mfma_f32_16x16x32_bf16 v[72:75], v[132:135], v[196:199], v[72:75]
	v_mfma_f32_16x16x32_bf16 v[76:79], v[156:159], v[196:199], v[76:79]
	s_barrier
	s_add_i32 s40, 0, 0x1c000
	s_add_i32 s41, s64, s49
	v_add_u32_e32 v212, s40, v162
	s_mov_b32 m0, s41
	ds_read_b128 v[200:203], v212
	ds_read_b128 v[204:207], v212 offset:1024
	ds_read_b128 v[208:211], v212 offset:2048
	ds_read_b128 v[212:215], v212 offset:3072
	global_load_lds_dwordx4 v138, s[98:99]
	s_add_i32 m0, s41, 0x2000
	s_nop 0
	global_load_lds_dwordx4 v142, s[98:99]
	s_barrier
	s_waitcnt lgkmcnt(0)
	v_mfma_f32_16x16x32_bf16 v[112:115], v[200:203], v[168:171], v[112:115]
	v_mfma_f32_16x16x32_bf16 v[116:119], v[208:211], v[168:171], v[116:119]
	v_mfma_f32_16x16x32_bf16 v[96:99], v[200:203], v[176:179], v[96:99]
	v_mfma_f32_16x16x32_bf16 v[100:103], v[208:211], v[176:179], v[100:103]
	v_mfma_f32_16x16x32_bf16 v[80:83], v[200:203], v[184:187], v[80:83]
	v_mfma_f32_16x16x32_bf16 v[84:87], v[208:211], v[184:187], v[84:87]
	v_mfma_f32_16x16x32_bf16 v[64:67], v[200:203], v[192:195], v[64:67]
	v_mfma_f32_16x16x32_bf16 v[68:71], v[208:211], v[192:195], v[68:71]
	v_mfma_f32_16x16x32_bf16 v[112:115], v[204:207], v[172:175], v[112:115]
	v_mfma_f32_16x16x32_bf16 v[116:119], v[212:215], v[172:175], v[116:119]
	v_mfma_f32_16x16x32_bf16 v[96:99], v[204:207], v[180:183], v[96:99]
	v_mfma_f32_16x16x32_bf16 v[100:103], v[212:215], v[180:183], v[100:103]
	v_mfma_f32_16x16x32_bf16 v[80:83], v[204:207], v[188:191], v[80:83]
	v_mfma_f32_16x16x32_bf16 v[84:87], v[212:215], v[188:191], v[84:87]
	v_mfma_f32_16x16x32_bf16 v[64:67], v[204:207], v[196:199], v[64:67]
	v_mfma_f32_16x16x32_bf16 v[68:71], v[212:215], v[196:199], v[68:71]
	s_mov_b32 m0, s55
	s_barrier
	ds_read_b128 v[168:171], v165 offset:49152
	ds_read_b128 v[172:175], v165 offset:50176
	ds_read_b128 v[176:179], v165 offset:51200
	ds_read_b128 v[180:183], v165 offset:52224
	ds_read_b128 v[184:187], v165 offset:53248
	ds_read_b128 v[188:191], v165 offset:54272
	ds_read_b128 v[192:195], v165 offset:55296
	ds_read_b128 v[196:199], v165 offset:56320
	global_load_lds_dwordx4 v136, s[100:101]
	s_mov_b32 m0, s56
	s_nop 0
	global_load_lds_dwordx4 v140, s[100:101]
	s_barrier
	s_waitcnt lgkmcnt(0)
	v_mfma_f32_16x16x32_bf16 v[56:59], v[128:131], v[168:171], v[56:59]
	v_mfma_f32_16x16x32_bf16 v[60:63], v[152:155], v[168:171], v[60:63]
	v_mfma_f32_16x16x32_bf16 v[40:43], v[128:131], v[176:179], v[40:43]
	v_mfma_f32_16x16x32_bf16 v[44:47], v[152:155], v[176:179], v[44:47]
	v_mfma_f32_16x16x32_bf16 v[24:27], v[128:131], v[184:187], v[24:27]
	v_mfma_f32_16x16x32_bf16 v[28:31], v[152:155], v[184:187], v[28:31]
	v_mfma_f32_16x16x32_bf16 v[8:11], v[128:131], v[192:195], v[8:11]
	v_mfma_f32_16x16x32_bf16 v[12:15], v[152:155], v[192:195], v[12:15]
	v_mfma_f32_16x16x32_bf16 v[56:59], v[132:135], v[172:175], v[56:59]
	v_mfma_f32_16x16x32_bf16 v[60:63], v[156:159], v[172:175], v[60:63]
	v_mfma_f32_16x16x32_bf16 v[40:43], v[132:135], v[180:183], v[40:43]
	v_mfma_f32_16x16x32_bf16 v[44:47], v[156:159], v[180:183], v[44:47]
	v_mfma_f32_16x16x32_bf16 v[24:27], v[132:135], v[188:191], v[24:27]
	v_mfma_f32_16x16x32_bf16 v[28:31], v[156:159], v[188:191], v[28:31]
	v_mfma_f32_16x16x32_bf16 v[8:11], v[132:135], v[196:199], v[8:11]
	v_mfma_f32_16x16x32_bf16 v[12:15], v[156:159], v[196:199], v[12:15]
	s_barrier
	s_add_u32 s38, s38, 0x40080
	s_addc_u32 s39, s39, 0
	s_add_i32 s40, s40, s49
	s_mov_b32 m0, s40
	s_nop 0
	global_load_lds_dwordx4 v138, s[38:39]
	s_add_i32 m0, s40, 0x2000
	s_nop 0
	global_load_lds_dwordx4 v142, s[38:39]
	s_add_i32 s63, s63, 2
	s_add_u32 s36, s36, 0x100
	s_addc_u32 s37, s37, 0
	s_add_u32 s61, s61, 0x100
	s_addc_u32 s62, s62, 0
	s_waitcnt vmcnt(6)
	s_barrier
	v_mfma_f32_16x16x32_bf16 v[48:51], v[200:203], v[168:171], v[48:51]
	v_mfma_f32_16x16x32_bf16 v[52:55], v[208:211], v[168:171], v[52:55]
	v_mfma_f32_16x16x32_bf16 v[32:35], v[200:203], v[176:179], v[32:35]
	v_mfma_f32_16x16x32_bf16 v[36:39], v[208:211], v[176:179], v[36:39]
	v_mfma_f32_16x16x32_bf16 v[16:19], v[200:203], v[184:187], v[16:19]
	v_mfma_f32_16x16x32_bf16 v[20:23], v[208:211], v[184:187], v[20:23]
	v_mfma_f32_16x16x32_bf16 v[4:7], v[200:203], v[192:195], v[4:7]
	v_mfma_f32_16x16x32_bf16 v[0:3], v[208:211], v[192:195], v[0:3]
	v_mfma_f32_16x16x32_bf16 v[48:51], v[204:207], v[172:175], v[48:51]
	v_mfma_f32_16x16x32_bf16 v[52:55], v[212:215], v[172:175], v[52:55]
	v_mfma_f32_16x16x32_bf16 v[32:35], v[204:207], v[180:183], v[32:35]
	v_mfma_f32_16x16x32_bf16 v[36:39], v[212:215], v[180:183], v[36:39]
	v_mfma_f32_16x16x32_bf16 v[16:19], v[204:207], v[188:191], v[16:19]
	v_mfma_f32_16x16x32_bf16 v[20:23], v[212:215], v[188:191], v[20:23]
	v_mfma_f32_16x16x32_bf16 v[4:7], v[204:207], v[196:199], v[4:7]
	v_mfma_f32_16x16x32_bf16 v[0:3], v[212:215], v[196:199], v[0:3]
	s_cmp_gt_u32 s63, 13
	s_barrier
	s_cbranch_scc0 .LBB0_583
	v_lshl_add_u32 v152, s8, 8, v161
	v_lshl_or_b32 v153, s16, 8, v163
	s_lshl_b32 s36, s16, 2
	s_ashr_i32 s37, s36, 31
	s_lshl_b32 s16, s54, 2
	v_lshl_add_u32 v154, v152, 10, v153
	v_lshl_add_u32 v156, v152, 6, s16
	v_lshl_add_u32 v156, s36, 2, v156
	v_lshlrev_b32_e32 v155, 1, v154
	v_lshlrev_b32_e32 v154, 2, v154
	global_load_dwordx4 v[168:171], v154, s[14:15]
	global_load_dwordx4 v[172:175], v154, s[14:15] offset:16
	global_load_dwordx4 v[176:179], v154, s[14:15] offset:512
	global_load_dwordx4 v[180:183], v154, s[14:15] offset:528
	v_add_u32_e32 v154, 0x10000, v154
	global_load_dwordx4 v[184:187], v154, s[14:15]
	global_load_dwordx4 v[188:191], v154, s[14:15] offset:16
	global_load_dwordx4 v[192:195], v154, s[14:15] offset:512
	global_load_dwordx4 v[196:199], v154, s[14:15] offset:528
	v_add_u32_e32 v154, 0x10000, v154
	global_load_dwordx4 v[200:203], v154, s[14:15]
	global_load_dwordx4 v[204:207], v154, s[14:15] offset:16
	global_load_dwordx4 v[208:211], v154, s[14:15] offset:512
	global_load_dwordx4 v[212:215], v154, s[14:15] offset:528
	v_add_u32_e32 v154, 0x10000, v154
	global_load_dwordx4 v[216:219], v154, s[14:15]
	global_load_dwordx4 v[220:223], v154, s[14:15] offset:16
	global_load_dwordx4 v[128:131], v154, s[14:15] offset:512
	global_load_dwordx4 v[132:135], v154, s[14:15] offset:528
	v_add_u32_e32 v154, 0x50000, v154
	s_waitcnt vmcnt(12)
	v_pk_add_f32 v[120:121], v[120:121], v[168:169]
	v_pk_add_f32 v[122:123], v[122:123], v[170:171]
	v_pk_add_f32 v[124:125], v[124:125], v[172:173]
	v_pk_add_f32 v[126:127], v[126:127], v[174:175]
	v_cvt_pk_bf16_f32 v168, v120, v121
	v_cvt_pk_bf16_f32 v169, v122, v123
	v_cvt_pk_bf16_f32 v170, v124, v125
	v_cvt_pk_bf16_f32 v171, v126, v127
	v_pk_mul_f32 v[172:173], v[120:121], v[120:121]
	global_store_dwordx4 v155, v[168:171], s[18:19]
	v_pk_fma_f32 v[172:173], v[122:123], v[122:123], v[172:173]
	v_pk_fma_f32 v[172:173], v[124:125], v[124:125], v[172:173]
	v_pk_fma_f32 v[172:173], v[126:127], v[126:127], v[172:173]
	v_pk_add_f32 v[112:113], v[112:113], v[176:177]
	v_pk_add_f32 v[114:115], v[114:115], v[178:179]
	v_pk_add_f32 v[116:117], v[116:117], v[180:181]
	v_pk_add_f32 v[118:119], v[118:119], v[182:183]
	v_cvt_pk_bf16_f32 v176, v112, v113
	v_cvt_pk_bf16_f32 v177, v114, v115
	v_cvt_pk_bf16_f32 v178, v116, v117
	v_cvt_pk_bf16_f32 v179, v118, v119
	v_pk_fma_f32 v[172:173], v[112:113], v[112:113], v[172:173]
	global_store_dwordx4 v155, v[176:179], s[18:19] offset:256
	v_pk_fma_f32 v[172:173], v[114:115], v[114:115], v[172:173]
	v_pk_fma_f32 v[172:173], v[116:117], v[116:117], v[172:173]
	v_pk_fma_f32 v[172:173], v[118:119], v[118:119], v[172:173]
	v_add_f32_e32 v157, v172, v173
	v_add_u32_e32 v155, 0x8000, v155
	v_mov_b32_e32 v158, v157
	s_nop 1
	v_permlane16_swap_b32_e32 v157, v158
	s_nop 0
	v_add_f32_e32 v157, v157, v158
	v_mov_b32_e32 v158, v157
	s_nop 1
	v_permlane32_swap_b32_e32 v157, v158
	s_nop 0
	v_add_f32_e32 v157, v157, v158
	s_and_saveexec_b64 s[38:39], s[4:5]
	global_store_dword v156, v157, s[20:21]
	s_mov_b64 exec, s[38:39]
	global_load_dwordx4 v[168:171], v154, s[14:15]
	global_load_dwordx4 v[172:175], v154, s[14:15] offset:16
	global_load_dwordx4 v[176:179], v154, s[14:15] offset:512
	global_load_dwordx4 v[180:183], v154, s[14:15] offset:528
	v_add_u32_e32 v154, 0x10000, v154
	s_waitcnt vmcnt(15)
	v_pk_add_f32 v[104:105], v[104:105], v[184:185]
	v_pk_add_f32 v[106:107], v[106:107], v[186:187]
	v_pk_add_f32 v[108:109], v[108:109], v[188:189]
	v_pk_add_f32 v[110:111], v[110:111], v[190:191]
	v_cvt_pk_bf16_f32 v184, v104, v105
	v_cvt_pk_bf16_f32 v185, v106, v107
	v_cvt_pk_bf16_f32 v186, v108, v109
	v_cvt_pk_bf16_f32 v187, v110, v111
	v_pk_mul_f32 v[188:189], v[104:105], v[104:105]
	global_store_dwordx4 v155, v[184:187], s[18:19]
	v_pk_fma_f32 v[188:189], v[106:107], v[106:107], v[188:189]
	v_pk_fma_f32 v[188:189], v[108:109], v[108:109], v[188:189]
	v_pk_fma_f32 v[188:189], v[110:111], v[110:111], v[188:189]
	v_pk_add_f32 v[96:97], v[96:97], v[192:193]
	v_pk_add_f32 v[98:99], v[98:99], v[194:195]
	v_pk_add_f32 v[100:101], v[100:101], v[196:197]
	v_pk_add_f32 v[102:103], v[102:103], v[198:199]
	v_cvt_pk_bf16_f32 v192, v96, v97
	v_cvt_pk_bf16_f32 v193, v98, v99
	v_cvt_pk_bf16_f32 v194, v100, v101
	v_cvt_pk_bf16_f32 v195, v102, v103
	v_pk_fma_f32 v[188:189], v[96:97], v[96:97], v[188:189]
	global_store_dwordx4 v155, v[192:195], s[18:19] offset:256
	v_pk_fma_f32 v[188:189], v[98:99], v[98:99], v[188:189]
	v_pk_fma_f32 v[188:189], v[100:101], v[100:101], v[188:189]
	v_pk_fma_f32 v[188:189], v[102:103], v[102:103], v[188:189]
	v_add_f32_e32 v157, v188, v189
	v_add_u32_e32 v155, 0x8000, v155
	v_mov_b32_e32 v158, v157
	s_nop 1
	v_permlane16_swap_b32_e32 v157, v158
	s_nop 0
	v_add_f32_e32 v157, v157, v158
	v_mov_b32_e32 v158, v157
	s_nop 1
	v_permlane32_swap_b32_e32 v157, v158
	s_nop 0
	v_add_f32_e32 v157, v157, v158
	s_and_saveexec_b64 s[38:39], s[4:5]
	global_store_dword v156, v157, s[20:21] offset:1024
	s_mov_b64 exec, s[38:39]
	global_load_dwordx4 v[184:187], v154, s[14:15]
	global_load_dwordx4 v[188:191], v154, s[14:15] offset:16
	global_load_dwordx4 v[192:195], v154, s[14:15] offset:512
	global_load_dwordx4 v[196:199], v154, s[14:15] offset:528
	v_add_u32_e32 v154, 0x10000, v154
	s_waitcnt vmcnt(18)
	v_pk_add_f32 v[88:89], v[88:89], v[200:201]
	v_pk_add_f32 v[90:91], v[90:91], v[202:203]
	v_pk_add_f32 v[92:93], v[92:93], v[204:205]
	v_pk_add_f32 v[94:95], v[94:95], v[206:207]
	v_cvt_pk_bf16_f32 v200, v88, v89
	v_cvt_pk_bf16_f32 v201, v90, v91
	v_cvt_pk_bf16_f32 v202, v92, v93
	v_cvt_pk_bf16_f32 v203, v94, v95
	v_pk_mul_f32 v[204:205], v[88:89], v[88:89]
	global_store_dwordx4 v155, v[200:203], s[18:19]
	v_pk_fma_f32 v[204:205], v[90:91], v[90:91], v[204:205]
	v_pk_fma_f32 v[204:205], v[92:93], v[92:93], v[204:205]
	v_pk_fma_f32 v[204:205], v[94:95], v[94:95], v[204:205]
	v_pk_add_f32 v[80:81], v[80:81], v[208:209]
	v_pk_add_f32 v[82:83], v[82:83], v[210:211]
	v_pk_add_f32 v[84:85], v[84:85], v[212:213]
	v_pk_add_f32 v[86:87], v[86:87], v[214:215]
	v_cvt_pk_bf16_f32 v208, v80, v81
	v_cvt_pk_bf16_f32 v209, v82, v83
	v_cvt_pk_bf16_f32 v210, v84, v85
	v_cvt_pk_bf16_f32 v211, v86, v87
	v_pk_fma_f32 v[204:205], v[80:81], v[80:81], v[204:205]
	global_store_dwordx4 v155, v[208:211], s[18:19] offset:256
	v_pk_fma_f32 v[204:205], v[82:83], v[82:83], v[204:205]
	v_pk_fma_f32 v[204:205], v[84:85], v[84:85], v[204:205]
	v_pk_fma_f32 v[204:205], v[86:87], v[86:87], v[204:205]
	v_add_f32_e32 v157, v204, v205
	v_add_u32_e32 v155, 0x8000, v155
	v_mov_b32_e32 v158, v157
	s_nop 1
	v_permlane16_swap_b32_e32 v157, v158
	s_nop 0
	v_add_f32_e32 v157, v157, v158
	v_mov_b32_e32 v158, v157
	s_nop 1
	v_permlane32_swap_b32_e32 v157, v158
	s_nop 0
	v_add_f32_e32 v157, v157, v158
	s_and_saveexec_b64 s[38:39], s[4:5]
	global_store_dword v156, v157, s[20:21] offset:2048
	s_mov_b64 exec, s[38:39]
	global_load_dwordx4 v[200:203], v154, s[14:15]
	global_load_dwordx4 v[204:207], v154, s[14:15] offset:16
	global_load_dwordx4 v[208:211], v154, s[14:15] offset:512
	global_load_dwordx4 v[212:215], v154, s[14:15] offset:528
	v_add_u32_e32 v154, 0x10000, v154
	s_waitcnt vmcnt(21)
	v_pk_add_f32 v[72:73], v[72:73], v[216:217]
	v_pk_add_f32 v[74:75], v[74:75], v[218:219]
	v_pk_add_f32 v[76:77], v[76:77], v[220:221]
	v_pk_add_f32 v[78:79], v[78:79], v[222:223]
	v_cvt_pk_bf16_f32 v216, v72, v73
	v_cvt_pk_bf16_f32 v217, v74, v75
	v_cvt_pk_bf16_f32 v218, v76, v77
	v_cvt_pk_bf16_f32 v219, v78, v79
	v_pk_mul_f32 v[220:221], v[72:73], v[72:73]
	global_store_dwordx4 v155, v[216:219], s[18:19]
	v_pk_fma_f32 v[220:221], v[74:75], v[74:75], v[220:221]
	v_pk_fma_f32 v[220:221], v[76:77], v[76:77], v[220:221]
	v_pk_fma_f32 v[220:221], v[78:79], v[78:79], v[220:221]
	v_pk_add_f32 v[64:65], v[64:65], v[128:129]
	v_pk_add_f32 v[66:67], v[66:67], v[130:131]
	v_pk_add_f32 v[68:69], v[68:69], v[132:133]
	v_pk_add_f32 v[70:71], v[70:71], v[134:135]
	v_cvt_pk_bf16_f32 v128, v64, v65
	v_cvt_pk_bf16_f32 v129, v66, v67
	v_cvt_pk_bf16_f32 v130, v68, v69
	v_cvt_pk_bf16_f32 v131, v70, v71
	v_pk_fma_f32 v[220:221], v[64:65], v[64:65], v[220:221]
	global_store_dwordx4 v155, v[128:131], s[18:19] offset:256
	v_pk_fma_f32 v[220:221], v[66:67], v[66:67], v[220:221]
	v_pk_fma_f32 v[220:221], v[68:69], v[68:69], v[220:221]
	v_pk_fma_f32 v[220:221], v[70:71], v[70:71], v[220:221]
	v_add_f32_e32 v157, v220, v221
	v_add_u32_e32 v155, 0x28000, v155
	v_mov_b32_e32 v158, v157
	s_nop 1
	v_permlane16_swap_b32_e32 v157, v158
	s_nop 0
	v_add_f32_e32 v157, v157, v158
	v_mov_b32_e32 v158, v157
	s_nop 1
	v_permlane32_swap_b32_e32 v157, v158
	s_nop 0
	v_add_f32_e32 v157, v157, v158
	s_and_saveexec_b64 s[38:39], s[4:5]
	global_store_dword v156, v157, s[20:21] offset:3072
	s_mov_b64 exec, s[38:39]
	v_add_u32_e32 v156, 0x2000, v156
	global_load_dwordx4 v[216:219], v154, s[14:15]
	global_load_dwordx4 v[220:223], v154, s[14:15] offset:16
	global_load_dwordx4 v[128:131], v154, s[14:15] offset:512
	global_load_dwordx4 v[132:135], v154, s[14:15] offset:528
	s_waitcnt vmcnt(21)
	v_pk_add_f32 v[56:57], v[56:57], v[168:169]
	v_pk_add_f32 v[58:59], v[58:59], v[170:171]
	v_pk_add_f32 v[60:61], v[60:61], v[172:173]
	v_pk_add_f32 v[62:63], v[62:63], v[174:175]
	v_cvt_pk_bf16_f32 v168, v56, v57
	v_cvt_pk_bf16_f32 v169, v58, v59
	v_cvt_pk_bf16_f32 v170, v60, v61
	v_cvt_pk_bf16_f32 v171, v62, v63
	v_pk_mul_f32 v[172:173], v[56:57], v[56:57]
	global_store_dwordx4 v155, v[168:171], s[18:19]
	v_pk_fma_f32 v[172:173], v[58:59], v[58:59], v[172:173]
	v_pk_fma_f32 v[172:173], v[60:61], v[60:61], v[172:173]
	v_pk_fma_f32 v[172:173], v[62:63], v[62:63], v[172:173]
	v_pk_add_f32 v[48:49], v[48:49], v[176:177]
	v_pk_add_f32 v[50:51], v[50:51], v[178:179]
	v_pk_add_f32 v[52:53], v[52:53], v[180:181]
	v_pk_add_f32 v[54:55], v[54:55], v[182:183]
	v_cvt_pk_bf16_f32 v176, v48, v49
	v_cvt_pk_bf16_f32 v177, v50, v51
	v_cvt_pk_bf16_f32 v178, v52, v53
	v_cvt_pk_bf16_f32 v179, v54, v55
	v_pk_fma_f32 v[172:173], v[48:49], v[48:49], v[172:173]
	global_store_dwordx4 v155, v[176:179], s[18:19] offset:256
	v_pk_fma_f32 v[172:173], v[50:51], v[50:51], v[172:173]
	v_pk_fma_f32 v[172:173], v[52:53], v[52:53], v[172:173]
	v_pk_fma_f32 v[172:173], v[54:55], v[54:55], v[172:173]
	v_add_f32_e32 v157, v172, v173
	v_add_u32_e32 v155, 0x8000, v155
	v_mov_b32_e32 v158, v157
	s_nop 1
	v_permlane16_swap_b32_e32 v157, v158
	s_nop 0
	v_add_f32_e32 v157, v157, v158
	v_mov_b32_e32 v158, v157
	s_nop 1
	v_permlane32_swap_b32_e32 v157, v158
	s_nop 0
	v_add_f32_e32 v157, v157, v158
	s_and_saveexec_b64 s[38:39], s[4:5]
	global_store_dword v156, v157, s[20:21]
	s_mov_b64 exec, s[38:39]
	s_waitcnt vmcnt(17)
	v_pk_add_f32 v[40:41], v[40:41], v[184:185]
	v_pk_add_f32 v[42:43], v[42:43], v[186:187]
	v_pk_add_f32 v[44:45], v[44:45], v[188:189]
	v_pk_add_f32 v[46:47], v[46:47], v[190:191]
	v_cvt_pk_bf16_f32 v184, v40, v41
	v_cvt_pk_bf16_f32 v185, v42, v43
	v_cvt_pk_bf16_f32 v186, v44, v45
	v_cvt_pk_bf16_f32 v187, v46, v47
	v_pk_mul_f32 v[188:189], v[40:41], v[40:41]
	global_store_dwordx4 v155, v[184:187], s[18:19]
	v_pk_fma_f32 v[188:189], v[42:43], v[42:43], v[188:189]
	v_pk_fma_f32 v[188:189], v[44:45], v[44:45], v[188:189]
	v_pk_fma_f32 v[188:189], v[46:47], v[46:47], v[188:189]
	v_pk_add_f32 v[32:33], v[32:33], v[192:193]
	v_pk_add_f32 v[34:35], v[34:35], v[194:195]
	v_pk_add_f32 v[36:37], v[36:37], v[196:197]
	v_pk_add_f32 v[38:39], v[38:39], v[198:199]
	v_cvt_pk_bf16_f32 v192, v32, v33
	v_cvt_pk_bf16_f32 v193, v34, v35
	v_cvt_pk_bf16_f32 v194, v36, v37
	v_cvt_pk_bf16_f32 v195, v38, v39
	v_pk_fma_f32 v[188:189], v[32:33], v[32:33], v[188:189]
	global_store_dwordx4 v155, v[192:195], s[18:19] offset:256
	v_pk_fma_f32 v[188:189], v[34:35], v[34:35], v[188:189]
	v_pk_fma_f32 v[188:189], v[36:37], v[36:37], v[188:189]
	v_pk_fma_f32 v[188:189], v[38:39], v[38:39], v[188:189]
	v_add_f32_e32 v157, v188, v189
	v_add_u32_e32 v155, 0x8000, v155
	v_mov_b32_e32 v158, v157
	s_nop 1
	v_permlane16_swap_b32_e32 v157, v158
	s_nop 0
	v_add_f32_e32 v157, v157, v158
	v_mov_b32_e32 v158, v157
	s_nop 1
	v_permlane32_swap_b32_e32 v157, v158
	s_nop 0
	v_add_f32_e32 v157, v157, v158
	s_and_saveexec_b64 s[38:39], s[4:5]
	global_store_dword v156, v157, s[20:21] offset:1024
	s_mov_b64 exec, s[38:39]
	s_waitcnt vmcnt(13)
	v_pk_add_f32 v[24:25], v[24:25], v[200:201]
	v_pk_add_f32 v[26:27], v[26:27], v[202:203]
	v_pk_add_f32 v[28:29], v[28:29], v[204:205]
	v_pk_add_f32 v[30:31], v[30:31], v[206:207]
	v_cvt_pk_bf16_f32 v200, v24, v25
	v_cvt_pk_bf16_f32 v201, v26, v27
	v_cvt_pk_bf16_f32 v202, v28, v29
	v_cvt_pk_bf16_f32 v203, v30, v31
	v_pk_mul_f32 v[204:205], v[24:25], v[24:25]
	global_store_dwordx4 v155, v[200:203], s[18:19]
	v_pk_fma_f32 v[204:205], v[26:27], v[26:27], v[204:205]
	v_pk_fma_f32 v[204:205], v[28:29], v[28:29], v[204:205]
	v_pk_fma_f32 v[204:205], v[30:31], v[30:31], v[204:205]
	v_pk_add_f32 v[16:17], v[16:17], v[208:209]
	v_pk_add_f32 v[18:19], v[18:19], v[210:211]
	v_pk_add_f32 v[20:21], v[20:21], v[212:213]
	v_pk_add_f32 v[22:23], v[22:23], v[214:215]
	v_cvt_pk_bf16_f32 v208, v16, v17
	v_cvt_pk_bf16_f32 v209, v18, v19
	v_cvt_pk_bf16_f32 v210, v20, v21
	v_cvt_pk_bf16_f32 v211, v22, v23
	v_pk_fma_f32 v[204:205], v[16:17], v[16:17], v[204:205]
	global_store_dwordx4 v155, v[208:211], s[18:19] offset:256
	v_pk_fma_f32 v[204:205], v[18:19], v[18:19], v[204:205]
	v_pk_fma_f32 v[204:205], v[20:21], v[20:21], v[204:205]
	v_pk_fma_f32 v[204:205], v[22:23], v[22:23], v[204:205]
	v_add_f32_e32 v157, v204, v205
	v_add_u32_e32 v155, 0x8000, v155
	v_mov_b32_e32 v158, v157
	s_nop 1
	v_permlane16_swap_b32_e32 v157, v158
	s_nop 0
	v_add_f32_e32 v157, v157, v158
	v_mov_b32_e32 v158, v157
	s_nop 1
	v_permlane32_swap_b32_e32 v157, v158
	s_nop 0
	v_add_f32_e32 v157, v157, v158
	s_and_saveexec_b64 s[38:39], s[4:5]
	global_store_dword v156, v157, s[20:21] offset:2048
	s_mov_b64 exec, s[38:39]
	s_waitcnt vmcnt(9)
	v_pk_add_f32 v[8:9], v[8:9], v[216:217]
	v_pk_add_f32 v[10:11], v[10:11], v[218:219]
	v_pk_add_f32 v[12:13], v[12:13], v[220:221]
	v_pk_add_f32 v[14:15], v[14:15], v[222:223]
	v_cvt_pk_bf16_f32 v216, v8, v9
	v_cvt_pk_bf16_f32 v217, v10, v11
	v_cvt_pk_bf16_f32 v218, v12, v13
	v_cvt_pk_bf16_f32 v219, v14, v15
	v_pk_mul_f32 v[220:221], v[8:9], v[8:9]
	global_store_dwordx4 v155, v[216:219], s[18:19]
	v_pk_fma_f32 v[220:221], v[10:11], v[10:11], v[220:221]
	v_pk_fma_f32 v[220:221], v[12:13], v[12:13], v[220:221]
	v_pk_fma_f32 v[220:221], v[14:15], v[14:15], v[220:221]
	v_pk_add_f32 v[4:5], v[4:5], v[128:129]
	v_pk_add_f32 v[6:7], v[6:7], v[130:131]
	v_pk_add_f32 v[0:1], v[0:1], v[132:133]
	v_pk_add_f32 v[2:3], v[2:3], v[134:135]
	v_cvt_pk_bf16_f32 v128, v4, v5
	v_cvt_pk_bf16_f32 v129, v6, v7
	v_cvt_pk_bf16_f32 v130, v0, v1
	v_cvt_pk_bf16_f32 v131, v2, v3
	v_pk_fma_f32 v[220:221], v[4:5], v[4:5], v[220:221]
	global_store_dwordx4 v155, v[128:131], s[18:19] offset:256
	v_pk_fma_f32 v[220:221], v[6:7], v[6:7], v[220:221]
	v_pk_fma_f32 v[220:221], v[0:1], v[0:1], v[220:221]
	v_pk_fma_f32 v[220:221], v[2:3], v[2:3], v[220:221]
	v_add_f32_e32 v157, v220, v221
	v_add_u32_e32 v155, 0x8000, v155
	v_mov_b32_e32 v158, v157
	s_nop 1
	v_permlane16_swap_b32_e32 v157, v158
	s_nop 0
	v_add_f32_e32 v157, v157, v158
	v_mov_b32_e32 v158, v157
	s_nop 1
	v_permlane32_swap_b32_e32 v157, v158
	s_nop 0
	v_add_f32_e32 v157, v157, v158
	s_and_saveexec_b64 s[38:39], s[4:5]
	global_store_dword v156, v157, s[20:21] offset:3072
	s_mov_b64 exec, s[38:39]
	s_branch .LBB0_575

.LBB0_698:
	s_add_u32 s28, s26, 0xfffc0080
	s_addc_u32 s29, s27, -1
	s_add_i32 s68, 0, 0x10000
	v_add_u32_e32 v155, s68, v153
	ds_read_b128 v[138:141], v155
	ds_read_b128 v[142:145], v155 offset:1024
	ds_read_b128 v[146:149], v155 offset:2048
	ds_read_b128 v[156:159], v155 offset:3072
	s_cmp_eq_u32 s51, 12
	s_cselect_b32 s31, s21, s29
	s_cselect_b32 s30, s38, s28
	s_cselect_b32 s29, s7, s50
	s_cselect_b32 s28, s39, s46
	s_add_i32 m0, s58, 0xc000
	ds_read_b128 v[160:163], v154
	ds_read_b128 v[164:167], v154 offset:1024
	ds_read_b128 v[168:171], v154 offset:2048
	ds_read_b128 v[172:175], v154 offset:3072
	ds_read_b128 v[176:179], v154 offset:4096
	ds_read_b128 v[180:183], v154 offset:5120
	ds_read_b128 v[184:187], v154 offset:6144
	ds_read_b128 v[188:191], v154 offset:7168
	global_load_lds_dwordx4 v134, s[26:27]
	s_add_i32 m0, s58, 0xe000
	s_nop 0
	global_load_lds_dwordx4 v136, s[26:27]
	s_waitcnt lgkmcnt(8)
	s_barrier
	s_waitcnt lgkmcnt(0)
	v_mfma_f32_16x16x32_bf16 v[124:127], v[138:141], v[160:163], v[124:127]
	v_mfma_f32_16x16x32_bf16 v[120:123], v[146:149], v[160:163], v[120:123]
	v_mfma_f32_16x16x32_bf16 v[108:111], v[138:141], v[168:171], v[108:111]
	v_mfma_f32_16x16x32_bf16 v[104:107], v[146:149], v[168:171], v[104:107]
	v_mfma_f32_16x16x32_bf16 v[92:95], v[138:141], v[176:179], v[92:95]
	v_mfma_f32_16x16x32_bf16 v[88:91], v[146:149], v[176:179], v[88:91]
	v_mfma_f32_16x16x32_bf16 v[76:79], v[138:141], v[184:187], v[76:79]
	v_mfma_f32_16x16x32_bf16 v[72:75], v[146:149], v[184:187], v[72:75]
	v_mfma_f32_16x16x32_bf16 v[124:127], v[142:145], v[164:167], v[124:127]
	v_mfma_f32_16x16x32_bf16 v[120:123], v[156:159], v[164:167], v[120:123]
	v_mfma_f32_16x16x32_bf16 v[108:111], v[142:145], v[172:175], v[108:111]
	v_mfma_f32_16x16x32_bf16 v[104:107], v[156:159], v[172:175], v[104:107]
	v_mfma_f32_16x16x32_bf16 v[92:95], v[142:145], v[180:183], v[92:95]
	v_mfma_f32_16x16x32_bf16 v[88:91], v[156:159], v[180:183], v[88:91]
	v_mfma_f32_16x16x32_bf16 v[76:79], v[142:145], v[188:191], v[76:79]
	v_mfma_f32_16x16x32_bf16 v[72:75], v[156:159], v[188:191], v[72:75]
	s_barrier
	s_add_i32 s70, 0, 0x14000
	s_add_i32 s68, s68, s57
	v_add_u32_e32 v155, s70, v153
	s_add_u32 s98, s28, s40
	s_addc_u32 s99, s29, s41
	s_mov_b32 m0, s68
	ds_read_b128 v[192:195], v155
	ds_read_b128 v[196:199], v155 offset:1024
	ds_read_b128 v[200:203], v155 offset:2048
	ds_read_b128 v[204:207], v155 offset:3072
	global_load_lds_dwordx4 v208, s[28:29]
	s_add_i32 m0, s68, 0x2000
	s_nop 0
	global_load_lds_dwordx4 v128, s[28:29]
	s_barrier
	s_waitcnt lgkmcnt(0)
	v_mfma_f32_16x16x32_bf16 v[116:119], v[192:195], v[160:163], v[116:119]
	v_mfma_f32_16x16x32_bf16 v[112:115], v[200:203], v[160:163], v[112:115]
	v_mfma_f32_16x16x32_bf16 v[100:103], v[192:195], v[168:171], v[100:103]
	v_mfma_f32_16x16x32_bf16 v[96:99], v[200:203], v[168:171], v[96:99]
	v_mfma_f32_16x16x32_bf16 v[84:87], v[192:195], v[176:179], v[84:87]
	v_mfma_f32_16x16x32_bf16 v[80:83], v[200:203], v[176:179], v[80:83]
	v_mfma_f32_16x16x32_bf16 v[68:71], v[192:195], v[184:187], v[68:71]
	v_mfma_f32_16x16x32_bf16 v[64:67], v[200:203], v[184:187], v[64:67]
	v_mfma_f32_16x16x32_bf16 v[116:119], v[196:199], v[164:167], v[116:119]
	v_mfma_f32_16x16x32_bf16 v[112:115], v[204:207], v[164:167], v[112:115]
	v_mfma_f32_16x16x32_bf16 v[100:103], v[196:199], v[172:175], v[100:103]
	v_mfma_f32_16x16x32_bf16 v[96:99], v[204:207], v[172:175], v[96:99]
	v_mfma_f32_16x16x32_bf16 v[84:87], v[196:199], v[180:183], v[84:87]
	v_mfma_f32_16x16x32_bf16 v[80:83], v[204:207], v[180:183], v[80:83]
	v_mfma_f32_16x16x32_bf16 v[68:71], v[196:199], v[188:191], v[68:71]
	v_mfma_f32_16x16x32_bf16 v[64:67], v[204:207], v[188:191], v[64:67]
	s_mov_b32 m0, s58
	s_add_u32 s100, s30, s40
	s_addc_u32 s101, s31, s41
	s_barrier
	ds_read_b128 v[160:163], v154 offset:16384
	ds_read_b128 v[164:167], v154 offset:17408
	ds_read_b128 v[168:171], v154 offset:18432
	ds_read_b128 v[172:175], v154 offset:19456
	ds_read_b128 v[176:179], v154 offset:20480
	ds_read_b128 v[180:183], v154 offset:21504
	ds_read_b128 v[184:187], v154 offset:22528
	ds_read_b128 v[188:191], v154 offset:23552
	global_load_lds_dwordx4 v132, s[30:31]
	s_mov_b32 m0, s59
	s_nop 0
	global_load_lds_dwordx4 v130, s[30:31]
	s_barrier
	s_waitcnt lgkmcnt(0)
	v_mfma_f32_16x16x32_bf16 v[60:63], v[138:141], v[160:163], v[60:63]
	v_mfma_f32_16x16x32_bf16 v[56:59], v[146:149], v[160:163], v[56:59]
	v_mfma_f32_16x16x32_bf16 v[44:47], v[138:141], v[168:171], v[44:47]
	v_mfma_f32_16x16x32_bf16 v[40:43], v[146:149], v[168:171], v[40:43]
	v_mfma_f32_16x16x32_bf16 v[28:31], v[138:141], v[176:179], v[28:31]
	v_mfma_f32_16x16x32_bf16 v[24:27], v[146:149], v[176:179], v[24:27]
	v_mfma_f32_16x16x32_bf16 v[12:15], v[138:141], v[184:187], v[12:15]
	v_mfma_f32_16x16x32_bf16 v[8:11], v[146:149], v[184:187], v[8:11]
	v_mfma_f32_16x16x32_bf16 v[60:63], v[142:145], v[164:167], v[60:63]
	v_mfma_f32_16x16x32_bf16 v[56:59], v[156:159], v[164:167], v[56:59]
	v_mfma_f32_16x16x32_bf16 v[44:47], v[142:145], v[172:175], v[44:47]
	v_mfma_f32_16x16x32_bf16 v[40:43], v[156:159], v[172:175], v[40:43]
	v_mfma_f32_16x16x32_bf16 v[28:31], v[142:145], v[180:183], v[28:31]
	v_mfma_f32_16x16x32_bf16 v[24:27], v[156:159], v[180:183], v[24:27]
	v_mfma_f32_16x16x32_bf16 v[12:15], v[142:145], v[188:191], v[12:15]
	v_mfma_f32_16x16x32_bf16 v[8:11], v[156:159], v[188:191], v[8:11]
	s_barrier
	s_add_u32 s68, s28, 0x40000
	s_addc_u32 s69, s29, 0
	s_add_i32 s70, s70, s57
	s_mov_b32 m0, s70
	s_nop 0
	global_load_lds_dwordx4 v208, s[68:69]
	s_add_i32 m0, s70, 0x2000
	s_nop 0
	global_load_lds_dwordx4 v128, s[68:69]
	s_waitcnt vmcnt(6)
	s_barrier
	v_mfma_f32_16x16x32_bf16 v[52:55], v[192:195], v[160:163], v[52:55]
	v_mfma_f32_16x16x32_bf16 v[48:51], v[200:203], v[160:163], v[48:51]
	v_mfma_f32_16x16x32_bf16 v[36:39], v[192:195], v[168:171], v[36:39]
	v_mfma_f32_16x16x32_bf16 v[32:35], v[200:203], v[168:171], v[32:35]
	v_mfma_f32_16x16x32_bf16 v[20:23], v[192:195], v[176:179], v[20:23]
	v_mfma_f32_16x16x32_bf16 v[16:19], v[200:203], v[176:179], v[16:19]
	v_mfma_f32_16x16x32_bf16 v[4:7], v[192:195], v[184:187], v[4:7]
	v_mfma_f32_16x16x32_bf16 v[0:3], v[200:203], v[184:187], v[0:3]
	v_mfma_f32_16x16x32_bf16 v[52:55], v[196:199], v[164:167], v[52:55]
	v_mfma_f32_16x16x32_bf16 v[48:51], v[204:207], v[164:167], v[48:51]
	v_mfma_f32_16x16x32_bf16 v[36:39], v[196:199], v[172:175], v[36:39]
	v_mfma_f32_16x16x32_bf16 v[32:35], v[204:207], v[172:175], v[32:35]
	v_mfma_f32_16x16x32_bf16 v[20:23], v[196:199], v[180:183], v[20:23]
	v_mfma_f32_16x16x32_bf16 v[16:19], v[204:207], v[180:183], v[16:19]
	v_mfma_f32_16x16x32_bf16 v[4:7], v[196:199], v[188:191], v[4:7]
	v_mfma_f32_16x16x32_bf16 v[0:3], v[204:207], v[188:191], v[0:3]
	s_add_i32 s68, 0, 0x18000
	v_add_u32_e32 v155, s68, v153
	s_barrier
	ds_read_b128 v[138:141], v155
	ds_read_b128 v[142:145], v155 offset:1024
	ds_read_b128 v[146:149], v155 offset:2048
	ds_read_b128 v[156:159], v155 offset:3072
	s_add_u32 s30, s30, 0x40000
	s_addc_u32 s31, s31, 0
	s_mov_b32 m0, s60
	ds_read_b128 v[160:163], v154 offset:32768
	ds_read_b128 v[164:167], v154 offset:33792
	ds_read_b128 v[168:171], v154 offset:34816
	ds_read_b128 v[172:175], v154 offset:35840
	ds_read_b128 v[176:179], v154 offset:36864
	ds_read_b128 v[180:183], v154 offset:37888
	ds_read_b128 v[184:187], v154 offset:38912
	ds_read_b128 v[188:191], v154 offset:39936
	global_load_lds_dwordx4 v132, s[30:31]
	s_mov_b32 m0, s61
	s_nop 0
	global_load_lds_dwordx4 v130, s[30:31]
	s_waitcnt lgkmcnt(8)
	s_barrier
	s_waitcnt lgkmcnt(0)
	v_mfma_f32_16x16x32_bf16 v[124:127], v[138:141], v[160:163], v[124:127]
	v_mfma_f32_16x16x32_bf16 v[120:123], v[146:149], v[160:163], v[120:123]
	v_mfma_f32_16x16x32_bf16 v[108:111], v[138:141], v[168:171], v[108:111]
	v_mfma_f32_16x16x32_bf16 v[104:107], v[146:149], v[168:171], v[104:107]
	v_mfma_f32_16x16x32_bf16 v[92:95], v[138:141], v[176:179], v[92:95]
	v_mfma_f32_16x16x32_bf16 v[88:91], v[146:149], v[176:179], v[88:91]
	v_mfma_f32_16x16x32_bf16 v[76:79], v[138:141], v[184:187], v[76:79]
	v_mfma_f32_16x16x32_bf16 v[72:75], v[146:149], v[184:187], v[72:75]
	v_mfma_f32_16x16x32_bf16 v[124:127], v[142:145], v[164:167], v[124:127]
	v_mfma_f32_16x16x32_bf16 v[120:123], v[156:159], v[164:167], v[120:123]
	v_mfma_f32_16x16x32_bf16 v[108:111], v[142:145], v[172:175], v[108:111]
	v_mfma_f32_16x16x32_bf16 v[104:107], v[156:159], v[172:175], v[104:107]
	v_mfma_f32_16x16x32_bf16 v[92:95], v[142:145], v[180:183], v[92:95]
	v_mfma_f32_16x16x32_bf16 v[88:91], v[156:159], v[180:183], v[88:91]
	v_mfma_f32_16x16x32_bf16 v[76:79], v[142:145], v[188:191], v[76:79]
	v_mfma_f32_16x16x32_bf16 v[72:75], v[156:159], v[188:191], v[72:75]
	s_barrier
	s_add_i32 s30, 0, 0x1c000
	s_add_i32 s31, s68, s57
	v_add_u32_e32 v155, s30, v153
	s_mov_b32 m0, s31
	ds_read_b128 v[192:195], v155
	ds_read_b128 v[196:199], v155 offset:1024
	ds_read_b128 v[200:203], v155 offset:2048
	ds_read_b128 v[204:207], v155 offset:3072
	global_load_lds_dwordx4 v208, s[98:99]
	s_add_i32 m0, s31, 0x2000
	s_nop 0
	global_load_lds_dwordx4 v128, s[98:99]
	s_barrier
	s_waitcnt lgkmcnt(0)
	v_mfma_f32_16x16x32_bf16 v[116:119], v[192:195], v[160:163], v[116:119]
	v_mfma_f32_16x16x32_bf16 v[112:115], v[200:203], v[160:163], v[112:115]
	v_mfma_f32_16x16x32_bf16 v[100:103], v[192:195], v[168:171], v[100:103]
	v_mfma_f32_16x16x32_bf16 v[96:99], v[200:203], v[168:171], v[96:99]
	v_mfma_f32_16x16x32_bf16 v[84:87], v[192:195], v[176:179], v[84:87]
	v_mfma_f32_16x16x32_bf16 v[80:83], v[200:203], v[176:179], v[80:83]
	v_mfma_f32_16x16x32_bf16 v[68:71], v[192:195], v[184:187], v[68:71]
	v_mfma_f32_16x16x32_bf16 v[64:67], v[200:203], v[184:187], v[64:67]
	v_mfma_f32_16x16x32_bf16 v[116:119], v[196:199], v[164:167], v[116:119]
	v_mfma_f32_16x16x32_bf16 v[112:115], v[204:207], v[164:167], v[112:115]
	v_mfma_f32_16x16x32_bf16 v[100:103], v[196:199], v[172:175], v[100:103]
	v_mfma_f32_16x16x32_bf16 v[96:99], v[204:207], v[172:175], v[96:99]
	v_mfma_f32_16x16x32_bf16 v[84:87], v[196:199], v[180:183], v[84:87]
	v_mfma_f32_16x16x32_bf16 v[80:83], v[204:207], v[180:183], v[80:83]
	v_mfma_f32_16x16x32_bf16 v[68:71], v[196:199], v[188:191], v[68:71]
	v_mfma_f32_16x16x32_bf16 v[64:67], v[204:207], v[188:191], v[64:67]
	s_mov_b32 m0, s64
	s_barrier
	ds_read_b128 v[160:163], v154 offset:49152
	ds_read_b128 v[164:167], v154 offset:50176
	ds_read_b128 v[168:171], v154 offset:51200
	ds_read_b128 v[172:175], v154 offset:52224
	ds_read_b128 v[176:179], v154 offset:53248
	ds_read_b128 v[180:183], v154 offset:54272
	ds_read_b128 v[184:187], v154 offset:55296
	ds_read_b128 v[188:191], v154 offset:56320
	global_load_lds_dwordx4 v132, s[100:101]
	s_mov_b32 m0, s65
	s_nop 0
	global_load_lds_dwordx4 v130, s[100:101]
	s_barrier
	s_waitcnt lgkmcnt(0)
	v_mfma_f32_16x16x32_bf16 v[60:63], v[138:141], v[160:163], v[60:63]
	v_mfma_f32_16x16x32_bf16 v[56:59], v[146:149], v[160:163], v[56:59]
	v_mfma_f32_16x16x32_bf16 v[44:47], v[138:141], v[168:171], v[44:47]
	v_mfma_f32_16x16x32_bf16 v[40:43], v[146:149], v[168:171], v[40:43]
	v_mfma_f32_16x16x32_bf16 v[28:31], v[138:141], v[176:179], v[28:31]
	v_mfma_f32_16x16x32_bf16 v[24:27], v[146:149], v[176:179], v[24:27]
	v_mfma_f32_16x16x32_bf16 v[12:15], v[138:141], v[184:187], v[12:15]
	v_mfma_f32_16x16x32_bf16 v[8:11], v[146:149], v[184:187], v[8:11]
	v_mfma_f32_16x16x32_bf16 v[60:63], v[142:145], v[164:167], v[60:63]
	v_mfma_f32_16x16x32_bf16 v[56:59], v[156:159], v[164:167], v[56:59]
	v_mfma_f32_16x16x32_bf16 v[44:47], v[142:145], v[172:175], v[44:47]
	v_mfma_f32_16x16x32_bf16 v[40:43], v[156:159], v[172:175], v[40:43]
	v_mfma_f32_16x16x32_bf16 v[28:31], v[142:145], v[180:183], v[28:31]
	v_mfma_f32_16x16x32_bf16 v[24:27], v[156:159], v[180:183], v[24:27]
	v_mfma_f32_16x16x32_bf16 v[12:15], v[142:145], v[188:191], v[12:15]
	v_mfma_f32_16x16x32_bf16 v[8:11], v[156:159], v[188:191], v[8:11]
	s_barrier
	s_add_u32 s28, s28, 0x40080
	s_addc_u32 s29, s29, 0
	s_add_i32 s30, s30, s57
	s_mov_b32 m0, s30
	s_nop 0
	global_load_lds_dwordx4 v208, s[28:29]
	s_add_i32 m0, s30, 0x2000
	s_nop 0
	global_load_lds_dwordx4 v128, s[28:29]
	s_add_i32 s51, s51, 2
	s_add_u32 s26, s26, 0x100
	s_addc_u32 s27, s27, 0
	s_add_u32 s46, s46, 0x100
	s_addc_u32 s50, s50, 0
	s_waitcnt vmcnt(6)
	s_barrier
	v_mfma_f32_16x16x32_bf16 v[52:55], v[192:195], v[160:163], v[52:55]
	v_mfma_f32_16x16x32_bf16 v[48:51], v[200:203], v[160:163], v[48:51]
	v_mfma_f32_16x16x32_bf16 v[36:39], v[192:195], v[168:171], v[36:39]
	v_mfma_f32_16x16x32_bf16 v[32:35], v[200:203], v[168:171], v[32:35]
	v_mfma_f32_16x16x32_bf16 v[20:23], v[192:195], v[176:179], v[20:23]
	v_mfma_f32_16x16x32_bf16 v[16:19], v[200:203], v[176:179], v[16:19]
	v_mfma_f32_16x16x32_bf16 v[4:7], v[192:195], v[184:187], v[4:7]
	v_mfma_f32_16x16x32_bf16 v[0:3], v[200:203], v[184:187], v[0:3]
	v_mfma_f32_16x16x32_bf16 v[52:55], v[196:199], v[164:167], v[52:55]
	v_mfma_f32_16x16x32_bf16 v[48:51], v[204:207], v[164:167], v[48:51]
	v_mfma_f32_16x16x32_bf16 v[36:39], v[196:199], v[172:175], v[36:39]
	v_mfma_f32_16x16x32_bf16 v[32:35], v[204:207], v[172:175], v[32:35]
	v_mfma_f32_16x16x32_bf16 v[20:23], v[196:199], v[180:183], v[20:23]
	v_mfma_f32_16x16x32_bf16 v[16:19], v[204:207], v[180:183], v[16:19]
	v_mfma_f32_16x16x32_bf16 v[4:7], v[196:199], v[188:191], v[4:7]
	v_mfma_f32_16x16x32_bf16 v[0:3], v[204:207], v[188:191], v[0:3]
	s_cmp_gt_u32 s51, 13
	s_barrier
	s_cbranch_scc0 .LBB0_698
	s_cmp_lt_i32 s34, 4
	s_cselect_b64 vcc, -1, 0
	v_mov_b32_e32 v138, 0x3e38aa3b
	s_nop 0
	v_cndmask_b32_e32 v155, 1.0, v138, vcc
	s_and_b64 s[26:27], vcc, exec
	v_lshl_add_u32 v140, s35, 8, v152
	s_cselect_b32 s7, s9, s11
	s_cselect_b32 s21, s8, s10
	v_mov_b32_e32 v138, s21
	v_mov_b32_e32 v139, s7
	v_lshlrev_b32_e32 v142, 3, v151
	v_mov_b32_e32 v143, 0
	v_lshl_add_u64 v[138:139], v[142:143], 2, v[138:139]
	global_load_dwordx4 v[188:191], v[138:139], off
	global_load_dwordx4 v[192:195], v[138:139], off offset:16
	global_load_dwordx4 v[196:199], v[138:139], off offset:128
	global_load_dwordx4 v[200:203], v[138:139], off offset:144
	s_lshl_b32 s7, s34, 8
	s_or_b32 s26, s7, s66
	s_ashr_i32 s27, s26, 31
	s_lshl_b64 s[26:27], s[26:27], 1
	s_add_u32 s26, s62, s26
	s_addc_u32 s27, s63, s27
	s_mov_b32 s34, s6
	s_mov_b32 s35, s20
	s_mov_b64 s[28:29], s[24:25]
	v_mbcnt_lo_u32_b32 v210, -1, 0
	v_mbcnt_hi_u32_b32 v210, -1, v210
	v_and_b32_e32 v210, 48, v210
	v_lshl_add_u32 v210, v140, 6, v210
	v_lshlrev_b32_e32 v211, 12, v140
	v_lshl_add_u32 v211, v151, 4, v211
	global_load_dwordx4 v[156:159], v210, s[18:19]
	global_load_dwordx4 v[160:163], v210, s[18:19] offset:1024
	global_load_dwordx4 v[164:167], v210, s[18:19] offset:2048
	global_load_dwordx4 v[168:171], v210, s[18:19] offset:3072
	v_add_u32_e32 v210, 0x2000, v210
	global_load_dwordx4 v[172:175], v210, s[18:19]
	global_load_dwordx4 v[176:179], v210, s[18:19] offset:1024
	global_load_dwordx4 v[180:183], v210, s[18:19] offset:2048
	global_load_dwordx4 v[184:187], v210, s[18:19] offset:3072
	s_waitcnt vmcnt(7)
	v_pk_add_f32 v[156:157], v[156:157], v[158:159]
	s_nop 0
	v_add_f32_e32 v214, v156, v157
	v_mov_b32_e32 v215, v214
	s_nop 1
	v_permlane16_swap_b32_e32 v214, v215
	s_nop 0
	v_add_f32_e32 v214, v214, v215
	v_mov_b32_e32 v215, v214
	s_nop 1
	v_permlane32_swap_b32_e32 v214, v215
	s_nop 0
	v_add_f32_e32 v214, v214, v215
	v_fmamk_f32 v214, v214, 0x3a800000, v248
	v_rsq_f32_e32 v216, v214
	s_nop 0
	v_pk_mul_f32 v[124:125], v[124:125], v[216:217] op_sel_hi:[1,0]
	v_pk_mul_f32 v[126:127], v[126:127], v[216:217] op_sel_hi:[1,0]
	v_pk_mul_f32 v[120:121], v[120:121], v[216:217] op_sel_hi:[1,0]
	v_pk_mul_f32 v[122:123], v[122:123], v[216:217] op_sel_hi:[1,0]
	v_pk_mul_f32 v[116:117], v[116:117], v[216:217] op_sel_hi:[1,0]
	v_pk_mul_f32 v[118:119], v[118:119], v[216:217] op_sel_hi:[1,0]
	v_pk_mul_f32 v[112:113], v[112:113], v[216:217] op_sel_hi:[1,0]
	v_pk_mul_f32 v[114:115], v[114:115], v[216:217] op_sel_hi:[1,0]
	v_pk_mul_f32 v[148:149], v[124:125], v[124:125]
	v_pk_fma_f32 v[148:149], v[126:127], v[126:127], v[148:149]
	v_pk_fma_f32 v[148:149], v[120:121], v[120:121], v[148:149]
	v_pk_fma_f32 v[148:149], v[122:123], v[122:123], v[148:149]
	v_pk_fma_f32 v[148:149], v[116:117], v[116:117], v[148:149]
	v_pk_fma_f32 v[148:149], v[118:119], v[118:119], v[148:149]
	v_pk_fma_f32 v[148:149], v[112:113], v[112:113], v[148:149]
	v_pk_fma_f32 v[148:149], v[114:115], v[114:115], v[148:149]
	v_add_f32_e32 v214, v148, v149
	v_mov_b32_e32 v215, v214
	s_nop 1
	v_permlane16_swap_b32_e32 v214, v215
	s_nop 0
	v_add_f32_e32 v214, v214, v215
	v_mov_b32_e32 v215, v214
	s_nop 1
	v_permlane32_swap_b32_e32 v214, v215
	s_nop 0
	v_add_f32_e32 v214, v214, v215
	v_fmamk_f32 v214, v214, 0x3c800000, v248
	v_rsq_f32_e32 v214, v214
	s_nop 0
	v_mul_f32_e32 v218, v155, v214
	v_pk_mul_f32 v[156:157], v[188:189], v[218:219] op_sel_hi:[1,0]
	v_pk_mul_f32 v[124:125], v[124:125], v[156:157]
	v_pk_mul_f32 v[156:157], v[190:191], v[218:219] op_sel_hi:[1,0]
	v_pk_mul_f32 v[126:127], v[126:127], v[156:157]
	v_pk_mul_f32 v[156:157], v[192:193], v[218:219] op_sel_hi:[1,0]
	v_pk_mul_f32 v[120:121], v[120:121], v[156:157]
	v_pk_mul_f32 v[156:157], v[194:195], v[218:219] op_sel_hi:[1,0]
	v_pk_mul_f32 v[122:123], v[122:123], v[156:157]
	v_cvt_pk_bf16_f32 v204, v124, v125
	v_cvt_pk_bf16_f32 v205, v126, v127
	v_cvt_pk_bf16_f32 v206, v120, v121
	v_cvt_pk_bf16_f32 v207, v122, v123
	global_store_dwordx4 v211, v[204:207], s[26:27]
	v_pk_mul_f32 v[156:157], v[196:197], v[218:219] op_sel_hi:[1,0]
	v_pk_mul_f32 v[116:117], v[116:117], v[156:157]
	v_pk_mul_f32 v[156:157], v[198:199], v[218:219] op_sel_hi:[1,0]
	v_pk_mul_f32 v[118:119], v[118:119], v[156:157]
	v_pk_mul_f32 v[156:157], v[200:201], v[218:219] op_sel_hi:[1,0]
	v_pk_mul_f32 v[112:113], v[112:113], v[156:157]
	v_pk_mul_f32 v[156:157], v[202:203], v[218:219] op_sel_hi:[1,0]
	v_pk_mul_f32 v[114:115], v[114:115], v[156:157]
	v_cvt_pk_bf16_f32 v144, v116, v117
	v_cvt_pk_bf16_f32 v145, v118, v119
	v_cvt_pk_bf16_f32 v146, v112, v113
	v_cvt_pk_bf16_f32 v147, v114, v115
	global_store_dwordx4 v211, v[144:147], s[26:27] offset:64
	v_add_u32_e32 v211, 0x10000, v211
	s_waitcnt vmcnt(8)
	v_pk_add_f32 v[160:161], v[160:161], v[162:163]
	s_nop 0
	v_add_f32_e32 v214, v160, v161
	v_mov_b32_e32 v215, v214
	s_nop 1
	v_permlane16_swap_b32_e32 v214, v215
	s_nop 0
	v_add_f32_e32 v214, v214, v215
	v_mov_b32_e32 v215, v214
	s_nop 1
	v_permlane32_swap_b32_e32 v214, v215
	s_nop 0
	v_add_f32_e32 v214, v214, v215
	v_fmamk_f32 v214, v214, 0x3a800000, v248
	v_rsq_f32_e32 v216, v214
	s_nop 0
	v_pk_mul_f32 v[108:109], v[108:109], v[216:217] op_sel_hi:[1,0]
	v_pk_mul_f32 v[110:111], v[110:111], v[216:217] op_sel_hi:[1,0]
	v_pk_mul_f32 v[104:105], v[104:105], v[216:217] op_sel_hi:[1,0]
	v_pk_mul_f32 v[106:107], v[106:107], v[216:217] op_sel_hi:[1,0]
	v_pk_mul_f32 v[100:101], v[100:101], v[216:217] op_sel_hi:[1,0]
	v_pk_mul_f32 v[102:103], v[102:103], v[216:217] op_sel_hi:[1,0]
	v_pk_mul_f32 v[96:97], v[96:97], v[216:217] op_sel_hi:[1,0]
	v_pk_mul_f32 v[98:99], v[98:99], v[216:217] op_sel_hi:[1,0]
	v_pk_mul_f32 v[148:149], v[108:109], v[108:109]
	v_pk_fma_f32 v[148:149], v[110:111], v[110:111], v[148:149]
	v_pk_fma_f32 v[148:149], v[104:105], v[104:105], v[148:149]
	v_pk_fma_f32 v[148:149], v[106:107], v[106:107], v[148:149]
	v_pk_fma_f32 v[148:149], v[100:101], v[100:101], v[148:149]
	v_pk_fma_f32 v[148:149], v[102:103], v[102:103], v[148:149]
	v_pk_fma_f32 v[148:149], v[96:97], v[96:97], v[148:149]
	v_pk_fma_f32 v[148:149], v[98:99], v[98:99], v[148:149]
	v_add_f32_e32 v214, v148, v149
	v_mov_b32_e32 v215, v214
	s_nop 1
	v_permlane16_swap_b32_e32 v214, v215
	s_nop 0
	v_add_f32_e32 v214, v214, v215
	v_mov_b32_e32 v215, v214
	s_nop 1
	v_permlane32_swap_b32_e32 v214, v215
	s_nop 0
	v_add_f32_e32 v214, v214, v215
	v_fmamk_f32 v214, v214, 0x3c800000, v248
	v_rsq_f32_e32 v214, v214
	s_nop 0
	v_mul_f32_e32 v218, v155, v214
	v_pk_mul_f32 v[160:161], v[188:189], v[218:219] op_sel_hi:[1,0]
	v_pk_mul_f32 v[108:109], v[108:109], v[160:161]
	v_pk_mul_f32 v[160:161], v[190:191], v[218:219] op_sel_hi:[1,0]
	v_pk_mul_f32 v[110:111], v[110:111], v[160:161]
	v_pk_mul_f32 v[160:161], v[192:193], v[218:219] op_sel_hi:[1,0]
	v_pk_mul_f32 v[104:105], v[104:105], v[160:161]
	v_pk_mul_f32 v[160:161], v[194:195], v[218:219] op_sel_hi:[1,0]
	v_pk_mul_f32 v[106:107], v[106:107], v[160:161]
	v_cvt_pk_bf16_f32 v204, v108, v109
	v_cvt_pk_bf16_f32 v205, v110, v111
	v_cvt_pk_bf16_f32 v206, v104, v105
	v_cvt_pk_bf16_f32 v207, v106, v107
	global_store_dwordx4 v211, v[204:207], s[26:27]
	v_pk_mul_f32 v[160:161], v[196:197], v[218:219] op_sel_hi:[1,0]
	v_pk_mul_f32 v[100:101], v[100:101], v[160:161]
	v_pk_mul_f32 v[160:161], v[198:199], v[218:219] op_sel_hi:[1,0]
	v_pk_mul_f32 v[102:103], v[102:103], v[160:161]
	v_pk_mul_f32 v[160:161], v[200:201], v[218:219] op_sel_hi:[1,0]
	v_pk_mul_f32 v[96:97], v[96:97], v[160:161]
	v_pk_mul_f32 v[160:161], v[202:203], v[218:219] op_sel_hi:[1,0]
	v_pk_mul_f32 v[98:99], v[98:99], v[160:161]
	v_cvt_pk_bf16_f32 v144, v100, v101
	v_cvt_pk_bf16_f32 v145, v102, v103
	v_cvt_pk_bf16_f32 v146, v96, v97
	v_cvt_pk_bf16_f32 v147, v98, v99
	global_store_dwordx4 v211, v[144:147], s[26:27] offset:64
	v_add_u32_e32 v211, 0x10000, v211
	s_waitcnt vmcnt(9)
	v_pk_add_f32 v[164:165], v[164:165], v[166:167]
	s_nop 0
	v_add_f32_e32 v214, v164, v165
	v_mov_b32_e32 v215, v214
	s_nop 1
	v_permlane16_swap_b32_e32 v214, v215
	s_nop 0
	v_add_f32_e32 v214, v214, v215
	v_mov_b32_e32 v215, v214
	s_nop 1
	v_permlane32_swap_b32_e32 v214, v215
	s_nop 0
	v_add_f32_e32 v214, v214, v215
	v_fmamk_f32 v214, v214, 0x3a800000, v248
	v_rsq_f32_e32 v216, v214
	s_nop 0
	v_pk_mul_f32 v[92:93], v[92:93], v[216:217] op_sel_hi:[1,0]
	v_pk_mul_f32 v[94:95], v[94:95], v[216:217] op_sel_hi:[1,0]
	v_pk_mul_f32 v[88:89], v[88:89], v[216:217] op_sel_hi:[1,0]
	v_pk_mul_f32 v[90:91], v[90:91], v[216:217] op_sel_hi:[1,0]
	v_pk_mul_f32 v[84:85], v[84:85], v[216:217] op_sel_hi:[1,0]
	v_pk_mul_f32 v[86:87], v[86:87], v[216:217] op_sel_hi:[1,0]
	v_pk_mul_f32 v[80:81], v[80:81], v[216:217] op_sel_hi:[1,0]
	v_pk_mul_f32 v[82:83], v[82:83], v[216:217] op_sel_hi:[1,0]
	v_pk_mul_f32 v[148:149], v[92:93], v[92:93]
	v_pk_fma_f32 v[148:149], v[94:95], v[94:95], v[148:149]
	v_pk_fma_f32 v[148:149], v[88:89], v[88:89], v[148:149]
	v_pk_fma_f32 v[148:149], v[90:91], v[90:91], v[148:149]
	v_pk_fma_f32 v[148:149], v[84:85], v[84:85], v[148:149]
	v_pk_fma_f32 v[148:149], v[86:87], v[86:87], v[148:149]
	v_pk_fma_f32 v[148:149], v[80:81], v[80:81], v[148:149]
	v_pk_fma_f32 v[148:149], v[82:83], v[82:83], v[148:149]
	v_add_f32_e32 v214, v148, v149
	v_mov_b32_e32 v215, v214
	s_nop 1
	v_permlane16_swap_b32_e32 v214, v215
	s_nop 0
	v_add_f32_e32 v214, v214, v215
	v_mov_b32_e32 v215, v214
	s_nop 1
	v_permlane32_swap_b32_e32 v214, v215
	s_nop 0
	v_add_f32_e32 v214, v214, v215
	v_fmamk_f32 v214, v214, 0x3c800000, v248
	v_rsq_f32_e32 v214, v214
	s_nop 0
	v_mul_f32_e32 v218, v155, v214
	v_pk_mul_f32 v[164:165], v[188:189], v[218:219] op_sel_hi:[1,0]
	v_pk_mul_f32 v[92:93], v[92:93], v[164:165]
	v_pk_mul_f32 v[164:165], v[190:191], v[218:219] op_sel_hi:[1,0]
	v_pk_mul_f32 v[94:95], v[94:95], v[164:165]
	v_pk_mul_f32 v[164:165], v[192:193], v[218:219] op_sel_hi:[1,0]
	v_pk_mul_f32 v[88:89], v[88:89], v[164:165]
	v_pk_mul_f32 v[164:165], v[194:195], v[218:219] op_sel_hi:[1,0]
	v_pk_mul_f32 v[90:91], v[90:91], v[164:165]
	v_cvt_pk_bf16_f32 v204, v92, v93
	v_cvt_pk_bf16_f32 v205, v94, v95
	v_cvt_pk_bf16_f32 v206, v88, v89
	v_cvt_pk_bf16_f32 v207, v90, v91
	global_store_dwordx4 v211, v[204:207], s[26:27]
	v_pk_mul_f32 v[164:165], v[196:197], v[218:219] op_sel_hi:[1,0]
	v_pk_mul_f32 v[84:85], v[84:85], v[164:165]
	v_pk_mul_f32 v[164:165], v[198:199], v[218:219] op_sel_hi:[1,0]
	v_pk_mul_f32 v[86:87], v[86:87], v[164:165]
	v_pk_mul_f32 v[164:165], v[200:201], v[218:219] op_sel_hi:[1,0]
	v_pk_mul_f32 v[80:81], v[80:81], v[164:165]
	v_pk_mul_f32 v[164:165], v[202:203], v[218:219] op_sel_hi:[1,0]
	v_pk_mul_f32 v[82:83], v[82:83], v[164:165]
	v_cvt_pk_bf16_f32 v144, v84, v85
	v_cvt_pk_bf16_f32 v145, v86, v87
	v_cvt_pk_bf16_f32 v146, v80, v81
	v_cvt_pk_bf16_f32 v147, v82, v83
	global_store_dwordx4 v211, v[144:147], s[26:27] offset:64
	v_add_u32_e32 v211, 0x10000, v211
	s_waitcnt vmcnt(10)
	v_pk_add_f32 v[168:169], v[168:169], v[170:171]
	s_nop 0
	v_add_f32_e32 v214, v168, v169
	v_mov_b32_e32 v215, v214
	s_nop 1
	v_permlane16_swap_b32_e32 v214, v215
	s_nop 0
	v_add_f32_e32 v214, v214, v215
	v_mov_b32_e32 v215, v214
	s_nop 1
	v_permlane32_swap_b32_e32 v214, v215
	s_nop 0
	v_add_f32_e32 v214, v214, v215
	v_fmamk_f32 v214, v214, 0x3a800000, v248
	v_rsq_f32_e32 v216, v214
	s_nop 0
	v_pk_mul_f32 v[76:77], v[76:77], v[216:217] op_sel_hi:[1,0]
	v_pk_mul_f32 v[78:79], v[78:79], v[216:217] op_sel_hi:[1,0]
	v_pk_mul_f32 v[72:73], v[72:73], v[216:217] op_sel_hi:[1,0]
	v_pk_mul_f32 v[74:75], v[74:75], v[216:217] op_sel_hi:[1,0]
	v_pk_mul_f32 v[68:69], v[68:69], v[216:217] op_sel_hi:[1,0]
	v_pk_mul_f32 v[70:71], v[70:71], v[216:217] op_sel_hi:[1,0]
	v_pk_mul_f32 v[64:65], v[64:65], v[216:217] op_sel_hi:[1,0]
	v_pk_mul_f32 v[66:67], v[66:67], v[216:217] op_sel_hi:[1,0]
	v_pk_mul_f32 v[148:149], v[76:77], v[76:77]
	v_pk_fma_f32 v[148:149], v[78:79], v[78:79], v[148:149]
	v_pk_fma_f32 v[148:149], v[72:73], v[72:73], v[148:149]
	v_pk_fma_f32 v[148:149], v[74:75], v[74:75], v[148:149]
	v_pk_fma_f32 v[148:149], v[68:69], v[68:69], v[148:149]
	v_pk_fma_f32 v[148:149], v[70:71], v[70:71], v[148:149]
	v_pk_fma_f32 v[148:149], v[64:65], v[64:65], v[148:149]
	v_pk_fma_f32 v[148:149], v[66:67], v[66:67], v[148:149]
	v_add_f32_e32 v214, v148, v149
	v_mov_b32_e32 v215, v214
	s_nop 1
	v_permlane16_swap_b32_e32 v214, v215
	s_nop 0
	v_add_f32_e32 v214, v214, v215
	v_mov_b32_e32 v215, v214
	s_nop 1
	v_permlane32_swap_b32_e32 v214, v215
	s_nop 0
	v_add_f32_e32 v214, v214, v215
	v_fmamk_f32 v214, v214, 0x3c800000, v248
	v_rsq_f32_e32 v214, v214
	s_nop 0
	v_mul_f32_e32 v218, v155, v214
	v_pk_mul_f32 v[168:169], v[188:189], v[218:219] op_sel_hi:[1,0]
	v_pk_mul_f32 v[76:77], v[76:77], v[168:169]
	v_pk_mul_f32 v[168:169], v[190:191], v[218:219] op_sel_hi:[1,0]
	v_pk_mul_f32 v[78:79], v[78:79], v[168:169]
	v_pk_mul_f32 v[168:169], v[192:193], v[218:219] op_sel_hi:[1,0]
	v_pk_mul_f32 v[72:73], v[72:73], v[168:169]
	v_pk_mul_f32 v[168:169], v[194:195], v[218:219] op_sel_hi:[1,0]
	v_pk_mul_f32 v[74:75], v[74:75], v[168:169]
	v_cvt_pk_bf16_f32 v204, v76, v77
	v_cvt_pk_bf16_f32 v205, v78, v79
	v_cvt_pk_bf16_f32 v206, v72, v73
	v_cvt_pk_bf16_f32 v207, v74, v75
	global_store_dwordx4 v211, v[204:207], s[26:27]
	v_pk_mul_f32 v[168:169], v[196:197], v[218:219] op_sel_hi:[1,0]
	v_pk_mul_f32 v[68:69], v[68:69], v[168:169]
	v_pk_mul_f32 v[168:169], v[198:199], v[218:219] op_sel_hi:[1,0]
	v_pk_mul_f32 v[70:71], v[70:71], v[168:169]
	v_pk_mul_f32 v[168:169], v[200:201], v[218:219] op_sel_hi:[1,0]
	v_pk_mul_f32 v[64:65], v[64:65], v[168:169]
	v_pk_mul_f32 v[168:169], v[202:203], v[218:219] op_sel_hi:[1,0]
	v_pk_mul_f32 v[66:67], v[66:67], v[168:169]
	v_cvt_pk_bf16_f32 v144, v68, v69
	v_cvt_pk_bf16_f32 v145, v70, v71
	v_cvt_pk_bf16_f32 v146, v64, v65
	v_cvt_pk_bf16_f32 v147, v66, v67
	global_store_dwordx4 v211, v[144:147], s[26:27] offset:64
	v_add_u32_e32 v211, 0x50000, v211
	s_waitcnt vmcnt(11)
	v_pk_add_f32 v[172:173], v[172:173], v[174:175]
	s_nop 0
	v_add_f32_e32 v214, v172, v173
	v_mov_b32_e32 v215, v214
	s_nop 1
	v_permlane16_swap_b32_e32 v214, v215
	s_nop 0
	v_add_f32_e32 v214, v214, v215
	v_mov_b32_e32 v215, v214
	s_nop 1
	v_permlane32_swap_b32_e32 v214, v215
	s_nop 0
	v_add_f32_e32 v214, v214, v215
	v_fmamk_f32 v214, v214, 0x3a800000, v248
	v_rsq_f32_e32 v216, v214
	s_nop 0
	v_pk_mul_f32 v[60:61], v[60:61], v[216:217] op_sel_hi:[1,0]
	v_pk_mul_f32 v[62:63], v[62:63], v[216:217] op_sel_hi:[1,0]
	v_pk_mul_f32 v[56:57], v[56:57], v[216:217] op_sel_hi:[1,0]
	v_pk_mul_f32 v[58:59], v[58:59], v[216:217] op_sel_hi:[1,0]
	v_pk_mul_f32 v[52:53], v[52:53], v[216:217] op_sel_hi:[1,0]
	v_pk_mul_f32 v[54:55], v[54:55], v[216:217] op_sel_hi:[1,0]
	v_pk_mul_f32 v[48:49], v[48:49], v[216:217] op_sel_hi:[1,0]
	v_pk_mul_f32 v[50:51], v[50:51], v[216:217] op_sel_hi:[1,0]
	v_pk_mul_f32 v[148:149], v[60:61], v[60:61]
	v_pk_fma_f32 v[148:149], v[62:63], v[62:63], v[148:149]
	v_pk_fma_f32 v[148:149], v[56:57], v[56:57], v[148:149]
	v_pk_fma_f32 v[148:149], v[58:59], v[58:59], v[148:149]
	v_pk_fma_f32 v[148:149], v[52:53], v[52:53], v[148:149]
	v_pk_fma_f32 v[148:149], v[54:55], v[54:55], v[148:149]
	v_pk_fma_f32 v[148:149], v[48:49], v[48:49], v[148:149]
	v_pk_fma_f32 v[148:149], v[50:51], v[50:51], v[148:149]
	v_add_f32_e32 v214, v148, v149
	v_mov_b32_e32 v215, v214
	s_nop 1
	v_permlane16_swap_b32_e32 v214, v215
	s_nop 0
	v_add_f32_e32 v214, v214, v215
	v_mov_b32_e32 v215, v214
	s_nop 1
	v_permlane32_swap_b32_e32 v214, v215
	s_nop 0
	v_add_f32_e32 v214, v214, v215
	v_fmamk_f32 v214, v214, 0x3c800000, v248
	v_rsq_f32_e32 v214, v214
	s_nop 0
	v_mul_f32_e32 v218, v155, v214
	v_pk_mul_f32 v[172:173], v[188:189], v[218:219] op_sel_hi:[1,0]
	v_pk_mul_f32 v[60:61], v[60:61], v[172:173]
	v_pk_mul_f32 v[172:173], v[190:191], v[218:219] op_sel_hi:[1,0]
	v_pk_mul_f32 v[62:63], v[62:63], v[172:173]
	v_pk_mul_f32 v[172:173], v[192:193], v[218:219] op_sel_hi:[1,0]
	v_pk_mul_f32 v[56:57], v[56:57], v[172:173]
	v_pk_mul_f32 v[172:173], v[194:195], v[218:219] op_sel_hi:[1,0]
	v_pk_mul_f32 v[58:59], v[58:59], v[172:173]
	v_cvt_pk_bf16_f32 v204, v60, v61
	v_cvt_pk_bf16_f32 v205, v62, v63
	v_cvt_pk_bf16_f32 v206, v56, v57
	v_cvt_pk_bf16_f32 v207, v58, v59
	global_store_dwordx4 v211, v[204:207], s[26:27]
	v_pk_mul_f32 v[172:173], v[196:197], v[218:219] op_sel_hi:[1,0]
	v_pk_mul_f32 v[52:53], v[52:53], v[172:173]
	v_pk_mul_f32 v[172:173], v[198:199], v[218:219] op_sel_hi:[1,0]
	v_pk_mul_f32 v[54:55], v[54:55], v[172:173]
	v_pk_mul_f32 v[172:173], v[200:201], v[218:219] op_sel_hi:[1,0]
	v_pk_mul_f32 v[48:49], v[48:49], v[172:173]
	v_pk_mul_f32 v[172:173], v[202:203], v[218:219] op_sel_hi:[1,0]
	v_pk_mul_f32 v[50:51], v[50:51], v[172:173]
	v_cvt_pk_bf16_f32 v144, v52, v53
	v_cvt_pk_bf16_f32 v145, v54, v55
	v_cvt_pk_bf16_f32 v146, v48, v49
	v_cvt_pk_bf16_f32 v147, v50, v51
	global_store_dwordx4 v211, v[144:147], s[26:27] offset:64
	v_add_u32_e32 v211, 0x10000, v211
	s_waitcnt vmcnt(12)
	v_pk_add_f32 v[176:177], v[176:177], v[178:179]
	s_nop 0
	v_add_f32_e32 v214, v176, v177
	v_mov_b32_e32 v215, v214
	s_nop 1
	v_permlane16_swap_b32_e32 v214, v215
	s_nop 0
	v_add_f32_e32 v214, v214, v215
	v_mov_b32_e32 v215, v214
	s_nop 1
	v_permlane32_swap_b32_e32 v214, v215
	s_nop 0
	v_add_f32_e32 v214, v214, v215
	v_fmamk_f32 v214, v214, 0x3a800000, v248
	v_rsq_f32_e32 v216, v214
	s_nop 0
	v_pk_mul_f32 v[44:45], v[44:45], v[216:217] op_sel_hi:[1,0]
	v_pk_mul_f32 v[46:47], v[46:47], v[216:217] op_sel_hi:[1,0]
	v_pk_mul_f32 v[40:41], v[40:41], v[216:217] op_sel_hi:[1,0]
	v_pk_mul_f32 v[42:43], v[42:43], v[216:217] op_sel_hi:[1,0]
	v_pk_mul_f32 v[36:37], v[36:37], v[216:217] op_sel_hi:[1,0]
	v_pk_mul_f32 v[38:39], v[38:39], v[216:217] op_sel_hi:[1,0]
	v_pk_mul_f32 v[32:33], v[32:33], v[216:217] op_sel_hi:[1,0]
	v_pk_mul_f32 v[34:35], v[34:35], v[216:217] op_sel_hi:[1,0]
	v_pk_mul_f32 v[148:149], v[44:45], v[44:45]
	v_pk_fma_f32 v[148:149], v[46:47], v[46:47], v[148:149]
	v_pk_fma_f32 v[148:149], v[40:41], v[40:41], v[148:149]
	v_pk_fma_f32 v[148:149], v[42:43], v[42:43], v[148:149]
	v_pk_fma_f32 v[148:149], v[36:37], v[36:37], v[148:149]
	v_pk_fma_f32 v[148:149], v[38:39], v[38:39], v[148:149]
	v_pk_fma_f32 v[148:149], v[32:33], v[32:33], v[148:149]
	v_pk_fma_f32 v[148:149], v[34:35], v[34:35], v[148:149]
	v_add_f32_e32 v214, v148, v149
	v_mov_b32_e32 v215, v214
	s_nop 1
	v_permlane16_swap_b32_e32 v214, v215
	s_nop 0
	v_add_f32_e32 v214, v214, v215
	v_mov_b32_e32 v215, v214
	s_nop 1
	v_permlane32_swap_b32_e32 v214, v215
	s_nop 0
	v_add_f32_e32 v214, v214, v215
	v_fmamk_f32 v214, v214, 0x3c800000, v248
	v_rsq_f32_e32 v214, v214
	s_nop 0
	v_mul_f32_e32 v218, v155, v214
	v_pk_mul_f32 v[176:177], v[188:189], v[218:219] op_sel_hi:[1,0]
	v_pk_mul_f32 v[44:45], v[44:45], v[176:177]
	v_pk_mul_f32 v[176:177], v[190:191], v[218:219] op_sel_hi:[1,0]
	v_pk_mul_f32 v[46:47], v[46:47], v[176:177]
	v_pk_mul_f32 v[176:177], v[192:193], v[218:219] op_sel_hi:[1,0]
	v_pk_mul_f32 v[40:41], v[40:41], v[176:177]
	v_pk_mul_f32 v[176:177], v[194:195], v[218:219] op_sel_hi:[1,0]
	v_pk_mul_f32 v[42:43], v[42:43], v[176:177]
	v_cvt_pk_bf16_f32 v204, v44, v45
	v_cvt_pk_bf16_f32 v205, v46, v47
	v_cvt_pk_bf16_f32 v206, v40, v41
	v_cvt_pk_bf16_f32 v207, v42, v43
	global_store_dwordx4 v211, v[204:207], s[26:27]
	v_pk_mul_f32 v[176:177], v[196:197], v[218:219] op_sel_hi:[1,0]
	v_pk_mul_f32 v[36:37], v[36:37], v[176:177]
	v_pk_mul_f32 v[176:177], v[198:199], v[218:219] op_sel_hi:[1,0]
	v_pk_mul_f32 v[38:39], v[38:39], v[176:177]
	v_pk_mul_f32 v[176:177], v[200:201], v[218:219] op_sel_hi:[1,0]
	v_pk_mul_f32 v[32:33], v[32:33], v[176:177]
	v_pk_mul_f32 v[176:177], v[202:203], v[218:219] op_sel_hi:[1,0]
	v_pk_mul_f32 v[34:35], v[34:35], v[176:177]
	v_cvt_pk_bf16_f32 v144, v36, v37
	v_cvt_pk_bf16_f32 v145, v38, v39
	v_cvt_pk_bf16_f32 v146, v32, v33
	v_cvt_pk_bf16_f32 v147, v34, v35
	global_store_dwordx4 v211, v[144:147], s[26:27] offset:64
	v_add_u32_e32 v211, 0x10000, v211
	s_waitcnt vmcnt(13)
	v_pk_add_f32 v[180:181], v[180:181], v[182:183]
	s_nop 0
	v_add_f32_e32 v214, v180, v181
	v_mov_b32_e32 v215, v214
	s_nop 1
	v_permlane16_swap_b32_e32 v214, v215
	s_nop 0
	v_add_f32_e32 v214, v214, v215
	v_mov_b32_e32 v215, v214
	s_nop 1
	v_permlane32_swap_b32_e32 v214, v215
	s_nop 0
	v_add_f32_e32 v214, v214, v215
	v_fmamk_f32 v214, v214, 0x3a800000, v248
	v_rsq_f32_e32 v216, v214
	s_nop 0
	v_pk_mul_f32 v[28:29], v[28:29], v[216:217] op_sel_hi:[1,0]
	v_pk_mul_f32 v[30:31], v[30:31], v[216:217] op_sel_hi:[1,0]
	v_pk_mul_f32 v[24:25], v[24:25], v[216:217] op_sel_hi:[1,0]
	v_pk_mul_f32 v[26:27], v[26:27], v[216:217] op_sel_hi:[1,0]
	v_pk_mul_f32 v[20:21], v[20:21], v[216:217] op_sel_hi:[1,0]
	v_pk_mul_f32 v[22:23], v[22:23], v[216:217] op_sel_hi:[1,0]
	v_pk_mul_f32 v[16:17], v[16:17], v[216:217] op_sel_hi:[1,0]
	v_pk_mul_f32 v[18:19], v[18:19], v[216:217] op_sel_hi:[1,0]
	v_pk_mul_f32 v[148:149], v[28:29], v[28:29]
	v_pk_fma_f32 v[148:149], v[30:31], v[30:31], v[148:149]
	v_pk_fma_f32 v[148:149], v[24:25], v[24:25], v[148:149]
	v_pk_fma_f32 v[148:149], v[26:27], v[26:27], v[148:149]
	v_pk_fma_f32 v[148:149], v[20:21], v[20:21], v[148:149]
	v_pk_fma_f32 v[148:149], v[22:23], v[22:23], v[148:149]
	v_pk_fma_f32 v[148:149], v[16:17], v[16:17], v[148:149]
	v_pk_fma_f32 v[148:149], v[18:19], v[18:19], v[148:149]
	v_add_f32_e32 v214, v148, v149
	v_mov_b32_e32 v215, v214
	s_nop 1
	v_permlane16_swap_b32_e32 v214, v215
	s_nop 0
	v_add_f32_e32 v214, v214, v215
	v_mov_b32_e32 v215, v214
	s_nop 1
	v_permlane32_swap_b32_e32 v214, v215
	s_nop 0
	v_add_f32_e32 v214, v214, v215
	v_fmamk_f32 v214, v214, 0x3c800000, v248
	v_rsq_f32_e32 v214, v214
	s_nop 0
	v_mul_f32_e32 v218, v155, v214
	v_pk_mul_f32 v[180:181], v[188:189], v[218:219] op_sel_hi:[1,0]
	v_pk_mul_f32 v[28:29], v[28:29], v[180:181]
	v_pk_mul_f32 v[180:181], v[190:191], v[218:219] op_sel_hi:[1,0]
	v_pk_mul_f32 v[30:31], v[30:31], v[180:181]
	v_pk_mul_f32 v[180:181], v[192:193], v[218:219] op_sel_hi:[1,0]
	v_pk_mul_f32 v[24:25], v[24:25], v[180:181]
	v_pk_mul_f32 v[180:181], v[194:195], v[218:219] op_sel_hi:[1,0]
	v_pk_mul_f32 v[26:27], v[26:27], v[180:181]
	v_cvt_pk_bf16_f32 v204, v28, v29
	v_cvt_pk_bf16_f32 v205, v30, v31
	v_cvt_pk_bf16_f32 v206, v24, v25
	v_cvt_pk_bf16_f32 v207, v26, v27
	global_store_dwordx4 v211, v[204:207], s[26:27]
	v_pk_mul_f32 v[180:181], v[196:197], v[218:219] op_sel_hi:[1,0]
	v_pk_mul_f32 v[20:21], v[20:21], v[180:181]
	v_pk_mul_f32 v[180:181], v[198:199], v[218:219] op_sel_hi:[1,0]
	v_pk_mul_f32 v[22:23], v[22:23], v[180:181]
	v_pk_mul_f32 v[180:181], v[200:201], v[218:219] op_sel_hi:[1,0]
	v_pk_mul_f32 v[16:17], v[16:17], v[180:181]
	v_pk_mul_f32 v[180:181], v[202:203], v[218:219] op_sel_hi:[1,0]
	v_pk_mul_f32 v[18:19], v[18:19], v[180:181]
	v_cvt_pk_bf16_f32 v144, v20, v21
	v_cvt_pk_bf16_f32 v145, v22, v23
	v_cvt_pk_bf16_f32 v146, v16, v17
	v_cvt_pk_bf16_f32 v147, v18, v19
	global_store_dwordx4 v211, v[144:147], s[26:27] offset:64
	v_add_u32_e32 v211, 0x10000, v211
	s_waitcnt vmcnt(14)
	v_pk_add_f32 v[184:185], v[184:185], v[186:187]
	s_nop 0
	v_add_f32_e32 v214, v184, v185
	v_mov_b32_e32 v215, v214
	s_nop 1
	v_permlane16_swap_b32_e32 v214, v215
	s_nop 0
	v_add_f32_e32 v214, v214, v215
	v_mov_b32_e32 v215, v214
	s_nop 1
	v_permlane32_swap_b32_e32 v214, v215
	s_nop 0
	v_add_f32_e32 v214, v214, v215
	v_fmamk_f32 v214, v214, 0x3a800000, v248
	v_rsq_f32_e32 v216, v214
	s_nop 0
	v_pk_mul_f32 v[12:13], v[12:13], v[216:217] op_sel_hi:[1,0]
	v_pk_mul_f32 v[14:15], v[14:15], v[216:217] op_sel_hi:[1,0]
	v_pk_mul_f32 v[8:9], v[8:9], v[216:217] op_sel_hi:[1,0]
	v_pk_mul_f32 v[10:11], v[10:11], v[216:217] op_sel_hi:[1,0]
	v_pk_mul_f32 v[4:5], v[4:5], v[216:217] op_sel_hi:[1,0]
	v_pk_mul_f32 v[6:7], v[6:7], v[216:217] op_sel_hi:[1,0]
	v_pk_mul_f32 v[0:1], v[0:1], v[216:217] op_sel_hi:[1,0]
	v_pk_mul_f32 v[2:3], v[2:3], v[216:217] op_sel_hi:[1,0]
	v_pk_mul_f32 v[148:149], v[12:13], v[12:13]
	v_pk_fma_f32 v[148:149], v[14:15], v[14:15], v[148:149]
	v_pk_fma_f32 v[148:149], v[8:9], v[8:9], v[148:149]
	v_pk_fma_f32 v[148:149], v[10:11], v[10:11], v[148:149]
	v_pk_fma_f32 v[148:149], v[4:5], v[4:5], v[148:149]
	v_pk_fma_f32 v[148:149], v[6:7], v[6:7], v[148:149]
	v_pk_fma_f32 v[148:149], v[0:1], v[0:1], v[148:149]
	v_pk_fma_f32 v[148:149], v[2:3], v[2:3], v[148:149]
	v_add_f32_e32 v214, v148, v149
	v_mov_b32_e32 v215, v214
	s_nop 1
	v_permlane16_swap_b32_e32 v214, v215
	s_nop 0
	v_add_f32_e32 v214, v214, v215
	v_mov_b32_e32 v215, v214
	s_nop 1
	v_permlane32_swap_b32_e32 v214, v215
	s_nop 0
	v_add_f32_e32 v214, v214, v215
	v_fmamk_f32 v214, v214, 0x3c800000, v248
	v_rsq_f32_e32 v214, v214
	s_nop 0
	v_mul_f32_e32 v218, v155, v214
	v_pk_mul_f32 v[184:185], v[188:189], v[218:219] op_sel_hi:[1,0]
	v_pk_mul_f32 v[12:13], v[12:13], v[184:185]
	v_pk_mul_f32 v[184:185], v[190:191], v[218:219] op_sel_hi:[1,0]
	v_pk_mul_f32 v[14:15], v[14:15], v[184:185]
	v_pk_mul_f32 v[184:185], v[192:193], v[218:219] op_sel_hi:[1,0]
	v_pk_mul_f32 v[8:9], v[8:9], v[184:185]
	v_pk_mul_f32 v[184:185], v[194:195], v[218:219] op_sel_hi:[1,0]
	v_pk_mul_f32 v[10:11], v[10:11], v[184:185]
	v_cvt_pk_bf16_f32 v204, v12, v13
	v_cvt_pk_bf16_f32 v205, v14, v15
	v_cvt_pk_bf16_f32 v206, v8, v9
	v_cvt_pk_bf16_f32 v207, v10, v11
	global_store_dwordx4 v211, v[204:207], s[26:27]
	v_pk_mul_f32 v[184:185], v[196:197], v[218:219] op_sel_hi:[1,0]
	v_pk_mul_f32 v[4:5], v[4:5], v[184:185]
	v_pk_mul_f32 v[184:185], v[198:199], v[218:219] op_sel_hi:[1,0]
	v_pk_mul_f32 v[6:7], v[6:7], v[184:185]
	v_pk_mul_f32 v[184:185], v[200:201], v[218:219] op_sel_hi:[1,0]
	v_pk_mul_f32 v[0:1], v[0:1], v[184:185]
	v_pk_mul_f32 v[184:185], v[202:203], v[218:219] op_sel_hi:[1,0]
	v_pk_mul_f32 v[2:3], v[2:3], v[184:185]
	v_cvt_pk_bf16_f32 v144, v4, v5
	v_cvt_pk_bf16_f32 v145, v6, v7
	v_cvt_pk_bf16_f32 v146, v0, v1
	v_cvt_pk_bf16_f32 v147, v2, v3
	global_store_dwordx4 v211, v[144:147], s[26:27] offset:64
	s_and_b64 vcc, exec, s[4:5]
	s_mov_b64 s[26:27], s[22:23]
	s_cbranch_vccz .LBB0_691
	s_waitcnt vmcnt(0)
	s_cmpk_gt_u32 s54, 0xff
	s_cbranch_scc1 .LBB0_702
	s_barrier

.LBB0_714:
	s_add_u32 s26, s6, 0xfffc0080
	s_addc_u32 s27, s7, -1
	s_add_i32 s63, 0, 0x10000
	v_add_u32_e32 v140, s63, v165
	ds_read_b128 v[128:131], v140
	ds_read_b128 v[132:135], v140 offset:1024
	ds_read_b128 v[136:139], v140 offset:2048
	ds_read_b128 v[140:143], v140 offset:3072
	s_cmp_eq_u32 s51, 12
	s_cselect_b32 s29, s21, s27
	s_cselect_b32 s28, s38, s26
	s_cselect_b32 s27, s11, s50
	s_cselect_b32 s26, s39, s46
	s_add_i32 m0, s56, 0xc000
	ds_read_b128 v[154:157], v167
	ds_read_b128 v[158:161], v167 offset:1024
	ds_read_b128 v[168:171], v167 offset:2048
	ds_read_b128 v[172:175], v167 offset:3072
	ds_read_b128 v[176:179], v167 offset:4096
	ds_read_b128 v[180:183], v167 offset:5120
	ds_read_b128 v[184:187], v167 offset:6144
	ds_read_b128 v[188:191], v167 offset:7168
	global_load_lds_dwordx4 v150, s[6:7]
	s_add_i32 m0, s56, 0xe000
	s_nop 0
	global_load_lds_dwordx4 v152, s[6:7]
	s_waitcnt lgkmcnt(8)
	s_barrier
	s_waitcnt lgkmcnt(0)
	v_mfma_f32_16x16x32_bf16 v[124:127], v[128:131], v[154:157], v[124:127]
	v_mfma_f32_16x16x32_bf16 v[120:123], v[136:139], v[154:157], v[120:123]
	v_mfma_f32_16x16x32_bf16 v[116:119], v[128:131], v[168:171], v[116:119]
	v_mfma_f32_16x16x32_bf16 v[112:115], v[136:139], v[168:171], v[112:115]
	v_mfma_f32_16x16x32_bf16 v[108:111], v[128:131], v[176:179], v[108:111]
	v_mfma_f32_16x16x32_bf16 v[104:107], v[136:139], v[176:179], v[104:107]
	v_mfma_f32_16x16x32_bf16 v[100:103], v[128:131], v[184:187], v[100:103]
	v_mfma_f32_16x16x32_bf16 v[96:99], v[136:139], v[184:187], v[96:99]
	v_mfma_f32_16x16x32_bf16 v[124:127], v[132:135], v[158:161], v[124:127]
	v_mfma_f32_16x16x32_bf16 v[120:123], v[140:143], v[158:161], v[120:123]
	v_mfma_f32_16x16x32_bf16 v[116:119], v[132:135], v[172:175], v[116:119]
	v_mfma_f32_16x16x32_bf16 v[112:115], v[140:143], v[172:175], v[112:115]
	v_mfma_f32_16x16x32_bf16 v[108:111], v[132:135], v[180:183], v[108:111]
	v_mfma_f32_16x16x32_bf16 v[104:107], v[140:143], v[180:183], v[104:107]
	v_mfma_f32_16x16x32_bf16 v[100:103], v[132:135], v[188:191], v[100:103]
	v_mfma_f32_16x16x32_bf16 v[96:99], v[140:143], v[188:191], v[96:99]
	s_barrier
	s_add_i32 s66, 0, 0x14000
	v_add_u32_e32 v162, s66, v165
	s_add_i32 s63, s63, s55
	ds_read_b128 v[192:195], v162
	ds_read_b128 v[196:199], v162 offset:1024
	ds_read_b128 v[200:203], v162 offset:2048
	ds_read_b128 v[204:207], v162 offset:3072
	s_add_u32 s98, s26, s40
	s_addc_u32 s99, s27, s41
	s_mov_b32 m0, s63
	s_nop 0
	global_load_lds_dwordx4 v208, s[26:27]
	s_add_i32 m0, s63, 0x2000
	s_nop 0
	global_load_lds_dwordx4 v144, s[26:27]
	s_barrier
	s_waitcnt lgkmcnt(0)
	v_mfma_f32_16x16x32_bf16 v[60:63], v[192:195], v[154:157], v[60:63]
	v_mfma_f32_16x16x32_bf16 v[56:59], v[200:203], v[154:157], v[56:59]
	v_mfma_f32_16x16x32_bf16 v[52:55], v[192:195], v[168:171], v[52:55]
	v_mfma_f32_16x16x32_bf16 v[48:51], v[200:203], v[168:171], v[48:51]
	v_mfma_f32_16x16x32_bf16 v[44:47], v[192:195], v[176:179], v[44:47]
	v_mfma_f32_16x16x32_bf16 v[40:43], v[200:203], v[176:179], v[40:43]
	v_mfma_f32_16x16x32_bf16 v[36:39], v[192:195], v[184:187], v[36:39]
	v_mfma_f32_16x16x32_bf16 v[32:35], v[200:203], v[184:187], v[32:35]
	v_mfma_f32_16x16x32_bf16 v[60:63], v[196:199], v[158:161], v[60:63]
	v_mfma_f32_16x16x32_bf16 v[56:59], v[204:207], v[158:161], v[56:59]
	v_mfma_f32_16x16x32_bf16 v[52:55], v[196:199], v[172:175], v[52:55]
	v_mfma_f32_16x16x32_bf16 v[48:51], v[204:207], v[172:175], v[48:51]
	v_mfma_f32_16x16x32_bf16 v[44:47], v[196:199], v[180:183], v[44:47]
	v_mfma_f32_16x16x32_bf16 v[40:43], v[204:207], v[180:183], v[40:43]
	v_mfma_f32_16x16x32_bf16 v[36:39], v[196:199], v[188:191], v[36:39]
	v_mfma_f32_16x16x32_bf16 v[32:35], v[204:207], v[188:191], v[32:35]
	s_mov_b32 m0, s56
	s_add_u32 s100, s28, s40
	s_addc_u32 s101, s29, s41
	s_barrier
	ds_read_b128 v[154:157], v167 offset:16384
	ds_read_b128 v[158:161], v167 offset:17408
	ds_read_b128 v[168:171], v167 offset:18432
	ds_read_b128 v[172:175], v167 offset:19456
	ds_read_b128 v[176:179], v167 offset:20480
	ds_read_b128 v[180:183], v167 offset:21504
	ds_read_b128 v[184:187], v167 offset:22528
	ds_read_b128 v[188:191], v167 offset:23552
	global_load_lds_dwordx4 v148, s[28:29]
	s_mov_b32 m0, s57
	s_nop 0
	global_load_lds_dwordx4 v146, s[28:29]
	s_barrier
	s_waitcnt lgkmcnt(0)
	v_mfma_f32_16x16x32_bf16 v[92:95], v[128:131], v[154:157], v[92:95]
	v_mfma_f32_16x16x32_bf16 v[88:91], v[136:139], v[154:157], v[88:91]
	v_mfma_f32_16x16x32_bf16 v[84:87], v[128:131], v[168:171], v[84:87]
	v_mfma_f32_16x16x32_bf16 v[80:83], v[136:139], v[168:171], v[80:83]
	v_mfma_f32_16x16x32_bf16 v[76:79], v[128:131], v[176:179], v[76:79]
	v_mfma_f32_16x16x32_bf16 v[72:75], v[136:139], v[176:179], v[72:75]
	v_mfma_f32_16x16x32_bf16 v[68:71], v[128:131], v[184:187], v[68:71]
	v_mfma_f32_16x16x32_bf16 v[64:67], v[136:139], v[184:187], v[64:67]
	v_mfma_f32_16x16x32_bf16 v[92:95], v[132:135], v[158:161], v[92:95]
	v_mfma_f32_16x16x32_bf16 v[88:91], v[140:143], v[158:161], v[88:91]
	v_mfma_f32_16x16x32_bf16 v[84:87], v[132:135], v[172:175], v[84:87]
	v_mfma_f32_16x16x32_bf16 v[80:83], v[140:143], v[172:175], v[80:83]
	v_mfma_f32_16x16x32_bf16 v[76:79], v[132:135], v[180:183], v[76:79]
	v_mfma_f32_16x16x32_bf16 v[72:75], v[140:143], v[180:183], v[72:75]
	v_mfma_f32_16x16x32_bf16 v[68:71], v[132:135], v[188:191], v[68:71]
	v_mfma_f32_16x16x32_bf16 v[64:67], v[140:143], v[188:191], v[64:67]
	s_barrier
	s_add_u32 s64, s26, 0x40000
	s_addc_u32 s65, s27, 0
	s_add_i32 s63, s66, s55
	s_mov_b32 m0, s63
	s_nop 0
	global_load_lds_dwordx4 v208, s[64:65]
	s_add_i32 m0, s63, 0x2000
	s_nop 0
	global_load_lds_dwordx4 v144, s[64:65]
	s_waitcnt vmcnt(6)
	s_barrier
	v_mfma_f32_16x16x32_bf16 v[28:31], v[192:195], v[154:157], v[28:31]
	v_mfma_f32_16x16x32_bf16 v[24:27], v[200:203], v[154:157], v[24:27]
	v_mfma_f32_16x16x32_bf16 v[20:23], v[192:195], v[168:171], v[20:23]
	v_mfma_f32_16x16x32_bf16 v[16:19], v[200:203], v[168:171], v[16:19]
	v_mfma_f32_16x16x32_bf16 v[12:15], v[192:195], v[176:179], v[12:15]
	v_mfma_f32_16x16x32_bf16 v[8:11], v[200:203], v[176:179], v[8:11]
	v_mfma_f32_16x16x32_bf16 v[4:7], v[192:195], v[184:187], v[4:7]
	v_mfma_f32_16x16x32_bf16 v[0:3], v[200:203], v[184:187], v[0:3]
	v_mfma_f32_16x16x32_bf16 v[28:31], v[196:199], v[158:161], v[28:31]
	v_mfma_f32_16x16x32_bf16 v[24:27], v[204:207], v[158:161], v[24:27]
	v_mfma_f32_16x16x32_bf16 v[20:23], v[196:199], v[172:175], v[20:23]
	v_mfma_f32_16x16x32_bf16 v[16:19], v[204:207], v[172:175], v[16:19]
	v_mfma_f32_16x16x32_bf16 v[12:15], v[196:199], v[180:183], v[12:15]
	v_mfma_f32_16x16x32_bf16 v[8:11], v[204:207], v[180:183], v[8:11]
	v_mfma_f32_16x16x32_bf16 v[4:7], v[196:199], v[188:191], v[4:7]
	v_mfma_f32_16x16x32_bf16 v[0:3], v[204:207], v[188:191], v[0:3]
	s_add_i32 s63, 0, 0x18000
	v_add_u32_e32 v140, s63, v165
	s_barrier
	ds_read_b128 v[128:131], v140
	ds_read_b128 v[132:135], v140 offset:1024
	ds_read_b128 v[136:139], v140 offset:2048
	ds_read_b128 v[140:143], v140 offset:3072
	s_add_u32 s28, s28, 0x40000
	s_addc_u32 s29, s29, 0
	s_mov_b32 m0, s58
	ds_read_b128 v[154:157], v167 offset:32768
	ds_read_b128 v[158:161], v167 offset:33792
	ds_read_b128 v[168:171], v167 offset:34816
	ds_read_b128 v[172:175], v167 offset:35840
	ds_read_b128 v[176:179], v167 offset:36864
	ds_read_b128 v[180:183], v167 offset:37888
	ds_read_b128 v[184:187], v167 offset:38912
	ds_read_b128 v[188:191], v167 offset:39936
	global_load_lds_dwordx4 v148, s[28:29]
	s_mov_b32 m0, s59
	s_nop 0
	global_load_lds_dwordx4 v146, s[28:29]
	s_waitcnt lgkmcnt(8)
	s_barrier
	s_waitcnt lgkmcnt(0)
	v_mfma_f32_16x16x32_bf16 v[124:127], v[128:131], v[154:157], v[124:127]
	v_mfma_f32_16x16x32_bf16 v[120:123], v[136:139], v[154:157], v[120:123]
	v_mfma_f32_16x16x32_bf16 v[116:119], v[128:131], v[168:171], v[116:119]
	v_mfma_f32_16x16x32_bf16 v[112:115], v[136:139], v[168:171], v[112:115]
	v_mfma_f32_16x16x32_bf16 v[108:111], v[128:131], v[176:179], v[108:111]
	v_mfma_f32_16x16x32_bf16 v[104:107], v[136:139], v[176:179], v[104:107]
	v_mfma_f32_16x16x32_bf16 v[100:103], v[128:131], v[184:187], v[100:103]
	v_mfma_f32_16x16x32_bf16 v[96:99], v[136:139], v[184:187], v[96:99]
	v_mfma_f32_16x16x32_bf16 v[124:127], v[132:135], v[158:161], v[124:127]
	v_mfma_f32_16x16x32_bf16 v[120:123], v[140:143], v[158:161], v[120:123]
	v_mfma_f32_16x16x32_bf16 v[116:119], v[132:135], v[172:175], v[116:119]
	v_mfma_f32_16x16x32_bf16 v[112:115], v[140:143], v[172:175], v[112:115]
	v_mfma_f32_16x16x32_bf16 v[108:111], v[132:135], v[180:183], v[108:111]
	v_mfma_f32_16x16x32_bf16 v[104:107], v[140:143], v[180:183], v[104:107]
	v_mfma_f32_16x16x32_bf16 v[100:103], v[132:135], v[188:191], v[100:103]
	v_mfma_f32_16x16x32_bf16 v[96:99], v[140:143], v[188:191], v[96:99]
	s_barrier
	s_add_i32 s28, 0, 0x1c000
	s_add_i32 s29, s63, s55
	v_add_u32_e32 v204, s28, v165
	s_mov_b32 m0, s29
	ds_read_b128 v[192:195], v204
	ds_read_b128 v[196:199], v204 offset:1024
	ds_read_b128 v[200:203], v204 offset:2048
	ds_read_b128 v[204:207], v204 offset:3072
	global_load_lds_dwordx4 v208, s[98:99]
	s_add_i32 m0, s29, 0x2000
	s_nop 0
	global_load_lds_dwordx4 v144, s[98:99]
	s_barrier
	s_waitcnt lgkmcnt(0)
	v_mfma_f32_16x16x32_bf16 v[60:63], v[192:195], v[154:157], v[60:63]
	v_mfma_f32_16x16x32_bf16 v[56:59], v[200:203], v[154:157], v[56:59]
	v_mfma_f32_16x16x32_bf16 v[52:55], v[192:195], v[168:171], v[52:55]
	v_mfma_f32_16x16x32_bf16 v[48:51], v[200:203], v[168:171], v[48:51]
	v_mfma_f32_16x16x32_bf16 v[44:47], v[192:195], v[176:179], v[44:47]
	v_mfma_f32_16x16x32_bf16 v[40:43], v[200:203], v[176:179], v[40:43]
	v_mfma_f32_16x16x32_bf16 v[36:39], v[192:195], v[184:187], v[36:39]
	v_mfma_f32_16x16x32_bf16 v[32:35], v[200:203], v[184:187], v[32:35]
	v_mfma_f32_16x16x32_bf16 v[60:63], v[196:199], v[158:161], v[60:63]
	v_mfma_f32_16x16x32_bf16 v[56:59], v[204:207], v[158:161], v[56:59]
	v_mfma_f32_16x16x32_bf16 v[52:55], v[196:199], v[172:175], v[52:55]
	v_mfma_f32_16x16x32_bf16 v[48:51], v[204:207], v[172:175], v[48:51]
	v_mfma_f32_16x16x32_bf16 v[44:47], v[196:199], v[180:183], v[44:47]
	v_mfma_f32_16x16x32_bf16 v[40:43], v[204:207], v[180:183], v[40:43]
	v_mfma_f32_16x16x32_bf16 v[36:39], v[196:199], v[188:191], v[36:39]
	v_mfma_f32_16x16x32_bf16 v[32:35], v[204:207], v[188:191], v[32:35]
	s_mov_b32 m0, s60
	s_barrier
	ds_read_b128 v[154:157], v167 offset:49152
	ds_read_b128 v[158:161], v167 offset:50176
	ds_read_b128 v[168:171], v167 offset:51200
	ds_read_b128 v[172:175], v167 offset:52224
	ds_read_b128 v[176:179], v167 offset:53248
	ds_read_b128 v[180:183], v167 offset:54272
	ds_read_b128 v[184:187], v167 offset:55296
	ds_read_b128 v[188:191], v167 offset:56320
	global_load_lds_dwordx4 v148, s[100:101]
	s_mov_b32 m0, s61
	s_nop 0
	global_load_lds_dwordx4 v146, s[100:101]
	s_barrier
	s_waitcnt lgkmcnt(0)
	v_mfma_f32_16x16x32_bf16 v[92:95], v[128:131], v[154:157], v[92:95]
	v_mfma_f32_16x16x32_bf16 v[88:91], v[136:139], v[154:157], v[88:91]
	v_mfma_f32_16x16x32_bf16 v[84:87], v[128:131], v[168:171], v[84:87]
	v_mfma_f32_16x16x32_bf16 v[80:83], v[136:139], v[168:171], v[80:83]
	v_mfma_f32_16x16x32_bf16 v[76:79], v[128:131], v[176:179], v[76:79]
	v_mfma_f32_16x16x32_bf16 v[72:75], v[136:139], v[176:179], v[72:75]
	v_mfma_f32_16x16x32_bf16 v[68:71], v[128:131], v[184:187], v[68:71]
	v_mfma_f32_16x16x32_bf16 v[64:67], v[136:139], v[184:187], v[64:67]
	v_mfma_f32_16x16x32_bf16 v[92:95], v[132:135], v[158:161], v[92:95]
	v_mfma_f32_16x16x32_bf16 v[88:91], v[140:143], v[158:161], v[88:91]
	v_mfma_f32_16x16x32_bf16 v[84:87], v[132:135], v[172:175], v[84:87]
	v_mfma_f32_16x16x32_bf16 v[80:83], v[140:143], v[172:175], v[80:83]
	v_mfma_f32_16x16x32_bf16 v[76:79], v[132:135], v[180:183], v[76:79]
	v_mfma_f32_16x16x32_bf16 v[72:75], v[140:143], v[180:183], v[72:75]
	v_mfma_f32_16x16x32_bf16 v[68:71], v[132:135], v[188:191], v[68:71]
	v_mfma_f32_16x16x32_bf16 v[64:67], v[140:143], v[188:191], v[64:67]
	s_barrier
	s_add_u32 s26, s26, 0x40080
	s_addc_u32 s27, s27, 0
	s_add_i32 s28, s28, s55
	s_mov_b32 m0, s28
	s_nop 0
	global_load_lds_dwordx4 v208, s[26:27]
	s_add_i32 m0, s28, 0x2000
	s_nop 0
	global_load_lds_dwordx4 v144, s[26:27]
	s_add_i32 s51, s51, 2
	s_add_u32 s6, s6, 0x100
	s_addc_u32 s7, s7, 0
	s_add_u32 s46, s46, 0x100
	s_addc_u32 s50, s50, 0
	s_waitcnt vmcnt(6)
	s_barrier
	v_mfma_f32_16x16x32_bf16 v[28:31], v[192:195], v[154:157], v[28:31]
	v_mfma_f32_16x16x32_bf16 v[24:27], v[200:203], v[154:157], v[24:27]
	v_mfma_f32_16x16x32_bf16 v[20:23], v[192:195], v[168:171], v[20:23]
	v_mfma_f32_16x16x32_bf16 v[16:19], v[200:203], v[168:171], v[16:19]
	v_mfma_f32_16x16x32_bf16 v[12:15], v[192:195], v[176:179], v[12:15]
	v_mfma_f32_16x16x32_bf16 v[8:11], v[200:203], v[176:179], v[8:11]
	v_mfma_f32_16x16x32_bf16 v[4:7], v[192:195], v[184:187], v[4:7]
	v_mfma_f32_16x16x32_bf16 v[0:3], v[200:203], v[184:187], v[0:3]
	v_mfma_f32_16x16x32_bf16 v[28:31], v[196:199], v[158:161], v[28:31]
	v_mfma_f32_16x16x32_bf16 v[24:27], v[204:207], v[158:161], v[24:27]
	v_mfma_f32_16x16x32_bf16 v[20:23], v[196:199], v[172:175], v[20:23]
	v_mfma_f32_16x16x32_bf16 v[16:19], v[204:207], v[172:175], v[16:19]
	v_mfma_f32_16x16x32_bf16 v[12:15], v[196:199], v[180:183], v[12:15]
	v_mfma_f32_16x16x32_bf16 v[8:11], v[204:207], v[180:183], v[8:11]
	v_mfma_f32_16x16x32_bf16 v[4:7], v[196:199], v[188:191], v[4:7]
	v_mfma_f32_16x16x32_bf16 v[0:3], v[204:207], v[188:191], v[0:3]
	s_cmp_gt_u32 s51, 13
	s_barrier
	s_cbranch_scc0 .LBB0_714
	v_lshl_or_b32 v158, s34, 8, v166
	v_lshl_add_u32 v159, s35, 8, v164
	s_mov_b32 s34, s10
	s_mov_b32 s35, s20
	s_mov_b64 s[26:27], s[24:25]
	v_mbcnt_lo_u32_b32 v160, -1, 0
	v_mbcnt_hi_u32_b32 v160, -1, v160
	v_and_b32_e32 v157, 7, v160
	v_and_b32_e32 v160, 8, v160
	v_add_u32_e32 v157, v158, v157
	v_lshlrev_b32_e32 v157, 6, v157
	v_lshl_add_u32 v157, v160, 2, v157
	v_add_u32_e32 v161, 0x2000, v157
	global_load_dwordx4 v[128:131], v157, s[18:19]
	global_load_dwordx4 v[132:135], v157, s[18:19] offset:16
	global_load_dwordx4 v[136:139], v161, s[18:19]
	global_load_dwordx4 v[140:143], v161, s[18:19] offset:16
	v_mov_b32_e32 v155, 0x358637bd
	v_lshlrev_b32_e32 v156, 17, v159
	v_lshl_add_u32 v156, v158, 1, v156
	s_waitcnt vmcnt(0)
	v_pk_add_f32 v[128:129], v[128:129], v[130:131]
	v_pk_add_f32 v[132:133], v[132:133], v[134:135]
	v_pk_add_f32 v[128:129], v[128:129], v[132:133]
	s_nop 0
	v_add_f32_e32 v154, v128, v129
	s_nop 1
	v_add_f32_dpp v154, v154, v154 row_ror:8 row_mask:0xf bank_mask:0xf
	s_nop 0
	v_fmamk_f32 v154, v154, 0x3a800000, v155
	v_rsq_f32_e32 v154, v154
	s_nop 1
	v_mov_b32_dpp v168, v154 row_newbcast:0 row_mask:0xf bank_mask:0xf
	v_mov_b32_dpp v169, v154 row_newbcast:1 row_mask:0xf bank_mask:0xf
	v_mov_b32_dpp v170, v154 row_newbcast:2 row_mask:0xf bank_mask:0xf
	v_mov_b32_dpp v171, v154 row_newbcast:3 row_mask:0xf bank_mask:0xf
	v_mov_b32_dpp v172, v154 row_newbcast:4 row_mask:0xf bank_mask:0xf
	v_mov_b32_dpp v173, v154 row_newbcast:5 row_mask:0xf bank_mask:0xf
	v_mov_b32_dpp v174, v154 row_newbcast:6 row_mask:0xf bank_mask:0xf
	v_mov_b32_dpp v175, v154 row_newbcast:7 row_mask:0xf bank_mask:0xf
	v_pk_add_f32 v[136:137], v[136:137], v[138:139]
	v_pk_add_f32 v[140:141], v[140:141], v[142:143]
	v_pk_add_f32 v[136:137], v[136:137], v[140:141]
	s_nop 0
	v_add_f32_e32 v154, v136, v137
	s_nop 1
	v_add_f32_dpp v154, v154, v154 row_ror:8 row_mask:0xf bank_mask:0xf
	s_nop 0
	v_fmamk_f32 v154, v154, 0x3a800000, v155
	v_rsq_f32_e32 v154, v154
	s_nop 1
	v_mov_b32_dpp v176, v154 row_newbcast:0 row_mask:0xf bank_mask:0xf
	v_mov_b32_dpp v177, v154 row_newbcast:1 row_mask:0xf bank_mask:0xf
	v_mov_b32_dpp v178, v154 row_newbcast:2 row_mask:0xf bank_mask:0xf
	v_mov_b32_dpp v179, v154 row_newbcast:3 row_mask:0xf bank_mask:0xf
	v_mov_b32_dpp v180, v154 row_newbcast:4 row_mask:0xf bank_mask:0xf
	v_mov_b32_dpp v181, v154 row_newbcast:5 row_mask:0xf bank_mask:0xf
	v_mov_b32_dpp v182, v154 row_newbcast:6 row_mask:0xf bank_mask:0xf
	v_mov_b32_dpp v183, v154 row_newbcast:7 row_mask:0xf bank_mask:0xf
	v_pk_mul_f32 v[124:125], v[124:125], v[168:169]
	v_pk_mul_f32 v[126:127], v[126:127], v[170:171]
	v_pk_mul_f32 v[120:121], v[120:121], v[172:173]
	v_pk_mul_f32 v[122:123], v[122:123], v[174:175]
	v_cvt_pk_bf16_f32 v184, v124, v125
	v_cvt_pk_bf16_f32 v185, v126, v127
	v_cvt_pk_bf16_f32 v186, v120, v121
	v_cvt_pk_bf16_f32 v187, v122, v123
	global_store_dwordx4 v156, v[184:187], s[8:9]
	v_pk_mul_f32 v[60:61], v[60:61], v[176:177]
	v_pk_mul_f32 v[62:63], v[62:63], v[178:179]
	v_pk_mul_f32 v[56:57], v[56:57], v[180:181]
	v_pk_mul_f32 v[58:59], v[58:59], v[182:183]
	v_cvt_pk_bf16_f32 v188, v60, v61
	v_cvt_pk_bf16_f32 v189, v62, v63
	v_cvt_pk_bf16_f32 v190, v56, v57
	v_cvt_pk_bf16_f32 v191, v58, v59
	global_store_dwordx4 v156, v[188:191], s[8:9] offset:256
	v_add_u32_e32 v156, 0x200000, v156
	v_pk_mul_f32 v[116:117], v[116:117], v[168:169]
	v_pk_mul_f32 v[118:119], v[118:119], v[170:171]
	v_pk_mul_f32 v[112:113], v[112:113], v[172:173]
	v_pk_mul_f32 v[114:115], v[114:115], v[174:175]
	v_cvt_pk_bf16_f32 v184, v116, v117
	v_cvt_pk_bf16_f32 v185, v118, v119
	v_cvt_pk_bf16_f32 v186, v112, v113
	v_cvt_pk_bf16_f32 v187, v114, v115
	global_store_dwordx4 v156, v[184:187], s[8:9]
	v_pk_mul_f32 v[52:53], v[52:53], v[176:177]
	v_pk_mul_f32 v[54:55], v[54:55], v[178:179]
	v_pk_mul_f32 v[48:49], v[48:49], v[180:181]
	v_pk_mul_f32 v[50:51], v[50:51], v[182:183]
	v_cvt_pk_bf16_f32 v188, v52, v53
	v_cvt_pk_bf16_f32 v189, v54, v55
	v_cvt_pk_bf16_f32 v190, v48, v49
	v_cvt_pk_bf16_f32 v191, v50, v51
	global_store_dwordx4 v156, v[188:191], s[8:9] offset:256
	v_add_u32_e32 v156, 0x200000, v156
	v_pk_mul_f32 v[108:109], v[108:109], v[168:169]
	v_pk_mul_f32 v[110:111], v[110:111], v[170:171]
	v_pk_mul_f32 v[104:105], v[104:105], v[172:173]
	v_pk_mul_f32 v[106:107], v[106:107], v[174:175]
	v_cvt_pk_bf16_f32 v184, v108, v109
	v_cvt_pk_bf16_f32 v185, v110, v111
	v_cvt_pk_bf16_f32 v186, v104, v105
	v_cvt_pk_bf16_f32 v187, v106, v107
	global_store_dwordx4 v156, v[184:187], s[8:9]
	v_pk_mul_f32 v[44:45], v[44:45], v[176:177]
	v_pk_mul_f32 v[46:47], v[46:47], v[178:179]
	v_pk_mul_f32 v[40:41], v[40:41], v[180:181]
	v_pk_mul_f32 v[42:43], v[42:43], v[182:183]
	v_cvt_pk_bf16_f32 v188, v44, v45
	v_cvt_pk_bf16_f32 v189, v46, v47
	v_cvt_pk_bf16_f32 v190, v40, v41
	v_cvt_pk_bf16_f32 v191, v42, v43
	global_store_dwordx4 v156, v[188:191], s[8:9] offset:256
	v_add_u32_e32 v156, 0x200000, v156
	v_pk_mul_f32 v[100:101], v[100:101], v[168:169]
	v_pk_mul_f32 v[102:103], v[102:103], v[170:171]
	v_pk_mul_f32 v[96:97], v[96:97], v[172:173]
	v_pk_mul_f32 v[98:99], v[98:99], v[174:175]
	v_cvt_pk_bf16_f32 v184, v100, v101
	v_cvt_pk_bf16_f32 v185, v102, v103
	v_cvt_pk_bf16_f32 v186, v96, v97
	v_cvt_pk_bf16_f32 v187, v98, v99
	global_store_dwordx4 v156, v[184:187], s[8:9]
	v_pk_mul_f32 v[36:37], v[36:37], v[176:177]
	v_pk_mul_f32 v[38:39], v[38:39], v[178:179]
	v_pk_mul_f32 v[32:33], v[32:33], v[180:181]
	v_pk_mul_f32 v[34:35], v[34:35], v[182:183]
	v_cvt_pk_bf16_f32 v188, v36, v37
	v_cvt_pk_bf16_f32 v189, v38, v39
	v_cvt_pk_bf16_f32 v190, v32, v33
	v_cvt_pk_bf16_f32 v191, v34, v35
	global_store_dwordx4 v156, v[188:191], s[8:9] offset:256
	v_add_u32_e32 v156, 0xa00000, v156
	v_pk_mul_f32 v[92:93], v[92:93], v[168:169]
	v_pk_mul_f32 v[94:95], v[94:95], v[170:171]
	v_pk_mul_f32 v[88:89], v[88:89], v[172:173]
	v_pk_mul_f32 v[90:91], v[90:91], v[174:175]
	v_cvt_pk_bf16_f32 v184, v92, v93
	v_cvt_pk_bf16_f32 v185, v94, v95
	v_cvt_pk_bf16_f32 v186, v88, v89
	v_cvt_pk_bf16_f32 v187, v90, v91
	global_store_dwordx4 v156, v[184:187], s[8:9]
	v_pk_mul_f32 v[28:29], v[28:29], v[176:177]
	v_pk_mul_f32 v[30:31], v[30:31], v[178:179]
	v_pk_mul_f32 v[24:25], v[24:25], v[180:181]
	v_pk_mul_f32 v[26:27], v[26:27], v[182:183]
	v_cvt_pk_bf16_f32 v188, v28, v29
	v_cvt_pk_bf16_f32 v189, v30, v31
	v_cvt_pk_bf16_f32 v190, v24, v25
	v_cvt_pk_bf16_f32 v191, v26, v27
	global_store_dwordx4 v156, v[188:191], s[8:9] offset:256
	v_add_u32_e32 v156, 0x200000, v156
	v_pk_mul_f32 v[84:85], v[84:85], v[168:169]
	v_pk_mul_f32 v[86:87], v[86:87], v[170:171]
	v_pk_mul_f32 v[80:81], v[80:81], v[172:173]
	v_pk_mul_f32 v[82:83], v[82:83], v[174:175]
	v_cvt_pk_bf16_f32 v184, v84, v85
	v_cvt_pk_bf16_f32 v185, v86, v87
	v_cvt_pk_bf16_f32 v186, v80, v81
	v_cvt_pk_bf16_f32 v187, v82, v83
	global_store_dwordx4 v156, v[184:187], s[8:9]
	v_pk_mul_f32 v[20:21], v[20:21], v[176:177]
	v_pk_mul_f32 v[22:23], v[22:23], v[178:179]
	v_pk_mul_f32 v[16:17], v[16:17], v[180:181]
	v_pk_mul_f32 v[18:19], v[18:19], v[182:183]
	v_cvt_pk_bf16_f32 v188, v20, v21
	v_cvt_pk_bf16_f32 v189, v22, v23
	v_cvt_pk_bf16_f32 v190, v16, v17
	v_cvt_pk_bf16_f32 v191, v18, v19
	global_store_dwordx4 v156, v[188:191], s[8:9] offset:256
	v_add_u32_e32 v156, 0x200000, v156
	v_pk_mul_f32 v[76:77], v[76:77], v[168:169]
	v_pk_mul_f32 v[78:79], v[78:79], v[170:171]
	v_pk_mul_f32 v[72:73], v[72:73], v[172:173]
	v_pk_mul_f32 v[74:75], v[74:75], v[174:175]
	v_cvt_pk_bf16_f32 v184, v76, v77
	v_cvt_pk_bf16_f32 v185, v78, v79
	v_cvt_pk_bf16_f32 v186, v72, v73
	v_cvt_pk_bf16_f32 v187, v74, v75
	global_store_dwordx4 v156, v[184:187], s[8:9]
	v_pk_mul_f32 v[12:13], v[12:13], v[176:177]
	v_pk_mul_f32 v[14:15], v[14:15], v[178:179]
	v_pk_mul_f32 v[8:9], v[8:9], v[180:181]
	v_pk_mul_f32 v[10:11], v[10:11], v[182:183]
	v_cvt_pk_bf16_f32 v188, v12, v13
	v_cvt_pk_bf16_f32 v189, v14, v15
	v_cvt_pk_bf16_f32 v190, v8, v9
	v_cvt_pk_bf16_f32 v191, v10, v11
	global_store_dwordx4 v156, v[188:191], s[8:9] offset:256
	v_add_u32_e32 v156, 0x200000, v156
	v_pk_mul_f32 v[68:69], v[68:69], v[168:169]
	v_pk_mul_f32 v[70:71], v[70:71], v[170:171]
	v_pk_mul_f32 v[64:65], v[64:65], v[172:173]
	v_pk_mul_f32 v[66:67], v[66:67], v[174:175]
	v_cvt_pk_bf16_f32 v184, v68, v69
	v_cvt_pk_bf16_f32 v185, v70, v71
	v_cvt_pk_bf16_f32 v186, v64, v65
	v_cvt_pk_bf16_f32 v187, v66, v67
	global_store_dwordx4 v156, v[184:187], s[8:9]
	v_pk_mul_f32 v[4:5], v[4:5], v[176:177]
	v_pk_mul_f32 v[6:7], v[6:7], v[178:179]
	v_pk_mul_f32 v[0:1], v[0:1], v[180:181]
	v_pk_mul_f32 v[2:3], v[2:3], v[182:183]
	v_cvt_pk_bf16_f32 v188, v4, v5
	v_cvt_pk_bf16_f32 v189, v6, v7
	v_cvt_pk_bf16_f32 v190, v0, v1
	v_cvt_pk_bf16_f32 v191, v2, v3
	global_store_dwordx4 v156, v[188:191], s[8:9] offset:256
	s_mov_b64 s[6:7], s[22:23]
	s_and_b64 vcc, exec, s[4:5]
	s_cbranch_vccz .LBB0_707
	s_waitcnt vmcnt(0)
	s_cmpk_gt_u32 s30, 0xff
	s_cbranch_scc1 .LBB0_718
	s_barrier

.LBB0_776:
	s_add_u32 s28, s26, 0xfffc0080
	s_addc_u32 s29, s27, -1
	s_add_i32 s66, 0, 0x10000
	v_add_u32_e32 v154, s66, v143
	ds_read_b128 v[138:141], v154
	ds_read_b128 v[146:149], v154 offset:1024
	ds_read_b128 v[150:153], v154 offset:2048
	ds_read_b128 v[154:157], v154 offset:3072
	s_cmp_eq_u32 s65, 12
	s_cselect_b32 s31, s21, s29
	s_cselect_b32 s30, s39, s28
	s_cselect_b32 s29, s19, s64
	s_cselect_b32 s28, s62, s63
	s_add_i32 m0, s54, 0xc000
	ds_read_b128 v[158:161], v145
	ds_read_b128 v[162:165], v145 offset:1024
	ds_read_b128 v[166:169], v145 offset:2048
	ds_read_b128 v[170:173], v145 offset:3072
	ds_read_b128 v[174:177], v145 offset:4096
	ds_read_b128 v[178:181], v145 offset:5120
	ds_read_b128 v[182:185], v145 offset:6144
	ds_read_b128 v[186:189], v145 offset:7168
	global_load_lds_dwordx4 v134, s[26:27]
	s_add_i32 m0, s54, 0xe000
	s_nop 0
	global_load_lds_dwordx4 v136, s[26:27]
	s_waitcnt lgkmcnt(8)
	s_barrier
	s_waitcnt lgkmcnt(0)
	v_mfma_f32_16x16x32_bf16 v[124:127], v[138:141], v[158:161], v[124:127]
	v_mfma_f32_16x16x32_bf16 v[120:123], v[150:153], v[158:161], v[120:123]
	v_mfma_f32_16x16x32_bf16 v[108:111], v[138:141], v[166:169], v[108:111]
	v_mfma_f32_16x16x32_bf16 v[104:107], v[150:153], v[166:169], v[104:107]
	v_mfma_f32_16x16x32_bf16 v[92:95], v[138:141], v[174:177], v[92:95]
	v_mfma_f32_16x16x32_bf16 v[88:91], v[150:153], v[174:177], v[88:91]
	v_mfma_f32_16x16x32_bf16 v[76:79], v[138:141], v[182:185], v[76:79]
	v_mfma_f32_16x16x32_bf16 v[72:75], v[150:153], v[182:185], v[72:75]
	v_mfma_f32_16x16x32_bf16 v[124:127], v[146:149], v[162:165], v[124:127]
	v_mfma_f32_16x16x32_bf16 v[120:123], v[154:157], v[162:165], v[120:123]
	v_mfma_f32_16x16x32_bf16 v[108:111], v[146:149], v[170:173], v[108:111]
	v_mfma_f32_16x16x32_bf16 v[104:107], v[154:157], v[170:173], v[104:107]
	v_mfma_f32_16x16x32_bf16 v[92:95], v[146:149], v[178:181], v[92:95]
	v_mfma_f32_16x16x32_bf16 v[88:91], v[154:157], v[178:181], v[88:91]
	v_mfma_f32_16x16x32_bf16 v[76:79], v[146:149], v[186:189], v[76:79]
	v_mfma_f32_16x16x32_bf16 v[72:75], v[154:157], v[186:189], v[72:75]
	s_barrier
	s_add_i32 s68, 0, 0x14000
	s_add_i32 s66, s66, s53
	v_add_u32_e32 v202, s68, v143
	s_add_u32 s98, s28, s40
	s_addc_u32 s99, s29, s41
	s_mov_b32 m0, s66
	ds_read_b128 v[190:193], v202
	ds_read_b128 v[194:197], v202 offset:1024
	ds_read_b128 v[198:201], v202 offset:2048
	ds_read_b128 v[202:205], v202 offset:3072
	global_load_lds_dwordx4 v208, s[28:29]
	s_add_i32 m0, s66, 0x2000
	s_nop 0
	global_load_lds_dwordx4 v128, s[28:29]
	s_barrier
	s_waitcnt lgkmcnt(0)
	v_mfma_f32_16x16x32_bf16 v[116:119], v[190:193], v[158:161], v[116:119]
	v_mfma_f32_16x16x32_bf16 v[112:115], v[198:201], v[158:161], v[112:115]
	v_mfma_f32_16x16x32_bf16 v[100:103], v[190:193], v[166:169], v[100:103]
	v_mfma_f32_16x16x32_bf16 v[96:99], v[198:201], v[166:169], v[96:99]
	v_mfma_f32_16x16x32_bf16 v[84:87], v[190:193], v[174:177], v[84:87]
	v_mfma_f32_16x16x32_bf16 v[80:83], v[198:201], v[174:177], v[80:83]
	v_mfma_f32_16x16x32_bf16 v[68:71], v[190:193], v[182:185], v[68:71]
	v_mfma_f32_16x16x32_bf16 v[64:67], v[198:201], v[182:185], v[64:67]
	v_mfma_f32_16x16x32_bf16 v[116:119], v[194:197], v[162:165], v[116:119]
	v_mfma_f32_16x16x32_bf16 v[112:115], v[202:205], v[162:165], v[112:115]
	v_mfma_f32_16x16x32_bf16 v[100:103], v[194:197], v[170:173], v[100:103]
	v_mfma_f32_16x16x32_bf16 v[96:99], v[202:205], v[170:173], v[96:99]
	v_mfma_f32_16x16x32_bf16 v[84:87], v[194:197], v[178:181], v[84:87]
	v_mfma_f32_16x16x32_bf16 v[80:83], v[202:205], v[178:181], v[80:83]
	v_mfma_f32_16x16x32_bf16 v[68:71], v[194:197], v[186:189], v[68:71]
	v_mfma_f32_16x16x32_bf16 v[64:67], v[202:205], v[186:189], v[64:67]
	s_mov_b32 m0, s54
	s_add_u32 s100, s30, s40
	s_addc_u32 s101, s31, s41
	s_barrier
	ds_read_b128 v[158:161], v145 offset:16384
	ds_read_b128 v[162:165], v145 offset:17408
	ds_read_b128 v[166:169], v145 offset:18432
	ds_read_b128 v[170:173], v145 offset:19456
	ds_read_b128 v[174:177], v145 offset:20480
	ds_read_b128 v[178:181], v145 offset:21504
	ds_read_b128 v[182:185], v145 offset:22528
	ds_read_b128 v[186:189], v145 offset:23552
	global_load_lds_dwordx4 v132, s[30:31]
	s_mov_b32 m0, s55
	s_nop 0
	global_load_lds_dwordx4 v130, s[30:31]
	s_barrier
	s_waitcnt lgkmcnt(0)
	v_mfma_f32_16x16x32_bf16 v[60:63], v[138:141], v[158:161], v[60:63]
	v_mfma_f32_16x16x32_bf16 v[56:59], v[150:153], v[158:161], v[56:59]
	v_mfma_f32_16x16x32_bf16 v[44:47], v[138:141], v[166:169], v[44:47]
	v_mfma_f32_16x16x32_bf16 v[40:43], v[150:153], v[166:169], v[40:43]
	v_mfma_f32_16x16x32_bf16 v[28:31], v[138:141], v[174:177], v[28:31]
	v_mfma_f32_16x16x32_bf16 v[24:27], v[150:153], v[174:177], v[24:27]
	v_mfma_f32_16x16x32_bf16 v[12:15], v[138:141], v[182:185], v[12:15]
	v_mfma_f32_16x16x32_bf16 v[8:11], v[150:153], v[182:185], v[8:11]
	v_mfma_f32_16x16x32_bf16 v[60:63], v[146:149], v[162:165], v[60:63]
	v_mfma_f32_16x16x32_bf16 v[56:59], v[154:157], v[162:165], v[56:59]
	v_mfma_f32_16x16x32_bf16 v[44:47], v[146:149], v[170:173], v[44:47]
	v_mfma_f32_16x16x32_bf16 v[40:43], v[154:157], v[170:173], v[40:43]
	v_mfma_f32_16x16x32_bf16 v[28:31], v[146:149], v[178:181], v[28:31]
	v_mfma_f32_16x16x32_bf16 v[24:27], v[154:157], v[178:181], v[24:27]
	v_mfma_f32_16x16x32_bf16 v[12:15], v[146:149], v[186:189], v[12:15]
	v_mfma_f32_16x16x32_bf16 v[8:11], v[154:157], v[186:189], v[8:11]
	s_barrier
	s_add_u32 s66, s28, 0x40000
	s_addc_u32 s67, s29, 0
	s_add_i32 s68, s68, s53
	s_mov_b32 m0, s68
	s_nop 0
	global_load_lds_dwordx4 v208, s[66:67]
	s_add_i32 m0, s68, 0x2000
	s_nop 0
	global_load_lds_dwordx4 v128, s[66:67]
	s_waitcnt vmcnt(6)
	s_barrier
	v_mfma_f32_16x16x32_bf16 v[52:55], v[190:193], v[158:161], v[52:55]
	v_mfma_f32_16x16x32_bf16 v[48:51], v[198:201], v[158:161], v[48:51]
	v_mfma_f32_16x16x32_bf16 v[36:39], v[190:193], v[166:169], v[36:39]
	v_mfma_f32_16x16x32_bf16 v[32:35], v[198:201], v[166:169], v[32:35]
	v_mfma_f32_16x16x32_bf16 v[20:23], v[190:193], v[174:177], v[20:23]
	v_mfma_f32_16x16x32_bf16 v[16:19], v[198:201], v[174:177], v[16:19]
	v_mfma_f32_16x16x32_bf16 v[4:7], v[190:193], v[182:185], v[4:7]
	v_mfma_f32_16x16x32_bf16 v[0:3], v[198:201], v[182:185], v[0:3]
	v_mfma_f32_16x16x32_bf16 v[52:55], v[194:197], v[162:165], v[52:55]
	v_mfma_f32_16x16x32_bf16 v[48:51], v[202:205], v[162:165], v[48:51]
	v_mfma_f32_16x16x32_bf16 v[36:39], v[194:197], v[170:173], v[36:39]
	v_mfma_f32_16x16x32_bf16 v[32:35], v[202:205], v[170:173], v[32:35]
	v_mfma_f32_16x16x32_bf16 v[20:23], v[194:197], v[178:181], v[20:23]
	v_mfma_f32_16x16x32_bf16 v[16:19], v[202:205], v[178:181], v[16:19]
	v_mfma_f32_16x16x32_bf16 v[4:7], v[194:197], v[186:189], v[4:7]
	v_mfma_f32_16x16x32_bf16 v[0:3], v[202:205], v[186:189], v[0:3]
	s_add_i32 s66, 0, 0x18000
	v_add_u32_e32 v154, s66, v143
	s_barrier
	ds_read_b128 v[138:141], v154
	ds_read_b128 v[146:149], v154 offset:1024
	ds_read_b128 v[150:153], v154 offset:2048
	ds_read_b128 v[154:157], v154 offset:3072
	s_add_u32 s30, s30, 0x40000
	s_addc_u32 s31, s31, 0
	s_mov_b32 m0, s56
	ds_read_b128 v[158:161], v145 offset:32768
	ds_read_b128 v[162:165], v145 offset:33792
	ds_read_b128 v[166:169], v145 offset:34816
	ds_read_b128 v[170:173], v145 offset:35840
	ds_read_b128 v[174:177], v145 offset:36864
	ds_read_b128 v[178:181], v145 offset:37888
	ds_read_b128 v[182:185], v145 offset:38912
	ds_read_b128 v[186:189], v145 offset:39936
	global_load_lds_dwordx4 v132, s[30:31]
	s_mov_b32 m0, s57
	s_nop 0
	global_load_lds_dwordx4 v130, s[30:31]
	s_waitcnt lgkmcnt(8)
	s_barrier
	s_waitcnt lgkmcnt(0)
	v_mfma_f32_16x16x32_bf16 v[124:127], v[138:141], v[158:161], v[124:127]
	v_mfma_f32_16x16x32_bf16 v[120:123], v[150:153], v[158:161], v[120:123]
	v_mfma_f32_16x16x32_bf16 v[108:111], v[138:141], v[166:169], v[108:111]
	v_mfma_f32_16x16x32_bf16 v[104:107], v[150:153], v[166:169], v[104:107]
	v_mfma_f32_16x16x32_bf16 v[92:95], v[138:141], v[174:177], v[92:95]
	v_mfma_f32_16x16x32_bf16 v[88:91], v[150:153], v[174:177], v[88:91]
	v_mfma_f32_16x16x32_bf16 v[76:79], v[138:141], v[182:185], v[76:79]
	v_mfma_f32_16x16x32_bf16 v[72:75], v[150:153], v[182:185], v[72:75]
	v_mfma_f32_16x16x32_bf16 v[124:127], v[146:149], v[162:165], v[124:127]
	v_mfma_f32_16x16x32_bf16 v[120:123], v[154:157], v[162:165], v[120:123]
	v_mfma_f32_16x16x32_bf16 v[108:111], v[146:149], v[170:173], v[108:111]
	v_mfma_f32_16x16x32_bf16 v[104:107], v[154:157], v[170:173], v[104:107]
	v_mfma_f32_16x16x32_bf16 v[92:95], v[146:149], v[178:181], v[92:95]
	v_mfma_f32_16x16x32_bf16 v[88:91], v[154:157], v[178:181], v[88:91]
	v_mfma_f32_16x16x32_bf16 v[76:79], v[146:149], v[186:189], v[76:79]
	v_mfma_f32_16x16x32_bf16 v[72:75], v[154:157], v[186:189], v[72:75]
	s_barrier
	s_add_i32 s30, 0, 0x1c000
	s_add_i32 s31, s66, s53
	v_add_u32_e32 v202, s30, v143
	s_mov_b32 m0, s31
	ds_read_b128 v[190:193], v202
	ds_read_b128 v[194:197], v202 offset:1024
	ds_read_b128 v[198:201], v202 offset:2048
	ds_read_b128 v[202:205], v202 offset:3072
	global_load_lds_dwordx4 v208, s[98:99]
	s_add_i32 m0, s31, 0x2000
	s_nop 0
	global_load_lds_dwordx4 v128, s[98:99]
	s_barrier
	s_waitcnt lgkmcnt(0)
	v_mfma_f32_16x16x32_bf16 v[116:119], v[190:193], v[158:161], v[116:119]
	v_mfma_f32_16x16x32_bf16 v[112:115], v[198:201], v[158:161], v[112:115]
	v_mfma_f32_16x16x32_bf16 v[100:103], v[190:193], v[166:169], v[100:103]
	v_mfma_f32_16x16x32_bf16 v[96:99], v[198:201], v[166:169], v[96:99]
	v_mfma_f32_16x16x32_bf16 v[84:87], v[190:193], v[174:177], v[84:87]
	v_mfma_f32_16x16x32_bf16 v[80:83], v[198:201], v[174:177], v[80:83]
	v_mfma_f32_16x16x32_bf16 v[68:71], v[190:193], v[182:185], v[68:71]
	v_mfma_f32_16x16x32_bf16 v[64:67], v[198:201], v[182:185], v[64:67]
	v_mfma_f32_16x16x32_bf16 v[116:119], v[194:197], v[162:165], v[116:119]
	v_mfma_f32_16x16x32_bf16 v[112:115], v[202:205], v[162:165], v[112:115]
	v_mfma_f32_16x16x32_bf16 v[100:103], v[194:197], v[170:173], v[100:103]
	v_mfma_f32_16x16x32_bf16 v[96:99], v[202:205], v[170:173], v[96:99]
	v_mfma_f32_16x16x32_bf16 v[84:87], v[194:197], v[178:181], v[84:87]
	v_mfma_f32_16x16x32_bf16 v[80:83], v[202:205], v[178:181], v[80:83]
	v_mfma_f32_16x16x32_bf16 v[68:71], v[194:197], v[186:189], v[68:71]
	v_mfma_f32_16x16x32_bf16 v[64:67], v[202:205], v[186:189], v[64:67]
	s_mov_b32 m0, s59
	s_barrier
	ds_read_b128 v[158:161], v145 offset:49152
	ds_read_b128 v[162:165], v145 offset:50176
	ds_read_b128 v[166:169], v145 offset:51200
	ds_read_b128 v[170:173], v145 offset:52224
	ds_read_b128 v[174:177], v145 offset:53248
	ds_read_b128 v[178:181], v145 offset:54272
	ds_read_b128 v[182:185], v145 offset:55296
	ds_read_b128 v[186:189], v145 offset:56320
	global_load_lds_dwordx4 v132, s[100:101]
	s_mov_b32 m0, s60
	s_nop 0
	global_load_lds_dwordx4 v130, s[100:101]
	s_barrier
	s_waitcnt lgkmcnt(0)
	v_mfma_f32_16x16x32_bf16 v[60:63], v[138:141], v[158:161], v[60:63]
	v_mfma_f32_16x16x32_bf16 v[56:59], v[150:153], v[158:161], v[56:59]
	v_mfma_f32_16x16x32_bf16 v[44:47], v[138:141], v[166:169], v[44:47]
	v_mfma_f32_16x16x32_bf16 v[40:43], v[150:153], v[166:169], v[40:43]
	v_mfma_f32_16x16x32_bf16 v[28:31], v[138:141], v[174:177], v[28:31]
	v_mfma_f32_16x16x32_bf16 v[24:27], v[150:153], v[174:177], v[24:27]
	v_mfma_f32_16x16x32_bf16 v[12:15], v[138:141], v[182:185], v[12:15]
	v_mfma_f32_16x16x32_bf16 v[8:11], v[150:153], v[182:185], v[8:11]
	v_mfma_f32_16x16x32_bf16 v[60:63], v[146:149], v[162:165], v[60:63]
	v_mfma_f32_16x16x32_bf16 v[56:59], v[154:157], v[162:165], v[56:59]
	v_mfma_f32_16x16x32_bf16 v[44:47], v[146:149], v[170:173], v[44:47]
	v_mfma_f32_16x16x32_bf16 v[40:43], v[154:157], v[170:173], v[40:43]
	v_mfma_f32_16x16x32_bf16 v[28:31], v[146:149], v[178:181], v[28:31]
	v_mfma_f32_16x16x32_bf16 v[24:27], v[154:157], v[178:181], v[24:27]
	v_mfma_f32_16x16x32_bf16 v[12:15], v[146:149], v[186:189], v[12:15]
	v_mfma_f32_16x16x32_bf16 v[8:11], v[154:157], v[186:189], v[8:11]
	s_barrier
	s_add_u32 s28, s28, 0x40080
	s_addc_u32 s29, s29, 0
	s_add_i32 s30, s30, s53
	s_mov_b32 m0, s30
	s_nop 0
	global_load_lds_dwordx4 v208, s[28:29]
	s_add_i32 m0, s30, 0x2000
	s_nop 0
	global_load_lds_dwordx4 v128, s[28:29]
	s_add_i32 s65, s65, 2
	s_add_u32 s26, s26, 0x100
	s_addc_u32 s27, s27, 0
	s_add_u32 s63, s63, 0x100
	s_addc_u32 s64, s64, 0
	s_waitcnt vmcnt(6)
	s_barrier
	v_mfma_f32_16x16x32_bf16 v[52:55], v[190:193], v[158:161], v[52:55]
	v_mfma_f32_16x16x32_bf16 v[48:51], v[198:201], v[158:161], v[48:51]
	v_mfma_f32_16x16x32_bf16 v[36:39], v[190:193], v[166:169], v[36:39]
	v_mfma_f32_16x16x32_bf16 v[32:35], v[198:201], v[166:169], v[32:35]
	v_mfma_f32_16x16x32_bf16 v[20:23], v[190:193], v[174:177], v[20:23]
	v_mfma_f32_16x16x32_bf16 v[16:19], v[198:201], v[174:177], v[16:19]
	v_mfma_f32_16x16x32_bf16 v[4:7], v[190:193], v[182:185], v[4:7]
	v_mfma_f32_16x16x32_bf16 v[0:3], v[198:201], v[182:185], v[0:3]
	v_mfma_f32_16x16x32_bf16 v[52:55], v[194:197], v[162:165], v[52:55]
	v_mfma_f32_16x16x32_bf16 v[48:51], v[202:205], v[162:165], v[48:51]
	v_mfma_f32_16x16x32_bf16 v[36:39], v[194:197], v[170:173], v[36:39]
	v_mfma_f32_16x16x32_bf16 v[32:35], v[202:205], v[170:173], v[32:35]
	v_mfma_f32_16x16x32_bf16 v[20:23], v[194:197], v[178:181], v[20:23]
	v_mfma_f32_16x16x32_bf16 v[16:19], v[202:205], v[178:181], v[16:19]
	v_mfma_f32_16x16x32_bf16 v[4:7], v[194:197], v[186:189], v[4:7]
	v_mfma_f32_16x16x32_bf16 v[0:3], v[202:205], v[186:189], v[0:3]
	s_cmp_gt_u32 s65, 13
	s_barrier
	s_cbranch_scc0 .LBB0_776
	v_lshl_add_u32 v140, s38, 8, v142
	v_lshl_or_b32 v141, s36, 8, v144
	s_lshl_b32 s26, s36, 2
	s_ashr_i32 s27, s26, 31
	s_lshl_b32 s36, s58, 2
	v_lshlrev_b32_e32 v206, 11, v140
	v_lshl_add_u32 v206, v141, 1, v206
	v_lshl_add_u32 v210, v140, 6, s36
	v_lshl_add_u32 v210, s26, 2, v210
	v_mov_b32_e32 v207, v206
	global_load_dwordx4 v[146:149], v206, s[10:11]
	global_load_dwordx4 v[150:153], v206, s[10:11] offset:256
	v_add_u32_e32 v206, 0x8000, v206
	global_load_dwordx4 v[154:157], v206, s[10:11]
	global_load_dwordx4 v[158:161], v206, s[10:11] offset:256
	v_add_u32_e32 v206, 0x8000, v206
	global_load_dwordx4 v[162:165], v206, s[10:11]
	global_load_dwordx4 v[166:169], v206, s[10:11] offset:256
	v_add_u32_e32 v206, 0x8000, v206
	global_load_dwordx4 v[170:173], v206, s[10:11]
	global_load_dwordx4 v[174:177], v206, s[10:11] offset:256
	v_add_u32_e32 v206, 0x28000, v206
	global_load_dwordx4 v[178:181], v206, s[10:11]
	global_load_dwordx4 v[182:185], v206, s[10:11] offset:256
	v_add_u32_e32 v206, 0x8000, v206
	global_load_dwordx4 v[186:189], v206, s[10:11]
	global_load_dwordx4 v[190:193], v206, s[10:11] offset:256
	v_add_u32_e32 v206, 0x8000, v206
	global_load_dwordx4 v[194:197], v206, s[10:11]
	global_load_dwordx4 v[198:201], v206, s[10:11] offset:256
	v_add_u32_e32 v206, 0x8000, v206
	s_waitcnt vmcnt(12)
	v_lshlrev_b32_e32 v202, 16, v146
	v_and_b32_e32 v203, 0xffff0000, v146
	v_lshlrev_b32_e32 v204, 16, v147
	v_and_b32_e32 v205, 0xffff0000, v147
	v_pk_add_f32 v[124:125], v[124:125], v[202:203]
	v_pk_add_f32 v[126:127], v[126:127], v[204:205]
	v_lshlrev_b32_e32 v202, 16, v148
	v_and_b32_e32 v203, 0xffff0000, v148
	v_lshlrev_b32_e32 v204, 16, v149
	v_and_b32_e32 v205, 0xffff0000, v149
	v_pk_add_f32 v[120:121], v[120:121], v[202:203]
	v_pk_add_f32 v[122:123], v[122:123], v[204:205]
	v_cvt_pk_bf16_f32 v146, v124, v125
	v_cvt_pk_bf16_f32 v147, v126, v127
	v_cvt_pk_bf16_f32 v148, v120, v121
	v_cvt_pk_bf16_f32 v149, v122, v123
	v_pk_mul_f32 v[138:139], v[124:125], v[124:125]
	global_store_dwordx4 v207, v[146:149], s[10:11]
	v_pk_fma_f32 v[138:139], v[126:127], v[126:127], v[138:139]
	v_pk_fma_f32 v[138:139], v[120:121], v[120:121], v[138:139]
	v_pk_fma_f32 v[138:139], v[122:123], v[122:123], v[138:139]
	v_lshlrev_b32_e32 v202, 16, v150
	v_and_b32_e32 v203, 0xffff0000, v150
	v_lshlrev_b32_e32 v204, 16, v151
	v_and_b32_e32 v205, 0xffff0000, v151
	v_pk_add_f32 v[116:117], v[116:117], v[202:203]
	v_pk_add_f32 v[118:119], v[118:119], v[204:205]
	v_lshlrev_b32_e32 v202, 16, v152
	v_and_b32_e32 v203, 0xffff0000, v152
	v_lshlrev_b32_e32 v204, 16, v153
	v_and_b32_e32 v205, 0xffff0000, v153
	v_pk_add_f32 v[112:113], v[112:113], v[202:203]
	v_pk_add_f32 v[114:115], v[114:115], v[204:205]
	v_cvt_pk_bf16_f32 v150, v116, v117
	v_cvt_pk_bf16_f32 v151, v118, v119
	v_cvt_pk_bf16_f32 v152, v112, v113
	v_cvt_pk_bf16_f32 v153, v114, v115
	v_pk_fma_f32 v[138:139], v[116:117], v[116:117], v[138:139]
	global_store_dwordx4 v207, v[150:153], s[10:11] offset:256
	v_pk_fma_f32 v[138:139], v[118:119], v[118:119], v[138:139]
	v_pk_fma_f32 v[138:139], v[112:113], v[112:113], v[138:139]
	v_pk_fma_f32 v[138:139], v[114:115], v[114:115], v[138:139]
	v_add_f32_e32 v214, v138, v139
	v_add_u32_e32 v207, 0x8000, v207
	v_mov_b32_e32 v215, v214
	s_nop 1
	v_permlane16_swap_b32_e32 v214, v215
	s_nop 0
	v_add_f32_e32 v214, v214, v215
	v_mov_b32_e32 v215, v214
	s_nop 1
	v_permlane32_swap_b32_e32 v214, v215
	s_nop 0
	v_add_f32_e32 v214, v214, v215
	s_and_saveexec_b64 s[28:29], s[4:5]
	global_store_dword v210, v214, s[16:17]
	s_mov_b64 exec, s[28:29]
	global_load_dwordx4 v[146:149], v206, s[10:11]
	global_load_dwordx4 v[150:153], v206, s[10:11] offset:256
	s_waitcnt vmcnt(15)
	v_lshlrev_b32_e32 v202, 16, v154
	v_and_b32_e32 v203, 0xffff0000, v154
	v_lshlrev_b32_e32 v204, 16, v155
	v_and_b32_e32 v205, 0xffff0000, v155
	v_pk_add_f32 v[108:109], v[108:109], v[202:203]
	v_pk_add_f32 v[110:111], v[110:111], v[204:205]
	v_lshlrev_b32_e32 v202, 16, v156
	v_and_b32_e32 v203, 0xffff0000, v156
	v_lshlrev_b32_e32 v204, 16, v157
	v_and_b32_e32 v205, 0xffff0000, v157
	v_pk_add_f32 v[104:105], v[104:105], v[202:203]
	v_pk_add_f32 v[106:107], v[106:107], v[204:205]
	v_cvt_pk_bf16_f32 v154, v108, v109
	v_cvt_pk_bf16_f32 v155, v110, v111
	v_cvt_pk_bf16_f32 v156, v104, v105
	v_cvt_pk_bf16_f32 v157, v106, v107
	v_pk_mul_f32 v[138:139], v[108:109], v[108:109]
	global_store_dwordx4 v207, v[154:157], s[10:11]
	v_pk_fma_f32 v[138:139], v[110:111], v[110:111], v[138:139]
	v_pk_fma_f32 v[138:139], v[104:105], v[104:105], v[138:139]
	v_pk_fma_f32 v[138:139], v[106:107], v[106:107], v[138:139]
	v_lshlrev_b32_e32 v202, 16, v158
	v_and_b32_e32 v203, 0xffff0000, v158
	v_lshlrev_b32_e32 v204, 16, v159
	v_and_b32_e32 v205, 0xffff0000, v159
	v_pk_add_f32 v[100:101], v[100:101], v[202:203]
	v_pk_add_f32 v[102:103], v[102:103], v[204:205]
	v_lshlrev_b32_e32 v202, 16, v160
	v_and_b32_e32 v203, 0xffff0000, v160
	v_lshlrev_b32_e32 v204, 16, v161
	v_and_b32_e32 v205, 0xffff0000, v161
	v_pk_add_f32 v[96:97], v[96:97], v[202:203]
	v_pk_add_f32 v[98:99], v[98:99], v[204:205]
	v_cvt_pk_bf16_f32 v158, v100, v101
	v_cvt_pk_bf16_f32 v159, v102, v103
	v_cvt_pk_bf16_f32 v160, v96, v97
	v_cvt_pk_bf16_f32 v161, v98, v99
	v_pk_fma_f32 v[138:139], v[100:101], v[100:101], v[138:139]
	global_store_dwordx4 v207, v[158:161], s[10:11] offset:256
	v_pk_fma_f32 v[138:139], v[102:103], v[102:103], v[138:139]
	v_pk_fma_f32 v[138:139], v[96:97], v[96:97], v[138:139]
	v_pk_fma_f32 v[138:139], v[98:99], v[98:99], v[138:139]
	v_add_f32_e32 v214, v138, v139
	v_add_u32_e32 v207, 0x8000, v207
	v_mov_b32_e32 v215, v214
	s_nop 1
	v_permlane16_swap_b32_e32 v214, v215
	s_nop 0
	v_add_f32_e32 v214, v214, v215
	v_mov_b32_e32 v215, v214
	s_nop 1
	v_permlane32_swap_b32_e32 v214, v215
	s_nop 0
	v_add_f32_e32 v214, v214, v215
	s_and_saveexec_b64 s[28:29], s[4:5]
	global_store_dword v210, v214, s[16:17] offset:1024
	s_mov_b64 exec, s[28:29]
	s_waitcnt vmcnt(16)
	v_lshlrev_b32_e32 v202, 16, v162
	v_and_b32_e32 v203, 0xffff0000, v162
	v_lshlrev_b32_e32 v204, 16, v163
	v_and_b32_e32 v205, 0xffff0000, v163
	v_pk_add_f32 v[92:93], v[92:93], v[202:203]
	v_pk_add_f32 v[94:95], v[94:95], v[204:205]
	v_lshlrev_b32_e32 v202, 16, v164
	v_and_b32_e32 v203, 0xffff0000, v164
	v_lshlrev_b32_e32 v204, 16, v165
	v_and_b32_e32 v205, 0xffff0000, v165
	v_pk_add_f32 v[88:89], v[88:89], v[202:203]
	v_pk_add_f32 v[90:91], v[90:91], v[204:205]
	v_cvt_pk_bf16_f32 v162, v92, v93
	v_cvt_pk_bf16_f32 v163, v94, v95
	v_cvt_pk_bf16_f32 v164, v88, v89
	v_cvt_pk_bf16_f32 v165, v90, v91
	v_pk_mul_f32 v[138:139], v[92:93], v[92:93]
	global_store_dwordx4 v207, v[162:165], s[10:11]
	v_pk_fma_f32 v[138:139], v[94:95], v[94:95], v[138:139]
	v_pk_fma_f32 v[138:139], v[88:89], v[88:89], v[138:139]
	v_pk_fma_f32 v[138:139], v[90:91], v[90:91], v[138:139]
	v_lshlrev_b32_e32 v202, 16, v166
	v_and_b32_e32 v203, 0xffff0000, v166
	v_lshlrev_b32_e32 v204, 16, v167
	v_and_b32_e32 v205, 0xffff0000, v167
	v_pk_add_f32 v[84:85], v[84:85], v[202:203]
	v_pk_add_f32 v[86:87], v[86:87], v[204:205]
	v_lshlrev_b32_e32 v202, 16, v168
	v_and_b32_e32 v203, 0xffff0000, v168
	v_lshlrev_b32_e32 v204, 16, v169
	v_and_b32_e32 v205, 0xffff0000, v169
	v_pk_add_f32 v[80:81], v[80:81], v[202:203]
	v_pk_add_f32 v[82:83], v[82:83], v[204:205]
	v_cvt_pk_bf16_f32 v166, v84, v85
	v_cvt_pk_bf16_f32 v167, v86, v87
	v_cvt_pk_bf16_f32 v168, v80, v81
	v_cvt_pk_bf16_f32 v169, v82, v83
	v_pk_fma_f32 v[138:139], v[84:85], v[84:85], v[138:139]
	global_store_dwordx4 v207, v[166:169], s[10:11] offset:256
	v_pk_fma_f32 v[138:139], v[86:87], v[86:87], v[138:139]
	v_pk_fma_f32 v[138:139], v[80:81], v[80:81], v[138:139]
	v_pk_fma_f32 v[138:139], v[82:83], v[82:83], v[138:139]
	v_add_f32_e32 v214, v138, v139
	v_add_u32_e32 v207, 0x8000, v207
	v_mov_b32_e32 v215, v214
	s_nop 1
	v_permlane16_swap_b32_e32 v214, v215
	s_nop 0
	v_add_f32_e32 v214, v214, v215
	v_mov_b32_e32 v215, v214
	s_nop 1
	v_permlane32_swap_b32_e32 v214, v215
	s_nop 0
	v_add_f32_e32 v214, v214, v215
	s_and_saveexec_b64 s[28:29], s[4:5]
	global_store_dword v210, v214, s[16:17] offset:2048
	s_mov_b64 exec, s[28:29]
	s_waitcnt vmcnt(17)
	v_lshlrev_b32_e32 v202, 16, v170
	v_and_b32_e32 v203, 0xffff0000, v170
	v_lshlrev_b32_e32 v204, 16, v171
	v_and_b32_e32 v205, 0xffff0000, v171
	v_pk_add_f32 v[76:77], v[76:77], v[202:203]
	v_pk_add_f32 v[78:79], v[78:79], v[204:205]
	v_lshlrev_b32_e32 v202, 16, v172
	v_and_b32_e32 v203, 0xffff0000, v172
	v_lshlrev_b32_e32 v204, 16, v173
	v_and_b32_e32 v205, 0xffff0000, v173
	v_pk_add_f32 v[72:73], v[72:73], v[202:203]
	v_pk_add_f32 v[74:75], v[74:75], v[204:205]
	v_cvt_pk_bf16_f32 v170, v76, v77
	v_cvt_pk_bf16_f32 v171, v78, v79
	v_cvt_pk_bf16_f32 v172, v72, v73
	v_cvt_pk_bf16_f32 v173, v74, v75
	v_pk_mul_f32 v[138:139], v[76:77], v[76:77]
	global_store_dwordx4 v207, v[170:173], s[10:11]
	v_pk_fma_f32 v[138:139], v[78:79], v[78:79], v[138:139]
	v_pk_fma_f32 v[138:139], v[72:73], v[72:73], v[138:139]
	v_pk_fma_f32 v[138:139], v[74:75], v[74:75], v[138:139]
	v_lshlrev_b32_e32 v202, 16, v174
	v_and_b32_e32 v203, 0xffff0000, v174
	v_lshlrev_b32_e32 v204, 16, v175
	v_and_b32_e32 v205, 0xffff0000, v175
	v_pk_add_f32 v[68:69], v[68:69], v[202:203]
	v_pk_add_f32 v[70:71], v[70:71], v[204:205]
	v_lshlrev_b32_e32 v202, 16, v176
	v_and_b32_e32 v203, 0xffff0000, v176
	v_lshlrev_b32_e32 v204, 16, v177
	v_and_b32_e32 v205, 0xffff0000, v177
	v_pk_add_f32 v[64:65], v[64:65], v[202:203]
	v_pk_add_f32 v[66:67], v[66:67], v[204:205]
	v_cvt_pk_bf16_f32 v174, v68, v69
	v_cvt_pk_bf16_f32 v175, v70, v71
	v_cvt_pk_bf16_f32 v176, v64, v65
	v_cvt_pk_bf16_f32 v177, v66, v67
	v_pk_fma_f32 v[138:139], v[68:69], v[68:69], v[138:139]
	global_store_dwordx4 v207, v[174:177], s[10:11] offset:256
	v_pk_fma_f32 v[138:139], v[70:71], v[70:71], v[138:139]
	v_pk_fma_f32 v[138:139], v[64:65], v[64:65], v[138:139]
	v_pk_fma_f32 v[138:139], v[66:67], v[66:67], v[138:139]
	v_add_f32_e32 v214, v138, v139
	v_add_u32_e32 v207, 0x28000, v207
	v_mov_b32_e32 v215, v214
	s_nop 1
	v_permlane16_swap_b32_e32 v214, v215
	s_nop 0
	v_add_f32_e32 v214, v214, v215
	v_mov_b32_e32 v215, v214
	s_nop 1
	v_permlane32_swap_b32_e32 v214, v215
	s_nop 0
	v_add_f32_e32 v214, v214, v215
	s_and_saveexec_b64 s[28:29], s[4:5]
	global_store_dword v210, v214, s[16:17] offset:3072
	s_mov_b64 exec, s[28:29]
	v_add_u32_e32 v210, 0x2000, v210
	s_waitcnt vmcnt(18)
	v_lshlrev_b32_e32 v202, 16, v178
	v_and_b32_e32 v203, 0xffff0000, v178
	v_lshlrev_b32_e32 v204, 16, v179
	v_and_b32_e32 v205, 0xffff0000, v179
	v_pk_add_f32 v[60:61], v[60:61], v[202:203]
	v_pk_add_f32 v[62:63], v[62:63], v[204:205]
	v_lshlrev_b32_e32 v202, 16, v180
	v_and_b32_e32 v203, 0xffff0000, v180
	v_lshlrev_b32_e32 v204, 16, v181
	v_and_b32_e32 v205, 0xffff0000, v181
	v_pk_add_f32 v[56:57], v[56:57], v[202:203]
	v_pk_add_f32 v[58:59], v[58:59], v[204:205]
	v_cvt_pk_bf16_f32 v178, v60, v61
	v_cvt_pk_bf16_f32 v179, v62, v63
	v_cvt_pk_bf16_f32 v180, v56, v57
	v_cvt_pk_bf16_f32 v181, v58, v59
	v_pk_mul_f32 v[138:139], v[60:61], v[60:61]
	global_store_dwordx4 v207, v[178:181], s[10:11]
	v_pk_fma_f32 v[138:139], v[62:63], v[62:63], v[138:139]
	v_pk_fma_f32 v[138:139], v[56:57], v[56:57], v[138:139]
	v_pk_fma_f32 v[138:139], v[58:59], v[58:59], v[138:139]
	v_lshlrev_b32_e32 v202, 16, v182
	v_and_b32_e32 v203, 0xffff0000, v182
	v_lshlrev_b32_e32 v204, 16, v183
	v_and_b32_e32 v205, 0xffff0000, v183
	v_pk_add_f32 v[52:53], v[52:53], v[202:203]
	v_pk_add_f32 v[54:55], v[54:55], v[204:205]
	v_lshlrev_b32_e32 v202, 16, v184
	v_and_b32_e32 v203, 0xffff0000, v184
	v_lshlrev_b32_e32 v204, 16, v185
	v_and_b32_e32 v205, 0xffff0000, v185
	v_pk_add_f32 v[48:49], v[48:49], v[202:203]
	v_pk_add_f32 v[50:51], v[50:51], v[204:205]
	v_cvt_pk_bf16_f32 v182, v52, v53
	v_cvt_pk_bf16_f32 v183, v54, v55
	v_cvt_pk_bf16_f32 v184, v48, v49
	v_cvt_pk_bf16_f32 v185, v50, v51
	v_pk_fma_f32 v[138:139], v[52:53], v[52:53], v[138:139]
	global_store_dwordx4 v207, v[182:185], s[10:11] offset:256
	v_pk_fma_f32 v[138:139], v[54:55], v[54:55], v[138:139]
	v_pk_fma_f32 v[138:139], v[48:49], v[48:49], v[138:139]
	v_pk_fma_f32 v[138:139], v[50:51], v[50:51], v[138:139]
	v_add_f32_e32 v214, v138, v139
	v_add_u32_e32 v207, 0x8000, v207
	v_mov_b32_e32 v215, v214
	s_nop 1
	v_permlane16_swap_b32_e32 v214, v215
	s_nop 0
	v_add_f32_e32 v214, v214, v215
	v_mov_b32_e32 v215, v214
	s_nop 1
	v_permlane32_swap_b32_e32 v214, v215
	s_nop 0
	v_add_f32_e32 v214, v214, v215
	s_and_saveexec_b64 s[28:29], s[4:5]
	global_store_dword v210, v214, s[16:17]
	s_mov_b64 exec, s[28:29]
	s_waitcnt vmcnt(19)
	v_lshlrev_b32_e32 v202, 16, v186
	v_and_b32_e32 v203, 0xffff0000, v186
	v_lshlrev_b32_e32 v204, 16, v187
	v_and_b32_e32 v205, 0xffff0000, v187
	v_pk_add_f32 v[44:45], v[44:45], v[202:203]
	v_pk_add_f32 v[46:47], v[46:47], v[204:205]
	v_lshlrev_b32_e32 v202, 16, v188
	v_and_b32_e32 v203, 0xffff0000, v188
	v_lshlrev_b32_e32 v204, 16, v189
	v_and_b32_e32 v205, 0xffff0000, v189
	v_pk_add_f32 v[40:41], v[40:41], v[202:203]
	v_pk_add_f32 v[42:43], v[42:43], v[204:205]
	v_cvt_pk_bf16_f32 v186, v44, v45
	v_cvt_pk_bf16_f32 v187, v46, v47
	v_cvt_pk_bf16_f32 v188, v40, v41
	v_cvt_pk_bf16_f32 v189, v42, v43
	v_pk_mul_f32 v[138:139], v[44:45], v[44:45]
	global_store_dwordx4 v207, v[186:189], s[10:11]
	v_pk_fma_f32 v[138:139], v[46:47], v[46:47], v[138:139]
	v_pk_fma_f32 v[138:139], v[40:41], v[40:41], v[138:139]
	v_pk_fma_f32 v[138:139], v[42:43], v[42:43], v[138:139]
	v_lshlrev_b32_e32 v202, 16, v190
	v_and_b32_e32 v203, 0xffff0000, v190
	v_lshlrev_b32_e32 v204, 16, v191
	v_and_b32_e32 v205, 0xffff0000, v191
	v_pk_add_f32 v[36:37], v[36:37], v[202:203]
	v_pk_add_f32 v[38:39], v[38:39], v[204:205]
	v_lshlrev_b32_e32 v202, 16, v192
	v_and_b32_e32 v203, 0xffff0000, v192
	v_lshlrev_b32_e32 v204, 16, v193
	v_and_b32_e32 v205, 0xffff0000, v193
	v_pk_add_f32 v[32:33], v[32:33], v[202:203]
	v_pk_add_f32 v[34:35], v[34:35], v[204:205]
	v_cvt_pk_bf16_f32 v190, v36, v37
	v_cvt_pk_bf16_f32 v191, v38, v39
	v_cvt_pk_bf16_f32 v192, v32, v33
	v_cvt_pk_bf16_f32 v193, v34, v35
	v_pk_fma_f32 v[138:139], v[36:37], v[36:37], v[138:139]
	global_store_dwordx4 v207, v[190:193], s[10:11] offset:256
	v_pk_fma_f32 v[138:139], v[38:39], v[38:39], v[138:139]
	v_pk_fma_f32 v[138:139], v[32:33], v[32:33], v[138:139]
	v_pk_fma_f32 v[138:139], v[34:35], v[34:35], v[138:139]
	v_add_f32_e32 v214, v138, v139
	v_add_u32_e32 v207, 0x8000, v207
	v_mov_b32_e32 v215, v214
	s_nop 1
	v_permlane16_swap_b32_e32 v214, v215
	s_nop 0
	v_add_f32_e32 v214, v214, v215
	v_mov_b32_e32 v215, v214
	s_nop 1
	v_permlane32_swap_b32_e32 v214, v215
	s_nop 0
	v_add_f32_e32 v214, v214, v215
	s_and_saveexec_b64 s[28:29], s[4:5]
	global_store_dword v210, v214, s[16:17] offset:1024
	s_mov_b64 exec, s[28:29]
	s_waitcnt vmcnt(20)
	v_lshlrev_b32_e32 v202, 16, v194
	v_and_b32_e32 v203, 0xffff0000, v194
	v_lshlrev_b32_e32 v204, 16, v195
	v_and_b32_e32 v205, 0xffff0000, v195
	v_pk_add_f32 v[28:29], v[28:29], v[202:203]
	v_pk_add_f32 v[30:31], v[30:31], v[204:205]
	v_lshlrev_b32_e32 v202, 16, v196
	v_and_b32_e32 v203, 0xffff0000, v196
	v_lshlrev_b32_e32 v204, 16, v197
	v_and_b32_e32 v205, 0xffff0000, v197
	v_pk_add_f32 v[24:25], v[24:25], v[202:203]
	v_pk_add_f32 v[26:27], v[26:27], v[204:205]
	v_cvt_pk_bf16_f32 v194, v28, v29
	v_cvt_pk_bf16_f32 v195, v30, v31
	v_cvt_pk_bf16_f32 v196, v24, v25
	v_cvt_pk_bf16_f32 v197, v26, v27
	v_pk_mul_f32 v[138:139], v[28:29], v[28:29]
	global_store_dwordx4 v207, v[194:197], s[10:11]
	v_pk_fma_f32 v[138:139], v[30:31], v[30:31], v[138:139]
	v_pk_fma_f32 v[138:139], v[24:25], v[24:25], v[138:139]
	v_pk_fma_f32 v[138:139], v[26:27], v[26:27], v[138:139]
	v_lshlrev_b32_e32 v202, 16, v198
	v_and_b32_e32 v203, 0xffff0000, v198
	v_lshlrev_b32_e32 v204, 16, v199
	v_and_b32_e32 v205, 0xffff0000, v199
	v_pk_add_f32 v[20:21], v[20:21], v[202:203]
	v_pk_add_f32 v[22:23], v[22:23], v[204:205]
	v_lshlrev_b32_e32 v202, 16, v200
	v_and_b32_e32 v203, 0xffff0000, v200
	v_lshlrev_b32_e32 v204, 16, v201
	v_and_b32_e32 v205, 0xffff0000, v201
	v_pk_add_f32 v[16:17], v[16:17], v[202:203]
	v_pk_add_f32 v[18:19], v[18:19], v[204:205]
	v_cvt_pk_bf16_f32 v198, v20, v21
	v_cvt_pk_bf16_f32 v199, v22, v23
	v_cvt_pk_bf16_f32 v200, v16, v17
	v_cvt_pk_bf16_f32 v201, v18, v19
	v_pk_fma_f32 v[138:139], v[20:21], v[20:21], v[138:139]
	global_store_dwordx4 v207, v[198:201], s[10:11] offset:256
	v_pk_fma_f32 v[138:139], v[22:23], v[22:23], v[138:139]
	v_pk_fma_f32 v[138:139], v[16:17], v[16:17], v[138:139]
	v_pk_fma_f32 v[138:139], v[18:19], v[18:19], v[138:139]
	v_add_f32_e32 v214, v138, v139
	v_add_u32_e32 v207, 0x8000, v207
	v_mov_b32_e32 v215, v214
	s_nop 1
	v_permlane16_swap_b32_e32 v214, v215
	s_nop 0
	v_add_f32_e32 v214, v214, v215
	v_mov_b32_e32 v215, v214
	s_nop 1
	v_permlane32_swap_b32_e32 v214, v215
	s_nop 0
	v_add_f32_e32 v214, v214, v215
	s_and_saveexec_b64 s[28:29], s[4:5]
	global_store_dword v210, v214, s[16:17] offset:2048
	s_mov_b64 exec, s[28:29]
	s_waitcnt vmcnt(18)
	v_lshlrev_b32_e32 v202, 16, v146
	v_and_b32_e32 v203, 0xffff0000, v146
	v_lshlrev_b32_e32 v204, 16, v147
	v_and_b32_e32 v205, 0xffff0000, v147
	v_pk_add_f32 v[12:13], v[12:13], v[202:203]
	v_pk_add_f32 v[14:15], v[14:15], v[204:205]
	v_lshlrev_b32_e32 v202, 16, v148
	v_and_b32_e32 v203, 0xffff0000, v148
	v_lshlrev_b32_e32 v204, 16, v149
	v_and_b32_e32 v205, 0xffff0000, v149
	v_pk_add_f32 v[8:9], v[8:9], v[202:203]
	v_pk_add_f32 v[10:11], v[10:11], v[204:205]
	v_cvt_pk_bf16_f32 v146, v12, v13
	v_cvt_pk_bf16_f32 v147, v14, v15
	v_cvt_pk_bf16_f32 v148, v8, v9
	v_cvt_pk_bf16_f32 v149, v10, v11
	v_pk_mul_f32 v[138:139], v[12:13], v[12:13]
	global_store_dwordx4 v207, v[146:149], s[10:11]
	v_pk_fma_f32 v[138:139], v[14:15], v[14:15], v[138:139]
	v_pk_fma_f32 v[138:139], v[8:9], v[8:9], v[138:139]
	v_pk_fma_f32 v[138:139], v[10:11], v[10:11], v[138:139]
	v_lshlrev_b32_e32 v202, 16, v150
	v_and_b32_e32 v203, 0xffff0000, v150
	v_lshlrev_b32_e32 v204, 16, v151
	v_and_b32_e32 v205, 0xffff0000, v151
	v_pk_add_f32 v[4:5], v[4:5], v[202:203]
	v_pk_add_f32 v[6:7], v[6:7], v[204:205]
	v_lshlrev_b32_e32 v202, 16, v152
	v_and_b32_e32 v203, 0xffff0000, v152
	v_lshlrev_b32_e32 v204, 16, v153
	v_and_b32_e32 v205, 0xffff0000, v153
	v_pk_add_f32 v[0:1], v[0:1], v[202:203]
	v_pk_add_f32 v[2:3], v[2:3], v[204:205]
	v_cvt_pk_bf16_f32 v150, v4, v5
	v_cvt_pk_bf16_f32 v151, v6, v7
	v_cvt_pk_bf16_f32 v152, v0, v1
	v_cvt_pk_bf16_f32 v153, v2, v3
	v_pk_fma_f32 v[138:139], v[4:5], v[4:5], v[138:139]
	global_store_dwordx4 v207, v[150:153], s[10:11] offset:256
	v_pk_fma_f32 v[138:139], v[6:7], v[6:7], v[138:139]
	v_pk_fma_f32 v[138:139], v[0:1], v[0:1], v[138:139]
	v_pk_fma_f32 v[138:139], v[2:3], v[2:3], v[138:139]
	v_add_f32_e32 v214, v138, v139
	v_add_u32_e32 v207, 0x8000, v207
	v_mov_b32_e32 v215, v214
	s_nop 1
	v_permlane16_swap_b32_e32 v214, v215
	s_nop 0
	v_add_f32_e32 v214, v214, v215
	v_mov_b32_e32 v215, v214
	s_nop 1
	v_permlane32_swap_b32_e32 v214, v215
	s_nop 0
	v_add_f32_e32 v214, v214, v215
	s_and_saveexec_b64 s[28:29], s[4:5]
	global_store_dword v210, v214, s[16:17] offset:3072
	s_mov_b64 exec, s[28:29]
	s_branch .LBB0_768

.LBB0_823:
	s_add_u32 s26, s24, 0xfffc0080
	s_addc_u32 s27, s25, -1
	s_add_i32 s65, 0, 0x10000
	v_add_u32_e32 v154, s65, v143
	ds_read_b128 v[138:141], v154
	ds_read_b128 v[146:149], v154 offset:1024
	ds_read_b128 v[150:153], v154 offset:2048
	ds_read_b128 v[154:157], v154 offset:3072
	s_cmp_eq_u32 s51, 12
	s_cselect_b32 s29, s19, s27
	s_cselect_b32 s28, s38, s26
	s_cselect_b32 s27, s17, s50
	s_cselect_b32 s26, s39, s46
	s_add_i32 m0, s58, 0xc000
	ds_read_b128 v[158:161], v145
	ds_read_b128 v[162:165], v145 offset:1024
	ds_read_b128 v[166:169], v145 offset:2048
	ds_read_b128 v[170:173], v145 offset:3072
	ds_read_b128 v[174:177], v145 offset:4096
	ds_read_b128 v[178:181], v145 offset:5120
	ds_read_b128 v[182:185], v145 offset:6144
	ds_read_b128 v[186:189], v145 offset:7168
	global_load_lds_dwordx4 v134, s[24:25]
	s_add_i32 m0, s58, 0xe000
	s_nop 0
	global_load_lds_dwordx4 v136, s[24:25]
	s_waitcnt lgkmcnt(8)
	s_barrier
	s_waitcnt lgkmcnt(0)
	v_mfma_f32_16x16x32_bf16 v[124:127], v[138:141], v[158:161], v[124:127]
	v_mfma_f32_16x16x32_bf16 v[120:123], v[150:153], v[158:161], v[120:123]
	v_mfma_f32_16x16x32_bf16 v[108:111], v[138:141], v[166:169], v[108:111]
	v_mfma_f32_16x16x32_bf16 v[104:107], v[150:153], v[166:169], v[104:107]
	v_mfma_f32_16x16x32_bf16 v[92:95], v[138:141], v[174:177], v[92:95]
	v_mfma_f32_16x16x32_bf16 v[88:91], v[150:153], v[174:177], v[88:91]
	v_mfma_f32_16x16x32_bf16 v[76:79], v[138:141], v[182:185], v[76:79]
	v_mfma_f32_16x16x32_bf16 v[72:75], v[150:153], v[182:185], v[72:75]
	v_mfma_f32_16x16x32_bf16 v[124:127], v[146:149], v[162:165], v[124:127]
	v_mfma_f32_16x16x32_bf16 v[120:123], v[154:157], v[162:165], v[120:123]
	v_mfma_f32_16x16x32_bf16 v[108:111], v[146:149], v[170:173], v[108:111]
	v_mfma_f32_16x16x32_bf16 v[104:107], v[154:157], v[170:173], v[104:107]
	v_mfma_f32_16x16x32_bf16 v[92:95], v[146:149], v[178:181], v[92:95]
	v_mfma_f32_16x16x32_bf16 v[88:91], v[154:157], v[178:181], v[88:91]
	v_mfma_f32_16x16x32_bf16 v[76:79], v[146:149], v[186:189], v[76:79]
	v_mfma_f32_16x16x32_bf16 v[72:75], v[154:157], v[186:189], v[72:75]
	s_barrier
	s_add_i32 s68, 0, 0x14000
	s_add_i32 s65, s65, s57
	v_add_u32_e32 v202, s68, v143
	s_add_u32 s98, s26, s40
	s_addc_u32 s99, s27, s41
	s_mov_b32 m0, s65
	ds_read_b128 v[190:193], v202
	ds_read_b128 v[194:197], v202 offset:1024
	ds_read_b128 v[198:201], v202 offset:2048
	ds_read_b128 v[202:205], v202 offset:3072
	global_load_lds_dwordx4 v208, s[26:27]
	s_add_i32 m0, s65, 0x2000
	s_nop 0
	global_load_lds_dwordx4 v128, s[26:27]
	s_barrier
	s_waitcnt lgkmcnt(0)
	v_mfma_f32_16x16x32_bf16 v[116:119], v[190:193], v[158:161], v[116:119]
	v_mfma_f32_16x16x32_bf16 v[112:115], v[198:201], v[158:161], v[112:115]
	v_mfma_f32_16x16x32_bf16 v[100:103], v[190:193], v[166:169], v[100:103]
	v_mfma_f32_16x16x32_bf16 v[96:99], v[198:201], v[166:169], v[96:99]
	v_mfma_f32_16x16x32_bf16 v[84:87], v[190:193], v[174:177], v[84:87]
	v_mfma_f32_16x16x32_bf16 v[80:83], v[198:201], v[174:177], v[80:83]
	v_mfma_f32_16x16x32_bf16 v[68:71], v[190:193], v[182:185], v[68:71]
	v_mfma_f32_16x16x32_bf16 v[64:67], v[198:201], v[182:185], v[64:67]
	v_mfma_f32_16x16x32_bf16 v[116:119], v[194:197], v[162:165], v[116:119]
	v_mfma_f32_16x16x32_bf16 v[112:115], v[202:205], v[162:165], v[112:115]
	v_mfma_f32_16x16x32_bf16 v[100:103], v[194:197], v[170:173], v[100:103]
	v_mfma_f32_16x16x32_bf16 v[96:99], v[202:205], v[170:173], v[96:99]
	v_mfma_f32_16x16x32_bf16 v[84:87], v[194:197], v[178:181], v[84:87]
	v_mfma_f32_16x16x32_bf16 v[80:83], v[202:205], v[178:181], v[80:83]
	v_mfma_f32_16x16x32_bf16 v[68:71], v[194:197], v[186:189], v[68:71]
	v_mfma_f32_16x16x32_bf16 v[64:67], v[202:205], v[186:189], v[64:67]
	s_mov_b32 m0, s58
	s_add_u32 s100, s28, s40
	s_addc_u32 s101, s29, s41
	s_barrier
	ds_read_b128 v[158:161], v145 offset:16384
	ds_read_b128 v[162:165], v145 offset:17408
	ds_read_b128 v[166:169], v145 offset:18432
	ds_read_b128 v[170:173], v145 offset:19456
	ds_read_b128 v[174:177], v145 offset:20480
	ds_read_b128 v[178:181], v145 offset:21504
	ds_read_b128 v[182:185], v145 offset:22528
	ds_read_b128 v[186:189], v145 offset:23552
	global_load_lds_dwordx4 v132, s[28:29]
	s_mov_b32 m0, s59
	s_nop 0
	global_load_lds_dwordx4 v130, s[28:29]
	s_barrier
	s_waitcnt lgkmcnt(0)
	v_mfma_f32_16x16x32_bf16 v[60:63], v[138:141], v[158:161], v[60:63]
	v_mfma_f32_16x16x32_bf16 v[56:59], v[150:153], v[158:161], v[56:59]
	v_mfma_f32_16x16x32_bf16 v[44:47], v[138:141], v[166:169], v[44:47]
	v_mfma_f32_16x16x32_bf16 v[40:43], v[150:153], v[166:169], v[40:43]
	v_mfma_f32_16x16x32_bf16 v[28:31], v[138:141], v[174:177], v[28:31]
	v_mfma_f32_16x16x32_bf16 v[24:27], v[150:153], v[174:177], v[24:27]
	v_mfma_f32_16x16x32_bf16 v[12:15], v[138:141], v[182:185], v[12:15]
	v_mfma_f32_16x16x32_bf16 v[8:11], v[150:153], v[182:185], v[8:11]
	v_mfma_f32_16x16x32_bf16 v[60:63], v[146:149], v[162:165], v[60:63]
	v_mfma_f32_16x16x32_bf16 v[56:59], v[154:157], v[162:165], v[56:59]
	v_mfma_f32_16x16x32_bf16 v[44:47], v[146:149], v[170:173], v[44:47]
	v_mfma_f32_16x16x32_bf16 v[40:43], v[154:157], v[170:173], v[40:43]
	v_mfma_f32_16x16x32_bf16 v[28:31], v[146:149], v[178:181], v[28:31]
	v_mfma_f32_16x16x32_bf16 v[24:27], v[154:157], v[178:181], v[24:27]
	v_mfma_f32_16x16x32_bf16 v[12:15], v[146:149], v[186:189], v[12:15]
	v_mfma_f32_16x16x32_bf16 v[8:11], v[154:157], v[186:189], v[8:11]
	s_barrier
	s_add_u32 s66, s26, 0x40000
	s_addc_u32 s67, s27, 0
	s_add_i32 s65, s68, s57
	s_mov_b32 m0, s65
	s_nop 0
	global_load_lds_dwordx4 v208, s[66:67]
	s_add_i32 m0, s65, 0x2000
	s_nop 0
	global_load_lds_dwordx4 v128, s[66:67]
	s_waitcnt vmcnt(6)
	s_barrier
	v_mfma_f32_16x16x32_bf16 v[52:55], v[190:193], v[158:161], v[52:55]
	v_mfma_f32_16x16x32_bf16 v[48:51], v[198:201], v[158:161], v[48:51]
	v_mfma_f32_16x16x32_bf16 v[36:39], v[190:193], v[166:169], v[36:39]
	v_mfma_f32_16x16x32_bf16 v[32:35], v[198:201], v[166:169], v[32:35]
	v_mfma_f32_16x16x32_bf16 v[20:23], v[190:193], v[174:177], v[20:23]
	v_mfma_f32_16x16x32_bf16 v[16:19], v[198:201], v[174:177], v[16:19]
	v_mfma_f32_16x16x32_bf16 v[4:7], v[190:193], v[182:185], v[4:7]
	v_mfma_f32_16x16x32_bf16 v[0:3], v[198:201], v[182:185], v[0:3]
	v_mfma_f32_16x16x32_bf16 v[52:55], v[194:197], v[162:165], v[52:55]
	v_mfma_f32_16x16x32_bf16 v[48:51], v[202:205], v[162:165], v[48:51]
	v_mfma_f32_16x16x32_bf16 v[36:39], v[194:197], v[170:173], v[36:39]
	v_mfma_f32_16x16x32_bf16 v[32:35], v[202:205], v[170:173], v[32:35]
	v_mfma_f32_16x16x32_bf16 v[20:23], v[194:197], v[178:181], v[20:23]
	v_mfma_f32_16x16x32_bf16 v[16:19], v[202:205], v[178:181], v[16:19]
	v_mfma_f32_16x16x32_bf16 v[4:7], v[194:197], v[186:189], v[4:7]
	v_mfma_f32_16x16x32_bf16 v[0:3], v[202:205], v[186:189], v[0:3]
	s_add_i32 s65, 0, 0x18000
	v_add_u32_e32 v154, s65, v143
	s_barrier
	ds_read_b128 v[138:141], v154
	ds_read_b128 v[146:149], v154 offset:1024
	ds_read_b128 v[150:153], v154 offset:2048
	ds_read_b128 v[154:157], v154 offset:3072
	s_add_u32 s28, s28, 0x40000
	s_addc_u32 s29, s29, 0
	s_mov_b32 m0, s60
	ds_read_b128 v[158:161], v145 offset:32768
	ds_read_b128 v[162:165], v145 offset:33792
	ds_read_b128 v[166:169], v145 offset:34816
	ds_read_b128 v[170:173], v145 offset:35840
	ds_read_b128 v[174:177], v145 offset:36864
	ds_read_b128 v[178:181], v145 offset:37888
	ds_read_b128 v[182:185], v145 offset:38912
	ds_read_b128 v[186:189], v145 offset:39936
	global_load_lds_dwordx4 v132, s[28:29]
	s_mov_b32 m0, s61
	s_nop 0
	global_load_lds_dwordx4 v130, s[28:29]
	s_waitcnt lgkmcnt(8)
	s_barrier
	s_waitcnt lgkmcnt(0)
	v_mfma_f32_16x16x32_bf16 v[124:127], v[138:141], v[158:161], v[124:127]
	v_mfma_f32_16x16x32_bf16 v[120:123], v[150:153], v[158:161], v[120:123]
	v_mfma_f32_16x16x32_bf16 v[108:111], v[138:141], v[166:169], v[108:111]
	v_mfma_f32_16x16x32_bf16 v[104:107], v[150:153], v[166:169], v[104:107]
	v_mfma_f32_16x16x32_bf16 v[92:95], v[138:141], v[174:177], v[92:95]
	v_mfma_f32_16x16x32_bf16 v[88:91], v[150:153], v[174:177], v[88:91]
	v_mfma_f32_16x16x32_bf16 v[76:79], v[138:141], v[182:185], v[76:79]
	v_mfma_f32_16x16x32_bf16 v[72:75], v[150:153], v[182:185], v[72:75]
	v_mfma_f32_16x16x32_bf16 v[124:127], v[146:149], v[162:165], v[124:127]
	v_mfma_f32_16x16x32_bf16 v[120:123], v[154:157], v[162:165], v[120:123]
	v_mfma_f32_16x16x32_bf16 v[108:111], v[146:149], v[170:173], v[108:111]
	v_mfma_f32_16x16x32_bf16 v[104:107], v[154:157], v[170:173], v[104:107]
	v_mfma_f32_16x16x32_bf16 v[92:95], v[146:149], v[178:181], v[92:95]
	v_mfma_f32_16x16x32_bf16 v[88:91], v[154:157], v[178:181], v[88:91]
	v_mfma_f32_16x16x32_bf16 v[76:79], v[146:149], v[186:189], v[76:79]
	v_mfma_f32_16x16x32_bf16 v[72:75], v[154:157], v[186:189], v[72:75]
	s_barrier
	s_add_i32 s28, 0, 0x1c000
	s_add_i32 s29, s65, s57
	v_add_u32_e32 v202, s28, v143
	s_mov_b32 m0, s29
	ds_read_b128 v[190:193], v202
	ds_read_b128 v[194:197], v202 offset:1024
	ds_read_b128 v[198:201], v202 offset:2048
	ds_read_b128 v[202:205], v202 offset:3072
	global_load_lds_dwordx4 v208, s[98:99]
	s_add_i32 m0, s29, 0x2000
	s_nop 0
	global_load_lds_dwordx4 v128, s[98:99]
	s_barrier
	s_waitcnt lgkmcnt(0)
	v_mfma_f32_16x16x32_bf16 v[116:119], v[190:193], v[158:161], v[116:119]
	v_mfma_f32_16x16x32_bf16 v[112:115], v[198:201], v[158:161], v[112:115]
	v_mfma_f32_16x16x32_bf16 v[100:103], v[190:193], v[166:169], v[100:103]
	v_mfma_f32_16x16x32_bf16 v[96:99], v[198:201], v[166:169], v[96:99]
	v_mfma_f32_16x16x32_bf16 v[84:87], v[190:193], v[174:177], v[84:87]
	v_mfma_f32_16x16x32_bf16 v[80:83], v[198:201], v[174:177], v[80:83]
	v_mfma_f32_16x16x32_bf16 v[68:71], v[190:193], v[182:185], v[68:71]
	v_mfma_f32_16x16x32_bf16 v[64:67], v[198:201], v[182:185], v[64:67]
	v_mfma_f32_16x16x32_bf16 v[116:119], v[194:197], v[162:165], v[116:119]
	v_mfma_f32_16x16x32_bf16 v[112:115], v[202:205], v[162:165], v[112:115]
	v_mfma_f32_16x16x32_bf16 v[100:103], v[194:197], v[170:173], v[100:103]
	v_mfma_f32_16x16x32_bf16 v[96:99], v[202:205], v[170:173], v[96:99]
	v_mfma_f32_16x16x32_bf16 v[84:87], v[194:197], v[178:181], v[84:87]
	v_mfma_f32_16x16x32_bf16 v[80:83], v[202:205], v[178:181], v[80:83]
	v_mfma_f32_16x16x32_bf16 v[68:71], v[194:197], v[186:189], v[68:71]
	v_mfma_f32_16x16x32_bf16 v[64:67], v[202:205], v[186:189], v[64:67]
	s_mov_b32 m0, s62
	s_barrier
	ds_read_b128 v[158:161], v145 offset:49152
	ds_read_b128 v[162:165], v145 offset:50176
	ds_read_b128 v[166:169], v145 offset:51200
	ds_read_b128 v[170:173], v145 offset:52224
	ds_read_b128 v[174:177], v145 offset:53248
	ds_read_b128 v[178:181], v145 offset:54272
	ds_read_b128 v[182:185], v145 offset:55296
	ds_read_b128 v[186:189], v145 offset:56320
	global_load_lds_dwordx4 v132, s[100:101]
	s_mov_b32 m0, s63
	s_nop 0
	global_load_lds_dwordx4 v130, s[100:101]
	s_barrier
	s_waitcnt lgkmcnt(0)
	v_mfma_f32_16x16x32_bf16 v[60:63], v[138:141], v[158:161], v[60:63]
	v_mfma_f32_16x16x32_bf16 v[56:59], v[150:153], v[158:161], v[56:59]
	v_mfma_f32_16x16x32_bf16 v[44:47], v[138:141], v[166:169], v[44:47]
	v_mfma_f32_16x16x32_bf16 v[40:43], v[150:153], v[166:169], v[40:43]
	v_mfma_f32_16x16x32_bf16 v[28:31], v[138:141], v[174:177], v[28:31]
	v_mfma_f32_16x16x32_bf16 v[24:27], v[150:153], v[174:177], v[24:27]
	v_mfma_f32_16x16x32_bf16 v[12:15], v[138:141], v[182:185], v[12:15]
	v_mfma_f32_16x16x32_bf16 v[8:11], v[150:153], v[182:185], v[8:11]
	v_mfma_f32_16x16x32_bf16 v[60:63], v[146:149], v[162:165], v[60:63]
	v_mfma_f32_16x16x32_bf16 v[56:59], v[154:157], v[162:165], v[56:59]
	v_mfma_f32_16x16x32_bf16 v[44:47], v[146:149], v[170:173], v[44:47]
	v_mfma_f32_16x16x32_bf16 v[40:43], v[154:157], v[170:173], v[40:43]
	v_mfma_f32_16x16x32_bf16 v[28:31], v[146:149], v[178:181], v[28:31]
	v_mfma_f32_16x16x32_bf16 v[24:27], v[154:157], v[178:181], v[24:27]
	v_mfma_f32_16x16x32_bf16 v[12:15], v[146:149], v[186:189], v[12:15]
	v_mfma_f32_16x16x32_bf16 v[8:11], v[154:157], v[186:189], v[8:11]
	s_barrier
	s_add_u32 s26, s26, 0x40080
	s_addc_u32 s27, s27, 0
	s_add_i32 s28, s28, s57
	s_mov_b32 m0, s28
	s_nop 0
	global_load_lds_dwordx4 v208, s[26:27]
	s_add_i32 m0, s28, 0x2000
	s_nop 0
	global_load_lds_dwordx4 v128, s[26:27]
	s_add_i32 s51, s51, 2
	s_add_u32 s24, s24, 0x100
	s_addc_u32 s25, s25, 0
	s_add_u32 s46, s46, 0x100
	s_addc_u32 s50, s50, 0
	s_waitcnt vmcnt(6)
	s_barrier
	v_mfma_f32_16x16x32_bf16 v[52:55], v[190:193], v[158:161], v[52:55]
	v_mfma_f32_16x16x32_bf16 v[48:51], v[198:201], v[158:161], v[48:51]
	v_mfma_f32_16x16x32_bf16 v[36:39], v[190:193], v[166:169], v[36:39]
	v_mfma_f32_16x16x32_bf16 v[32:35], v[198:201], v[166:169], v[32:35]
	v_mfma_f32_16x16x32_bf16 v[20:23], v[190:193], v[174:177], v[20:23]
	v_mfma_f32_16x16x32_bf16 v[16:19], v[198:201], v[174:177], v[16:19]
	v_mfma_f32_16x16x32_bf16 v[4:7], v[190:193], v[182:185], v[4:7]
	v_mfma_f32_16x16x32_bf16 v[0:3], v[198:201], v[182:185], v[0:3]
	v_mfma_f32_16x16x32_bf16 v[52:55], v[194:197], v[162:165], v[52:55]
	v_mfma_f32_16x16x32_bf16 v[48:51], v[202:205], v[162:165], v[48:51]
	v_mfma_f32_16x16x32_bf16 v[36:39], v[194:197], v[170:173], v[36:39]
	v_mfma_f32_16x16x32_bf16 v[32:35], v[202:205], v[170:173], v[32:35]
	v_mfma_f32_16x16x32_bf16 v[20:23], v[194:197], v[178:181], v[20:23]
	v_mfma_f32_16x16x32_bf16 v[16:19], v[202:205], v[178:181], v[16:19]
	v_mfma_f32_16x16x32_bf16 v[4:7], v[194:197], v[186:189], v[4:7]
	v_mfma_f32_16x16x32_bf16 v[0:3], v[202:205], v[186:189], v[0:3]
	s_cmp_gt_u32 s51, 13
	s_barrier
	s_cbranch_scc0 .LBB0_823
	v_lshl_add_u32 v140, s35, 8, v142
	v_lshl_or_b32 v141, s34, 8, v144
	s_mov_b32 s34, s16
	s_mov_b32 s35, s18
	s_mov_b64 s[26:27], s[22:23]
	s_mov_b64 s[24:25], s[20:21]
	v_mbcnt_lo_u32_b32 v206, -1, 0
	v_mbcnt_hi_u32_b32 v206, -1, v206
	v_and_b32_e32 v206, 48, v206
	v_lshl_add_u32 v206, v140, 6, v206
	v_lshlrev_b32_e32 v207, 11, v140
	v_lshl_add_u32 v207, v141, 1, v207
	global_load_dwordx4 v[146:149], v206, s[14:15]
	global_load_dwordx4 v[150:153], v206, s[14:15] offset:1024
	global_load_dwordx4 v[154:157], v206, s[14:15] offset:2048
	global_load_dwordx4 v[158:161], v206, s[14:15] offset:3072
	v_add_u32_e32 v206, 0x2000, v206
	global_load_dwordx4 v[162:165], v206, s[14:15]
	global_load_dwordx4 v[166:169], v206, s[14:15] offset:1024
	global_load_dwordx4 v[170:173], v206, s[14:15] offset:2048
	global_load_dwordx4 v[174:177], v206, s[14:15] offset:3072
	s_waitcnt vmcnt(7)
	v_pk_add_f32 v[146:147], v[146:147], v[148:149]
	s_nop 0
	v_add_f32_e32 v214, v146, v147
	v_mov_b32_e32 v215, v214
	s_nop 1
	v_permlane16_swap_b32_e32 v214, v215
	s_nop 0
	v_add_f32_e32 v214, v214, v215
	v_mov_b32_e32 v215, v214
	s_nop 1
	v_permlane32_swap_b32_e32 v214, v215
	s_nop 0
	v_add_f32_e32 v214, v214, v215
	v_fmamk_f32 v214, v214, 0x3a800000, v248
	v_rsq_f32_e32 v178, v214
	s_nop 0
	v_pk_mul_f32 v[124:125], v[124:125], v[178:179] op_sel_hi:[1,0]
	v_pk_mul_f32 v[126:127], v[126:127], v[178:179] op_sel_hi:[1,0]
	v_pk_mul_f32 v[120:121], v[120:121], v[178:179] op_sel_hi:[1,0]
	v_pk_mul_f32 v[122:123], v[122:123], v[178:179] op_sel_hi:[1,0]
	v_cvt_pk_bf16_f32 v198, v124, v125
	v_cvt_pk_bf16_f32 v199, v126, v127
	v_cvt_pk_bf16_f32 v200, v120, v121
	v_cvt_pk_bf16_f32 v201, v122, v123
	global_store_dwordx4 v207, v[198:201], s[10:11]
	v_pk_mul_f32 v[116:117], v[116:117], v[178:179] op_sel_hi:[1,0]
	v_pk_mul_f32 v[118:119], v[118:119], v[178:179] op_sel_hi:[1,0]
	v_pk_mul_f32 v[112:113], v[112:113], v[178:179] op_sel_hi:[1,0]
	v_pk_mul_f32 v[114:115], v[114:115], v[178:179] op_sel_hi:[1,0]
	v_cvt_pk_bf16_f32 v202, v116, v117
	v_cvt_pk_bf16_f32 v203, v118, v119
	v_cvt_pk_bf16_f32 v204, v112, v113
	v_cvt_pk_bf16_f32 v205, v114, v115
	global_store_dwordx4 v207, v[202:205], s[10:11] offset:256
	v_add_u32_e32 v207, 0x8000, v207
	s_waitcnt vmcnt(8)
	v_pk_add_f32 v[150:151], v[150:151], v[152:153]
	s_nop 0
	v_add_f32_e32 v214, v150, v151
	v_mov_b32_e32 v215, v214
	s_nop 1
	v_permlane16_swap_b32_e32 v214, v215
	s_nop 0
	v_add_f32_e32 v214, v214, v215
	v_mov_b32_e32 v215, v214
	s_nop 1
	v_permlane32_swap_b32_e32 v214, v215
	s_nop 0
	v_add_f32_e32 v214, v214, v215
	v_fmamk_f32 v214, v214, 0x3a800000, v248
	v_rsq_f32_e32 v180, v214
	s_nop 0
	v_pk_mul_f32 v[108:109], v[108:109], v[180:181] op_sel_hi:[1,0]
	v_pk_mul_f32 v[110:111], v[110:111], v[180:181] op_sel_hi:[1,0]
	v_pk_mul_f32 v[104:105], v[104:105], v[180:181] op_sel_hi:[1,0]
	v_pk_mul_f32 v[106:107], v[106:107], v[180:181] op_sel_hi:[1,0]
	v_cvt_pk_bf16_f32 v198, v108, v109
	v_cvt_pk_bf16_f32 v199, v110, v111
	v_cvt_pk_bf16_f32 v200, v104, v105
	v_cvt_pk_bf16_f32 v201, v106, v107
	global_store_dwordx4 v207, v[198:201], s[10:11]
	v_pk_mul_f32 v[100:101], v[100:101], v[180:181] op_sel_hi:[1,0]
	v_pk_mul_f32 v[102:103], v[102:103], v[180:181] op_sel_hi:[1,0]
	v_pk_mul_f32 v[96:97], v[96:97], v[180:181] op_sel_hi:[1,0]
	v_pk_mul_f32 v[98:99], v[98:99], v[180:181] op_sel_hi:[1,0]
	v_cvt_pk_bf16_f32 v202, v100, v101
	v_cvt_pk_bf16_f32 v203, v102, v103
	v_cvt_pk_bf16_f32 v204, v96, v97
	v_cvt_pk_bf16_f32 v205, v98, v99
	global_store_dwordx4 v207, v[202:205], s[10:11] offset:256
	v_add_u32_e32 v207, 0x8000, v207
	s_waitcnt vmcnt(9)
	v_pk_add_f32 v[154:155], v[154:155], v[156:157]
	s_nop 0
	v_add_f32_e32 v214, v154, v155
	v_mov_b32_e32 v215, v214
	s_nop 1
	v_permlane16_swap_b32_e32 v214, v215
	s_nop 0
	v_add_f32_e32 v214, v214, v215
	v_mov_b32_e32 v215, v214
	s_nop 1
	v_permlane32_swap_b32_e32 v214, v215
	s_nop 0
	v_add_f32_e32 v214, v214, v215
	v_fmamk_f32 v214, v214, 0x3a800000, v248
	v_rsq_f32_e32 v182, v214
	s_nop 0
	v_pk_mul_f32 v[92:93], v[92:93], v[182:183] op_sel_hi:[1,0]
	v_pk_mul_f32 v[94:95], v[94:95], v[182:183] op_sel_hi:[1,0]
	v_pk_mul_f32 v[88:89], v[88:89], v[182:183] op_sel_hi:[1,0]
	v_pk_mul_f32 v[90:91], v[90:91], v[182:183] op_sel_hi:[1,0]
	v_cvt_pk_bf16_f32 v198, v92, v93
	v_cvt_pk_bf16_f32 v199, v94, v95
	v_cvt_pk_bf16_f32 v200, v88, v89
	v_cvt_pk_bf16_f32 v201, v90, v91
	global_store_dwordx4 v207, v[198:201], s[10:11]
	v_pk_mul_f32 v[84:85], v[84:85], v[182:183] op_sel_hi:[1,0]
	v_pk_mul_f32 v[86:87], v[86:87], v[182:183] op_sel_hi:[1,0]
	v_pk_mul_f32 v[80:81], v[80:81], v[182:183] op_sel_hi:[1,0]
	v_pk_mul_f32 v[82:83], v[82:83], v[182:183] op_sel_hi:[1,0]
	v_cvt_pk_bf16_f32 v202, v84, v85
	v_cvt_pk_bf16_f32 v203, v86, v87
	v_cvt_pk_bf16_f32 v204, v80, v81
	v_cvt_pk_bf16_f32 v205, v82, v83
	global_store_dwordx4 v207, v[202:205], s[10:11] offset:256
	v_add_u32_e32 v207, 0x8000, v207
	s_waitcnt vmcnt(10)
	v_pk_add_f32 v[158:159], v[158:159], v[160:161]
	s_nop 0
	v_add_f32_e32 v214, v158, v159
	v_mov_b32_e32 v215, v214
	s_nop 1
	v_permlane16_swap_b32_e32 v214, v215
	s_nop 0
	v_add_f32_e32 v214, v214, v215
	v_mov_b32_e32 v215, v214
	s_nop 1
	v_permlane32_swap_b32_e32 v214, v215
	s_nop 0
	v_add_f32_e32 v214, v214, v215
	v_fmamk_f32 v214, v214, 0x3a800000, v248
	v_rsq_f32_e32 v184, v214
	s_nop 0
	v_pk_mul_f32 v[76:77], v[76:77], v[184:185] op_sel_hi:[1,0]
	v_pk_mul_f32 v[78:79], v[78:79], v[184:185] op_sel_hi:[1,0]
	v_pk_mul_f32 v[72:73], v[72:73], v[184:185] op_sel_hi:[1,0]
	v_pk_mul_f32 v[74:75], v[74:75], v[184:185] op_sel_hi:[1,0]
	v_cvt_pk_bf16_f32 v198, v76, v77
	v_cvt_pk_bf16_f32 v199, v78, v79
	v_cvt_pk_bf16_f32 v200, v72, v73
	v_cvt_pk_bf16_f32 v201, v74, v75
	global_store_dwordx4 v207, v[198:201], s[10:11]
	v_pk_mul_f32 v[68:69], v[68:69], v[184:185] op_sel_hi:[1,0]
	v_pk_mul_f32 v[70:71], v[70:71], v[184:185] op_sel_hi:[1,0]
	v_pk_mul_f32 v[64:65], v[64:65], v[184:185] op_sel_hi:[1,0]
	v_pk_mul_f32 v[66:67], v[66:67], v[184:185] op_sel_hi:[1,0]
	v_cvt_pk_bf16_f32 v202, v68, v69
	v_cvt_pk_bf16_f32 v203, v70, v71
	v_cvt_pk_bf16_f32 v204, v64, v65
	v_cvt_pk_bf16_f32 v205, v66, v67
	global_store_dwordx4 v207, v[202:205], s[10:11] offset:256
	v_add_u32_e32 v207, 0x28000, v207
	s_waitcnt vmcnt(11)
	v_pk_add_f32 v[162:163], v[162:163], v[164:165]
	s_nop 0
	v_add_f32_e32 v214, v162, v163
	v_mov_b32_e32 v215, v214
	s_nop 1
	v_permlane16_swap_b32_e32 v214, v215
	s_nop 0
	v_add_f32_e32 v214, v214, v215
	v_mov_b32_e32 v215, v214
	s_nop 1
	v_permlane32_swap_b32_e32 v214, v215
	s_nop 0
	v_add_f32_e32 v214, v214, v215
	v_fmamk_f32 v214, v214, 0x3a800000, v248
	v_rsq_f32_e32 v186, v214
	s_nop 0
	v_pk_mul_f32 v[60:61], v[60:61], v[186:187] op_sel_hi:[1,0]
	v_pk_mul_f32 v[62:63], v[62:63], v[186:187] op_sel_hi:[1,0]
	v_pk_mul_f32 v[56:57], v[56:57], v[186:187] op_sel_hi:[1,0]
	v_pk_mul_f32 v[58:59], v[58:59], v[186:187] op_sel_hi:[1,0]
	v_cvt_pk_bf16_f32 v198, v60, v61
	v_cvt_pk_bf16_f32 v199, v62, v63
	v_cvt_pk_bf16_f32 v200, v56, v57
	v_cvt_pk_bf16_f32 v201, v58, v59
	global_store_dwordx4 v207, v[198:201], s[10:11]
	v_pk_mul_f32 v[52:53], v[52:53], v[186:187] op_sel_hi:[1,0]
	v_pk_mul_f32 v[54:55], v[54:55], v[186:187] op_sel_hi:[1,0]
	v_pk_mul_f32 v[48:49], v[48:49], v[186:187] op_sel_hi:[1,0]
	v_pk_mul_f32 v[50:51], v[50:51], v[186:187] op_sel_hi:[1,0]
	v_cvt_pk_bf16_f32 v202, v52, v53
	v_cvt_pk_bf16_f32 v203, v54, v55
	v_cvt_pk_bf16_f32 v204, v48, v49
	v_cvt_pk_bf16_f32 v205, v50, v51
	global_store_dwordx4 v207, v[202:205], s[10:11] offset:256
	v_add_u32_e32 v207, 0x8000, v207
	s_waitcnt vmcnt(12)
	v_pk_add_f32 v[166:167], v[166:167], v[168:169]
	s_nop 0
	v_add_f32_e32 v214, v166, v167
	v_mov_b32_e32 v215, v214
	s_nop 1
	v_permlane16_swap_b32_e32 v214, v215
	s_nop 0
	v_add_f32_e32 v214, v214, v215
	v_mov_b32_e32 v215, v214
	s_nop 1
	v_permlane32_swap_b32_e32 v214, v215
	s_nop 0
	v_add_f32_e32 v214, v214, v215
	v_fmamk_f32 v214, v214, 0x3a800000, v248
	v_rsq_f32_e32 v188, v214
	s_nop 0
	v_pk_mul_f32 v[44:45], v[44:45], v[188:189] op_sel_hi:[1,0]
	v_pk_mul_f32 v[46:47], v[46:47], v[188:189] op_sel_hi:[1,0]
	v_pk_mul_f32 v[40:41], v[40:41], v[188:189] op_sel_hi:[1,0]
	v_pk_mul_f32 v[42:43], v[42:43], v[188:189] op_sel_hi:[1,0]
	v_cvt_pk_bf16_f32 v198, v44, v45
	v_cvt_pk_bf16_f32 v199, v46, v47
	v_cvt_pk_bf16_f32 v200, v40, v41
	v_cvt_pk_bf16_f32 v201, v42, v43
	global_store_dwordx4 v207, v[198:201], s[10:11]
	v_pk_mul_f32 v[36:37], v[36:37], v[188:189] op_sel_hi:[1,0]
	v_pk_mul_f32 v[38:39], v[38:39], v[188:189] op_sel_hi:[1,0]
	v_pk_mul_f32 v[32:33], v[32:33], v[188:189] op_sel_hi:[1,0]
	v_pk_mul_f32 v[34:35], v[34:35], v[188:189] op_sel_hi:[1,0]
	v_cvt_pk_bf16_f32 v202, v36, v37
	v_cvt_pk_bf16_f32 v203, v38, v39
	v_cvt_pk_bf16_f32 v204, v32, v33
	v_cvt_pk_bf16_f32 v205, v34, v35
	global_store_dwordx4 v207, v[202:205], s[10:11] offset:256
	v_add_u32_e32 v207, 0x8000, v207
	s_waitcnt vmcnt(13)
	v_pk_add_f32 v[170:171], v[170:171], v[172:173]
	s_nop 0
	v_add_f32_e32 v214, v170, v171
	v_mov_b32_e32 v215, v214
	s_nop 1
	v_permlane16_swap_b32_e32 v214, v215
	s_nop 0
	v_add_f32_e32 v214, v214, v215
	v_mov_b32_e32 v215, v214
	s_nop 1
	v_permlane32_swap_b32_e32 v214, v215
	s_nop 0
	v_add_f32_e32 v214, v214, v215
	v_fmamk_f32 v214, v214, 0x3a800000, v248
	v_rsq_f32_e32 v190, v214
	s_nop 0
	v_pk_mul_f32 v[28:29], v[28:29], v[190:191] op_sel_hi:[1,0]
	v_pk_mul_f32 v[30:31], v[30:31], v[190:191] op_sel_hi:[1,0]
	v_pk_mul_f32 v[24:25], v[24:25], v[190:191] op_sel_hi:[1,0]
	v_pk_mul_f32 v[26:27], v[26:27], v[190:191] op_sel_hi:[1,0]
	v_cvt_pk_bf16_f32 v198, v28, v29
	v_cvt_pk_bf16_f32 v199, v30, v31
	v_cvt_pk_bf16_f32 v200, v24, v25
	v_cvt_pk_bf16_f32 v201, v26, v27
	global_store_dwordx4 v207, v[198:201], s[10:11]
	v_pk_mul_f32 v[20:21], v[20:21], v[190:191] op_sel_hi:[1,0]
	v_pk_mul_f32 v[22:23], v[22:23], v[190:191] op_sel_hi:[1,0]
	v_pk_mul_f32 v[16:17], v[16:17], v[190:191] op_sel_hi:[1,0]
	v_pk_mul_f32 v[18:19], v[18:19], v[190:191] op_sel_hi:[1,0]
	v_cvt_pk_bf16_f32 v202, v20, v21
	v_cvt_pk_bf16_f32 v203, v22, v23
	v_cvt_pk_bf16_f32 v204, v16, v17
	v_cvt_pk_bf16_f32 v205, v18, v19
	global_store_dwordx4 v207, v[202:205], s[10:11] offset:256
	v_add_u32_e32 v207, 0x8000, v207
	s_waitcnt vmcnt(14)
	v_pk_add_f32 v[174:175], v[174:175], v[176:177]
	s_nop 0
	v_add_f32_e32 v214, v174, v175
	v_mov_b32_e32 v215, v214
	s_nop 1
	v_permlane16_swap_b32_e32 v214, v215
	s_nop 0
	v_add_f32_e32 v214, v214, v215
	v_mov_b32_e32 v215, v214
	s_nop 1
	v_permlane32_swap_b32_e32 v214, v215
	s_nop 0
	v_add_f32_e32 v214, v214, v215
	v_fmamk_f32 v214, v214, 0x3a800000, v248
	v_rsq_f32_e32 v192, v214
	s_nop 0
	v_pk_mul_f32 v[12:13], v[12:13], v[192:193] op_sel_hi:[1,0]
	v_pk_mul_f32 v[14:15], v[14:15], v[192:193] op_sel_hi:[1,0]
	v_pk_mul_f32 v[8:9], v[8:9], v[192:193] op_sel_hi:[1,0]
	v_pk_mul_f32 v[10:11], v[10:11], v[192:193] op_sel_hi:[1,0]
	v_cvt_pk_bf16_f32 v198, v12, v13
	v_cvt_pk_bf16_f32 v199, v14, v15
	v_cvt_pk_bf16_f32 v200, v8, v9
	v_cvt_pk_bf16_f32 v201, v10, v11
	global_store_dwordx4 v207, v[198:201], s[10:11]
	v_pk_mul_f32 v[4:5], v[4:5], v[192:193] op_sel_hi:[1,0]
	v_pk_mul_f32 v[6:7], v[6:7], v[192:193] op_sel_hi:[1,0]
	v_pk_mul_f32 v[0:1], v[0:1], v[192:193] op_sel_hi:[1,0]
	v_pk_mul_f32 v[2:3], v[2:3], v[192:193] op_sel_hi:[1,0]
	v_cvt_pk_bf16_f32 v202, v4, v5
	v_cvt_pk_bf16_f32 v203, v6, v7
	v_cvt_pk_bf16_f32 v204, v0, v1
	v_cvt_pk_bf16_f32 v205, v2, v3
	global_store_dwordx4 v207, v[202:205], s[10:11] offset:256
	s_and_b64 vcc, exec, s[4:5]
	s_cbranch_vccz .LBB0_816
	s_waitcnt vmcnt(0)
	s_cmpk_gt_u32 s30, 0xff
	s_cbranch_scc1 .LBB0_827
	s_barrier

.LBB0_878:
	s_add_u32 s26, s24, 0xfffc0080
	s_addc_u32 s27, s25, -1
	s_add_i32 s65, 0, 0x10000
	v_add_u32_e32 v154, s65, v143
	ds_read_b128 v[138:141], v154
	ds_read_b128 v[146:149], v154 offset:1024
	ds_read_b128 v[150:153], v154 offset:2048
	ds_read_b128 v[154:157], v154 offset:3072
	s_cmp_eq_u32 s64, 12
	s_cselect_b32 s29, s19, s27
	s_cselect_b32 s28, s39, s26
	s_cselect_b32 s27, s17, s63
	s_cselect_b32 s26, s61, s62
	s_add_i32 m0, s50, 0xc000
	ds_read_b128 v[158:161], v145
	ds_read_b128 v[162:165], v145 offset:1024
	ds_read_b128 v[166:169], v145 offset:2048
	ds_read_b128 v[170:173], v145 offset:3072
	ds_read_b128 v[174:177], v145 offset:4096
	ds_read_b128 v[178:181], v145 offset:5120
	ds_read_b128 v[182:185], v145 offset:6144
	ds_read_b128 v[186:189], v145 offset:7168
	global_load_lds_dwordx4 v134, s[24:25]
	s_add_i32 m0, s50, 0xe000
	s_nop 0
	global_load_lds_dwordx4 v136, s[24:25]
	s_waitcnt lgkmcnt(8)
	s_barrier
	s_waitcnt lgkmcnt(0)
	v_mfma_f32_16x16x32_bf16 v[124:127], v[138:141], v[158:161], v[124:127]
	v_mfma_f32_16x16x32_bf16 v[120:123], v[150:153], v[158:161], v[120:123]
	v_mfma_f32_16x16x32_bf16 v[108:111], v[138:141], v[166:169], v[108:111]
	v_mfma_f32_16x16x32_bf16 v[104:107], v[150:153], v[166:169], v[104:107]
	v_mfma_f32_16x16x32_bf16 v[92:95], v[138:141], v[174:177], v[92:95]
	v_mfma_f32_16x16x32_bf16 v[88:91], v[150:153], v[174:177], v[88:91]
	v_mfma_f32_16x16x32_bf16 v[76:79], v[138:141], v[182:185], v[76:79]
	v_mfma_f32_16x16x32_bf16 v[72:75], v[150:153], v[182:185], v[72:75]
	v_mfma_f32_16x16x32_bf16 v[124:127], v[146:149], v[162:165], v[124:127]
	v_mfma_f32_16x16x32_bf16 v[120:123], v[154:157], v[162:165], v[120:123]
	v_mfma_f32_16x16x32_bf16 v[108:111], v[146:149], v[170:173], v[108:111]
	v_mfma_f32_16x16x32_bf16 v[104:107], v[154:157], v[170:173], v[104:107]
	v_mfma_f32_16x16x32_bf16 v[92:95], v[146:149], v[178:181], v[92:95]
	v_mfma_f32_16x16x32_bf16 v[88:91], v[154:157], v[178:181], v[88:91]
	v_mfma_f32_16x16x32_bf16 v[76:79], v[146:149], v[186:189], v[76:79]
	v_mfma_f32_16x16x32_bf16 v[72:75], v[154:157], v[186:189], v[72:75]
	s_barrier
	s_add_i32 s68, 0, 0x14000
	s_add_i32 s65, s65, s47
	v_add_u32_e32 v202, s68, v143
	s_add_u32 s98, s26, s40
	s_addc_u32 s99, s27, s41
	s_mov_b32 m0, s65
	ds_read_b128 v[190:193], v202
	ds_read_b128 v[194:197], v202 offset:1024
	ds_read_b128 v[198:201], v202 offset:2048
	ds_read_b128 v[202:205], v202 offset:3072
	global_load_lds_dwordx4 v208, s[26:27]
	s_add_i32 m0, s65, 0x2000
	s_nop 0
	global_load_lds_dwordx4 v128, s[26:27]
	s_barrier
	s_waitcnt lgkmcnt(0)
	v_mfma_f32_16x16x32_bf16 v[116:119], v[190:193], v[158:161], v[116:119]
	v_mfma_f32_16x16x32_bf16 v[112:115], v[198:201], v[158:161], v[112:115]
	v_mfma_f32_16x16x32_bf16 v[100:103], v[190:193], v[166:169], v[100:103]
	v_mfma_f32_16x16x32_bf16 v[96:99], v[198:201], v[166:169], v[96:99]
	v_mfma_f32_16x16x32_bf16 v[84:87], v[190:193], v[174:177], v[84:87]
	v_mfma_f32_16x16x32_bf16 v[80:83], v[198:201], v[174:177], v[80:83]
	v_mfma_f32_16x16x32_bf16 v[68:71], v[190:193], v[182:185], v[68:71]
	v_mfma_f32_16x16x32_bf16 v[64:67], v[198:201], v[182:185], v[64:67]
	v_mfma_f32_16x16x32_bf16 v[116:119], v[194:197], v[162:165], v[116:119]
	v_mfma_f32_16x16x32_bf16 v[112:115], v[202:205], v[162:165], v[112:115]
	v_mfma_f32_16x16x32_bf16 v[100:103], v[194:197], v[170:173], v[100:103]
	v_mfma_f32_16x16x32_bf16 v[96:99], v[202:205], v[170:173], v[96:99]
	v_mfma_f32_16x16x32_bf16 v[84:87], v[194:197], v[178:181], v[84:87]
	v_mfma_f32_16x16x32_bf16 v[80:83], v[202:205], v[178:181], v[80:83]
	v_mfma_f32_16x16x32_bf16 v[68:71], v[194:197], v[186:189], v[68:71]
	v_mfma_f32_16x16x32_bf16 v[64:67], v[202:205], v[186:189], v[64:67]
	s_mov_b32 m0, s50
	s_add_u32 s100, s28, s40
	s_addc_u32 s101, s29, s41
	s_barrier
	ds_read_b128 v[158:161], v145 offset:16384
	ds_read_b128 v[162:165], v145 offset:17408
	ds_read_b128 v[166:169], v145 offset:18432
	ds_read_b128 v[170:173], v145 offset:19456
	ds_read_b128 v[174:177], v145 offset:20480
	ds_read_b128 v[178:181], v145 offset:21504
	ds_read_b128 v[182:185], v145 offset:22528
	ds_read_b128 v[186:189], v145 offset:23552
	global_load_lds_dwordx4 v132, s[28:29]
	s_mov_b32 m0, s51
	s_nop 0
	global_load_lds_dwordx4 v130, s[28:29]
	s_barrier
	s_waitcnt lgkmcnt(0)
	v_mfma_f32_16x16x32_bf16 v[60:63], v[138:141], v[158:161], v[60:63]
	v_mfma_f32_16x16x32_bf16 v[56:59], v[150:153], v[158:161], v[56:59]
	v_mfma_f32_16x16x32_bf16 v[44:47], v[138:141], v[166:169], v[44:47]
	v_mfma_f32_16x16x32_bf16 v[40:43], v[150:153], v[166:169], v[40:43]
	v_mfma_f32_16x16x32_bf16 v[28:31], v[138:141], v[174:177], v[28:31]
	v_mfma_f32_16x16x32_bf16 v[24:27], v[150:153], v[174:177], v[24:27]
	v_mfma_f32_16x16x32_bf16 v[12:15], v[138:141], v[182:185], v[12:15]
	v_mfma_f32_16x16x32_bf16 v[8:11], v[150:153], v[182:185], v[8:11]
	v_mfma_f32_16x16x32_bf16 v[60:63], v[146:149], v[162:165], v[60:63]
	v_mfma_f32_16x16x32_bf16 v[56:59], v[154:157], v[162:165], v[56:59]
	v_mfma_f32_16x16x32_bf16 v[44:47], v[146:149], v[170:173], v[44:47]
	v_mfma_f32_16x16x32_bf16 v[40:43], v[154:157], v[170:173], v[40:43]
	v_mfma_f32_16x16x32_bf16 v[28:31], v[146:149], v[178:181], v[28:31]
	v_mfma_f32_16x16x32_bf16 v[24:27], v[154:157], v[178:181], v[24:27]
	v_mfma_f32_16x16x32_bf16 v[12:15], v[146:149], v[186:189], v[12:15]
	v_mfma_f32_16x16x32_bf16 v[8:11], v[154:157], v[186:189], v[8:11]
	s_barrier
	s_add_u32 s66, s26, 0x40000
	s_addc_u32 s67, s27, 0
	s_add_i32 s65, s68, s47
	s_mov_b32 m0, s65
	s_nop 0
	global_load_lds_dwordx4 v208, s[66:67]
	s_add_i32 m0, s65, 0x2000
	s_nop 0
	global_load_lds_dwordx4 v128, s[66:67]
	s_waitcnt vmcnt(6)
	s_barrier
	v_mfma_f32_16x16x32_bf16 v[52:55], v[190:193], v[158:161], v[52:55]
	v_mfma_f32_16x16x32_bf16 v[48:51], v[198:201], v[158:161], v[48:51]
	v_mfma_f32_16x16x32_bf16 v[36:39], v[190:193], v[166:169], v[36:39]
	v_mfma_f32_16x16x32_bf16 v[32:35], v[198:201], v[166:169], v[32:35]
	v_mfma_f32_16x16x32_bf16 v[20:23], v[190:193], v[174:177], v[20:23]
	v_mfma_f32_16x16x32_bf16 v[16:19], v[198:201], v[174:177], v[16:19]
	v_mfma_f32_16x16x32_bf16 v[4:7], v[190:193], v[182:185], v[4:7]
	v_mfma_f32_16x16x32_bf16 v[0:3], v[198:201], v[182:185], v[0:3]
	v_mfma_f32_16x16x32_bf16 v[52:55], v[194:197], v[162:165], v[52:55]
	v_mfma_f32_16x16x32_bf16 v[48:51], v[202:205], v[162:165], v[48:51]
	v_mfma_f32_16x16x32_bf16 v[36:39], v[194:197], v[170:173], v[36:39]
	v_mfma_f32_16x16x32_bf16 v[32:35], v[202:205], v[170:173], v[32:35]
	v_mfma_f32_16x16x32_bf16 v[20:23], v[194:197], v[178:181], v[20:23]
	v_mfma_f32_16x16x32_bf16 v[16:19], v[202:205], v[178:181], v[16:19]
	v_mfma_f32_16x16x32_bf16 v[4:7], v[194:197], v[186:189], v[4:7]
	v_mfma_f32_16x16x32_bf16 v[0:3], v[202:205], v[186:189], v[0:3]
	s_add_i32 s65, 0, 0x18000
	v_add_u32_e32 v154, s65, v143
	s_barrier
	ds_read_b128 v[138:141], v154
	ds_read_b128 v[146:149], v154 offset:1024
	ds_read_b128 v[150:153], v154 offset:2048
	ds_read_b128 v[154:157], v154 offset:3072
	s_add_u32 s28, s28, 0x40000
	s_addc_u32 s29, s29, 0
	s_mov_b32 m0, s53
	ds_read_b128 v[158:161], v145 offset:32768
	ds_read_b128 v[162:165], v145 offset:33792
	ds_read_b128 v[166:169], v145 offset:34816
	ds_read_b128 v[170:173], v145 offset:35840
	ds_read_b128 v[174:177], v145 offset:36864
	ds_read_b128 v[178:181], v145 offset:37888
	ds_read_b128 v[182:185], v145 offset:38912
	ds_read_b128 v[186:189], v145 offset:39936
	global_load_lds_dwordx4 v132, s[28:29]
	s_mov_b32 m0, s56
	s_nop 0
	global_load_lds_dwordx4 v130, s[28:29]
	s_waitcnt lgkmcnt(8)
	s_barrier
	s_waitcnt lgkmcnt(0)
	v_mfma_f32_16x16x32_bf16 v[124:127], v[138:141], v[158:161], v[124:127]
	v_mfma_f32_16x16x32_bf16 v[120:123], v[150:153], v[158:161], v[120:123]
	v_mfma_f32_16x16x32_bf16 v[108:111], v[138:141], v[166:169], v[108:111]
	v_mfma_f32_16x16x32_bf16 v[104:107], v[150:153], v[166:169], v[104:107]
	v_mfma_f32_16x16x32_bf16 v[92:95], v[138:141], v[174:177], v[92:95]
	v_mfma_f32_16x16x32_bf16 v[88:91], v[150:153], v[174:177], v[88:91]
	v_mfma_f32_16x16x32_bf16 v[76:79], v[138:141], v[182:185], v[76:79]
	v_mfma_f32_16x16x32_bf16 v[72:75], v[150:153], v[182:185], v[72:75]
	v_mfma_f32_16x16x32_bf16 v[124:127], v[146:149], v[162:165], v[124:127]
	v_mfma_f32_16x16x32_bf16 v[120:123], v[154:157], v[162:165], v[120:123]
	v_mfma_f32_16x16x32_bf16 v[108:111], v[146:149], v[170:173], v[108:111]
	v_mfma_f32_16x16x32_bf16 v[104:107], v[154:157], v[170:173], v[104:107]
	v_mfma_f32_16x16x32_bf16 v[92:95], v[146:149], v[178:181], v[92:95]
	v_mfma_f32_16x16x32_bf16 v[88:91], v[154:157], v[178:181], v[88:91]
	v_mfma_f32_16x16x32_bf16 v[76:79], v[146:149], v[186:189], v[76:79]
	v_mfma_f32_16x16x32_bf16 v[72:75], v[154:157], v[186:189], v[72:75]
	s_barrier
	s_add_i32 s28, 0, 0x1c000
	s_add_i32 s29, s65, s47
	v_add_u32_e32 v202, s28, v143
	s_mov_b32 m0, s29
	ds_read_b128 v[190:193], v202
	ds_read_b128 v[194:197], v202 offset:1024
	ds_read_b128 v[198:201], v202 offset:2048
	ds_read_b128 v[202:205], v202 offset:3072
	global_load_lds_dwordx4 v208, s[98:99]
	s_add_i32 m0, s29, 0x2000
	s_nop 0
	global_load_lds_dwordx4 v128, s[98:99]
	s_barrier
	s_waitcnt lgkmcnt(0)
	v_mfma_f32_16x16x32_bf16 v[116:119], v[190:193], v[158:161], v[116:119]
	v_mfma_f32_16x16x32_bf16 v[112:115], v[198:201], v[158:161], v[112:115]
	v_mfma_f32_16x16x32_bf16 v[100:103], v[190:193], v[166:169], v[100:103]
	v_mfma_f32_16x16x32_bf16 v[96:99], v[198:201], v[166:169], v[96:99]
	v_mfma_f32_16x16x32_bf16 v[84:87], v[190:193], v[174:177], v[84:87]
	v_mfma_f32_16x16x32_bf16 v[80:83], v[198:201], v[174:177], v[80:83]
	v_mfma_f32_16x16x32_bf16 v[68:71], v[190:193], v[182:185], v[68:71]
	v_mfma_f32_16x16x32_bf16 v[64:67], v[198:201], v[182:185], v[64:67]
	v_mfma_f32_16x16x32_bf16 v[116:119], v[194:197], v[162:165], v[116:119]
	v_mfma_f32_16x16x32_bf16 v[112:115], v[202:205], v[162:165], v[112:115]
	v_mfma_f32_16x16x32_bf16 v[100:103], v[194:197], v[170:173], v[100:103]
	v_mfma_f32_16x16x32_bf16 v[96:99], v[202:205], v[170:173], v[96:99]
	v_mfma_f32_16x16x32_bf16 v[84:87], v[194:197], v[178:181], v[84:87]
	v_mfma_f32_16x16x32_bf16 v[80:83], v[202:205], v[178:181], v[80:83]
	v_mfma_f32_16x16x32_bf16 v[68:71], v[194:197], v[186:189], v[68:71]
	v_mfma_f32_16x16x32_bf16 v[64:67], v[202:205], v[186:189], v[64:67]
	s_mov_b32 m0, s58
	s_barrier
	ds_read_b128 v[158:161], v145 offset:49152
	ds_read_b128 v[162:165], v145 offset:50176
	ds_read_b128 v[166:169], v145 offset:51200
	ds_read_b128 v[170:173], v145 offset:52224
	ds_read_b128 v[174:177], v145 offset:53248
	ds_read_b128 v[178:181], v145 offset:54272
	ds_read_b128 v[182:185], v145 offset:55296
	ds_read_b128 v[186:189], v145 offset:56320
	global_load_lds_dwordx4 v132, s[100:101]
	s_mov_b32 m0, s59
	s_nop 0
	global_load_lds_dwordx4 v130, s[100:101]
	s_barrier
	s_waitcnt lgkmcnt(0)
	v_mfma_f32_16x16x32_bf16 v[60:63], v[138:141], v[158:161], v[60:63]
	v_mfma_f32_16x16x32_bf16 v[56:59], v[150:153], v[158:161], v[56:59]
	v_mfma_f32_16x16x32_bf16 v[44:47], v[138:141], v[166:169], v[44:47]
	v_mfma_f32_16x16x32_bf16 v[40:43], v[150:153], v[166:169], v[40:43]
	v_mfma_f32_16x16x32_bf16 v[28:31], v[138:141], v[174:177], v[28:31]
	v_mfma_f32_16x16x32_bf16 v[24:27], v[150:153], v[174:177], v[24:27]
	v_mfma_f32_16x16x32_bf16 v[12:15], v[138:141], v[182:185], v[12:15]
	v_mfma_f32_16x16x32_bf16 v[8:11], v[150:153], v[182:185], v[8:11]
	v_mfma_f32_16x16x32_bf16 v[60:63], v[146:149], v[162:165], v[60:63]
	v_mfma_f32_16x16x32_bf16 v[56:59], v[154:157], v[162:165], v[56:59]
	v_mfma_f32_16x16x32_bf16 v[44:47], v[146:149], v[170:173], v[44:47]
	v_mfma_f32_16x16x32_bf16 v[40:43], v[154:157], v[170:173], v[40:43]
	v_mfma_f32_16x16x32_bf16 v[28:31], v[146:149], v[178:181], v[28:31]
	v_mfma_f32_16x16x32_bf16 v[24:27], v[154:157], v[178:181], v[24:27]
	v_mfma_f32_16x16x32_bf16 v[12:15], v[146:149], v[186:189], v[12:15]
	v_mfma_f32_16x16x32_bf16 v[8:11], v[154:157], v[186:189], v[8:11]
	s_barrier
	s_add_u32 s26, s26, 0x40080
	s_addc_u32 s27, s27, 0
	s_add_i32 s28, s28, s47
	s_mov_b32 m0, s28
	s_nop 0
	global_load_lds_dwordx4 v208, s[26:27]
	s_add_i32 m0, s28, 0x2000
	s_nop 0
	global_load_lds_dwordx4 v128, s[26:27]
	s_add_i32 s64, s64, 2
	s_add_u32 s24, s24, 0x100
	s_addc_u32 s25, s25, 0
	s_add_u32 s62, s62, 0x100
	s_addc_u32 s63, s63, 0
	s_waitcnt vmcnt(6)
	s_barrier
	v_mfma_f32_16x16x32_bf16 v[52:55], v[190:193], v[158:161], v[52:55]
	v_mfma_f32_16x16x32_bf16 v[48:51], v[198:201], v[158:161], v[48:51]
	v_mfma_f32_16x16x32_bf16 v[36:39], v[190:193], v[166:169], v[36:39]
	v_mfma_f32_16x16x32_bf16 v[32:35], v[198:201], v[166:169], v[32:35]
	v_mfma_f32_16x16x32_bf16 v[20:23], v[190:193], v[174:177], v[20:23]
	v_mfma_f32_16x16x32_bf16 v[16:19], v[198:201], v[174:177], v[16:19]
	v_mfma_f32_16x16x32_bf16 v[4:7], v[190:193], v[182:185], v[4:7]
	v_mfma_f32_16x16x32_bf16 v[0:3], v[198:201], v[182:185], v[0:3]
	v_mfma_f32_16x16x32_bf16 v[52:55], v[194:197], v[162:165], v[52:55]
	v_mfma_f32_16x16x32_bf16 v[48:51], v[202:205], v[162:165], v[48:51]
	v_mfma_f32_16x16x32_bf16 v[36:39], v[194:197], v[170:173], v[36:39]
	v_mfma_f32_16x16x32_bf16 v[32:35], v[202:205], v[170:173], v[32:35]
	v_mfma_f32_16x16x32_bf16 v[20:23], v[194:197], v[178:181], v[20:23]
	v_mfma_f32_16x16x32_bf16 v[16:19], v[202:205], v[178:181], v[16:19]
	v_mfma_f32_16x16x32_bf16 v[4:7], v[194:197], v[186:189], v[4:7]
	v_mfma_f32_16x16x32_bf16 v[0:3], v[202:205], v[186:189], v[0:3]
	s_cmp_gt_u32 s64, 13
	s_barrier
	s_cbranch_scc0 .LBB0_878
	v_lshl_add_u32 v140, s38, 8, v142
	v_lshl_or_b32 v141, s36, 8, v144
	s_lshl_b32 s24, s36, 2
	s_ashr_i32 s25, s24, 31
	s_lshl_b32 s36, s57, 2
	v_lshlrev_b32_e32 v206, 11, v140
	v_lshl_add_u32 v206, v141, 1, v206
	v_lshl_add_u32 v210, v140, 6, s36
	v_lshl_add_u32 v210, s24, 2, v210
	v_mov_b32_e32 v207, v206
	global_load_dwordx4 v[146:149], v206, s[8:9]
	global_load_dwordx4 v[150:153], v206, s[8:9] offset:256
	v_add_u32_e32 v206, 0x8000, v206
	global_load_dwordx4 v[154:157], v206, s[8:9]
	global_load_dwordx4 v[158:161], v206, s[8:9] offset:256
	v_add_u32_e32 v206, 0x8000, v206
	global_load_dwordx4 v[162:165], v206, s[8:9]
	global_load_dwordx4 v[166:169], v206, s[8:9] offset:256
	v_add_u32_e32 v206, 0x8000, v206
	global_load_dwordx4 v[170:173], v206, s[8:9]
	global_load_dwordx4 v[174:177], v206, s[8:9] offset:256
	v_add_u32_e32 v206, 0x28000, v206
	global_load_dwordx4 v[178:181], v206, s[8:9]
	global_load_dwordx4 v[182:185], v206, s[8:9] offset:256
	v_add_u32_e32 v206, 0x8000, v206
	global_load_dwordx4 v[186:189], v206, s[8:9]
	global_load_dwordx4 v[190:193], v206, s[8:9] offset:256
	v_add_u32_e32 v206, 0x8000, v206
	global_load_dwordx4 v[194:197], v206, s[8:9]
	global_load_dwordx4 v[198:201], v206, s[8:9] offset:256
	v_add_u32_e32 v206, 0x8000, v206
	s_waitcnt vmcnt(12)
	v_lshlrev_b32_e32 v202, 16, v146
	v_and_b32_e32 v203, 0xffff0000, v146
	v_lshlrev_b32_e32 v204, 16, v147
	v_and_b32_e32 v205, 0xffff0000, v147
	v_pk_add_f32 v[124:125], v[124:125], v[202:203]
	v_pk_add_f32 v[126:127], v[126:127], v[204:205]
	v_lshlrev_b32_e32 v202, 16, v148
	v_and_b32_e32 v203, 0xffff0000, v148
	v_lshlrev_b32_e32 v204, 16, v149
	v_and_b32_e32 v205, 0xffff0000, v149
	v_pk_add_f32 v[120:121], v[120:121], v[202:203]
	v_pk_add_f32 v[122:123], v[122:123], v[204:205]
	v_cvt_pk_bf16_f32 v146, v124, v125
	v_cvt_pk_bf16_f32 v147, v126, v127
	v_cvt_pk_bf16_f32 v148, v120, v121
	v_cvt_pk_bf16_f32 v149, v122, v123
	v_pk_mul_f32 v[138:139], v[124:125], v[124:125]
	global_store_dwordx4 v207, v[146:149], s[8:9]
	v_pk_fma_f32 v[138:139], v[126:127], v[126:127], v[138:139]
	v_pk_fma_f32 v[138:139], v[120:121], v[120:121], v[138:139]
	v_pk_fma_f32 v[138:139], v[122:123], v[122:123], v[138:139]
	v_lshlrev_b32_e32 v202, 16, v150
	v_and_b32_e32 v203, 0xffff0000, v150
	v_lshlrev_b32_e32 v204, 16, v151
	v_and_b32_e32 v205, 0xffff0000, v151
	v_pk_add_f32 v[116:117], v[116:117], v[202:203]
	v_pk_add_f32 v[118:119], v[118:119], v[204:205]
	v_lshlrev_b32_e32 v202, 16, v152
	v_and_b32_e32 v203, 0xffff0000, v152
	v_lshlrev_b32_e32 v204, 16, v153
	v_and_b32_e32 v205, 0xffff0000, v153
	v_pk_add_f32 v[112:113], v[112:113], v[202:203]
	v_pk_add_f32 v[114:115], v[114:115], v[204:205]
	v_cvt_pk_bf16_f32 v150, v116, v117
	v_cvt_pk_bf16_f32 v151, v118, v119
	v_cvt_pk_bf16_f32 v152, v112, v113
	v_cvt_pk_bf16_f32 v153, v114, v115
	v_pk_fma_f32 v[138:139], v[116:117], v[116:117], v[138:139]
	global_store_dwordx4 v207, v[150:153], s[8:9] offset:256
	v_pk_fma_f32 v[138:139], v[118:119], v[118:119], v[138:139]
	v_pk_fma_f32 v[138:139], v[112:113], v[112:113], v[138:139]
	v_pk_fma_f32 v[138:139], v[114:115], v[114:115], v[138:139]
	v_add_f32_e32 v214, v138, v139
	v_add_u32_e32 v207, 0x8000, v207
	v_mov_b32_e32 v215, v214
	s_nop 1
	v_permlane16_swap_b32_e32 v214, v215
	s_nop 0
	v_add_f32_e32 v214, v214, v215
	v_mov_b32_e32 v215, v214
	s_nop 1
	v_permlane32_swap_b32_e32 v214, v215
	s_nop 0
	v_add_f32_e32 v214, v214, v215
	s_and_saveexec_b64 s[26:27], s[4:5]
	global_store_dword v210, v214, s[14:15]
	s_mov_b64 exec, s[26:27]
	global_load_dwordx4 v[146:149], v206, s[8:9]
	global_load_dwordx4 v[150:153], v206, s[8:9] offset:256
	s_waitcnt vmcnt(15)
	v_lshlrev_b32_e32 v202, 16, v154
	v_and_b32_e32 v203, 0xffff0000, v154
	v_lshlrev_b32_e32 v204, 16, v155
	v_and_b32_e32 v205, 0xffff0000, v155
	v_pk_add_f32 v[108:109], v[108:109], v[202:203]
	v_pk_add_f32 v[110:111], v[110:111], v[204:205]
	v_lshlrev_b32_e32 v202, 16, v156
	v_and_b32_e32 v203, 0xffff0000, v156
	v_lshlrev_b32_e32 v204, 16, v157
	v_and_b32_e32 v205, 0xffff0000, v157
	v_pk_add_f32 v[104:105], v[104:105], v[202:203]
	v_pk_add_f32 v[106:107], v[106:107], v[204:205]
	v_cvt_pk_bf16_f32 v154, v108, v109
	v_cvt_pk_bf16_f32 v155, v110, v111
	v_cvt_pk_bf16_f32 v156, v104, v105
	v_cvt_pk_bf16_f32 v157, v106, v107
	v_pk_mul_f32 v[138:139], v[108:109], v[108:109]
	global_store_dwordx4 v207, v[154:157], s[8:9]
	v_pk_fma_f32 v[138:139], v[110:111], v[110:111], v[138:139]
	v_pk_fma_f32 v[138:139], v[104:105], v[104:105], v[138:139]
	v_pk_fma_f32 v[138:139], v[106:107], v[106:107], v[138:139]
	v_lshlrev_b32_e32 v202, 16, v158
	v_and_b32_e32 v203, 0xffff0000, v158
	v_lshlrev_b32_e32 v204, 16, v159
	v_and_b32_e32 v205, 0xffff0000, v159
	v_pk_add_f32 v[100:101], v[100:101], v[202:203]
	v_pk_add_f32 v[102:103], v[102:103], v[204:205]
	v_lshlrev_b32_e32 v202, 16, v160
	v_and_b32_e32 v203, 0xffff0000, v160
	v_lshlrev_b32_e32 v204, 16, v161
	v_and_b32_e32 v205, 0xffff0000, v161
	v_pk_add_f32 v[96:97], v[96:97], v[202:203]
	v_pk_add_f32 v[98:99], v[98:99], v[204:205]
	v_cvt_pk_bf16_f32 v158, v100, v101
	v_cvt_pk_bf16_f32 v159, v102, v103
	v_cvt_pk_bf16_f32 v160, v96, v97
	v_cvt_pk_bf16_f32 v161, v98, v99
	v_pk_fma_f32 v[138:139], v[100:101], v[100:101], v[138:139]
	global_store_dwordx4 v207, v[158:161], s[8:9] offset:256
	v_pk_fma_f32 v[138:139], v[102:103], v[102:103], v[138:139]
	v_pk_fma_f32 v[138:139], v[96:97], v[96:97], v[138:139]
	v_pk_fma_f32 v[138:139], v[98:99], v[98:99], v[138:139]
	v_add_f32_e32 v214, v138, v139
	v_add_u32_e32 v207, 0x8000, v207
	v_mov_b32_e32 v215, v214
	s_nop 1
	v_permlane16_swap_b32_e32 v214, v215
	s_nop 0
	v_add_f32_e32 v214, v214, v215
	v_mov_b32_e32 v215, v214
	s_nop 1
	v_permlane32_swap_b32_e32 v214, v215
	s_nop 0
	v_add_f32_e32 v214, v214, v215
	s_and_saveexec_b64 s[26:27], s[4:5]
	global_store_dword v210, v214, s[14:15] offset:1024
	s_mov_b64 exec, s[26:27]
	s_waitcnt vmcnt(16)
	v_lshlrev_b32_e32 v202, 16, v162
	v_and_b32_e32 v203, 0xffff0000, v162
	v_lshlrev_b32_e32 v204, 16, v163
	v_and_b32_e32 v205, 0xffff0000, v163
	v_pk_add_f32 v[92:93], v[92:93], v[202:203]
	v_pk_add_f32 v[94:95], v[94:95], v[204:205]
	v_lshlrev_b32_e32 v202, 16, v164
	v_and_b32_e32 v203, 0xffff0000, v164
	v_lshlrev_b32_e32 v204, 16, v165
	v_and_b32_e32 v205, 0xffff0000, v165
	v_pk_add_f32 v[88:89], v[88:89], v[202:203]
	v_pk_add_f32 v[90:91], v[90:91], v[204:205]
	v_cvt_pk_bf16_f32 v162, v92, v93
	v_cvt_pk_bf16_f32 v163, v94, v95
	v_cvt_pk_bf16_f32 v164, v88, v89
	v_cvt_pk_bf16_f32 v165, v90, v91
	v_pk_mul_f32 v[138:139], v[92:93], v[92:93]
	global_store_dwordx4 v207, v[162:165], s[8:9]
	v_pk_fma_f32 v[138:139], v[94:95], v[94:95], v[138:139]
	v_pk_fma_f32 v[138:139], v[88:89], v[88:89], v[138:139]
	v_pk_fma_f32 v[138:139], v[90:91], v[90:91], v[138:139]
	v_lshlrev_b32_e32 v202, 16, v166
	v_and_b32_e32 v203, 0xffff0000, v166
	v_lshlrev_b32_e32 v204, 16, v167
	v_and_b32_e32 v205, 0xffff0000, v167
	v_pk_add_f32 v[84:85], v[84:85], v[202:203]
	v_pk_add_f32 v[86:87], v[86:87], v[204:205]
	v_lshlrev_b32_e32 v202, 16, v168
	v_and_b32_e32 v203, 0xffff0000, v168
	v_lshlrev_b32_e32 v204, 16, v169
	v_and_b32_e32 v205, 0xffff0000, v169
	v_pk_add_f32 v[80:81], v[80:81], v[202:203]
	v_pk_add_f32 v[82:83], v[82:83], v[204:205]
	v_cvt_pk_bf16_f32 v166, v84, v85
	v_cvt_pk_bf16_f32 v167, v86, v87
	v_cvt_pk_bf16_f32 v168, v80, v81
	v_cvt_pk_bf16_f32 v169, v82, v83
	v_pk_fma_f32 v[138:139], v[84:85], v[84:85], v[138:139]
	global_store_dwordx4 v207, v[166:169], s[8:9] offset:256
	v_pk_fma_f32 v[138:139], v[86:87], v[86:87], v[138:139]
	v_pk_fma_f32 v[138:139], v[80:81], v[80:81], v[138:139]
	v_pk_fma_f32 v[138:139], v[82:83], v[82:83], v[138:139]
	v_add_f32_e32 v214, v138, v139
	v_add_u32_e32 v207, 0x8000, v207
	v_mov_b32_e32 v215, v214
	s_nop 1
	v_permlane16_swap_b32_e32 v214, v215
	s_nop 0
	v_add_f32_e32 v214, v214, v215
	v_mov_b32_e32 v215, v214
	s_nop 1
	v_permlane32_swap_b32_e32 v214, v215
	s_nop 0
	v_add_f32_e32 v214, v214, v215
	s_and_saveexec_b64 s[26:27], s[4:5]
	global_store_dword v210, v214, s[14:15] offset:2048
	s_mov_b64 exec, s[26:27]
	s_waitcnt vmcnt(17)
	v_lshlrev_b32_e32 v202, 16, v170
	v_and_b32_e32 v203, 0xffff0000, v170
	v_lshlrev_b32_e32 v204, 16, v171
	v_and_b32_e32 v205, 0xffff0000, v171
	v_pk_add_f32 v[76:77], v[76:77], v[202:203]
	v_pk_add_f32 v[78:79], v[78:79], v[204:205]
	v_lshlrev_b32_e32 v202, 16, v172
	v_and_b32_e32 v203, 0xffff0000, v172
	v_lshlrev_b32_e32 v204, 16, v173
	v_and_b32_e32 v205, 0xffff0000, v173
	v_pk_add_f32 v[72:73], v[72:73], v[202:203]
	v_pk_add_f32 v[74:75], v[74:75], v[204:205]
	v_cvt_pk_bf16_f32 v170, v76, v77
	v_cvt_pk_bf16_f32 v171, v78, v79
	v_cvt_pk_bf16_f32 v172, v72, v73
	v_cvt_pk_bf16_f32 v173, v74, v75
	v_pk_mul_f32 v[138:139], v[76:77], v[76:77]
	global_store_dwordx4 v207, v[170:173], s[8:9]
	v_pk_fma_f32 v[138:139], v[78:79], v[78:79], v[138:139]
	v_pk_fma_f32 v[138:139], v[72:73], v[72:73], v[138:139]
	v_pk_fma_f32 v[138:139], v[74:75], v[74:75], v[138:139]
	v_lshlrev_b32_e32 v202, 16, v174
	v_and_b32_e32 v203, 0xffff0000, v174
	v_lshlrev_b32_e32 v204, 16, v175
	v_and_b32_e32 v205, 0xffff0000, v175
	v_pk_add_f32 v[68:69], v[68:69], v[202:203]
	v_pk_add_f32 v[70:71], v[70:71], v[204:205]
	v_lshlrev_b32_e32 v202, 16, v176
	v_and_b32_e32 v203, 0xffff0000, v176
	v_lshlrev_b32_e32 v204, 16, v177
	v_and_b32_e32 v205, 0xffff0000, v177
	v_pk_add_f32 v[64:65], v[64:65], v[202:203]
	v_pk_add_f32 v[66:67], v[66:67], v[204:205]
	v_cvt_pk_bf16_f32 v174, v68, v69
	v_cvt_pk_bf16_f32 v175, v70, v71
	v_cvt_pk_bf16_f32 v176, v64, v65
	v_cvt_pk_bf16_f32 v177, v66, v67
	v_pk_fma_f32 v[138:139], v[68:69], v[68:69], v[138:139]
	global_store_dwordx4 v207, v[174:177], s[8:9] offset:256
	v_pk_fma_f32 v[138:139], v[70:71], v[70:71], v[138:139]
	v_pk_fma_f32 v[138:139], v[64:65], v[64:65], v[138:139]
	v_pk_fma_f32 v[138:139], v[66:67], v[66:67], v[138:139]
	v_add_f32_e32 v214, v138, v139
	v_add_u32_e32 v207, 0x28000, v207
	v_mov_b32_e32 v215, v214
	s_nop 1
	v_permlane16_swap_b32_e32 v214, v215
	s_nop 0
	v_add_f32_e32 v214, v214, v215
	v_mov_b32_e32 v215, v214
	s_nop 1
	v_permlane32_swap_b32_e32 v214, v215
	s_nop 0
	v_add_f32_e32 v214, v214, v215
	s_and_saveexec_b64 s[26:27], s[4:5]
	global_store_dword v210, v214, s[14:15] offset:3072
	s_mov_b64 exec, s[26:27]
	v_add_u32_e32 v210, 0x2000, v210
	s_waitcnt vmcnt(18)
	v_lshlrev_b32_e32 v202, 16, v178
	v_and_b32_e32 v203, 0xffff0000, v178
	v_lshlrev_b32_e32 v204, 16, v179
	v_and_b32_e32 v205, 0xffff0000, v179
	v_pk_add_f32 v[60:61], v[60:61], v[202:203]
	v_pk_add_f32 v[62:63], v[62:63], v[204:205]
	v_lshlrev_b32_e32 v202, 16, v180
	v_and_b32_e32 v203, 0xffff0000, v180
	v_lshlrev_b32_e32 v204, 16, v181
	v_and_b32_e32 v205, 0xffff0000, v181
	v_pk_add_f32 v[56:57], v[56:57], v[202:203]
	v_pk_add_f32 v[58:59], v[58:59], v[204:205]
	v_cvt_pk_bf16_f32 v178, v60, v61
	v_cvt_pk_bf16_f32 v179, v62, v63
	v_cvt_pk_bf16_f32 v180, v56, v57
	v_cvt_pk_bf16_f32 v181, v58, v59
	v_pk_mul_f32 v[138:139], v[60:61], v[60:61]
	global_store_dwordx4 v207, v[178:181], s[8:9]
	v_pk_fma_f32 v[138:139], v[62:63], v[62:63], v[138:139]
	v_pk_fma_f32 v[138:139], v[56:57], v[56:57], v[138:139]
	v_pk_fma_f32 v[138:139], v[58:59], v[58:59], v[138:139]
	v_lshlrev_b32_e32 v202, 16, v182
	v_and_b32_e32 v203, 0xffff0000, v182
	v_lshlrev_b32_e32 v204, 16, v183
	v_and_b32_e32 v205, 0xffff0000, v183
	v_pk_add_f32 v[52:53], v[52:53], v[202:203]
	v_pk_add_f32 v[54:55], v[54:55], v[204:205]
	v_lshlrev_b32_e32 v202, 16, v184
	v_and_b32_e32 v203, 0xffff0000, v184
	v_lshlrev_b32_e32 v204, 16, v185
	v_and_b32_e32 v205, 0xffff0000, v185
	v_pk_add_f32 v[48:49], v[48:49], v[202:203]
	v_pk_add_f32 v[50:51], v[50:51], v[204:205]
	v_cvt_pk_bf16_f32 v182, v52, v53
	v_cvt_pk_bf16_f32 v183, v54, v55
	v_cvt_pk_bf16_f32 v184, v48, v49
	v_cvt_pk_bf16_f32 v185, v50, v51
	v_pk_fma_f32 v[138:139], v[52:53], v[52:53], v[138:139]
	global_store_dwordx4 v207, v[182:185], s[8:9] offset:256
	v_pk_fma_f32 v[138:139], v[54:55], v[54:55], v[138:139]
	v_pk_fma_f32 v[138:139], v[48:49], v[48:49], v[138:139]
	v_pk_fma_f32 v[138:139], v[50:51], v[50:51], v[138:139]
	v_add_f32_e32 v214, v138, v139
	v_add_u32_e32 v207, 0x8000, v207
	v_mov_b32_e32 v215, v214
	s_nop 1
	v_permlane16_swap_b32_e32 v214, v215
	s_nop 0
	v_add_f32_e32 v214, v214, v215
	v_mov_b32_e32 v215, v214
	s_nop 1
	v_permlane32_swap_b32_e32 v214, v215
	s_nop 0
	v_add_f32_e32 v214, v214, v215
	s_and_saveexec_b64 s[26:27], s[4:5]
	global_store_dword v210, v214, s[14:15]
	s_mov_b64 exec, s[26:27]
	s_waitcnt vmcnt(19)
	v_lshlrev_b32_e32 v202, 16, v186
	v_and_b32_e32 v203, 0xffff0000, v186
	v_lshlrev_b32_e32 v204, 16, v187
	v_and_b32_e32 v205, 0xffff0000, v187
	v_pk_add_f32 v[44:45], v[44:45], v[202:203]
	v_pk_add_f32 v[46:47], v[46:47], v[204:205]
	v_lshlrev_b32_e32 v202, 16, v188
	v_and_b32_e32 v203, 0xffff0000, v188
	v_lshlrev_b32_e32 v204, 16, v189
	v_and_b32_e32 v205, 0xffff0000, v189
	v_pk_add_f32 v[40:41], v[40:41], v[202:203]
	v_pk_add_f32 v[42:43], v[42:43], v[204:205]
	v_cvt_pk_bf16_f32 v186, v44, v45
	v_cvt_pk_bf16_f32 v187, v46, v47
	v_cvt_pk_bf16_f32 v188, v40, v41
	v_cvt_pk_bf16_f32 v189, v42, v43
	v_pk_mul_f32 v[138:139], v[44:45], v[44:45]
	global_store_dwordx4 v207, v[186:189], s[8:9]
	v_pk_fma_f32 v[138:139], v[46:47], v[46:47], v[138:139]
	v_pk_fma_f32 v[138:139], v[40:41], v[40:41], v[138:139]
	v_pk_fma_f32 v[138:139], v[42:43], v[42:43], v[138:139]
	v_lshlrev_b32_e32 v202, 16, v190
	v_and_b32_e32 v203, 0xffff0000, v190
	v_lshlrev_b32_e32 v204, 16, v191
	v_and_b32_e32 v205, 0xffff0000, v191
	v_pk_add_f32 v[36:37], v[36:37], v[202:203]
	v_pk_add_f32 v[38:39], v[38:39], v[204:205]
	v_lshlrev_b32_e32 v202, 16, v192
	v_and_b32_e32 v203, 0xffff0000, v192
	v_lshlrev_b32_e32 v204, 16, v193
	v_and_b32_e32 v205, 0xffff0000, v193
	v_pk_add_f32 v[32:33], v[32:33], v[202:203]
	v_pk_add_f32 v[34:35], v[34:35], v[204:205]
	v_cvt_pk_bf16_f32 v190, v36, v37
	v_cvt_pk_bf16_f32 v191, v38, v39
	v_cvt_pk_bf16_f32 v192, v32, v33
	v_cvt_pk_bf16_f32 v193, v34, v35
	v_pk_fma_f32 v[138:139], v[36:37], v[36:37], v[138:139]
	global_store_dwordx4 v207, v[190:193], s[8:9] offset:256
	v_pk_fma_f32 v[138:139], v[38:39], v[38:39], v[138:139]
	v_pk_fma_f32 v[138:139], v[32:33], v[32:33], v[138:139]
	v_pk_fma_f32 v[138:139], v[34:35], v[34:35], v[138:139]
	v_add_f32_e32 v214, v138, v139
	v_add_u32_e32 v207, 0x8000, v207
	v_mov_b32_e32 v215, v214
	s_nop 1
	v_permlane16_swap_b32_e32 v214, v215
	s_nop 0
	v_add_f32_e32 v214, v214, v215
	v_mov_b32_e32 v215, v214
	s_nop 1
	v_permlane32_swap_b32_e32 v214, v215
	s_nop 0
	v_add_f32_e32 v214, v214, v215
	s_and_saveexec_b64 s[26:27], s[4:5]
	global_store_dword v210, v214, s[14:15] offset:1024
	s_mov_b64 exec, s[26:27]
	s_waitcnt vmcnt(20)
	v_lshlrev_b32_e32 v202, 16, v194
	v_and_b32_e32 v203, 0xffff0000, v194
	v_lshlrev_b32_e32 v204, 16, v195
	v_and_b32_e32 v205, 0xffff0000, v195
	v_pk_add_f32 v[28:29], v[28:29], v[202:203]
	v_pk_add_f32 v[30:31], v[30:31], v[204:205]
	v_lshlrev_b32_e32 v202, 16, v196
	v_and_b32_e32 v203, 0xffff0000, v196
	v_lshlrev_b32_e32 v204, 16, v197
	v_and_b32_e32 v205, 0xffff0000, v197
	v_pk_add_f32 v[24:25], v[24:25], v[202:203]
	v_pk_add_f32 v[26:27], v[26:27], v[204:205]
	v_cvt_pk_bf16_f32 v194, v28, v29
	v_cvt_pk_bf16_f32 v195, v30, v31
	v_cvt_pk_bf16_f32 v196, v24, v25
	v_cvt_pk_bf16_f32 v197, v26, v27
	v_pk_mul_f32 v[138:139], v[28:29], v[28:29]
	global_store_dwordx4 v207, v[194:197], s[8:9]
	v_pk_fma_f32 v[138:139], v[30:31], v[30:31], v[138:139]
	v_pk_fma_f32 v[138:139], v[24:25], v[24:25], v[138:139]
	v_pk_fma_f32 v[138:139], v[26:27], v[26:27], v[138:139]
	v_lshlrev_b32_e32 v202, 16, v198
	v_and_b32_e32 v203, 0xffff0000, v198
	v_lshlrev_b32_e32 v204, 16, v199
	v_and_b32_e32 v205, 0xffff0000, v199
	v_pk_add_f32 v[20:21], v[20:21], v[202:203]
	v_pk_add_f32 v[22:23], v[22:23], v[204:205]
	v_lshlrev_b32_e32 v202, 16, v200
	v_and_b32_e32 v203, 0xffff0000, v200
	v_lshlrev_b32_e32 v204, 16, v201
	v_and_b32_e32 v205, 0xffff0000, v201
	v_pk_add_f32 v[16:17], v[16:17], v[202:203]
	v_pk_add_f32 v[18:19], v[18:19], v[204:205]
	v_cvt_pk_bf16_f32 v198, v20, v21
	v_cvt_pk_bf16_f32 v199, v22, v23
	v_cvt_pk_bf16_f32 v200, v16, v17
	v_cvt_pk_bf16_f32 v201, v18, v19
	v_pk_fma_f32 v[138:139], v[20:21], v[20:21], v[138:139]
	global_store_dwordx4 v207, v[198:201], s[8:9] offset:256
	v_pk_fma_f32 v[138:139], v[22:23], v[22:23], v[138:139]
	v_pk_fma_f32 v[138:139], v[16:17], v[16:17], v[138:139]
	v_pk_fma_f32 v[138:139], v[18:19], v[18:19], v[138:139]
	v_add_f32_e32 v214, v138, v139
	v_add_u32_e32 v207, 0x8000, v207
	v_mov_b32_e32 v215, v214
	s_nop 1
	v_permlane16_swap_b32_e32 v214, v215
	s_nop 0
	v_add_f32_e32 v214, v214, v215
	v_mov_b32_e32 v215, v214
	s_nop 1
	v_permlane32_swap_b32_e32 v214, v215
	s_nop 0
	v_add_f32_e32 v214, v214, v215
	s_and_saveexec_b64 s[26:27], s[4:5]
	global_store_dword v210, v214, s[14:15] offset:2048
	s_mov_b64 exec, s[26:27]
	s_waitcnt vmcnt(18)
	v_lshlrev_b32_e32 v202, 16, v146
	v_and_b32_e32 v203, 0xffff0000, v146
	v_lshlrev_b32_e32 v204, 16, v147
	v_and_b32_e32 v205, 0xffff0000, v147
	v_pk_add_f32 v[12:13], v[12:13], v[202:203]
	v_pk_add_f32 v[14:15], v[14:15], v[204:205]
	v_lshlrev_b32_e32 v202, 16, v148
	v_and_b32_e32 v203, 0xffff0000, v148
	v_lshlrev_b32_e32 v204, 16, v149
	v_and_b32_e32 v205, 0xffff0000, v149
	v_pk_add_f32 v[8:9], v[8:9], v[202:203]
	v_pk_add_f32 v[10:11], v[10:11], v[204:205]
	v_cvt_pk_bf16_f32 v146, v12, v13
	v_cvt_pk_bf16_f32 v147, v14, v15
	v_cvt_pk_bf16_f32 v148, v8, v9
	v_cvt_pk_bf16_f32 v149, v10, v11
	v_pk_mul_f32 v[138:139], v[12:13], v[12:13]
	global_store_dwordx4 v207, v[146:149], s[8:9]
	v_pk_fma_f32 v[138:139], v[14:15], v[14:15], v[138:139]
	v_pk_fma_f32 v[138:139], v[8:9], v[8:9], v[138:139]
	v_pk_fma_f32 v[138:139], v[10:11], v[10:11], v[138:139]
	v_lshlrev_b32_e32 v202, 16, v150
	v_and_b32_e32 v203, 0xffff0000, v150
	v_lshlrev_b32_e32 v204, 16, v151
	v_and_b32_e32 v205, 0xffff0000, v151
	v_pk_add_f32 v[4:5], v[4:5], v[202:203]
	v_pk_add_f32 v[6:7], v[6:7], v[204:205]
	v_lshlrev_b32_e32 v202, 16, v152
	v_and_b32_e32 v203, 0xffff0000, v152
	v_lshlrev_b32_e32 v204, 16, v153
	v_and_b32_e32 v205, 0xffff0000, v153
	v_pk_add_f32 v[0:1], v[0:1], v[202:203]
	v_pk_add_f32 v[2:3], v[2:3], v[204:205]
	v_cvt_pk_bf16_f32 v150, v4, v5
	v_cvt_pk_bf16_f32 v151, v6, v7
	v_cvt_pk_bf16_f32 v152, v0, v1
	v_cvt_pk_bf16_f32 v153, v2, v3
	v_pk_fma_f32 v[138:139], v[4:5], v[4:5], v[138:139]
	global_store_dwordx4 v207, v[150:153], s[8:9] offset:256
	v_pk_fma_f32 v[138:139], v[6:7], v[6:7], v[138:139]
	v_pk_fma_f32 v[138:139], v[0:1], v[0:1], v[138:139]
	v_pk_fma_f32 v[138:139], v[2:3], v[2:3], v[138:139]
	v_add_f32_e32 v214, v138, v139
	v_add_u32_e32 v207, 0x8000, v207
	v_mov_b32_e32 v215, v214
	s_nop 1
	v_permlane16_swap_b32_e32 v214, v215
	s_nop 0
	v_add_f32_e32 v214, v214, v215
	v_mov_b32_e32 v215, v214
	s_nop 1
	v_permlane32_swap_b32_e32 v214, v215
	s_nop 0
	v_add_f32_e32 v214, v214, v215
	s_and_saveexec_b64 s[26:27], s[4:5]
	global_store_dword v210, v214, s[14:15] offset:3072
	s_mov_b64 exec, s[26:27]
	s_branch .LBB0_870

.LBB0_921:
	s_add_u32 s8, s6, 0xfffe0080
	s_addc_u32 s9, s7, -1
	s_add_i32 s84, 0, 0x10000
	v_add_u32_e32 v140, s84, v253
	ds_read_b128 v[128:131], v140
	ds_read_b128 v[132:135], v140 offset:1024
	ds_read_b128 v[136:139], v140 offset:2048
	ds_read_b128 v[140:143], v140 offset:3072
	s_cmp_eq_u32 s73, 12
	s_cselect_b32 s11, s15, s9
	s_cselect_b32 s10, s39, s8
	s_cselect_b32 s9, s65, vcc_hi
	s_cselect_b32 s8, s67, vcc_lo
	s_add_i32 m0, s46, 0xc000
	ds_read_b128 v[144:147], v251
	ds_read_b128 v[148:151], v251 offset:1024
	ds_read_b128 v[152:155], v251 offset:2048
	ds_read_b128 v[156:159], v251 offset:3072
	ds_read_b128 v[160:163], v251 offset:4096
	ds_read_b128 v[164:167], v251 offset:5120
	ds_read_b128 v[168:171], v251 offset:6144
	ds_read_b128 v[172:175], v251 offset:7168
	global_load_lds_dwordx4 v220, s[6:7]
	s_add_i32 m0, s46, 0xe000
	s_nop 0
	global_load_lds_dwordx4 v222, s[6:7]
	s_waitcnt lgkmcnt(8)
	s_barrier
	s_waitcnt lgkmcnt(0)
	v_mfma_f32_16x16x32_bf16 v[124:127], v[128:131], v[144:147], v[124:127]
	v_mfma_f32_16x16x32_bf16 v[120:123], v[136:139], v[144:147], v[120:123]
	v_mfma_f32_16x16x32_bf16 v[92:95], v[128:131], v[152:155], v[92:95]
	v_mfma_f32_16x16x32_bf16 v[44:47], v[136:139], v[152:155], v[44:47]
	v_mfma_f32_16x16x32_bf16 v[84:87], v[128:131], v[160:163], v[84:87]
	v_mfma_f32_16x16x32_bf16 v[40:43], v[136:139], v[160:163], v[40:43]
	v_mfma_f32_16x16x32_bf16 v[76:79], v[128:131], v[168:171], v[76:79]
	v_mfma_f32_16x16x32_bf16 v[36:39], v[136:139], v[168:171], v[36:39]
	v_mfma_f32_16x16x32_bf16 v[124:127], v[132:135], v[148:151], v[124:127]
	v_mfma_f32_16x16x32_bf16 v[120:123], v[140:143], v[148:151], v[120:123]
	v_mfma_f32_16x16x32_bf16 v[92:95], v[132:135], v[156:159], v[92:95]
	v_mfma_f32_16x16x32_bf16 v[44:47], v[140:143], v[156:159], v[44:47]
	v_mfma_f32_16x16x32_bf16 v[84:87], v[132:135], v[164:167], v[84:87]
	v_mfma_f32_16x16x32_bf16 v[40:43], v[140:143], v[164:167], v[40:43]
	v_mfma_f32_16x16x32_bf16 v[76:79], v[132:135], v[172:175], v[76:79]
	v_mfma_f32_16x16x32_bf16 v[36:39], v[140:143], v[172:175], v[36:39]
	s_barrier
	s_add_i32 s86, 0, 0x14000
	s_add_i32 s84, s84, s88
	v_add_u32_e32 v188, s86, v253
	s_add_u32 s98, s8, s40
	s_addc_u32 s99, s9, s41
	s_mov_b32 m0, s84
	ds_read_b128 v[176:179], v188
	ds_read_b128 v[180:183], v188 offset:1024
	ds_read_b128 v[184:187], v188 offset:2048
	ds_read_b128 v[188:191], v188 offset:3072
	global_load_lds_dwordx4 v208, s[8:9]
	s_add_i32 m0, s84, 0x2000
	s_nop 0
	global_load_lds_dwordx4 v214, s[8:9]
	s_barrier
	s_waitcnt lgkmcnt(0)
	v_mfma_f32_16x16x32_bf16 v[116:119], v[176:179], v[144:147], v[116:119]
	v_mfma_f32_16x16x32_bf16 v[112:115], v[184:187], v[144:147], v[112:115]
	v_mfma_f32_16x16x32_bf16 v[88:91], v[176:179], v[152:155], v[88:91]
	v_mfma_f32_16x16x32_bf16 v[32:35], v[184:187], v[152:155], v[32:35]
	v_mfma_f32_16x16x32_bf16 v[80:83], v[176:179], v[160:163], v[80:83]
	v_mfma_f32_16x16x32_bf16 v[28:31], v[184:187], v[160:163], v[28:31]
	v_mfma_f32_16x16x32_bf16 v[72:75], v[176:179], v[168:171], v[72:75]
	v_mfma_f32_16x16x32_bf16 v[24:27], v[184:187], v[168:171], v[24:27]
	v_mfma_f32_16x16x32_bf16 v[116:119], v[180:183], v[148:151], v[116:119]
	v_mfma_f32_16x16x32_bf16 v[112:115], v[188:191], v[148:151], v[112:115]
	v_mfma_f32_16x16x32_bf16 v[88:91], v[180:183], v[156:159], v[88:91]
	v_mfma_f32_16x16x32_bf16 v[32:35], v[188:191], v[156:159], v[32:35]
	v_mfma_f32_16x16x32_bf16 v[80:83], v[180:183], v[164:167], v[80:83]
	v_mfma_f32_16x16x32_bf16 v[28:31], v[188:191], v[164:167], v[28:31]
	v_mfma_f32_16x16x32_bf16 v[72:75], v[180:183], v[172:175], v[72:75]
	v_mfma_f32_16x16x32_bf16 v[24:27], v[188:191], v[172:175], v[24:27]
	s_mov_b32 m0, s46
	s_add_u32 s100, s10, s40
	s_addc_u32 s101, s11, s41
	s_barrier
	ds_read_b128 v[144:147], v251 offset:16384
	ds_read_b128 v[148:151], v251 offset:17408
	ds_read_b128 v[152:155], v251 offset:18432
	ds_read_b128 v[156:159], v251 offset:19456
	ds_read_b128 v[160:163], v251 offset:20480
	ds_read_b128 v[164:167], v251 offset:21504
	ds_read_b128 v[168:171], v251 offset:22528
	ds_read_b128 v[172:175], v251 offset:23552
	global_load_lds_dwordx4 v218, s[10:11]
	s_mov_b32 m0, s50
	s_nop 0
	global_load_lds_dwordx4 v216, s[10:11]
	s_barrier
	s_waitcnt lgkmcnt(0)
	v_mfma_f32_16x16x32_bf16 v[68:71], v[128:131], v[144:147], v[68:71]
	v_mfma_f32_16x16x32_bf16 v[20:23], v[136:139], v[144:147], v[20:23]
	v_mfma_f32_16x16x32_bf16 v[64:67], v[128:131], v[152:155], v[64:67]
	v_mfma_f32_16x16x32_bf16 v[16:19], v[136:139], v[152:155], v[16:19]
	v_mfma_f32_16x16x32_bf16 v[60:63], v[128:131], v[160:163], v[60:63]
	v_mfma_f32_16x16x32_bf16 v[12:15], v[136:139], v[160:163], v[12:15]
	v_mfma_f32_16x16x32_bf16 v[108:111], v[128:131], v[168:171], v[108:111]
	v_mfma_f32_16x16x32_bf16 v[104:107], v[136:139], v[168:171], v[104:107]
	v_mfma_f32_16x16x32_bf16 v[68:71], v[132:135], v[148:151], v[68:71]
	v_mfma_f32_16x16x32_bf16 v[20:23], v[140:143], v[148:151], v[20:23]
	v_mfma_f32_16x16x32_bf16 v[64:67], v[132:135], v[156:159], v[64:67]
	v_mfma_f32_16x16x32_bf16 v[16:19], v[140:143], v[156:159], v[16:19]
	v_mfma_f32_16x16x32_bf16 v[60:63], v[132:135], v[164:167], v[60:63]
	v_mfma_f32_16x16x32_bf16 v[12:15], v[140:143], v[164:167], v[12:15]
	v_mfma_f32_16x16x32_bf16 v[108:111], v[132:135], v[172:175], v[108:111]
	v_mfma_f32_16x16x32_bf16 v[104:107], v[140:143], v[172:175], v[104:107]
	s_barrier
	s_add_u32 s84, s8, 0x40000
	s_addc_u32 s85, s9, 0
	s_add_i32 s86, s86, s88
	s_mov_b32 m0, s86
	s_nop 0
	global_load_lds_dwordx4 v208, s[84:85]
	s_add_i32 m0, s86, 0x2000
	s_nop 0
	global_load_lds_dwordx4 v214, s[84:85]
	s_waitcnt vmcnt(6)
	s_barrier
	v_mfma_f32_16x16x32_bf16 v[56:59], v[176:179], v[144:147], v[56:59]
	v_mfma_f32_16x16x32_bf16 v[8:11], v[184:187], v[144:147], v[8:11]
	v_mfma_f32_16x16x32_bf16 v[52:55], v[176:179], v[152:155], v[52:55]
	v_mfma_f32_16x16x32_bf16 v[4:7], v[184:187], v[152:155], v[4:7]
	v_mfma_f32_16x16x32_bf16 v[48:51], v[176:179], v[160:163], v[48:51]
	v_mfma_f32_16x16x32_bf16 v[0:3], v[184:187], v[160:163], v[0:3]
	v_mfma_f32_16x16x32_bf16 v[100:103], v[176:179], v[168:171], v[100:103]
	v_mfma_f32_16x16x32_bf16 v[96:99], v[184:187], v[168:171], v[96:99]
	v_mfma_f32_16x16x32_bf16 v[56:59], v[180:183], v[148:151], v[56:59]
	v_mfma_f32_16x16x32_bf16 v[8:11], v[188:191], v[148:151], v[8:11]
	v_mfma_f32_16x16x32_bf16 v[52:55], v[180:183], v[156:159], v[52:55]
	v_mfma_f32_16x16x32_bf16 v[4:7], v[188:191], v[156:159], v[4:7]
	v_mfma_f32_16x16x32_bf16 v[48:51], v[180:183], v[164:167], v[48:51]
	v_mfma_f32_16x16x32_bf16 v[0:3], v[188:191], v[164:167], v[0:3]
	v_mfma_f32_16x16x32_bf16 v[100:103], v[180:183], v[172:175], v[100:103]
	v_mfma_f32_16x16x32_bf16 v[96:99], v[188:191], v[172:175], v[96:99]
	s_add_i32 s84, 0, 0x18000
	v_add_u32_e32 v140, s84, v253
	s_barrier
	ds_read_b128 v[128:131], v140
	ds_read_b128 v[132:135], v140 offset:1024
	ds_read_b128 v[136:139], v140 offset:2048
	ds_read_b128 v[140:143], v140 offset:3072
	s_add_u32 s10, s10, 0x20000
	s_addc_u32 s11, s11, 0
	s_mov_b32 m0, s51
	ds_read_b128 v[144:147], v251 offset:32768
	ds_read_b128 v[148:151], v251 offset:33792
	ds_read_b128 v[152:155], v251 offset:34816
	ds_read_b128 v[156:159], v251 offset:35840
	ds_read_b128 v[160:163], v251 offset:36864
	ds_read_b128 v[164:167], v251 offset:37888
	ds_read_b128 v[168:171], v251 offset:38912
	ds_read_b128 v[172:175], v251 offset:39936
	global_load_lds_dwordx4 v218, s[10:11]
	s_mov_b32 m0, s34
	s_nop 0
	global_load_lds_dwordx4 v216, s[10:11]
	s_waitcnt lgkmcnt(8)
	s_barrier
	s_waitcnt lgkmcnt(0)
	v_mfma_f32_16x16x32_bf16 v[124:127], v[128:131], v[144:147], v[124:127]
	v_mfma_f32_16x16x32_bf16 v[120:123], v[136:139], v[144:147], v[120:123]
	v_mfma_f32_16x16x32_bf16 v[92:95], v[128:131], v[152:155], v[92:95]
	v_mfma_f32_16x16x32_bf16 v[44:47], v[136:139], v[152:155], v[44:47]
	v_mfma_f32_16x16x32_bf16 v[84:87], v[128:131], v[160:163], v[84:87]
	v_mfma_f32_16x16x32_bf16 v[40:43], v[136:139], v[160:163], v[40:43]
	v_mfma_f32_16x16x32_bf16 v[76:79], v[128:131], v[168:171], v[76:79]
	v_mfma_f32_16x16x32_bf16 v[36:39], v[136:139], v[168:171], v[36:39]
	v_mfma_f32_16x16x32_bf16 v[124:127], v[132:135], v[148:151], v[124:127]
	v_mfma_f32_16x16x32_bf16 v[120:123], v[140:143], v[148:151], v[120:123]
	v_mfma_f32_16x16x32_bf16 v[92:95], v[132:135], v[156:159], v[92:95]
	v_mfma_f32_16x16x32_bf16 v[44:47], v[140:143], v[156:159], v[44:47]
	v_mfma_f32_16x16x32_bf16 v[84:87], v[132:135], v[164:167], v[84:87]
	v_mfma_f32_16x16x32_bf16 v[40:43], v[140:143], v[164:167], v[40:43]
	v_mfma_f32_16x16x32_bf16 v[76:79], v[132:135], v[172:175], v[76:79]
	v_mfma_f32_16x16x32_bf16 v[36:39], v[140:143], v[172:175], v[36:39]
	s_barrier
	s_add_i32 s10, 0, 0x1c000
	s_add_i32 s11, s84, s88
	v_add_u32_e32 v188, s10, v253
	s_mov_b32 m0, s11
	ds_read_b128 v[176:179], v188
	ds_read_b128 v[180:183], v188 offset:1024
	ds_read_b128 v[184:187], v188 offset:2048
	ds_read_b128 v[188:191], v188 offset:3072
	global_load_lds_dwordx4 v208, s[98:99]
	s_add_i32 m0, s11, 0x2000
	s_nop 0
	global_load_lds_dwordx4 v214, s[98:99]
	s_barrier
	s_waitcnt lgkmcnt(0)
	v_mfma_f32_16x16x32_bf16 v[116:119], v[176:179], v[144:147], v[116:119]
	v_mfma_f32_16x16x32_bf16 v[112:115], v[184:187], v[144:147], v[112:115]
	v_mfma_f32_16x16x32_bf16 v[88:91], v[176:179], v[152:155], v[88:91]
	v_mfma_f32_16x16x32_bf16 v[32:35], v[184:187], v[152:155], v[32:35]
	v_mfma_f32_16x16x32_bf16 v[80:83], v[176:179], v[160:163], v[80:83]
	v_mfma_f32_16x16x32_bf16 v[28:31], v[184:187], v[160:163], v[28:31]
	v_mfma_f32_16x16x32_bf16 v[72:75], v[176:179], v[168:171], v[72:75]
	v_mfma_f32_16x16x32_bf16 v[24:27], v[184:187], v[168:171], v[24:27]
	v_mfma_f32_16x16x32_bf16 v[116:119], v[180:183], v[148:151], v[116:119]
	v_mfma_f32_16x16x32_bf16 v[112:115], v[188:191], v[148:151], v[112:115]
	v_mfma_f32_16x16x32_bf16 v[88:91], v[180:183], v[156:159], v[88:91]
	v_mfma_f32_16x16x32_bf16 v[32:35], v[188:191], v[156:159], v[32:35]
	v_mfma_f32_16x16x32_bf16 v[80:83], v[180:183], v[164:167], v[80:83]
	v_mfma_f32_16x16x32_bf16 v[28:31], v[188:191], v[164:167], v[28:31]
	v_mfma_f32_16x16x32_bf16 v[72:75], v[180:183], v[172:175], v[72:75]
	v_mfma_f32_16x16x32_bf16 v[24:27], v[188:191], v[172:175], v[24:27]
	s_mov_b32 m0, s92
	s_barrier
	ds_read_b128 v[144:147], v251 offset:49152
	ds_read_b128 v[148:151], v251 offset:50176
	ds_read_b128 v[152:155], v251 offset:51200
	ds_read_b128 v[156:159], v251 offset:52224
	ds_read_b128 v[160:163], v251 offset:53248
	ds_read_b128 v[164:167], v251 offset:54272
	ds_read_b128 v[168:171], v251 offset:55296
	ds_read_b128 v[172:175], v251 offset:56320
	global_load_lds_dwordx4 v218, s[100:101]
	s_mov_b32 m0, s93
	s_nop 0
	global_load_lds_dwordx4 v216, s[100:101]
	s_barrier
	s_waitcnt lgkmcnt(0)
	v_mfma_f32_16x16x32_bf16 v[68:71], v[128:131], v[144:147], v[68:71]
	v_mfma_f32_16x16x32_bf16 v[20:23], v[136:139], v[144:147], v[20:23]
	v_mfma_f32_16x16x32_bf16 v[64:67], v[128:131], v[152:155], v[64:67]
	v_mfma_f32_16x16x32_bf16 v[16:19], v[136:139], v[152:155], v[16:19]
	v_mfma_f32_16x16x32_bf16 v[60:63], v[128:131], v[160:163], v[60:63]
	v_mfma_f32_16x16x32_bf16 v[12:15], v[136:139], v[160:163], v[12:15]
	v_mfma_f32_16x16x32_bf16 v[108:111], v[128:131], v[168:171], v[108:111]
	v_mfma_f32_16x16x32_bf16 v[104:107], v[136:139], v[168:171], v[104:107]
	v_mfma_f32_16x16x32_bf16 v[68:71], v[132:135], v[148:151], v[68:71]
	v_mfma_f32_16x16x32_bf16 v[20:23], v[140:143], v[148:151], v[20:23]
	v_mfma_f32_16x16x32_bf16 v[64:67], v[132:135], v[156:159], v[64:67]
	v_mfma_f32_16x16x32_bf16 v[16:19], v[140:143], v[156:159], v[16:19]
	v_mfma_f32_16x16x32_bf16 v[60:63], v[132:135], v[164:167], v[60:63]
	v_mfma_f32_16x16x32_bf16 v[12:15], v[140:143], v[164:167], v[12:15]
	v_mfma_f32_16x16x32_bf16 v[108:111], v[132:135], v[172:175], v[108:111]
	v_mfma_f32_16x16x32_bf16 v[104:107], v[140:143], v[172:175], v[104:107]
	s_barrier
	s_add_u32 s8, s8, 0x40080
	s_addc_u32 s9, s9, 0
	s_add_i32 s10, s10, s88
	s_mov_b32 m0, s10
	s_nop 0
	global_load_lds_dwordx4 v208, s[8:9]
	s_add_i32 m0, s10, 0x2000
	s_nop 0
	global_load_lds_dwordx4 v214, s[8:9]
	s_add_i32 s73, s73, 2
	s_add_u32 s6, s6, 0x100
	s_addc_u32 s7, s7, 0
	s_add_u32 vcc_lo, vcc_lo, 0x100
	s_addc_u32 vcc_hi, vcc_hi, 0
	s_waitcnt vmcnt(6)
	s_barrier
	v_mfma_f32_16x16x32_bf16 v[56:59], v[176:179], v[144:147], v[56:59]
	v_mfma_f32_16x16x32_bf16 v[8:11], v[184:187], v[144:147], v[8:11]
	v_mfma_f32_16x16x32_bf16 v[52:55], v[176:179], v[152:155], v[52:55]
	v_mfma_f32_16x16x32_bf16 v[4:7], v[184:187], v[152:155], v[4:7]
	v_mfma_f32_16x16x32_bf16 v[48:51], v[176:179], v[160:163], v[48:51]
	v_mfma_f32_16x16x32_bf16 v[0:3], v[184:187], v[160:163], v[0:3]
	v_mfma_f32_16x16x32_bf16 v[100:103], v[176:179], v[168:171], v[100:103]
	v_mfma_f32_16x16x32_bf16 v[96:99], v[184:187], v[168:171], v[96:99]
	v_mfma_f32_16x16x32_bf16 v[56:59], v[180:183], v[148:151], v[56:59]
	v_mfma_f32_16x16x32_bf16 v[8:11], v[188:191], v[148:151], v[8:11]
	v_mfma_f32_16x16x32_bf16 v[52:55], v[180:183], v[156:159], v[52:55]
	v_mfma_f32_16x16x32_bf16 v[4:7], v[188:191], v[156:159], v[4:7]
	v_mfma_f32_16x16x32_bf16 v[48:51], v[180:183], v[164:167], v[48:51]
	v_mfma_f32_16x16x32_bf16 v[0:3], v[188:191], v[164:167], v[0:3]
	v_mfma_f32_16x16x32_bf16 v[100:103], v[180:183], v[172:175], v[100:103]
	v_mfma_f32_16x16x32_bf16 v[96:99], v[188:191], v[172:175], v[96:99]
	s_cmp_gt_u32 s73, 13
	s_barrier
	s_cbranch_scc0 .LBB0_921
	s_lshl_b32 s6, s38, 8
	v_mov_b32_e32 v250, v210
	v_mov_b32_e32 v254, v249
	s_add_i32 s6, s6, s90
	v_mov_b64_e32 v[242:243], s[44:45]
	v_add_u32_e32 v234, s6, v254
	v_ashrrev_i32_e32 v235, 31, v234
	v_mbcnt_lo_u32_b32 v212, -1, 0
	v_mbcnt_hi_u32_b32 v212, -1, v212
	v_lshlrev_b32_e32 v244, 6, v234
	v_and_b32_e32 v212, 48, v212
	v_add_u32_e32 v212, v244, v212
	v_add_u32_e32 v213, 0x1000, v212
	v_add_u32_e32 v245, 0x1000, v244
	global_load_dwordx4 v[192:195], v212, s[20:21]
	global_load_dwordx4 v[196:199], v212, s[20:21] offset:1024
	global_load_dwordx4 v[200:203], v213, s[20:21] offset:2048
	global_load_dwordx4 v[204:207], v213, s[20:21] offset:3072
	global_load_dwordx4 v[160:163], v244, s[20:21] offset:2096
	global_load_dwordx4 v[164:167], v244, s[20:21] offset:2080
	global_load_dwordx4 v[176:179], v244, s[20:21] offset:2064
	global_load_dwordx4 v[180:183], v244, s[20:21] offset:2048
	global_load_dwordx4 v[168:171], v244, s[20:21] offset:3120
	global_load_dwordx4 v[172:175], v244, s[20:21] offset:3104
	global_load_dwordx4 v[184:187], v244, s[20:21] offset:3088
	global_load_dwordx4 v[188:191], v244, s[20:21] offset:3072
	global_load_dwordx4 v[144:147], v245, s[20:21] offset:48
	global_load_dwordx4 v[148:151], v245, s[20:21] offset:32
	global_load_dwordx4 v[152:155], v245, s[20:21] offset:16
	global_load_dwordx4 v[156:159], v245, s[20:21]
	global_load_dwordx4 v[128:131], v245, s[20:21] offset:1072
	global_load_dwordx4 v[132:135], v245, s[20:21] offset:1056
	global_load_dwordx4 v[136:139], v245, s[20:21] offset:1040
	global_load_dwordx4 v[140:143], v245, s[20:21] offset:1024
	v_add_u32_e32 v236, 16, v234
	v_ashrrev_i32_e32 v237, 31, v236
	v_add_u32_e32 v238, 32, v234
	v_ashrrev_i32_e32 v239, 31, v238
	v_add_u32_e32 v232, 48, v234
	v_ashrrev_i32_e32 v233, 31, v232
	v_add_u32_e32 v230, 64, v234
	v_ashrrev_i32_e32 v231, 31, v230
	v_add_u32_e32 v228, 0x50, v234
	v_ashrrev_i32_e32 v229, 31, v228
	v_add_u32_e32 v224, 0x60, v234
	v_ashrrev_i32_e32 v225, 31, v224
	v_add_u32_e32 v226, 0x70, v234
	v_ashrrev_i32_e32 v227, 31, v226
	s_lshl_b32 s14, s14, 7
	s_or_b32 s14, s14, s35
	s_waitcnt vmcnt(16)
	v_pk_add_f32 v[192:193], v[192:193], v[194:195]
	s_nop 0
	v_add_f32_e32 v246, v192, v193
	v_mov_b32_e32 v247, v246
	s_nop 1
	v_permlane16_swap_b32_e32 v246, v247
	s_nop 0
	v_add_f32_e32 v246, v246, v247
	v_mov_b32_e32 v247, v246
	s_nop 1
	v_permlane32_swap_b32_e32 v246, v247
	s_nop 0
	v_add_f32_e32 v193, v246, v247
	v_pk_add_f32 v[196:197], v[196:197], v[198:199]
	s_nop 0
	v_add_f32_e32 v246, v196, v197
	v_mov_b32_e32 v247, v246
	s_nop 1
	v_permlane16_swap_b32_e32 v246, v247
	s_nop 0
	v_add_f32_e32 v246, v246, v247
	v_mov_b32_e32 v247, v246
	s_nop 1
	v_permlane32_swap_b32_e32 v246, v247
	s_nop 0
	v_add_f32_e32 v192, v246, v247
	v_pk_add_f32 v[200:201], v[200:201], v[202:203]
	s_nop 0
	v_add_f32_e32 v246, v200, v201
	v_mov_b32_e32 v247, v246
	s_nop 1
	v_permlane16_swap_b32_e32 v246, v247
	s_nop 0
	v_add_f32_e32 v246, v246, v247
	v_mov_b32_e32 v247, v246
	s_nop 1
	v_permlane32_swap_b32_e32 v246, v247
	s_nop 0
	v_add_f32_e32 v197, v246, v247
	v_pk_add_f32 v[204:205], v[204:205], v[206:207]
	s_nop 0
	v_add_f32_e32 v246, v204, v205
	v_mov_b32_e32 v247, v246
	s_nop 1
	v_permlane16_swap_b32_e32 v246, v247
	s_nop 0
	v_add_f32_e32 v246, v246, v247
	v_mov_b32_e32 v247, v246
	s_nop 1
	v_permlane32_swap_b32_e32 v246, v247
	s_nop 0
	v_add_f32_e32 v196, v246, v247
	s_nop 0
	v_pk_fma_f32 v[240:241], v[192:193], s[42:43], v[242:243] op_sel_hi:[1,0,0]
	v_pk_fma_f32 v[202:203], v[196:197], s[42:43], v[242:243] op_sel_hi:[1,0,0]
	v_cmp_gt_f32_e64 s[6:7], s97, v240
	v_cmp_gt_f32_e32 vcc, s97, v241
	s_waitcnt vmcnt(0)
	v_lshl_add_u32 v192, v250, 3, s14
	v_add_u32_e32 v193, -14, v254
	v_cmp_gt_f32_e64 s[8:9], s97, v203
	v_cmp_gt_f32_e64 s[10:11], s97, v202
	v_cmp_lt_u32_e64 s[14:15], -13, v193
	v_ashrrev_i32_e32 v193, 31, v192
	s_and_saveexec_b64 s[86:87], s[14:15]
	s_xor_b64 s[14:15], exec, s[86:87]
	s_or_saveexec_b64 s[14:15], s[14:15]
	v_mul_f32_e32 v194, 0x4b800000, v241
	v_cndmask_b32_e32 v194, v241, v194, vcc
	v_rsq_f32_e32 v194, v194
	s_nop 0
	v_mul_f32_e32 v195, 0x45800000, v194
	v_cndmask_b32_e32 v204, v194, v195, vcc
	v_pk_mul_f32 v[196:197], v[118:119], v[204:205] op_sel_hi:[1,0]
	v_mul_f32_e32 v118, 0x4b800000, v202
	v_cndmask_b32_e64 v118, v202, v118, s[10:11]
	v_rsq_f32_e32 v118, v118
	v_pk_mul_f32 v[200:201], v[116:117], v[204:205] op_sel_hi:[1,0]
	v_pk_mul_f32 v[194:195], v[126:127], v[204:205] op_sel_hi:[1,0]
	v_pk_mul_f32 v[198:199], v[124:125], v[204:205] op_sel_hi:[1,0]
	v_mul_f32_e32 v116, 0x45800000, v118
	v_cndmask_b32_e64 v116, v118, v116, s[10:11]
	v_pk_mul_f32 v[122:123], v[122:123], v[204:205] op_sel_hi:[1,0]
	v_pk_mul_f32 v[120:121], v[120:121], v[204:205] op_sel_hi:[1,0]
	v_pk_mul_f32 v[114:115], v[114:115], v[204:205] op_sel_hi:[1,0]
	v_pk_mul_f32 v[112:113], v[112:113], v[204:205] op_sel_hi:[1,0]
	v_pk_mul_f32 v[110:111], v[110:111], v[116:117] op_sel_hi:[1,0]
	v_pk_mul_f32 v[108:109], v[108:109], v[116:117] op_sel_hi:[1,0]
	v_pk_mul_f32 v[106:107], v[106:107], v[116:117] op_sel_hi:[1,0]
	v_pk_mul_f32 v[104:105], v[104:105], v[116:117] op_sel_hi:[1,0]
	v_pk_mul_f32 v[102:103], v[102:103], v[116:117] op_sel_hi:[1,0]
	v_pk_mul_f32 v[100:101], v[100:101], v[116:117] op_sel_hi:[1,0]
	v_pk_mul_f32 v[98:99], v[98:99], v[116:117] op_sel_hi:[1,0]
	v_pk_mul_f32 v[96:97], v[96:97], v[116:117] op_sel_hi:[1,0]
	s_xor_b64 exec, exec, s[14:15]
	s_cbranch_execz .LBB0_917
	v_add_u32_e32 v116, -12, v254
	v_cmp_gt_i32_e64 s[10:11], 2, v254
	s_lshl_b32 s38, s38, 3
	s_add_i32 s38, s38, s91
	v_cndmask_b32_e64 v116, v116, v254, s[10:11]
	v_add_u32_e32 v126, s38, v116
	v_mov_b64_e32 v[124:125], s[22:23]
	s_movk_i32 s38, 0x5800
	v_mad_i64_i32 v[124:125], s[38:39], v126, s38, v[124:125]
	v_cndmask_b32_e64 v119, v111, v195, s[10:11]
	v_cndmask_b32_e64 v118, v110, v194, s[10:11]
	v_cndmask_b32_e64 v117, v109, v199, s[10:11]
	v_cndmask_b32_e64 v116, v108, v198, s[10:11]
	v_lshl_add_u64 v[124:125], v[192:193], 2, v[124:125]
	s_mov_b64 s[38:39], 0x2c00
	global_store_dwordx4 v[124:125], v[116:119], off
	v_lshl_add_u64 v[126:127], v[124:125], 0, s[38:39]
	s_movk_i32 s38, 0x2000
	v_cndmask_b32_e64 v119, v107, v123, s[10:11]
	v_cndmask_b32_e64 v118, v106, v122, s[10:11]
	v_cndmask_b32_e64 v117, v105, v121, s[10:11]
	v_cndmask_b32_e64 v116, v104, v120, s[10:11]
	global_store_dwordx4 v[124:125], v[116:119], off offset:16
	v_add_co_u32_e32 v124, vcc, s38, v124
	s_nop 0
	v_cndmask_b32_e64 v119, v103, v197, s[10:11]
	v_cndmask_b32_e64 v118, v102, v196, s[10:11]
	v_cndmask_b32_e64 v117, v101, v201, s[10:11]
	v_cndmask_b32_e64 v116, v100, v200, s[10:11]
	v_addc_co_u32_e32 v125, vcc, 0, v125, vcc
	global_store_dwordx4 v[124:125], v[116:119], off offset:3072
	s_nop 1
	v_cndmask_b32_e64 v119, v99, v115, s[10:11]
	v_cndmask_b32_e64 v118, v98, v114, s[10:11]
	v_cndmask_b32_e64 v117, v97, v113, s[10:11]
	v_cndmask_b32_e64 v116, v96, v112, s[10:11]
	global_store_dwordx4 v[126:127], v[116:119], off offset:16
	s_branch .LBB0_917

.LBB0_998:
	s_add_u32 s20, s10, 0x100
	s_addc_u32 s21, s11, 0
	s_add_i32 s60, 0, 0x10000
	v_add_u32_e32 v142, s60, v145
	ds_read_b128 v[138:141], v142
	ds_read_b128 v[148:151], v142 offset:1024
	ds_read_b128 v[152:155], v142 offset:2048
	ds_read_b128 v[156:159], v142 offset:3072
	s_cmp_eq_u32 s59, 40
	s_cselect_b32 s25, s7, s21
	s_cselect_b32 s24, s6, s20
	s_cselect_b32 s23, s9, s58
	s_cselect_b32 s22, s8, s57
	s_add_i32 m0, s34, 0xc000
	ds_read_b128 v[160:163], v147
	ds_read_b128 v[164:167], v147 offset:1024
	ds_read_b128 v[168:171], v147 offset:2048
	ds_read_b128 v[172:175], v147 offset:3072
	ds_read_b128 v[176:179], v147 offset:4096
	ds_read_b128 v[180:183], v147 offset:5120
	ds_read_b128 v[184:187], v147 offset:6144
	ds_read_b128 v[188:191], v147 offset:7168
	global_load_lds_dwordx4 v134, s[10:11]
	s_add_i32 m0, s34, 0xe000
	s_nop 0
	global_load_lds_dwordx4 v136, s[10:11]
	s_waitcnt lgkmcnt(8)
	s_barrier
	s_waitcnt lgkmcnt(0)
	v_mfma_f32_16x16x32_bf16 v[124:127], v[138:141], v[160:163], v[124:127]
	v_mfma_f32_16x16x32_bf16 v[120:123], v[152:155], v[160:163], v[120:123]
	v_mfma_f32_16x16x32_bf16 v[108:111], v[138:141], v[168:171], v[108:111]
	v_mfma_f32_16x16x32_bf16 v[104:107], v[152:155], v[168:171], v[104:107]
	v_mfma_f32_16x16x32_bf16 v[92:95], v[138:141], v[176:179], v[92:95]
	v_mfma_f32_16x16x32_bf16 v[88:91], v[152:155], v[176:179], v[88:91]
	v_mfma_f32_16x16x32_bf16 v[76:79], v[138:141], v[184:187], v[76:79]
	v_mfma_f32_16x16x32_bf16 v[72:75], v[152:155], v[184:187], v[72:75]
	v_mfma_f32_16x16x32_bf16 v[124:127], v[148:151], v[164:167], v[124:127]
	v_mfma_f32_16x16x32_bf16 v[120:123], v[156:159], v[164:167], v[120:123]
	v_mfma_f32_16x16x32_bf16 v[108:111], v[148:151], v[172:175], v[108:111]
	v_mfma_f32_16x16x32_bf16 v[104:107], v[156:159], v[172:175], v[104:107]
	v_mfma_f32_16x16x32_bf16 v[92:95], v[148:151], v[180:183], v[92:95]
	v_mfma_f32_16x16x32_bf16 v[88:91], v[156:159], v[180:183], v[88:91]
	v_mfma_f32_16x16x32_bf16 v[76:79], v[148:151], v[188:191], v[76:79]
	v_mfma_f32_16x16x32_bf16 v[72:75], v[156:159], v[188:191], v[72:75]
	s_barrier
	s_add_i32 s61, 0, 0x14000
	v_add_u32_e32 v142, s61, v145
	s_add_i32 s10, s60, s27
	ds_read_b128 v[192:195], v142
	ds_read_b128 v[196:199], v142 offset:1024
	ds_read_b128 v[200:203], v142 offset:2048
	ds_read_b128 v[204:207], v142 offset:3072
	s_add_u32 s98, s22, s40
	s_addc_u32 s99, s23, s41
	s_mov_b32 m0, s10
	s_nop 0
	global_load_lds_dwordx4 v208, s[22:23]
	s_add_i32 m0, s10, 0x2000
	s_nop 0
	global_load_lds_dwordx4 v128, s[22:23]
	s_barrier
	s_waitcnt lgkmcnt(0)
	v_mfma_f32_16x16x32_bf16 v[116:119], v[192:195], v[160:163], v[116:119]
	v_mfma_f32_16x16x32_bf16 v[112:115], v[200:203], v[160:163], v[112:115]
	v_mfma_f32_16x16x32_bf16 v[100:103], v[192:195], v[168:171], v[100:103]
	v_mfma_f32_16x16x32_bf16 v[96:99], v[200:203], v[168:171], v[96:99]
	v_mfma_f32_16x16x32_bf16 v[84:87], v[192:195], v[176:179], v[84:87]
	v_mfma_f32_16x16x32_bf16 v[80:83], v[200:203], v[176:179], v[80:83]
	v_mfma_f32_16x16x32_bf16 v[68:71], v[192:195], v[184:187], v[68:71]
	v_mfma_f32_16x16x32_bf16 v[64:67], v[200:203], v[184:187], v[64:67]
	v_mfma_f32_16x16x32_bf16 v[116:119], v[196:199], v[164:167], v[116:119]
	v_mfma_f32_16x16x32_bf16 v[112:115], v[204:207], v[164:167], v[112:115]
	v_mfma_f32_16x16x32_bf16 v[100:103], v[196:199], v[172:175], v[100:103]
	v_mfma_f32_16x16x32_bf16 v[96:99], v[204:207], v[172:175], v[96:99]
	v_mfma_f32_16x16x32_bf16 v[84:87], v[196:199], v[180:183], v[84:87]
	v_mfma_f32_16x16x32_bf16 v[80:83], v[204:207], v[180:183], v[80:83]
	v_mfma_f32_16x16x32_bf16 v[68:71], v[196:199], v[188:191], v[68:71]
	v_mfma_f32_16x16x32_bf16 v[64:67], v[204:207], v[188:191], v[64:67]
	s_mov_b32 m0, s34
	s_add_u32 s100, s24, s40
	s_addc_u32 s101, s25, s41
	s_barrier
	ds_read_b128 v[160:163], v147 offset:16384
	ds_read_b128 v[164:167], v147 offset:17408
	ds_read_b128 v[168:171], v147 offset:18432
	ds_read_b128 v[172:175], v147 offset:19456
	ds_read_b128 v[176:179], v147 offset:20480
	ds_read_b128 v[180:183], v147 offset:21504
	ds_read_b128 v[184:187], v147 offset:22528
	ds_read_b128 v[188:191], v147 offset:23552
	global_load_lds_dwordx4 v132, s[24:25]
	s_mov_b32 m0, s35
	s_nop 0
	global_load_lds_dwordx4 v130, s[24:25]
	s_barrier
	s_waitcnt lgkmcnt(0)
	v_mfma_f32_16x16x32_bf16 v[60:63], v[138:141], v[160:163], v[60:63]
	v_mfma_f32_16x16x32_bf16 v[56:59], v[152:155], v[160:163], v[56:59]
	v_mfma_f32_16x16x32_bf16 v[44:47], v[138:141], v[168:171], v[44:47]
	v_mfma_f32_16x16x32_bf16 v[40:43], v[152:155], v[168:171], v[40:43]
	v_mfma_f32_16x16x32_bf16 v[28:31], v[138:141], v[176:179], v[28:31]
	v_mfma_f32_16x16x32_bf16 v[24:27], v[152:155], v[176:179], v[24:27]
	v_mfma_f32_16x16x32_bf16 v[12:15], v[138:141], v[184:187], v[12:15]
	v_mfma_f32_16x16x32_bf16 v[8:11], v[152:155], v[184:187], v[8:11]
	v_mfma_f32_16x16x32_bf16 v[60:63], v[148:151], v[164:167], v[60:63]
	v_mfma_f32_16x16x32_bf16 v[56:59], v[156:159], v[164:167], v[56:59]
	v_mfma_f32_16x16x32_bf16 v[44:47], v[148:151], v[172:175], v[44:47]
	v_mfma_f32_16x16x32_bf16 v[40:43], v[156:159], v[172:175], v[40:43]
	v_mfma_f32_16x16x32_bf16 v[28:31], v[148:151], v[180:183], v[28:31]
	v_mfma_f32_16x16x32_bf16 v[24:27], v[156:159], v[180:183], v[24:27]
	v_mfma_f32_16x16x32_bf16 v[12:15], v[148:151], v[188:191], v[12:15]
	v_mfma_f32_16x16x32_bf16 v[8:11], v[156:159], v[188:191], v[8:11]
	s_barrier
	s_add_u32 s10, s22, 0xb0000
	s_addc_u32 s11, s23, 0
	s_add_i32 s60, s61, s27
	s_mov_b32 m0, s60
	s_nop 0
	global_load_lds_dwordx4 v208, s[10:11]
	s_add_i32 m0, s60, 0x2000
	s_nop 0
	global_load_lds_dwordx4 v128, s[10:11]
	s_waitcnt vmcnt(6)
	s_barrier
	v_mfma_f32_16x16x32_bf16 v[52:55], v[192:195], v[160:163], v[52:55]
	v_mfma_f32_16x16x32_bf16 v[48:51], v[200:203], v[160:163], v[48:51]
	v_mfma_f32_16x16x32_bf16 v[36:39], v[192:195], v[168:171], v[36:39]
	v_mfma_f32_16x16x32_bf16 v[32:35], v[200:203], v[168:171], v[32:35]
	v_mfma_f32_16x16x32_bf16 v[20:23], v[192:195], v[176:179], v[20:23]
	v_mfma_f32_16x16x32_bf16 v[16:19], v[200:203], v[176:179], v[16:19]
	v_mfma_f32_16x16x32_bf16 v[4:7], v[192:195], v[184:187], v[4:7]
	v_mfma_f32_16x16x32_bf16 v[0:3], v[200:203], v[184:187], v[0:3]
	v_mfma_f32_16x16x32_bf16 v[52:55], v[196:199], v[164:167], v[52:55]
	v_mfma_f32_16x16x32_bf16 v[48:51], v[204:207], v[164:167], v[48:51]
	v_mfma_f32_16x16x32_bf16 v[36:39], v[196:199], v[172:175], v[36:39]
	v_mfma_f32_16x16x32_bf16 v[32:35], v[204:207], v[172:175], v[32:35]
	v_mfma_f32_16x16x32_bf16 v[20:23], v[196:199], v[180:183], v[20:23]
	v_mfma_f32_16x16x32_bf16 v[16:19], v[204:207], v[180:183], v[16:19]
	v_mfma_f32_16x16x32_bf16 v[4:7], v[196:199], v[188:191], v[4:7]
	v_mfma_f32_16x16x32_bf16 v[0:3], v[204:207], v[188:191], v[0:3]
	s_add_i32 s60, 0, 0x18000
	v_add_u32_e32 v156, s60, v145
	s_barrier
	ds_read_b128 v[138:141], v156
	ds_read_b128 v[148:151], v156 offset:1024
	ds_read_b128 v[152:155], v156 offset:2048
	ds_read_b128 v[156:159], v156 offset:3072
	s_add_u32 s10, s24, 0xb0000
	s_addc_u32 s11, s25, 0
	s_mov_b32 m0, s36
	ds_read_b128 v[160:163], v147 offset:32768
	ds_read_b128 v[164:167], v147 offset:33792
	ds_read_b128 v[168:171], v147 offset:34816
	ds_read_b128 v[172:175], v147 offset:35840
	ds_read_b128 v[176:179], v147 offset:36864
	ds_read_b128 v[180:183], v147 offset:37888
	ds_read_b128 v[184:187], v147 offset:38912
	ds_read_b128 v[188:191], v147 offset:39936
	global_load_lds_dwordx4 v132, s[10:11]
	s_mov_b32 m0, s46
	s_nop 0
	global_load_lds_dwordx4 v130, s[10:11]
	s_waitcnt lgkmcnt(8)
	s_barrier
	s_waitcnt lgkmcnt(0)
	v_mfma_f32_16x16x32_bf16 v[124:127], v[138:141], v[160:163], v[124:127]
	v_mfma_f32_16x16x32_bf16 v[120:123], v[152:155], v[160:163], v[120:123]
	v_mfma_f32_16x16x32_bf16 v[108:111], v[138:141], v[168:171], v[108:111]
	v_mfma_f32_16x16x32_bf16 v[104:107], v[152:155], v[168:171], v[104:107]
	v_mfma_f32_16x16x32_bf16 v[92:95], v[138:141], v[176:179], v[92:95]
	v_mfma_f32_16x16x32_bf16 v[88:91], v[152:155], v[176:179], v[88:91]
	v_mfma_f32_16x16x32_bf16 v[76:79], v[138:141], v[184:187], v[76:79]
	v_mfma_f32_16x16x32_bf16 v[72:75], v[152:155], v[184:187], v[72:75]
	v_mfma_f32_16x16x32_bf16 v[124:127], v[148:151], v[164:167], v[124:127]
	v_mfma_f32_16x16x32_bf16 v[120:123], v[156:159], v[164:167], v[120:123]
	v_mfma_f32_16x16x32_bf16 v[108:111], v[148:151], v[172:175], v[108:111]
	v_mfma_f32_16x16x32_bf16 v[104:107], v[156:159], v[172:175], v[104:107]
	v_mfma_f32_16x16x32_bf16 v[92:95], v[148:151], v[180:183], v[92:95]
	v_mfma_f32_16x16x32_bf16 v[88:91], v[156:159], v[180:183], v[88:91]
	v_mfma_f32_16x16x32_bf16 v[76:79], v[148:151], v[188:191], v[76:79]
	v_mfma_f32_16x16x32_bf16 v[72:75], v[156:159], v[188:191], v[72:75]
	s_barrier
	s_add_i32 s24, 0, 0x1c000
	s_add_i32 s10, s60, s27
	v_add_u32_e32 v204, s24, v145
	s_mov_b32 m0, s10
	ds_read_b128 v[192:195], v204
	ds_read_b128 v[196:199], v204 offset:1024
	ds_read_b128 v[200:203], v204 offset:2048
	ds_read_b128 v[204:207], v204 offset:3072
	global_load_lds_dwordx4 v208, s[98:99]
	s_add_i32 m0, s10, 0x2000
	s_nop 0
	global_load_lds_dwordx4 v128, s[98:99]
	s_barrier
	s_waitcnt lgkmcnt(0)
	v_mfma_f32_16x16x32_bf16 v[116:119], v[192:195], v[160:163], v[116:119]
	v_mfma_f32_16x16x32_bf16 v[112:115], v[200:203], v[160:163], v[112:115]
	v_mfma_f32_16x16x32_bf16 v[100:103], v[192:195], v[168:171], v[100:103]
	v_mfma_f32_16x16x32_bf16 v[96:99], v[200:203], v[168:171], v[96:99]
	v_mfma_f32_16x16x32_bf16 v[84:87], v[192:195], v[176:179], v[84:87]
	v_mfma_f32_16x16x32_bf16 v[80:83], v[200:203], v[176:179], v[80:83]
	v_mfma_f32_16x16x32_bf16 v[68:71], v[192:195], v[184:187], v[68:71]
	v_mfma_f32_16x16x32_bf16 v[64:67], v[200:203], v[184:187], v[64:67]
	v_mfma_f32_16x16x32_bf16 v[116:119], v[196:199], v[164:167], v[116:119]
	v_mfma_f32_16x16x32_bf16 v[112:115], v[204:207], v[164:167], v[112:115]
	v_mfma_f32_16x16x32_bf16 v[100:103], v[196:199], v[172:175], v[100:103]
	v_mfma_f32_16x16x32_bf16 v[96:99], v[204:207], v[172:175], v[96:99]
	v_mfma_f32_16x16x32_bf16 v[84:87], v[196:199], v[180:183], v[84:87]
	v_mfma_f32_16x16x32_bf16 v[80:83], v[204:207], v[180:183], v[80:83]
	v_mfma_f32_16x16x32_bf16 v[68:71], v[196:199], v[188:191], v[68:71]
	v_mfma_f32_16x16x32_bf16 v[64:67], v[204:207], v[188:191], v[64:67]
	s_mov_b32 m0, s50
	s_barrier
	ds_read_b128 v[160:163], v147 offset:49152
	ds_read_b128 v[164:167], v147 offset:50176
	ds_read_b128 v[168:171], v147 offset:51200
	ds_read_b128 v[172:175], v147 offset:52224
	ds_read_b128 v[176:179], v147 offset:53248
	ds_read_b128 v[180:183], v147 offset:54272
	ds_read_b128 v[184:187], v147 offset:55296
	ds_read_b128 v[188:191], v147 offset:56320
	global_load_lds_dwordx4 v132, s[100:101]
	s_mov_b32 m0, s51
	s_nop 0
	global_load_lds_dwordx4 v130, s[100:101]
	s_barrier
	s_waitcnt lgkmcnt(0)
	v_mfma_f32_16x16x32_bf16 v[60:63], v[138:141], v[160:163], v[60:63]
	v_mfma_f32_16x16x32_bf16 v[56:59], v[152:155], v[160:163], v[56:59]
	v_mfma_f32_16x16x32_bf16 v[44:47], v[138:141], v[168:171], v[44:47]
	v_mfma_f32_16x16x32_bf16 v[40:43], v[152:155], v[168:171], v[40:43]
	v_mfma_f32_16x16x32_bf16 v[28:31], v[138:141], v[176:179], v[28:31]
	v_mfma_f32_16x16x32_bf16 v[24:27], v[152:155], v[176:179], v[24:27]
	v_mfma_f32_16x16x32_bf16 v[12:15], v[138:141], v[184:187], v[12:15]
	v_mfma_f32_16x16x32_bf16 v[8:11], v[152:155], v[184:187], v[8:11]
	v_mfma_f32_16x16x32_bf16 v[60:63], v[148:151], v[164:167], v[60:63]
	v_mfma_f32_16x16x32_bf16 v[56:59], v[156:159], v[164:167], v[56:59]
	v_mfma_f32_16x16x32_bf16 v[44:47], v[148:151], v[172:175], v[44:47]
	v_mfma_f32_16x16x32_bf16 v[40:43], v[156:159], v[172:175], v[40:43]
	v_mfma_f32_16x16x32_bf16 v[28:31], v[148:151], v[180:183], v[28:31]
	v_mfma_f32_16x16x32_bf16 v[24:27], v[156:159], v[180:183], v[24:27]
	v_mfma_f32_16x16x32_bf16 v[12:15], v[148:151], v[188:191], v[12:15]
	v_mfma_f32_16x16x32_bf16 v[8:11], v[156:159], v[188:191], v[8:11]
	s_barrier
	s_add_u32 s10, s22, 0xb0080
	s_addc_u32 s11, s23, 0
	s_add_i32 s22, s24, s27
	s_mov_b32 m0, s22
	s_nop 0
	global_load_lds_dwordx4 v208, s[10:11]
	s_add_i32 m0, s22, 0x2000
	s_nop 0
	global_load_lds_dwordx4 v128, s[10:11]
	s_add_i32 s59, s59, 2
	s_add_u32 s57, s57, 0x100
	s_addc_u32 s58, s58, 0
	s_mov_b64 s[10:11], s[20:21]
	s_waitcnt vmcnt(6)
	s_barrier
	v_mfma_f32_16x16x32_bf16 v[52:55], v[192:195], v[160:163], v[52:55]
	v_mfma_f32_16x16x32_bf16 v[48:51], v[200:203], v[160:163], v[48:51]
	v_mfma_f32_16x16x32_bf16 v[36:39], v[192:195], v[168:171], v[36:39]
	v_mfma_f32_16x16x32_bf16 v[32:35], v[200:203], v[168:171], v[32:35]
	v_mfma_f32_16x16x32_bf16 v[20:23], v[192:195], v[176:179], v[20:23]
	v_mfma_f32_16x16x32_bf16 v[16:19], v[200:203], v[176:179], v[16:19]
	v_mfma_f32_16x16x32_bf16 v[4:7], v[192:195], v[184:187], v[4:7]
	v_mfma_f32_16x16x32_bf16 v[0:3], v[200:203], v[184:187], v[0:3]
	v_mfma_f32_16x16x32_bf16 v[52:55], v[196:199], v[164:167], v[52:55]
	v_mfma_f32_16x16x32_bf16 v[48:51], v[204:207], v[164:167], v[48:51]
	v_mfma_f32_16x16x32_bf16 v[36:39], v[196:199], v[172:175], v[36:39]
	v_mfma_f32_16x16x32_bf16 v[32:35], v[204:207], v[172:175], v[32:35]
	v_mfma_f32_16x16x32_bf16 v[20:23], v[196:199], v[180:183], v[20:23]
	v_mfma_f32_16x16x32_bf16 v[16:19], v[204:207], v[180:183], v[16:19]
	v_mfma_f32_16x16x32_bf16 v[4:7], v[196:199], v[188:191], v[4:7]
	v_mfma_f32_16x16x32_bf16 v[0:3], v[204:207], v[188:191], v[0:3]
	s_cmp_gt_u32 s59, 41
	s_barrier
	s_cbranch_scc0 .LBB0_998
	v_lshl_add_u32 v142, s39, 8, v144
	v_lshl_or_b32 v143, s38, 8, v146
	s_and_b64 vcc, exec, s[4:5]
	s_mov_b32 s38, s53
	s_mov_b32 s39, s56
	s_mov_b64 s[20:21], s[8:9]
	s_mov_b64 s[10:11], s[6:7]
	v_lshl_add_u32 v210, v142, 10, v143
	v_lshlrev_b32_e32 v211, 2, v210
	v_lshlrev_b32_e32 v210, 1, v210
	global_load_dwordx4 v[148:151], v210, s[14:15]
	global_load_dwordx4 v[152:155], v210, s[14:15] offset:256
	v_add_u32_e32 v210, 0x8000, v210
	global_load_dwordx4 v[156:159], v210, s[14:15]
	global_load_dwordx4 v[160:163], v210, s[14:15] offset:256
	v_add_u32_e32 v210, 0x8000, v210
	global_load_dwordx4 v[164:167], v210, s[14:15]
	global_load_dwordx4 v[168:171], v210, s[14:15] offset:256
	v_add_u32_e32 v210, 0x8000, v210
	global_load_dwordx4 v[172:175], v210, s[14:15]
	global_load_dwordx4 v[176:179], v210, s[14:15] offset:256
	v_add_u32_e32 v210, 0x28000, v210
	global_load_dwordx4 v[180:183], v210, s[14:15]
	global_load_dwordx4 v[184:187], v210, s[14:15] offset:256
	v_add_u32_e32 v210, 0x8000, v210
	global_load_dwordx4 v[188:191], v210, s[14:15]
	global_load_dwordx4 v[192:195], v210, s[14:15] offset:256
	v_add_u32_e32 v210, 0x8000, v210
	global_load_dwordx4 v[196:199], v210, s[14:15]
	global_load_dwordx4 v[200:203], v210, s[14:15] offset:256
	v_add_u32_e32 v210, 0x8000, v210
	s_waitcnt vmcnt(12)
	v_lshlrev_b32_e32 v204, 16, v148
	v_and_b32_e32 v205, 0xffff0000, v148
	v_lshlrev_b32_e32 v206, 16, v149
	v_and_b32_e32 v207, 0xffff0000, v149
	v_pk_add_f32 v[124:125], v[124:125], v[204:205]
	v_pk_add_f32 v[126:127], v[126:127], v[206:207]
	v_lshlrev_b32_e32 v204, 16, v150
	v_and_b32_e32 v205, 0xffff0000, v150
	v_lshlrev_b32_e32 v206, 16, v151
	v_and_b32_e32 v207, 0xffff0000, v151
	v_pk_add_f32 v[120:121], v[120:121], v[204:205]
	v_pk_add_f32 v[122:123], v[122:123], v[206:207]
	global_store_dwordx4 v211, v[124:127], s[16:17]
	global_store_dwordx4 v211, v[120:123], s[16:17] offset:16
	v_lshlrev_b32_e32 v204, 16, v152
	v_and_b32_e32 v205, 0xffff0000, v152
	v_lshlrev_b32_e32 v206, 16, v153
	v_and_b32_e32 v207, 0xffff0000, v153
	v_pk_add_f32 v[116:117], v[116:117], v[204:205]
	v_pk_add_f32 v[118:119], v[118:119], v[206:207]
	v_lshlrev_b32_e32 v204, 16, v154
	v_and_b32_e32 v205, 0xffff0000, v154
	v_lshlrev_b32_e32 v206, 16, v155
	v_and_b32_e32 v207, 0xffff0000, v155
	v_pk_add_f32 v[112:113], v[112:113], v[204:205]
	v_pk_add_f32 v[114:115], v[114:115], v[206:207]
	global_store_dwordx4 v211, v[116:119], s[16:17] offset:512
	global_store_dwordx4 v211, v[112:115], s[16:17] offset:528
	v_add_u32_e32 v211, 0x10000, v211
	global_load_dwordx4 v[148:151], v210, s[14:15]
	global_load_dwordx4 v[152:155], v210, s[14:15] offset:256
	s_waitcnt vmcnt(16)
	v_lshlrev_b32_e32 v204, 16, v156
	v_and_b32_e32 v205, 0xffff0000, v156
	v_lshlrev_b32_e32 v206, 16, v157
	v_and_b32_e32 v207, 0xffff0000, v157
	v_pk_add_f32 v[108:109], v[108:109], v[204:205]
	v_pk_add_f32 v[110:111], v[110:111], v[206:207]
	v_lshlrev_b32_e32 v204, 16, v158
	v_and_b32_e32 v205, 0xffff0000, v158
	v_lshlrev_b32_e32 v206, 16, v159
	v_and_b32_e32 v207, 0xffff0000, v159
	v_pk_add_f32 v[104:105], v[104:105], v[204:205]
	v_pk_add_f32 v[106:107], v[106:107], v[206:207]
	global_store_dwordx4 v211, v[108:111], s[16:17]
	global_store_dwordx4 v211, v[104:107], s[16:17] offset:16
	v_lshlrev_b32_e32 v204, 16, v160
	v_and_b32_e32 v205, 0xffff0000, v160
	v_lshlrev_b32_e32 v206, 16, v161
	v_and_b32_e32 v207, 0xffff0000, v161
	v_pk_add_f32 v[100:101], v[100:101], v[204:205]
	v_pk_add_f32 v[102:103], v[102:103], v[206:207]
	v_lshlrev_b32_e32 v204, 16, v162
	v_and_b32_e32 v205, 0xffff0000, v162
	v_lshlrev_b32_e32 v206, 16, v163
	v_and_b32_e32 v207, 0xffff0000, v163
	v_pk_add_f32 v[96:97], v[96:97], v[204:205]
	v_pk_add_f32 v[98:99], v[98:99], v[206:207]
	global_store_dwordx4 v211, v[100:103], s[16:17] offset:512
	global_store_dwordx4 v211, v[96:99], s[16:17] offset:528
	v_add_u32_e32 v211, 0x10000, v211
	s_waitcnt vmcnt(18)
	v_lshlrev_b32_e32 v204, 16, v164
	v_and_b32_e32 v205, 0xffff0000, v164
	v_lshlrev_b32_e32 v206, 16, v165
	v_and_b32_e32 v207, 0xffff0000, v165
	v_pk_add_f32 v[92:93], v[92:93], v[204:205]
	v_pk_add_f32 v[94:95], v[94:95], v[206:207]
	v_lshlrev_b32_e32 v204, 16, v166
	v_and_b32_e32 v205, 0xffff0000, v166
	v_lshlrev_b32_e32 v206, 16, v167
	v_and_b32_e32 v207, 0xffff0000, v167
	v_pk_add_f32 v[88:89], v[88:89], v[204:205]
	v_pk_add_f32 v[90:91], v[90:91], v[206:207]
	global_store_dwordx4 v211, v[92:95], s[16:17]
	global_store_dwordx4 v211, v[88:91], s[16:17] offset:16
	v_lshlrev_b32_e32 v204, 16, v168
	v_and_b32_e32 v205, 0xffff0000, v168
	v_lshlrev_b32_e32 v206, 16, v169
	v_and_b32_e32 v207, 0xffff0000, v169
	v_pk_add_f32 v[84:85], v[84:85], v[204:205]
	v_pk_add_f32 v[86:87], v[86:87], v[206:207]
	v_lshlrev_b32_e32 v204, 16, v170
	v_and_b32_e32 v205, 0xffff0000, v170
	v_lshlrev_b32_e32 v206, 16, v171
	v_and_b32_e32 v207, 0xffff0000, v171
	v_pk_add_f32 v[80:81], v[80:81], v[204:205]
	v_pk_add_f32 v[82:83], v[82:83], v[206:207]
	global_store_dwordx4 v211, v[84:87], s[16:17] offset:512
	global_store_dwordx4 v211, v[80:83], s[16:17] offset:528
	v_add_u32_e32 v211, 0x10000, v211
	s_waitcnt vmcnt(20)
	v_lshlrev_b32_e32 v204, 16, v172
	v_and_b32_e32 v205, 0xffff0000, v172
	v_lshlrev_b32_e32 v206, 16, v173
	v_and_b32_e32 v207, 0xffff0000, v173
	v_pk_add_f32 v[76:77], v[76:77], v[204:205]
	v_pk_add_f32 v[78:79], v[78:79], v[206:207]
	v_lshlrev_b32_e32 v204, 16, v174
	v_and_b32_e32 v205, 0xffff0000, v174
	v_lshlrev_b32_e32 v206, 16, v175
	v_and_b32_e32 v207, 0xffff0000, v175
	v_pk_add_f32 v[72:73], v[72:73], v[204:205]
	v_pk_add_f32 v[74:75], v[74:75], v[206:207]
	global_store_dwordx4 v211, v[76:79], s[16:17]
	global_store_dwordx4 v211, v[72:75], s[16:17] offset:16
	v_lshlrev_b32_e32 v204, 16, v176
	v_and_b32_e32 v205, 0xffff0000, v176
	v_lshlrev_b32_e32 v206, 16, v177
	v_and_b32_e32 v207, 0xffff0000, v177
	v_pk_add_f32 v[68:69], v[68:69], v[204:205]
	v_pk_add_f32 v[70:71], v[70:71], v[206:207]
	v_lshlrev_b32_e32 v204, 16, v178
	v_and_b32_e32 v205, 0xffff0000, v178
	v_lshlrev_b32_e32 v206, 16, v179
	v_and_b32_e32 v207, 0xffff0000, v179
	v_pk_add_f32 v[64:65], v[64:65], v[204:205]
	v_pk_add_f32 v[66:67], v[66:67], v[206:207]
	global_store_dwordx4 v211, v[68:71], s[16:17] offset:512
	global_store_dwordx4 v211, v[64:67], s[16:17] offset:528
	v_add_u32_e32 v211, 0x50000, v211
	s_waitcnt vmcnt(22)
	v_lshlrev_b32_e32 v204, 16, v180
	v_and_b32_e32 v205, 0xffff0000, v180
	v_lshlrev_b32_e32 v206, 16, v181
	v_and_b32_e32 v207, 0xffff0000, v181
	v_pk_add_f32 v[60:61], v[60:61], v[204:205]
	v_pk_add_f32 v[62:63], v[62:63], v[206:207]
	v_lshlrev_b32_e32 v204, 16, v182
	v_and_b32_e32 v205, 0xffff0000, v182
	v_lshlrev_b32_e32 v206, 16, v183
	v_and_b32_e32 v207, 0xffff0000, v183
	v_pk_add_f32 v[56:57], v[56:57], v[204:205]
	v_pk_add_f32 v[58:59], v[58:59], v[206:207]
	global_store_dwordx4 v211, v[60:63], s[16:17]
	global_store_dwordx4 v211, v[56:59], s[16:17] offset:16
	v_lshlrev_b32_e32 v204, 16, v184
	v_and_b32_e32 v205, 0xffff0000, v184
	v_lshlrev_b32_e32 v206, 16, v185
	v_and_b32_e32 v207, 0xffff0000, v185
	v_pk_add_f32 v[52:53], v[52:53], v[204:205]
	v_pk_add_f32 v[54:55], v[54:55], v[206:207]
	v_lshlrev_b32_e32 v204, 16, v186
	v_and_b32_e32 v205, 0xffff0000, v186
	v_lshlrev_b32_e32 v206, 16, v187
	v_and_b32_e32 v207, 0xffff0000, v187
	v_pk_add_f32 v[48:49], v[48:49], v[204:205]
	v_pk_add_f32 v[50:51], v[50:51], v[206:207]
	global_store_dwordx4 v211, v[52:55], s[16:17] offset:512
	global_store_dwordx4 v211, v[48:51], s[16:17] offset:528
	v_add_u32_e32 v211, 0x10000, v211
	s_waitcnt vmcnt(24)
	v_lshlrev_b32_e32 v204, 16, v188
	v_and_b32_e32 v205, 0xffff0000, v188
	v_lshlrev_b32_e32 v206, 16, v189
	v_and_b32_e32 v207, 0xffff0000, v189
	v_pk_add_f32 v[44:45], v[44:45], v[204:205]
	v_pk_add_f32 v[46:47], v[46:47], v[206:207]
	v_lshlrev_b32_e32 v204, 16, v190
	v_and_b32_e32 v205, 0xffff0000, v190
	v_lshlrev_b32_e32 v206, 16, v191
	v_and_b32_e32 v207, 0xffff0000, v191
	v_pk_add_f32 v[40:41], v[40:41], v[204:205]
	v_pk_add_f32 v[42:43], v[42:43], v[206:207]
	global_store_dwordx4 v211, v[44:47], s[16:17]
	global_store_dwordx4 v211, v[40:43], s[16:17] offset:16
	v_lshlrev_b32_e32 v204, 16, v192
	v_and_b32_e32 v205, 0xffff0000, v192
	v_lshlrev_b32_e32 v206, 16, v193
	v_and_b32_e32 v207, 0xffff0000, v193
	v_pk_add_f32 v[36:37], v[36:37], v[204:205]
	v_pk_add_f32 v[38:39], v[38:39], v[206:207]
	v_lshlrev_b32_e32 v204, 16, v194
	v_and_b32_e32 v205, 0xffff0000, v194
	v_lshlrev_b32_e32 v206, 16, v195
	v_and_b32_e32 v207, 0xffff0000, v195
	v_pk_add_f32 v[32:33], v[32:33], v[204:205]
	v_pk_add_f32 v[34:35], v[34:35], v[206:207]
	global_store_dwordx4 v211, v[36:39], s[16:17] offset:512
	global_store_dwordx4 v211, v[32:35], s[16:17] offset:528
	v_add_u32_e32 v211, 0x10000, v211
	s_waitcnt vmcnt(26)
	v_lshlrev_b32_e32 v204, 16, v196
	v_and_b32_e32 v205, 0xffff0000, v196
	v_lshlrev_b32_e32 v206, 16, v197
	v_and_b32_e32 v207, 0xffff0000, v197
	v_pk_add_f32 v[28:29], v[28:29], v[204:205]
	v_pk_add_f32 v[30:31], v[30:31], v[206:207]
	v_lshlrev_b32_e32 v204, 16, v198
	v_and_b32_e32 v205, 0xffff0000, v198
	v_lshlrev_b32_e32 v206, 16, v199
	v_and_b32_e32 v207, 0xffff0000, v199
	v_pk_add_f32 v[24:25], v[24:25], v[204:205]
	v_pk_add_f32 v[26:27], v[26:27], v[206:207]
	global_store_dwordx4 v211, v[28:31], s[16:17]
	global_store_dwordx4 v211, v[24:27], s[16:17] offset:16
	v_lshlrev_b32_e32 v204, 16, v200
	v_and_b32_e32 v205, 0xffff0000, v200
	v_lshlrev_b32_e32 v206, 16, v201
	v_and_b32_e32 v207, 0xffff0000, v201
	v_pk_add_f32 v[20:21], v[20:21], v[204:205]
	v_pk_add_f32 v[22:23], v[22:23], v[206:207]
	v_lshlrev_b32_e32 v204, 16, v202
	v_and_b32_e32 v205, 0xffff0000, v202
	v_lshlrev_b32_e32 v206, 16, v203
	v_and_b32_e32 v207, 0xffff0000, v203
	v_pk_add_f32 v[16:17], v[16:17], v[204:205]
	v_pk_add_f32 v[18:19], v[18:19], v[206:207]
	global_store_dwordx4 v211, v[20:23], s[16:17] offset:512
	global_store_dwordx4 v211, v[16:19], s[16:17] offset:528
	v_add_u32_e32 v211, 0x10000, v211
	s_waitcnt vmcnt(24)
	v_lshlrev_b32_e32 v204, 16, v148
	v_and_b32_e32 v205, 0xffff0000, v148
	v_lshlrev_b32_e32 v206, 16, v149
	v_and_b32_e32 v207, 0xffff0000, v149
	v_pk_add_f32 v[12:13], v[12:13], v[204:205]
	v_pk_add_f32 v[14:15], v[14:15], v[206:207]
	v_lshlrev_b32_e32 v204, 16, v150
	v_and_b32_e32 v205, 0xffff0000, v150
	v_lshlrev_b32_e32 v206, 16, v151
	v_and_b32_e32 v207, 0xffff0000, v151
	v_pk_add_f32 v[8:9], v[8:9], v[204:205]
	v_pk_add_f32 v[10:11], v[10:11], v[206:207]
	global_store_dwordx4 v211, v[12:15], s[16:17]
	global_store_dwordx4 v211, v[8:11], s[16:17] offset:16
	v_lshlrev_b32_e32 v204, 16, v152
	v_and_b32_e32 v205, 0xffff0000, v152
	v_lshlrev_b32_e32 v206, 16, v153
	v_and_b32_e32 v207, 0xffff0000, v153
	v_pk_add_f32 v[4:5], v[4:5], v[204:205]
	v_pk_add_f32 v[6:7], v[6:7], v[206:207]
	v_lshlrev_b32_e32 v204, 16, v154
	v_and_b32_e32 v205, 0xffff0000, v154
	v_lshlrev_b32_e32 v206, 16, v155
	v_and_b32_e32 v207, 0xffff0000, v155
	v_pk_add_f32 v[0:1], v[0:1], v[204:205]
	v_pk_add_f32 v[2:3], v[2:3], v[206:207]
	global_store_dwordx4 v211, v[4:7], s[16:17] offset:512
	global_store_dwordx4 v211, v[0:3], s[16:17] offset:528
	v_add_u32_e32 v211, 0x10000, v211
	s_cbranch_vccz .LBB0_987
	s_waitcnt vmcnt(0)
	s_cmpk_gt_u32 s26, 0xff
	s_cbranch_scc1 .LBB0_1002
	s_barrier

.LBB0_1021:
	s_add_u32 s22, s20, 0x100
	s_addc_u32 s23, s21, 0
	s_add_i32 s62, 0, 0x10000
	v_add_u32_e32 v154, s62, v143
	ds_read_b128 v[138:141], v154
	ds_read_b128 v[146:149], v154 offset:1024
	ds_read_b128 v[150:153], v154 offset:2048
	ds_read_b128 v[154:157], v154 offset:3072
	s_cmp_eq_u32 s61, 40
	s_cselect_b32 s27, s9, s23
	s_cselect_b32 s26, s8, s22
	s_cselect_b32 s25, s11, s60
	s_cselect_b32 s24, s10, s39
	s_add_i32 m0, s46, 0xc000
	ds_read_b128 v[158:161], v145
	ds_read_b128 v[162:165], v145 offset:1024
	ds_read_b128 v[166:169], v145 offset:2048
	ds_read_b128 v[170:173], v145 offset:3072
	ds_read_b128 v[174:177], v145 offset:4096
	ds_read_b128 v[178:181], v145 offset:5120
	ds_read_b128 v[182:185], v145 offset:6144
	ds_read_b128 v[186:189], v145 offset:7168
	global_load_lds_dwordx4 v134, s[20:21]
	s_add_i32 m0, s46, 0xe000
	s_nop 0
	global_load_lds_dwordx4 v136, s[20:21]
	s_waitcnt lgkmcnt(8)
	s_barrier
	s_waitcnt lgkmcnt(0)
	v_mfma_f32_16x16x32_bf16 v[124:127], v[138:141], v[158:161], v[124:127]
	v_mfma_f32_16x16x32_bf16 v[120:123], v[150:153], v[158:161], v[120:123]
	v_mfma_f32_16x16x32_bf16 v[108:111], v[138:141], v[166:169], v[108:111]
	v_mfma_f32_16x16x32_bf16 v[104:107], v[150:153], v[166:169], v[104:107]
	v_mfma_f32_16x16x32_bf16 v[92:95], v[138:141], v[174:177], v[92:95]
	v_mfma_f32_16x16x32_bf16 v[88:91], v[150:153], v[174:177], v[88:91]
	v_mfma_f32_16x16x32_bf16 v[76:79], v[138:141], v[182:185], v[76:79]
	v_mfma_f32_16x16x32_bf16 v[72:75], v[150:153], v[182:185], v[72:75]
	v_mfma_f32_16x16x32_bf16 v[124:127], v[146:149], v[162:165], v[124:127]
	v_mfma_f32_16x16x32_bf16 v[120:123], v[154:157], v[162:165], v[120:123]
	v_mfma_f32_16x16x32_bf16 v[108:111], v[146:149], v[170:173], v[108:111]
	v_mfma_f32_16x16x32_bf16 v[104:107], v[154:157], v[170:173], v[104:107]
	v_mfma_f32_16x16x32_bf16 v[92:95], v[146:149], v[178:181], v[92:95]
	v_mfma_f32_16x16x32_bf16 v[88:91], v[154:157], v[178:181], v[88:91]
	v_mfma_f32_16x16x32_bf16 v[76:79], v[146:149], v[186:189], v[76:79]
	v_mfma_f32_16x16x32_bf16 v[72:75], v[154:157], v[186:189], v[72:75]
	s_barrier
	s_add_i32 s63, 0, 0x14000
	s_add_i32 s20, s62, s35
	v_add_u32_e32 v202, s63, v143
	s_add_u32 s98, s24, s40
	s_addc_u32 s99, s25, s41
	s_mov_b32 m0, s20
	ds_read_b128 v[190:193], v202
	ds_read_b128 v[194:197], v202 offset:1024
	ds_read_b128 v[198:201], v202 offset:2048
	ds_read_b128 v[202:205], v202 offset:3072
	global_load_lds_dwordx4 v208, s[24:25]
	s_add_i32 m0, s20, 0x2000
	s_nop 0
	global_load_lds_dwordx4 v128, s[24:25]
	s_barrier
	s_waitcnt lgkmcnt(0)
	v_mfma_f32_16x16x32_bf16 v[116:119], v[190:193], v[158:161], v[116:119]
	v_mfma_f32_16x16x32_bf16 v[112:115], v[198:201], v[158:161], v[112:115]
	v_mfma_f32_16x16x32_bf16 v[100:103], v[190:193], v[166:169], v[100:103]
	v_mfma_f32_16x16x32_bf16 v[96:99], v[198:201], v[166:169], v[96:99]
	v_mfma_f32_16x16x32_bf16 v[84:87], v[190:193], v[174:177], v[84:87]
	v_mfma_f32_16x16x32_bf16 v[80:83], v[198:201], v[174:177], v[80:83]
	v_mfma_f32_16x16x32_bf16 v[68:71], v[190:193], v[182:185], v[68:71]
	v_mfma_f32_16x16x32_bf16 v[64:67], v[198:201], v[182:185], v[64:67]
	v_mfma_f32_16x16x32_bf16 v[116:119], v[194:197], v[162:165], v[116:119]
	v_mfma_f32_16x16x32_bf16 v[112:115], v[202:205], v[162:165], v[112:115]
	v_mfma_f32_16x16x32_bf16 v[100:103], v[194:197], v[170:173], v[100:103]
	v_mfma_f32_16x16x32_bf16 v[96:99], v[202:205], v[170:173], v[96:99]
	v_mfma_f32_16x16x32_bf16 v[84:87], v[194:197], v[178:181], v[84:87]
	v_mfma_f32_16x16x32_bf16 v[80:83], v[202:205], v[178:181], v[80:83]
	v_mfma_f32_16x16x32_bf16 v[68:71], v[194:197], v[186:189], v[68:71]
	v_mfma_f32_16x16x32_bf16 v[64:67], v[202:205], v[186:189], v[64:67]
	s_mov_b32 m0, s46
	s_add_u32 s100, s26, s40
	s_addc_u32 s101, s27, s41
	s_barrier
	ds_read_b128 v[158:161], v145 offset:16384
	ds_read_b128 v[162:165], v145 offset:17408
	ds_read_b128 v[166:169], v145 offset:18432
	ds_read_b128 v[170:173], v145 offset:19456
	ds_read_b128 v[174:177], v145 offset:20480
	ds_read_b128 v[178:181], v145 offset:21504
	ds_read_b128 v[182:185], v145 offset:22528
	ds_read_b128 v[186:189], v145 offset:23552
	global_load_lds_dwordx4 v132, s[26:27]
	s_mov_b32 m0, s47
	s_nop 0
	global_load_lds_dwordx4 v130, s[26:27]
	s_barrier
	s_waitcnt lgkmcnt(0)
	v_mfma_f32_16x16x32_bf16 v[60:63], v[138:141], v[158:161], v[60:63]
	v_mfma_f32_16x16x32_bf16 v[56:59], v[150:153], v[158:161], v[56:59]
	v_mfma_f32_16x16x32_bf16 v[44:47], v[138:141], v[166:169], v[44:47]
	v_mfma_f32_16x16x32_bf16 v[40:43], v[150:153], v[166:169], v[40:43]
	v_mfma_f32_16x16x32_bf16 v[28:31], v[138:141], v[174:177], v[28:31]
	v_mfma_f32_16x16x32_bf16 v[24:27], v[150:153], v[174:177], v[24:27]
	v_mfma_f32_16x16x32_bf16 v[12:15], v[138:141], v[182:185], v[12:15]
	v_mfma_f32_16x16x32_bf16 v[8:11], v[150:153], v[182:185], v[8:11]
	v_mfma_f32_16x16x32_bf16 v[60:63], v[146:149], v[162:165], v[60:63]
	v_mfma_f32_16x16x32_bf16 v[56:59], v[154:157], v[162:165], v[56:59]
	v_mfma_f32_16x16x32_bf16 v[44:47], v[146:149], v[170:173], v[44:47]
	v_mfma_f32_16x16x32_bf16 v[40:43], v[154:157], v[170:173], v[40:43]
	v_mfma_f32_16x16x32_bf16 v[28:31], v[146:149], v[178:181], v[28:31]
	v_mfma_f32_16x16x32_bf16 v[24:27], v[154:157], v[178:181], v[24:27]
	v_mfma_f32_16x16x32_bf16 v[12:15], v[146:149], v[186:189], v[12:15]
	v_mfma_f32_16x16x32_bf16 v[8:11], v[154:157], v[186:189], v[8:11]
	s_barrier
	s_add_u32 s20, s24, 0xb0000
	s_addc_u32 s21, s25, 0
	s_add_i32 s62, s63, s35
	s_mov_b32 m0, s62
	s_nop 0
	global_load_lds_dwordx4 v208, s[20:21]
	s_add_i32 m0, s62, 0x2000
	s_nop 0
	global_load_lds_dwordx4 v128, s[20:21]
	s_waitcnt vmcnt(6)
	s_barrier
	v_mfma_f32_16x16x32_bf16 v[52:55], v[190:193], v[158:161], v[52:55]
	v_mfma_f32_16x16x32_bf16 v[48:51], v[198:201], v[158:161], v[48:51]
	v_mfma_f32_16x16x32_bf16 v[36:39], v[190:193], v[166:169], v[36:39]
	v_mfma_f32_16x16x32_bf16 v[32:35], v[198:201], v[166:169], v[32:35]
	v_mfma_f32_16x16x32_bf16 v[20:23], v[190:193], v[174:177], v[20:23]
	v_mfma_f32_16x16x32_bf16 v[16:19], v[198:201], v[174:177], v[16:19]
	v_mfma_f32_16x16x32_bf16 v[4:7], v[190:193], v[182:185], v[4:7]
	v_mfma_f32_16x16x32_bf16 v[0:3], v[198:201], v[182:185], v[0:3]
	v_mfma_f32_16x16x32_bf16 v[52:55], v[194:197], v[162:165], v[52:55]
	v_mfma_f32_16x16x32_bf16 v[48:51], v[202:205], v[162:165], v[48:51]
	v_mfma_f32_16x16x32_bf16 v[36:39], v[194:197], v[170:173], v[36:39]
	v_mfma_f32_16x16x32_bf16 v[32:35], v[202:205], v[170:173], v[32:35]
	v_mfma_f32_16x16x32_bf16 v[20:23], v[194:197], v[178:181], v[20:23]
	v_mfma_f32_16x16x32_bf16 v[16:19], v[202:205], v[178:181], v[16:19]
	v_mfma_f32_16x16x32_bf16 v[4:7], v[194:197], v[186:189], v[4:7]
	v_mfma_f32_16x16x32_bf16 v[0:3], v[202:205], v[186:189], v[0:3]
	s_add_i32 s62, 0, 0x18000
	v_add_u32_e32 v154, s62, v143
	s_barrier
	ds_read_b128 v[138:141], v154
	ds_read_b128 v[146:149], v154 offset:1024
	ds_read_b128 v[150:153], v154 offset:2048
	ds_read_b128 v[154:157], v154 offset:3072
	s_add_u32 s20, s26, 0xb0000
	s_addc_u32 s21, s27, 0
	s_mov_b32 m0, s50
	ds_read_b128 v[158:161], v145 offset:32768
	ds_read_b128 v[162:165], v145 offset:33792
	ds_read_b128 v[166:169], v145 offset:34816
	ds_read_b128 v[170:173], v145 offset:35840
	ds_read_b128 v[174:177], v145 offset:36864
	ds_read_b128 v[178:181], v145 offset:37888
	ds_read_b128 v[182:185], v145 offset:38912
	ds_read_b128 v[186:189], v145 offset:39936
	global_load_lds_dwordx4 v132, s[20:21]
	s_mov_b32 m0, s51
	s_nop 0
	global_load_lds_dwordx4 v130, s[20:21]
	s_waitcnt lgkmcnt(8)
	s_barrier
	s_waitcnt lgkmcnt(0)
	v_mfma_f32_16x16x32_bf16 v[124:127], v[138:141], v[158:161], v[124:127]
	v_mfma_f32_16x16x32_bf16 v[120:123], v[150:153], v[158:161], v[120:123]
	v_mfma_f32_16x16x32_bf16 v[108:111], v[138:141], v[166:169], v[108:111]
	v_mfma_f32_16x16x32_bf16 v[104:107], v[150:153], v[166:169], v[104:107]
	v_mfma_f32_16x16x32_bf16 v[92:95], v[138:141], v[174:177], v[92:95]
	v_mfma_f32_16x16x32_bf16 v[88:91], v[150:153], v[174:177], v[88:91]
	v_mfma_f32_16x16x32_bf16 v[76:79], v[138:141], v[182:185], v[76:79]
	v_mfma_f32_16x16x32_bf16 v[72:75], v[150:153], v[182:185], v[72:75]
	v_mfma_f32_16x16x32_bf16 v[124:127], v[146:149], v[162:165], v[124:127]
	v_mfma_f32_16x16x32_bf16 v[120:123], v[154:157], v[162:165], v[120:123]
	v_mfma_f32_16x16x32_bf16 v[108:111], v[146:149], v[170:173], v[108:111]
	v_mfma_f32_16x16x32_bf16 v[104:107], v[154:157], v[170:173], v[104:107]
	v_mfma_f32_16x16x32_bf16 v[92:95], v[146:149], v[178:181], v[92:95]
	v_mfma_f32_16x16x32_bf16 v[88:91], v[154:157], v[178:181], v[88:91]
	v_mfma_f32_16x16x32_bf16 v[76:79], v[146:149], v[186:189], v[76:79]
	v_mfma_f32_16x16x32_bf16 v[72:75], v[154:157], v[186:189], v[72:75]
	s_barrier
	s_add_i32 s26, 0, 0x1c000
	s_add_i32 s20, s62, s35
	v_add_u32_e32 v202, s26, v143
	s_mov_b32 m0, s20
	ds_read_b128 v[190:193], v202
	ds_read_b128 v[194:197], v202 offset:1024
	ds_read_b128 v[198:201], v202 offset:2048
	ds_read_b128 v[202:205], v202 offset:3072
	global_load_lds_dwordx4 v208, s[98:99]
	s_add_i32 m0, s20, 0x2000
	s_nop 0
	global_load_lds_dwordx4 v128, s[98:99]
	s_barrier
	s_waitcnt lgkmcnt(0)
	v_mfma_f32_16x16x32_bf16 v[116:119], v[190:193], v[158:161], v[116:119]
	v_mfma_f32_16x16x32_bf16 v[112:115], v[198:201], v[158:161], v[112:115]
	v_mfma_f32_16x16x32_bf16 v[100:103], v[190:193], v[166:169], v[100:103]
	v_mfma_f32_16x16x32_bf16 v[96:99], v[198:201], v[166:169], v[96:99]
	v_mfma_f32_16x16x32_bf16 v[84:87], v[190:193], v[174:177], v[84:87]
	v_mfma_f32_16x16x32_bf16 v[80:83], v[198:201], v[174:177], v[80:83]
	v_mfma_f32_16x16x32_bf16 v[68:71], v[190:193], v[182:185], v[68:71]
	v_mfma_f32_16x16x32_bf16 v[64:67], v[198:201], v[182:185], v[64:67]
	v_mfma_f32_16x16x32_bf16 v[116:119], v[194:197], v[162:165], v[116:119]
	v_mfma_f32_16x16x32_bf16 v[112:115], v[202:205], v[162:165], v[112:115]
	v_mfma_f32_16x16x32_bf16 v[100:103], v[194:197], v[170:173], v[100:103]
	v_mfma_f32_16x16x32_bf16 v[96:99], v[202:205], v[170:173], v[96:99]
	v_mfma_f32_16x16x32_bf16 v[84:87], v[194:197], v[178:181], v[84:87]
	v_mfma_f32_16x16x32_bf16 v[80:83], v[202:205], v[178:181], v[80:83]
	v_mfma_f32_16x16x32_bf16 v[68:71], v[194:197], v[186:189], v[68:71]
	v_mfma_f32_16x16x32_bf16 v[64:67], v[202:205], v[186:189], v[64:67]
	s_mov_b32 m0, s53
	s_barrier
	ds_read_b128 v[158:161], v145 offset:49152
	ds_read_b128 v[162:165], v145 offset:50176
	ds_read_b128 v[166:169], v145 offset:51200
	ds_read_b128 v[170:173], v145 offset:52224
	ds_read_b128 v[174:177], v145 offset:53248
	ds_read_b128 v[178:181], v145 offset:54272
	ds_read_b128 v[182:185], v145 offset:55296
	ds_read_b128 v[186:189], v145 offset:56320
	global_load_lds_dwordx4 v132, s[100:101]
	s_mov_b32 m0, s56
	s_nop 0
	global_load_lds_dwordx4 v130, s[100:101]
	s_barrier
	s_waitcnt lgkmcnt(0)
	v_mfma_f32_16x16x32_bf16 v[60:63], v[138:141], v[158:161], v[60:63]
	v_mfma_f32_16x16x32_bf16 v[56:59], v[150:153], v[158:161], v[56:59]
	v_mfma_f32_16x16x32_bf16 v[44:47], v[138:141], v[166:169], v[44:47]
	v_mfma_f32_16x16x32_bf16 v[40:43], v[150:153], v[166:169], v[40:43]
	v_mfma_f32_16x16x32_bf16 v[28:31], v[138:141], v[174:177], v[28:31]
	v_mfma_f32_16x16x32_bf16 v[24:27], v[150:153], v[174:177], v[24:27]
	v_mfma_f32_16x16x32_bf16 v[12:15], v[138:141], v[182:185], v[12:15]
	v_mfma_f32_16x16x32_bf16 v[8:11], v[150:153], v[182:185], v[8:11]
	v_mfma_f32_16x16x32_bf16 v[60:63], v[146:149], v[162:165], v[60:63]
	v_mfma_f32_16x16x32_bf16 v[56:59], v[154:157], v[162:165], v[56:59]
	v_mfma_f32_16x16x32_bf16 v[44:47], v[146:149], v[170:173], v[44:47]
	v_mfma_f32_16x16x32_bf16 v[40:43], v[154:157], v[170:173], v[40:43]
	v_mfma_f32_16x16x32_bf16 v[28:31], v[146:149], v[178:181], v[28:31]
	v_mfma_f32_16x16x32_bf16 v[24:27], v[154:157], v[178:181], v[24:27]
	v_mfma_f32_16x16x32_bf16 v[12:15], v[146:149], v[186:189], v[12:15]
	v_mfma_f32_16x16x32_bf16 v[8:11], v[154:157], v[186:189], v[8:11]
	s_barrier
	s_add_u32 s20, s24, 0xb0080
	s_addc_u32 s21, s25, 0
	s_add_i32 s24, s26, s35
	s_mov_b32 m0, s24
	s_nop 0
	global_load_lds_dwordx4 v208, s[20:21]
	s_add_i32 m0, s24, 0x2000
	s_nop 0
	global_load_lds_dwordx4 v128, s[20:21]
	s_add_i32 s61, s61, 2
	s_add_u32 s39, s39, 0x100
	s_addc_u32 s60, s60, 0
	s_mov_b64 s[20:21], s[22:23]
	s_waitcnt vmcnt(6)
	s_barrier
	v_mfma_f32_16x16x32_bf16 v[52:55], v[190:193], v[158:161], v[52:55]
	v_mfma_f32_16x16x32_bf16 v[48:51], v[198:201], v[158:161], v[48:51]
	v_mfma_f32_16x16x32_bf16 v[36:39], v[190:193], v[166:169], v[36:39]
	v_mfma_f32_16x16x32_bf16 v[32:35], v[198:201], v[166:169], v[32:35]
	v_mfma_f32_16x16x32_bf16 v[20:23], v[190:193], v[174:177], v[20:23]
	v_mfma_f32_16x16x32_bf16 v[16:19], v[198:201], v[174:177], v[16:19]
	v_mfma_f32_16x16x32_bf16 v[4:7], v[190:193], v[182:185], v[4:7]
	v_mfma_f32_16x16x32_bf16 v[0:3], v[198:201], v[182:185], v[0:3]
	v_mfma_f32_16x16x32_bf16 v[52:55], v[194:197], v[162:165], v[52:55]
	v_mfma_f32_16x16x32_bf16 v[48:51], v[202:205], v[162:165], v[48:51]
	v_mfma_f32_16x16x32_bf16 v[36:39], v[194:197], v[170:173], v[36:39]
	v_mfma_f32_16x16x32_bf16 v[32:35], v[202:205], v[170:173], v[32:35]
	v_mfma_f32_16x16x32_bf16 v[20:23], v[194:197], v[178:181], v[20:23]
	v_mfma_f32_16x16x32_bf16 v[16:19], v[202:205], v[178:181], v[16:19]
	v_mfma_f32_16x16x32_bf16 v[4:7], v[194:197], v[186:189], v[4:7]
	v_mfma_f32_16x16x32_bf16 v[0:3], v[202:205], v[186:189], v[0:3]
	s_cmp_gt_u32 s61, 41
	s_barrier
	s_cbranch_scc0 .LBB0_1021
	v_lshl_add_u32 v140, s38, 8, v142
	v_lshl_or_b32 v141, s36, 8, v144
	s_lshl_b32 s20, s36, 2
	s_ashr_i32 s21, s20, 31
	s_lshl_b32 s36, s52, 2
	v_lshlrev_b32_e32 v206, 11, v140
	v_lshl_add_u32 v206, v141, 1, v206
	v_lshl_add_u32 v210, v140, 6, s36
	v_lshl_add_u32 v210, s20, 2, v210
	v_mov_b32_e32 v207, v206
	global_load_dwordx4 v[146:149], v206, s[14:15]
	global_load_dwordx4 v[150:153], v206, s[14:15] offset:256
	v_add_u32_e32 v206, 0x8000, v206
	global_load_dwordx4 v[154:157], v206, s[14:15]
	global_load_dwordx4 v[158:161], v206, s[14:15] offset:256
	v_add_u32_e32 v206, 0x8000, v206
	global_load_dwordx4 v[162:165], v206, s[14:15]
	global_load_dwordx4 v[166:169], v206, s[14:15] offset:256
	v_add_u32_e32 v206, 0x8000, v206
	global_load_dwordx4 v[170:173], v206, s[14:15]
	global_load_dwordx4 v[174:177], v206, s[14:15] offset:256
	v_add_u32_e32 v206, 0x28000, v206
	global_load_dwordx4 v[178:181], v206, s[14:15]
	global_load_dwordx4 v[182:185], v206, s[14:15] offset:256
	v_add_u32_e32 v206, 0x8000, v206
	global_load_dwordx4 v[186:189], v206, s[14:15]
	global_load_dwordx4 v[190:193], v206, s[14:15] offset:256
	v_add_u32_e32 v206, 0x8000, v206
	global_load_dwordx4 v[194:197], v206, s[14:15]
	global_load_dwordx4 v[198:201], v206, s[14:15] offset:256
	v_add_u32_e32 v206, 0x8000, v206
	s_waitcnt vmcnt(12)
	v_lshlrev_b32_e32 v202, 16, v146
	v_and_b32_e32 v203, 0xffff0000, v146
	v_lshlrev_b32_e32 v204, 16, v147
	v_and_b32_e32 v205, 0xffff0000, v147
	v_pk_add_f32 v[124:125], v[124:125], v[202:203]
	v_pk_add_f32 v[126:127], v[126:127], v[204:205]
	v_lshlrev_b32_e32 v202, 16, v148
	v_and_b32_e32 v203, 0xffff0000, v148
	v_lshlrev_b32_e32 v204, 16, v149
	v_and_b32_e32 v205, 0xffff0000, v149
	v_pk_add_f32 v[120:121], v[120:121], v[202:203]
	v_pk_add_f32 v[122:123], v[122:123], v[204:205]
	v_cvt_pk_bf16_f32 v146, v124, v125
	v_cvt_pk_bf16_f32 v147, v126, v127
	v_cvt_pk_bf16_f32 v148, v120, v121
	v_cvt_pk_bf16_f32 v149, v122, v123
	v_pk_mul_f32 v[138:139], v[124:125], v[124:125]
	global_store_dwordx4 v207, v[146:149], s[14:15]
	v_pk_fma_f32 v[138:139], v[126:127], v[126:127], v[138:139]
	v_pk_fma_f32 v[138:139], v[120:121], v[120:121], v[138:139]
	v_pk_fma_f32 v[138:139], v[122:123], v[122:123], v[138:139]
	v_lshlrev_b32_e32 v202, 16, v150
	v_and_b32_e32 v203, 0xffff0000, v150
	v_lshlrev_b32_e32 v204, 16, v151
	v_and_b32_e32 v205, 0xffff0000, v151
	v_pk_add_f32 v[116:117], v[116:117], v[202:203]
	v_pk_add_f32 v[118:119], v[118:119], v[204:205]
	v_lshlrev_b32_e32 v202, 16, v152
	v_and_b32_e32 v203, 0xffff0000, v152
	v_lshlrev_b32_e32 v204, 16, v153
	v_and_b32_e32 v205, 0xffff0000, v153
	v_pk_add_f32 v[112:113], v[112:113], v[202:203]
	v_pk_add_f32 v[114:115], v[114:115], v[204:205]
	v_cvt_pk_bf16_f32 v150, v116, v117
	v_cvt_pk_bf16_f32 v151, v118, v119
	v_cvt_pk_bf16_f32 v152, v112, v113
	v_cvt_pk_bf16_f32 v153, v114, v115
	v_pk_fma_f32 v[138:139], v[116:117], v[116:117], v[138:139]
	global_store_dwordx4 v207, v[150:153], s[14:15] offset:256
	v_pk_fma_f32 v[138:139], v[118:119], v[118:119], v[138:139]
	v_pk_fma_f32 v[138:139], v[112:113], v[112:113], v[138:139]
	v_pk_fma_f32 v[138:139], v[114:115], v[114:115], v[138:139]
	v_add_f32_e32 v214, v138, v139
	v_add_u32_e32 v207, 0x8000, v207
	v_mov_b32_e32 v215, v214
	s_nop 1
	v_permlane16_swap_b32_e32 v214, v215
	s_nop 0
	v_add_f32_e32 v214, v214, v215
	v_mov_b32_e32 v215, v214
	s_nop 1
	v_permlane32_swap_b32_e32 v214, v215
	s_nop 0
	v_add_f32_e32 v214, v214, v215
	s_and_saveexec_b64 s[22:23], s[4:5]
	global_store_dword v210, v214, s[16:17]
	s_mov_b64 exec, s[22:23]
	global_load_dwordx4 v[146:149], v206, s[14:15]
	global_load_dwordx4 v[150:153], v206, s[14:15] offset:256
	s_waitcnt vmcnt(15)
	v_lshlrev_b32_e32 v202, 16, v154
	v_and_b32_e32 v203, 0xffff0000, v154
	v_lshlrev_b32_e32 v204, 16, v155
	v_and_b32_e32 v205, 0xffff0000, v155
	v_pk_add_f32 v[108:109], v[108:109], v[202:203]
	v_pk_add_f32 v[110:111], v[110:111], v[204:205]
	v_lshlrev_b32_e32 v202, 16, v156
	v_and_b32_e32 v203, 0xffff0000, v156
	v_lshlrev_b32_e32 v204, 16, v157
	v_and_b32_e32 v205, 0xffff0000, v157
	v_pk_add_f32 v[104:105], v[104:105], v[202:203]
	v_pk_add_f32 v[106:107], v[106:107], v[204:205]
	v_cvt_pk_bf16_f32 v154, v108, v109
	v_cvt_pk_bf16_f32 v155, v110, v111
	v_cvt_pk_bf16_f32 v156, v104, v105
	v_cvt_pk_bf16_f32 v157, v106, v107
	v_pk_mul_f32 v[138:139], v[108:109], v[108:109]
	global_store_dwordx4 v207, v[154:157], s[14:15]
	v_pk_fma_f32 v[138:139], v[110:111], v[110:111], v[138:139]
	v_pk_fma_f32 v[138:139], v[104:105], v[104:105], v[138:139]
	v_pk_fma_f32 v[138:139], v[106:107], v[106:107], v[138:139]
	v_lshlrev_b32_e32 v202, 16, v158
	v_and_b32_e32 v203, 0xffff0000, v158
	v_lshlrev_b32_e32 v204, 16, v159
	v_and_b32_e32 v205, 0xffff0000, v159
	v_pk_add_f32 v[100:101], v[100:101], v[202:203]
	v_pk_add_f32 v[102:103], v[102:103], v[204:205]
	v_lshlrev_b32_e32 v202, 16, v160
	v_and_b32_e32 v203, 0xffff0000, v160
	v_lshlrev_b32_e32 v204, 16, v161
	v_and_b32_e32 v205, 0xffff0000, v161
	v_pk_add_f32 v[96:97], v[96:97], v[202:203]
	v_pk_add_f32 v[98:99], v[98:99], v[204:205]
	v_cvt_pk_bf16_f32 v158, v100, v101
	v_cvt_pk_bf16_f32 v159, v102, v103
	v_cvt_pk_bf16_f32 v160, v96, v97
	v_cvt_pk_bf16_f32 v161, v98, v99
	v_pk_fma_f32 v[138:139], v[100:101], v[100:101], v[138:139]
	global_store_dwordx4 v207, v[158:161], s[14:15] offset:256
	v_pk_fma_f32 v[138:139], v[102:103], v[102:103], v[138:139]
	v_pk_fma_f32 v[138:139], v[96:97], v[96:97], v[138:139]
	v_pk_fma_f32 v[138:139], v[98:99], v[98:99], v[138:139]
	v_add_f32_e32 v214, v138, v139
	v_add_u32_e32 v207, 0x8000, v207
	v_mov_b32_e32 v215, v214
	s_nop 1
	v_permlane16_swap_b32_e32 v214, v215
	s_nop 0
	v_add_f32_e32 v214, v214, v215
	v_mov_b32_e32 v215, v214
	s_nop 1
	v_permlane32_swap_b32_e32 v214, v215
	s_nop 0
	v_add_f32_e32 v214, v214, v215
	s_and_saveexec_b64 s[22:23], s[4:5]
	global_store_dword v210, v214, s[16:17] offset:1024
	s_mov_b64 exec, s[22:23]
	s_waitcnt vmcnt(16)
	v_lshlrev_b32_e32 v202, 16, v162
	v_and_b32_e32 v203, 0xffff0000, v162
	v_lshlrev_b32_e32 v204, 16, v163
	v_and_b32_e32 v205, 0xffff0000, v163
	v_pk_add_f32 v[92:93], v[92:93], v[202:203]
	v_pk_add_f32 v[94:95], v[94:95], v[204:205]
	v_lshlrev_b32_e32 v202, 16, v164
	v_and_b32_e32 v203, 0xffff0000, v164
	v_lshlrev_b32_e32 v204, 16, v165
	v_and_b32_e32 v205, 0xffff0000, v165
	v_pk_add_f32 v[88:89], v[88:89], v[202:203]
	v_pk_add_f32 v[90:91], v[90:91], v[204:205]
	v_cvt_pk_bf16_f32 v162, v92, v93
	v_cvt_pk_bf16_f32 v163, v94, v95
	v_cvt_pk_bf16_f32 v164, v88, v89
	v_cvt_pk_bf16_f32 v165, v90, v91
	v_pk_mul_f32 v[138:139], v[92:93], v[92:93]
	global_store_dwordx4 v207, v[162:165], s[14:15]
	v_pk_fma_f32 v[138:139], v[94:95], v[94:95], v[138:139]
	v_pk_fma_f32 v[138:139], v[88:89], v[88:89], v[138:139]
	v_pk_fma_f32 v[138:139], v[90:91], v[90:91], v[138:139]
	v_lshlrev_b32_e32 v202, 16, v166
	v_and_b32_e32 v203, 0xffff0000, v166
	v_lshlrev_b32_e32 v204, 16, v167
	v_and_b32_e32 v205, 0xffff0000, v167
	v_pk_add_f32 v[84:85], v[84:85], v[202:203]
	v_pk_add_f32 v[86:87], v[86:87], v[204:205]
	v_lshlrev_b32_e32 v202, 16, v168
	v_and_b32_e32 v203, 0xffff0000, v168
	v_lshlrev_b32_e32 v204, 16, v169
	v_and_b32_e32 v205, 0xffff0000, v169
	v_pk_add_f32 v[80:81], v[80:81], v[202:203]
	v_pk_add_f32 v[82:83], v[82:83], v[204:205]
	v_cvt_pk_bf16_f32 v166, v84, v85
	v_cvt_pk_bf16_f32 v167, v86, v87
	v_cvt_pk_bf16_f32 v168, v80, v81
	v_cvt_pk_bf16_f32 v169, v82, v83
	v_pk_fma_f32 v[138:139], v[84:85], v[84:85], v[138:139]
	global_store_dwordx4 v207, v[166:169], s[14:15] offset:256
	v_pk_fma_f32 v[138:139], v[86:87], v[86:87], v[138:139]
	v_pk_fma_f32 v[138:139], v[80:81], v[80:81], v[138:139]
	v_pk_fma_f32 v[138:139], v[82:83], v[82:83], v[138:139]
	v_add_f32_e32 v214, v138, v139
	v_add_u32_e32 v207, 0x8000, v207
	v_mov_b32_e32 v215, v214
	s_nop 1
	v_permlane16_swap_b32_e32 v214, v215
	s_nop 0
	v_add_f32_e32 v214, v214, v215
	v_mov_b32_e32 v215, v214
	s_nop 1
	v_permlane32_swap_b32_e32 v214, v215
	s_nop 0
	v_add_f32_e32 v214, v214, v215
	s_and_saveexec_b64 s[22:23], s[4:5]
	global_store_dword v210, v214, s[16:17] offset:2048
	s_mov_b64 exec, s[22:23]
	s_waitcnt vmcnt(17)
	v_lshlrev_b32_e32 v202, 16, v170
	v_and_b32_e32 v203, 0xffff0000, v170
	v_lshlrev_b32_e32 v204, 16, v171
	v_and_b32_e32 v205, 0xffff0000, v171
	v_pk_add_f32 v[76:77], v[76:77], v[202:203]
	v_pk_add_f32 v[78:79], v[78:79], v[204:205]
	v_lshlrev_b32_e32 v202, 16, v172
	v_and_b32_e32 v203, 0xffff0000, v172
	v_lshlrev_b32_e32 v204, 16, v173
	v_and_b32_e32 v205, 0xffff0000, v173
	v_pk_add_f32 v[72:73], v[72:73], v[202:203]
	v_pk_add_f32 v[74:75], v[74:75], v[204:205]
	v_cvt_pk_bf16_f32 v170, v76, v77
	v_cvt_pk_bf16_f32 v171, v78, v79
	v_cvt_pk_bf16_f32 v172, v72, v73
	v_cvt_pk_bf16_f32 v173, v74, v75
	v_pk_mul_f32 v[138:139], v[76:77], v[76:77]
	global_store_dwordx4 v207, v[170:173], s[14:15]
	v_pk_fma_f32 v[138:139], v[78:79], v[78:79], v[138:139]
	v_pk_fma_f32 v[138:139], v[72:73], v[72:73], v[138:139]
	v_pk_fma_f32 v[138:139], v[74:75], v[74:75], v[138:139]
	v_lshlrev_b32_e32 v202, 16, v174
	v_and_b32_e32 v203, 0xffff0000, v174
	v_lshlrev_b32_e32 v204, 16, v175
	v_and_b32_e32 v205, 0xffff0000, v175
	v_pk_add_f32 v[68:69], v[68:69], v[202:203]
	v_pk_add_f32 v[70:71], v[70:71], v[204:205]
	v_lshlrev_b32_e32 v202, 16, v176
	v_and_b32_e32 v203, 0xffff0000, v176
	v_lshlrev_b32_e32 v204, 16, v177
	v_and_b32_e32 v205, 0xffff0000, v177
	v_pk_add_f32 v[64:65], v[64:65], v[202:203]
	v_pk_add_f32 v[66:67], v[66:67], v[204:205]
	v_cvt_pk_bf16_f32 v174, v68, v69
	v_cvt_pk_bf16_f32 v175, v70, v71
	v_cvt_pk_bf16_f32 v176, v64, v65
	v_cvt_pk_bf16_f32 v177, v66, v67
	v_pk_fma_f32 v[138:139], v[68:69], v[68:69], v[138:139]
	global_store_dwordx4 v207, v[174:177], s[14:15] offset:256
	v_pk_fma_f32 v[138:139], v[70:71], v[70:71], v[138:139]
	v_pk_fma_f32 v[138:139], v[64:65], v[64:65], v[138:139]
	v_pk_fma_f32 v[138:139], v[66:67], v[66:67], v[138:139]
	v_add_f32_e32 v214, v138, v139
	v_add_u32_e32 v207, 0x28000, v207
	v_mov_b32_e32 v215, v214
	s_nop 1
	v_permlane16_swap_b32_e32 v214, v215
	s_nop 0
	v_add_f32_e32 v214, v214, v215
	v_mov_b32_e32 v215, v214
	s_nop 1
	v_permlane32_swap_b32_e32 v214, v215
	s_nop 0
	v_add_f32_e32 v214, v214, v215
	s_and_saveexec_b64 s[22:23], s[4:5]
	global_store_dword v210, v214, s[16:17] offset:3072
	s_mov_b64 exec, s[22:23]
	v_add_u32_e32 v210, 0x2000, v210
	s_waitcnt vmcnt(18)
	v_lshlrev_b32_e32 v202, 16, v178
	v_and_b32_e32 v203, 0xffff0000, v178
	v_lshlrev_b32_e32 v204, 16, v179
	v_and_b32_e32 v205, 0xffff0000, v179
	v_pk_add_f32 v[60:61], v[60:61], v[202:203]
	v_pk_add_f32 v[62:63], v[62:63], v[204:205]
	v_lshlrev_b32_e32 v202, 16, v180
	v_and_b32_e32 v203, 0xffff0000, v180
	v_lshlrev_b32_e32 v204, 16, v181
	v_and_b32_e32 v205, 0xffff0000, v181
	v_pk_add_f32 v[56:57], v[56:57], v[202:203]
	v_pk_add_f32 v[58:59], v[58:59], v[204:205]
	v_cvt_pk_bf16_f32 v178, v60, v61
	v_cvt_pk_bf16_f32 v179, v62, v63
	v_cvt_pk_bf16_f32 v180, v56, v57
	v_cvt_pk_bf16_f32 v181, v58, v59
	v_pk_mul_f32 v[138:139], v[60:61], v[60:61]
	global_store_dwordx4 v207, v[178:181], s[14:15]
	v_pk_fma_f32 v[138:139], v[62:63], v[62:63], v[138:139]
	v_pk_fma_f32 v[138:139], v[56:57], v[56:57], v[138:139]
	v_pk_fma_f32 v[138:139], v[58:59], v[58:59], v[138:139]
	v_lshlrev_b32_e32 v202, 16, v182
	v_and_b32_e32 v203, 0xffff0000, v182
	v_lshlrev_b32_e32 v204, 16, v183
	v_and_b32_e32 v205, 0xffff0000, v183
	v_pk_add_f32 v[52:53], v[52:53], v[202:203]
	v_pk_add_f32 v[54:55], v[54:55], v[204:205]
	v_lshlrev_b32_e32 v202, 16, v184
	v_and_b32_e32 v203, 0xffff0000, v184
	v_lshlrev_b32_e32 v204, 16, v185
	v_and_b32_e32 v205, 0xffff0000, v185
	v_pk_add_f32 v[48:49], v[48:49], v[202:203]
	v_pk_add_f32 v[50:51], v[50:51], v[204:205]
	v_cvt_pk_bf16_f32 v182, v52, v53
	v_cvt_pk_bf16_f32 v183, v54, v55
	v_cvt_pk_bf16_f32 v184, v48, v49
	v_cvt_pk_bf16_f32 v185, v50, v51
	v_pk_fma_f32 v[138:139], v[52:53], v[52:53], v[138:139]
	global_store_dwordx4 v207, v[182:185], s[14:15] offset:256
	v_pk_fma_f32 v[138:139], v[54:55], v[54:55], v[138:139]
	v_pk_fma_f32 v[138:139], v[48:49], v[48:49], v[138:139]
	v_pk_fma_f32 v[138:139], v[50:51], v[50:51], v[138:139]
	v_add_f32_e32 v214, v138, v139
	v_add_u32_e32 v207, 0x8000, v207
	v_mov_b32_e32 v215, v214
	s_nop 1
	v_permlane16_swap_b32_e32 v214, v215
	s_nop 0
	v_add_f32_e32 v214, v214, v215
	v_mov_b32_e32 v215, v214
	s_nop 1
	v_permlane32_swap_b32_e32 v214, v215
	s_nop 0
	v_add_f32_e32 v214, v214, v215
	s_and_saveexec_b64 s[22:23], s[4:5]
	global_store_dword v210, v214, s[16:17]
	s_mov_b64 exec, s[22:23]
	s_waitcnt vmcnt(19)
	v_lshlrev_b32_e32 v202, 16, v186
	v_and_b32_e32 v203, 0xffff0000, v186
	v_lshlrev_b32_e32 v204, 16, v187
	v_and_b32_e32 v205, 0xffff0000, v187
	v_pk_add_f32 v[44:45], v[44:45], v[202:203]
	v_pk_add_f32 v[46:47], v[46:47], v[204:205]
	v_lshlrev_b32_e32 v202, 16, v188
	v_and_b32_e32 v203, 0xffff0000, v188
	v_lshlrev_b32_e32 v204, 16, v189
	v_and_b32_e32 v205, 0xffff0000, v189
	v_pk_add_f32 v[40:41], v[40:41], v[202:203]
	v_pk_add_f32 v[42:43], v[42:43], v[204:205]
	v_cvt_pk_bf16_f32 v186, v44, v45
	v_cvt_pk_bf16_f32 v187, v46, v47
	v_cvt_pk_bf16_f32 v188, v40, v41
	v_cvt_pk_bf16_f32 v189, v42, v43
	v_pk_mul_f32 v[138:139], v[44:45], v[44:45]
	global_store_dwordx4 v207, v[186:189], s[14:15]
	v_pk_fma_f32 v[138:139], v[46:47], v[46:47], v[138:139]
	v_pk_fma_f32 v[138:139], v[40:41], v[40:41], v[138:139]
	v_pk_fma_f32 v[138:139], v[42:43], v[42:43], v[138:139]
	v_lshlrev_b32_e32 v202, 16, v190
	v_and_b32_e32 v203, 0xffff0000, v190
	v_lshlrev_b32_e32 v204, 16, v191
	v_and_b32_e32 v205, 0xffff0000, v191
	v_pk_add_f32 v[36:37], v[36:37], v[202:203]
	v_pk_add_f32 v[38:39], v[38:39], v[204:205]
	v_lshlrev_b32_e32 v202, 16, v192
	v_and_b32_e32 v203, 0xffff0000, v192
	v_lshlrev_b32_e32 v204, 16, v193
	v_and_b32_e32 v205, 0xffff0000, v193
	v_pk_add_f32 v[32:33], v[32:33], v[202:203]
	v_pk_add_f32 v[34:35], v[34:35], v[204:205]
	v_cvt_pk_bf16_f32 v190, v36, v37
	v_cvt_pk_bf16_f32 v191, v38, v39
	v_cvt_pk_bf16_f32 v192, v32, v33
	v_cvt_pk_bf16_f32 v193, v34, v35
	v_pk_fma_f32 v[138:139], v[36:37], v[36:37], v[138:139]
	global_store_dwordx4 v207, v[190:193], s[14:15] offset:256
	v_pk_fma_f32 v[138:139], v[38:39], v[38:39], v[138:139]
	v_pk_fma_f32 v[138:139], v[32:33], v[32:33], v[138:139]
	v_pk_fma_f32 v[138:139], v[34:35], v[34:35], v[138:139]
	v_add_f32_e32 v214, v138, v139
	v_add_u32_e32 v207, 0x8000, v207
	v_mov_b32_e32 v215, v214
	s_nop 1
	v_permlane16_swap_b32_e32 v214, v215
	s_nop 0
	v_add_f32_e32 v214, v214, v215
	v_mov_b32_e32 v215, v214
	s_nop 1
	v_permlane32_swap_b32_e32 v214, v215
	s_nop 0
	v_add_f32_e32 v214, v214, v215
	s_and_saveexec_b64 s[22:23], s[4:5]
	global_store_dword v210, v214, s[16:17] offset:1024
	s_mov_b64 exec, s[22:23]
	s_waitcnt vmcnt(20)
	v_lshlrev_b32_e32 v202, 16, v194
	v_and_b32_e32 v203, 0xffff0000, v194
	v_lshlrev_b32_e32 v204, 16, v195
	v_and_b32_e32 v205, 0xffff0000, v195
	v_pk_add_f32 v[28:29], v[28:29], v[202:203]
	v_pk_add_f32 v[30:31], v[30:31], v[204:205]
	v_lshlrev_b32_e32 v202, 16, v196
	v_and_b32_e32 v203, 0xffff0000, v196
	v_lshlrev_b32_e32 v204, 16, v197
	v_and_b32_e32 v205, 0xffff0000, v197
	v_pk_add_f32 v[24:25], v[24:25], v[202:203]
	v_pk_add_f32 v[26:27], v[26:27], v[204:205]
	v_cvt_pk_bf16_f32 v194, v28, v29
	v_cvt_pk_bf16_f32 v195, v30, v31
	v_cvt_pk_bf16_f32 v196, v24, v25
	v_cvt_pk_bf16_f32 v197, v26, v27
	v_pk_mul_f32 v[138:139], v[28:29], v[28:29]
	global_store_dwordx4 v207, v[194:197], s[14:15]
	v_pk_fma_f32 v[138:139], v[30:31], v[30:31], v[138:139]
	v_pk_fma_f32 v[138:139], v[24:25], v[24:25], v[138:139]
	v_pk_fma_f32 v[138:139], v[26:27], v[26:27], v[138:139]
	v_lshlrev_b32_e32 v202, 16, v198
	v_and_b32_e32 v203, 0xffff0000, v198
	v_lshlrev_b32_e32 v204, 16, v199
	v_and_b32_e32 v205, 0xffff0000, v199
	v_pk_add_f32 v[20:21], v[20:21], v[202:203]
	v_pk_add_f32 v[22:23], v[22:23], v[204:205]
	v_lshlrev_b32_e32 v202, 16, v200
	v_and_b32_e32 v203, 0xffff0000, v200
	v_lshlrev_b32_e32 v204, 16, v201
	v_and_b32_e32 v205, 0xffff0000, v201
	v_pk_add_f32 v[16:17], v[16:17], v[202:203]
	v_pk_add_f32 v[18:19], v[18:19], v[204:205]
	v_cvt_pk_bf16_f32 v198, v20, v21
	v_cvt_pk_bf16_f32 v199, v22, v23
	v_cvt_pk_bf16_f32 v200, v16, v17
	v_cvt_pk_bf16_f32 v201, v18, v19
	v_pk_fma_f32 v[138:139], v[20:21], v[20:21], v[138:139]
	global_store_dwordx4 v207, v[198:201], s[14:15] offset:256
	v_pk_fma_f32 v[138:139], v[22:23], v[22:23], v[138:139]
	v_pk_fma_f32 v[138:139], v[16:17], v[16:17], v[138:139]
	v_pk_fma_f32 v[138:139], v[18:19], v[18:19], v[138:139]
	v_add_f32_e32 v214, v138, v139
	v_add_u32_e32 v207, 0x8000, v207
	v_mov_b32_e32 v215, v214
	s_nop 1
	v_permlane16_swap_b32_e32 v214, v215
	s_nop 0
	v_add_f32_e32 v214, v214, v215
	v_mov_b32_e32 v215, v214
	s_nop 1
	v_permlane32_swap_b32_e32 v214, v215
	s_nop 0
	v_add_f32_e32 v214, v214, v215
	s_and_saveexec_b64 s[22:23], s[4:5]
	global_store_dword v210, v214, s[16:17] offset:2048
	s_mov_b64 exec, s[22:23]
	s_waitcnt vmcnt(18)
	v_lshlrev_b32_e32 v202, 16, v146
	v_and_b32_e32 v203, 0xffff0000, v146
	v_lshlrev_b32_e32 v204, 16, v147
	v_and_b32_e32 v205, 0xffff0000, v147
	v_pk_add_f32 v[12:13], v[12:13], v[202:203]
	v_pk_add_f32 v[14:15], v[14:15], v[204:205]
	v_lshlrev_b32_e32 v202, 16, v148
	v_and_b32_e32 v203, 0xffff0000, v148
	v_lshlrev_b32_e32 v204, 16, v149
	v_and_b32_e32 v205, 0xffff0000, v149
	v_pk_add_f32 v[8:9], v[8:9], v[202:203]
	v_pk_add_f32 v[10:11], v[10:11], v[204:205]
	v_cvt_pk_bf16_f32 v146, v12, v13
	v_cvt_pk_bf16_f32 v147, v14, v15
	v_cvt_pk_bf16_f32 v148, v8, v9
	v_cvt_pk_bf16_f32 v149, v10, v11
	v_pk_mul_f32 v[138:139], v[12:13], v[12:13]
	global_store_dwordx4 v207, v[146:149], s[14:15]
	v_pk_fma_f32 v[138:139], v[14:15], v[14:15], v[138:139]
	v_pk_fma_f32 v[138:139], v[8:9], v[8:9], v[138:139]
	v_pk_fma_f32 v[138:139], v[10:11], v[10:11], v[138:139]
	v_lshlrev_b32_e32 v202, 16, v150
	v_and_b32_e32 v203, 0xffff0000, v150
	v_lshlrev_b32_e32 v204, 16, v151
	v_and_b32_e32 v205, 0xffff0000, v151
	v_pk_add_f32 v[4:5], v[4:5], v[202:203]
	v_pk_add_f32 v[6:7], v[6:7], v[204:205]
	v_lshlrev_b32_e32 v202, 16, v152
	v_and_b32_e32 v203, 0xffff0000, v152
	v_lshlrev_b32_e32 v204, 16, v153
	v_and_b32_e32 v205, 0xffff0000, v153
	v_pk_add_f32 v[0:1], v[0:1], v[202:203]
	v_pk_add_f32 v[2:3], v[2:3], v[204:205]
	v_cvt_pk_bf16_f32 v150, v4, v5
	v_cvt_pk_bf16_f32 v151, v6, v7
	v_cvt_pk_bf16_f32 v152, v0, v1
	v_cvt_pk_bf16_f32 v153, v2, v3
	v_pk_fma_f32 v[138:139], v[4:5], v[4:5], v[138:139]
	global_store_dwordx4 v207, v[150:153], s[14:15] offset:256
	v_pk_fma_f32 v[138:139], v[6:7], v[6:7], v[138:139]
	v_pk_fma_f32 v[138:139], v[0:1], v[0:1], v[138:139]
	v_pk_fma_f32 v[138:139], v[2:3], v[2:3], v[138:139]
	v_add_f32_e32 v214, v138, v139
	v_add_u32_e32 v207, 0x8000, v207
	v_mov_b32_e32 v215, v214
	s_nop 1
	v_permlane16_swap_b32_e32 v214, v215
	s_nop 0
	v_add_f32_e32 v214, v214, v215
	v_mov_b32_e32 v215, v214
	s_nop 1
	v_permlane32_swap_b32_e32 v214, v215
	s_nop 0
	v_add_f32_e32 v214, v214, v215
	s_and_saveexec_b64 s[22:23], s[4:5]
	global_store_dword v210, v214, s[16:17] offset:3072
	s_mov_b64 exec, s[22:23]
	s_branch .LBB0_1009
